# v45
# speedup vs baseline: 1.0150x; 1.0150x over previous
; #define PG8_STAGE(bufoff, gbase, voff) do { _Pragma("unroll") for (int _i = 0; _i < 2; ++_i) \
;         __builtin_amdgcn_global_load_lds((const unsigned*)((const char*)(gbase) + (voff)[_i]), (PG8_LAS unsigned*)(lds + (bufoff) + ldsw + _i * 8192), 16, 0, 0); } while (0)
; #define PG8_LDA(dst, b, h) do { _Pragma("unroll") for (int m = 0; m < 4; ++m) _Pragma("unroll") for (int k = 0; k < 2; ++k) dst[m][k] = *(const PG8_LAS bf16x8*)(lds + PG8_SA(b, h) + aoff + m * 2048 + k * 1024); } while (0)
; template <class Epi, class Sched, bool ALIGN_EPI = false, bool SP2 = false>
; __device__ __forceinline__ void gemm_phase(PG8_LAS unsigned char* lds, const Gemm g, const Sched& S, const Epi& E) {
;     ...
;         const bool has_next = S.next(ui + 1, nxt);
;         const char* nA = has_next ? (const char*)g.A + (size_t)nxt.pm * tstep : cA; const char* nB = has_next ? (const char*)g.Bt + (size_t)nxt.pn * tstep : cB;
;         for (int t = 0; t < nt; t += 2) {
;             const bool last = (t == nt - 2);
;             const char* a1 = cA + (size_t)(t + 1) * kstep;
;             const char* a2 = last ? nA : cA + (size_t)(t + 2) * kstep; const char* b2 = last ? nB : cB + (size_t)(t + 2) * kstep;
;             const char* a3 = a2 + kstep; const char* b3 = b2 + kstep;
;             if (last && has_next) S.a_ready(nxt);
;             if constexpr (SP2) {
;             PG8_LDB(B0, 0, 0); PG8_LDB(B1, 0, 1); PG8_SCHED; PG8_LDA(At, 0, 0); PG8_STAGE(PG8_SA(1, 1), a1 + hstep, voffA);
;             PG8_WAIT_V(8); PG8_WAIT_L(0); PG8_BAR; PG8_MMA(0, 0, At, B0); PG8_MMA(0, 1, At, B1); PG8_BAR; PG8_SCHED;
;             PG8_LDA(At, 0, 1); PG8_STAGE(PG8_SB(0, 0), b2, voffB); PG8_STAGE(PG8_SB(0, 1), b2 + hstep, voffB); PG8_STAGE(PG8_SA(0, 0), a2, voffA);
;             PG8_WAIT_V(8); PG8_WAIT_L(0); PG8_BAR; PG8_MMA(1, 0, At, B0); PG8_MMA(1, 1, At, B1); PG8_BAR; PG8_SCHED;
;             PG8_LDB(B0, 1, 0); PG8_LDB(B1, 1, 1); PG8_SCHED; PG8_LDA(At, 1, 0); PG8_STAGE(PG8_SA(0, 1), a2 + hstep, voffA);
;             PG8_WAIT_V(8); PG8_WAIT_L(0); PG8_BAR; PG8_MMA(0, 0, At, B0); PG8_MMA(0, 1, At, B1); PG8_BAR; PG8_SCHED;
;             PG8_LDA(At, 1, 1); PG8_STAGE(PG8_SB(1, 0), b3, voffB); PG8_STAGE(PG8_SB(1, 1), b3 + hstep, voffB); PG8_STAGE(PG8_SA(1, 0), a3, voffA);
;             PG8_WAIT_V(8); PG8_WAIT_L(0); PG8_BAR; PG8_MMA(1, 0, At, B0); PG8_MMA(1, 1, At, B1); PG8_BAR; PG8_SCHED;
.LBB0_168:
	s_ashr_i32 s29, s28, 31
	v_cmp_lt_i64_e32 vcc, s[30:31], v[140:141]
	s_lshl_b64 s[30:31], s[28:29], 20
	s_add_u32 s30, s6, s30
	s_addc_u32 s31, s7, s31
	s_and_b64 s[34:35], vcc, exec
	s_cselect_b32 s29, s31, s39
	s_cselect_b32 s57, s30, s38
	s_ashr_i32 s27, s26, 31
	s_lshl_b64 s[34:35], s[26:27], 20
	s_add_u32 s34, s22, s34
	s_addc_u32 s35, s23, s35
	s_and_b64 s[42:43], vcc, exec
	s_cselect_b32 s27, s35, s41
	s_cselect_b32 s58, s34, s40
	s_add_u32 s38, s38, 0x80080
	s_addc_u32 s39, s39, 0
	s_add_u32 s59, s40, 0x100
	s_addc_u32 s60, s41, 0
	s_mov_b32 s61, -2
	ds_read_b128 v[152:155], v149
	ds_read_b128 v[156:159], v149 offset:1024
	ds_read_b128 v[160:163], v149 offset:2048
	ds_read_b128 v[164:167], v149 offset:3072
	ds_read_b128 v[168:171], v150
	ds_read_b128 v[172:175], v150 offset:1024
	ds_read_b128 v[176:179], v150 offset:2048
	ds_read_b128 v[180:183], v150 offset:3072
	s_add_u32 s40, s38, 0xfff80080
	s_addc_u32 s41, s39, -1
	s_cmp_eq_u32 s61, 28
	s_cselect_b32 s43, s29, s41
	s_cselect_b32 s42, s57, s40
	s_cselect_b32 s41, s27, s60
	s_cselect_b32 s40, s58, s59
	s_add_i32 m0, s37, 0xc000
	ds_read_b128 v[184:187], v151
	ds_read_b128 v[188:191], v151 offset:1024
	ds_read_b128 v[192:195], v151 offset:2048
	ds_read_b128 v[196:199], v151 offset:3072
	ds_read_b128 v[200:203], v151 offset:4096
	ds_read_b128 v[204:207], v151 offset:5120
	ds_read_b128 v[208:211], v151 offset:6144
	ds_read_b128 v[214:217], v151 offset:7168
	global_load_lds_dwordx4 v136, s[38:39]
	s_add_i32 m0, s37, 0xe000
	s_nop 0
	global_load_lds_dwordx4 v138, s[38:39]
	s_waitcnt vmcnt(8) lgkmcnt(0)
	s_barrier
	v_mfma_f32_16x16x32_bf16 v[124:127], v[152:155], v[184:187], 0
	v_mfma_f32_16x16x32_bf16 v[120:123], v[160:163], v[184:187], 0
	v_mfma_f32_16x16x32_bf16 v[108:111], v[152:155], v[192:195], 0
	v_mfma_f32_16x16x32_bf16 v[104:107], v[160:163], v[192:195], 0
	v_mfma_f32_16x16x32_bf16 v[92:95], v[152:155], v[200:203], 0
	v_mfma_f32_16x16x32_bf16 v[88:91], v[160:163], v[200:203], 0
	v_mfma_f32_16x16x32_bf16 v[76:79], v[152:155], v[208:211], 0
	v_mfma_f32_16x16x32_bf16 v[72:75], v[160:163], v[208:211], 0
	v_mfma_f32_16x16x32_bf16 v[124:127], v[156:159], v[188:191], v[124:127]
	v_mfma_f32_16x16x32_bf16 v[120:123], v[164:167], v[188:191], v[120:123]
	v_mfma_f32_16x16x32_bf16 v[108:111], v[156:159], v[196:199], v[108:111]
	v_mfma_f32_16x16x32_bf16 v[104:107], v[164:167], v[196:199], v[104:107]
	v_mfma_f32_16x16x32_bf16 v[92:95], v[156:159], v[204:207], v[92:95]
	v_mfma_f32_16x16x32_bf16 v[88:91], v[164:167], v[204:207], v[88:91]
	v_mfma_f32_16x16x32_bf16 v[76:79], v[156:159], v[214:217], v[76:79]
	v_mfma_f32_16x16x32_bf16 v[72:75], v[164:167], v[214:217], v[72:75]
	v_mfma_f32_16x16x32_bf16 v[116:119], v[168:171], v[184:187], 0
	v_mfma_f32_16x16x32_bf16 v[112:115], v[176:179], v[184:187], 0
	v_mfma_f32_16x16x32_bf16 v[100:103], v[168:171], v[192:195], 0
	v_mfma_f32_16x16x32_bf16 v[96:99], v[176:179], v[192:195], 0
	v_mfma_f32_16x16x32_bf16 v[84:87], v[168:171], v[200:203], 0
	v_mfma_f32_16x16x32_bf16 v[80:83], v[176:179], v[200:203], 0
	v_mfma_f32_16x16x32_bf16 v[68:71], v[168:171], v[208:211], 0
	v_mfma_f32_16x16x32_bf16 v[64:67], v[176:179], v[208:211], 0
	v_mfma_f32_16x16x32_bf16 v[116:119], v[172:175], v[188:191], v[116:119]
	v_mfma_f32_16x16x32_bf16 v[112:115], v[180:183], v[188:191], v[112:115]
	v_mfma_f32_16x16x32_bf16 v[100:103], v[172:175], v[196:199], v[100:103]
	v_mfma_f32_16x16x32_bf16 v[96:99], v[180:183], v[196:199], v[96:99]
	v_mfma_f32_16x16x32_bf16 v[84:87], v[172:175], v[204:207], v[84:87]
	v_mfma_f32_16x16x32_bf16 v[80:83], v[180:183], v[204:207], v[80:83]
	v_mfma_f32_16x16x32_bf16 v[68:71], v[172:175], v[214:217], v[68:71]
	v_mfma_f32_16x16x32_bf16 v[64:67], v[180:183], v[214:217], v[64:67]
	s_barrier
	s_add_i32 s62, s53, s24
	s_mov_b32 m0, s62
	ds_read_b128 v[184:187], v151 offset:16384
	ds_read_b128 v[188:191], v151 offset:17408
	ds_read_b128 v[192:195], v151 offset:18432
	ds_read_b128 v[196:199], v151 offset:19456
	ds_read_b128 v[200:203], v151 offset:20480
	ds_read_b128 v[204:207], v151 offset:21504
	ds_read_b128 v[208:211], v151 offset:22528
	ds_read_b128 v[214:217], v151 offset:23552
	global_load_lds_dwordx4 v132, s[40:41]
	s_add_i32 m0, s62, 0x2000
	s_add_u32 s62, s40, 0x80000
	s_addc_u32 s63, s41, 0
	s_add_i32 s64, s54, s24
	global_load_lds_dwordx4 v128, s[40:41]
	s_mov_b32 m0, s64
	s_nop 0
	global_load_lds_dwordx4 v132, s[62:63]
	s_add_i32 m0, s64, 0x2000
	s_nop 0
	global_load_lds_dwordx4 v128, s[62:63]
	s_mov_b32 m0, s37
	s_nop 0
	global_load_lds_dwordx4 v134, s[42:43]
	s_mov_b32 m0, s45
	s_nop 0
	global_load_lds_dwordx4 v130, s[42:43]
	s_waitcnt vmcnt(8) lgkmcnt(0)
	s_barrier
; #define PG8_STAGE(bufoff, gbase, voff) do { _Pragma("unroll") for (int _i = 0; _i < 2; ++_i) \
;         __builtin_amdgcn_global_load_lds((const unsigned*)((const char*)(gbase) + (voff)[_i]), (PG8_LAS unsigned*)(lds + (bufoff) + ldsw + _i * 8192), 16, 0, 0); } while (0)
; #define PG8_LDA(dst, b, h) do { _Pragma("unroll") for (int m = 0; m < 4; ++m) _Pragma("unroll") for (int k = 0; k < 2; ++k) dst[m][k] = *(const PG8_LAS bf16x8*)(lds + PG8_SA(b, h) + aoff + m * 2048 + k * 1024); } while (0)
; #define PG8_LDB(dst, b, h) do { _Pragma("unroll") for (int n = 0; n < 2; ++n) _Pragma("unroll") for (int k = 0; k < 2; ++k) dst[n][k] = *(const PG8_LAS bf16x8*)(lds + PG8_SB(b, h) + boff + n * 2048 + k * 1024); } while (0)
; #define PG8_MMA(ai, bj, At, Bt) do { __builtin_amdgcn_s_setprio(1); _Pragma("unroll") for (int m = 0; m < 4; ++m) _Pragma("unroll") for (int n = 0; n < 2; ++n) _Pragma("unroll") for (int k = 0; k < 2; ++k) \
;         acc[ai][bj][m][n] = __builtin_amdgcn_mfma_f32_16x16x32_bf16(Bt[n][k], At[m][k], acc[ai][bj][m][n], 0, 0, 0); __builtin_amdgcn_s_setprio(0); } while (0)
; #define PG8_WAIT_V(n) asm volatile("s_waitcnt vmcnt(" #n ")" ::: "memory")
; #define PG8_WAIT_L(n) asm volatile("s_waitcnt lgkmcnt(" #n ")" ::: "memory")
; #define PG8_BAR __builtin_amdgcn_s_barrier()
; #define PG8_SCHED __builtin_amdgcn_sched_barrier(0)
; template <class Epi, class Sched, bool ALIGN_EPI = false, bool SP2 = false>
; __device__ __forceinline__ void gemm_phase(PG8_LAS unsigned char* lds, const Gemm g, const Sched& S, const Epi& E) {
;     ...
;             PG8_WAIT_V(8); PG8_WAIT_L(0); PG8_BAR; PG8_MMA(1, 0, At, B0); PG8_MMA(1, 1, At, B1); PG8_BAR; PG8_SCHED;
;             PG8_LDB(B0, 1, 0); PG8_LDB(B1, 1, 1); PG8_SCHED; PG8_LDA(At, 1, 0); PG8_STAGE(PG8_SA(0, 1), a2 + hstep, voffA);
;             PG8_WAIT_V(8); PG8_WAIT_L(0); PG8_BAR; PG8_MMA(0, 0, At, B0); PG8_MMA(0, 1, At, B1); PG8_BAR; PG8_SCHED;
	v_mfma_f32_16x16x32_bf16 v[60:63], v[152:155], v[184:187], 0
	v_mfma_f32_16x16x32_bf16 v[56:59], v[160:163], v[184:187], 0
	v_mfma_f32_16x16x32_bf16 v[44:47], v[152:155], v[192:195], 0
	v_mfma_f32_16x16x32_bf16 v[40:43], v[160:163], v[192:195], 0
	v_mfma_f32_16x16x32_bf16 v[28:31], v[152:155], v[200:203], 0
	v_mfma_f32_16x16x32_bf16 v[24:27], v[160:163], v[200:203], 0
	v_mfma_f32_16x16x32_bf16 v[12:15], v[152:155], v[208:211], 0
	v_mfma_f32_16x16x32_bf16 v[8:11], v[160:163], v[208:211], 0
	v_mfma_f32_16x16x32_bf16 v[60:63], v[156:159], v[188:191], v[60:63]
	v_mfma_f32_16x16x32_bf16 v[56:59], v[164:167], v[188:191], v[56:59]
	v_mfma_f32_16x16x32_bf16 v[44:47], v[156:159], v[196:199], v[44:47]
	v_mfma_f32_16x16x32_bf16 v[40:43], v[164:167], v[196:199], v[40:43]
	v_mfma_f32_16x16x32_bf16 v[28:31], v[156:159], v[204:207], v[28:31]
	v_mfma_f32_16x16x32_bf16 v[24:27], v[164:167], v[204:207], v[24:27]
	v_mfma_f32_16x16x32_bf16 v[12:15], v[156:159], v[214:217], v[12:15]
	v_mfma_f32_16x16x32_bf16 v[8:11], v[164:167], v[214:217], v[8:11]
	v_mfma_f32_16x16x32_bf16 v[52:55], v[168:171], v[184:187], 0
	v_mfma_f32_16x16x32_bf16 v[48:51], v[176:179], v[184:187], 0
	v_mfma_f32_16x16x32_bf16 v[36:39], v[168:171], v[192:195], 0
	v_mfma_f32_16x16x32_bf16 v[32:35], v[176:179], v[192:195], 0
	v_mfma_f32_16x16x32_bf16 v[20:23], v[168:171], v[200:203], 0
	v_mfma_f32_16x16x32_bf16 v[16:19], v[176:179], v[200:203], 0
	v_mfma_f32_16x16x32_bf16 v[4:7], v[168:171], v[208:211], 0
	v_mfma_f32_16x16x32_bf16 v[0:3], v[176:179], v[208:211], 0
	v_mfma_f32_16x16x32_bf16 v[52:55], v[172:175], v[188:191], v[52:55]
	v_mfma_f32_16x16x32_bf16 v[48:51], v[180:183], v[188:191], v[48:51]
	v_mfma_f32_16x16x32_bf16 v[36:39], v[172:175], v[196:199], v[36:39]
	v_mfma_f32_16x16x32_bf16 v[32:35], v[180:183], v[196:199], v[32:35]
	v_mfma_f32_16x16x32_bf16 v[20:23], v[172:175], v[204:207], v[20:23]
	v_mfma_f32_16x16x32_bf16 v[16:19], v[180:183], v[204:207], v[16:19]
	v_mfma_f32_16x16x32_bf16 v[4:7], v[172:175], v[214:217], v[4:7]
	v_mfma_f32_16x16x32_bf16 v[0:3], v[180:183], v[214:217], v[0:3]
	s_barrier
	s_add_i32 s62, 0, 0x18000
	s_add_i32 s63, 0, 0x1c000
	v_add_u32_e32 v164, s62, v147
	v_add_u32_e32 v180, s63, v147
	ds_read_b128 v[152:155], v164
	ds_read_b128 v[156:159], v164 offset:1024
	ds_read_b128 v[160:163], v164 offset:2048
	ds_read_b128 v[164:167], v164 offset:3072
	ds_read_b128 v[168:171], v180
	ds_read_b128 v[172:175], v180 offset:1024
	ds_read_b128 v[176:179], v180 offset:2048
	ds_read_b128 v[180:183], v180 offset:3072
	s_add_u32 s84, s42, 0x80
	s_addc_u32 s85, s43, 0
	s_add_u32 s42, s42, 0x80000
	s_addc_u32 s43, s43, 0
	s_mov_b32 m0, s46
	ds_read_b128 v[184:187], v151 offset:32768
	ds_read_b128 v[188:191], v151 offset:33792
	ds_read_b128 v[192:195], v151 offset:34816
	ds_read_b128 v[196:199], v151 offset:35840
	ds_read_b128 v[200:203], v151 offset:36864
	ds_read_b128 v[204:207], v151 offset:37888
	ds_read_b128 v[208:211], v151 offset:38912
	ds_read_b128 v[214:217], v151 offset:39936
	global_load_lds_dwordx4 v134, s[42:43]
	s_mov_b32 m0, s47
	s_nop 0
	global_load_lds_dwordx4 v130, s[42:43]
	s_waitcnt vmcnt(8) lgkmcnt(0)
	s_barrier
	v_mfma_f32_16x16x32_bf16 v[124:127], v[152:155], v[184:187], v[124:127]
	v_mfma_f32_16x16x32_bf16 v[120:123], v[160:163], v[184:187], v[120:123]
	v_mfma_f32_16x16x32_bf16 v[108:111], v[152:155], v[192:195], v[108:111]
	v_mfma_f32_16x16x32_bf16 v[104:107], v[160:163], v[192:195], v[104:107]
	v_mfma_f32_16x16x32_bf16 v[92:95], v[152:155], v[200:203], v[92:95]
	v_mfma_f32_16x16x32_bf16 v[88:91], v[160:163], v[200:203], v[88:91]
	v_mfma_f32_16x16x32_bf16 v[76:79], v[152:155], v[208:211], v[76:79]
	v_mfma_f32_16x16x32_bf16 v[72:75], v[160:163], v[208:211], v[72:75]
	v_mfma_f32_16x16x32_bf16 v[124:127], v[156:159], v[188:191], v[124:127]
	v_mfma_f32_16x16x32_bf16 v[120:123], v[164:167], v[188:191], v[120:123]
	v_mfma_f32_16x16x32_bf16 v[108:111], v[156:159], v[196:199], v[108:111]
	v_mfma_f32_16x16x32_bf16 v[104:107], v[164:167], v[196:199], v[104:107]
	v_mfma_f32_16x16x32_bf16 v[92:95], v[156:159], v[204:207], v[92:95]
	v_mfma_f32_16x16x32_bf16 v[88:91], v[164:167], v[204:207], v[88:91]
	v_mfma_f32_16x16x32_bf16 v[76:79], v[156:159], v[214:217], v[76:79]
	v_mfma_f32_16x16x32_bf16 v[72:75], v[164:167], v[214:217], v[72:75]
	v_mfma_f32_16x16x32_bf16 v[116:119], v[168:171], v[184:187], v[116:119]
	v_mfma_f32_16x16x32_bf16 v[112:115], v[176:179], v[184:187], v[112:115]
	v_mfma_f32_16x16x32_bf16 v[100:103], v[168:171], v[192:195], v[100:103]
	v_mfma_f32_16x16x32_bf16 v[96:99], v[176:179], v[192:195], v[96:99]
	v_mfma_f32_16x16x32_bf16 v[84:87], v[168:171], v[200:203], v[84:87]
	v_mfma_f32_16x16x32_bf16 v[80:83], v[176:179], v[200:203], v[80:83]
	v_mfma_f32_16x16x32_bf16 v[68:71], v[168:171], v[208:211], v[68:71]
	v_mfma_f32_16x16x32_bf16 v[64:67], v[176:179], v[208:211], v[64:67]
	v_mfma_f32_16x16x32_bf16 v[116:119], v[172:175], v[188:191], v[116:119]
	v_mfma_f32_16x16x32_bf16 v[112:115], v[180:183], v[188:191], v[112:115]
	v_mfma_f32_16x16x32_bf16 v[100:103], v[172:175], v[196:199], v[100:103]
	v_mfma_f32_16x16x32_bf16 v[96:99], v[180:183], v[196:199], v[96:99]
	v_mfma_f32_16x16x32_bf16 v[84:87], v[172:175], v[204:207], v[84:87]
	v_mfma_f32_16x16x32_bf16 v[80:83], v[180:183], v[204:207], v[80:83]
	v_mfma_f32_16x16x32_bf16 v[68:71], v[172:175], v[214:217], v[68:71]
	v_mfma_f32_16x16x32_bf16 v[64:67], v[180:183], v[214:217], v[64:67]
	s_barrier
; #define PG8_STAGE(bufoff, gbase, voff) do { _Pragma("unroll") for (int _i = 0; _i < 2; ++_i) \
;         __builtin_amdgcn_global_load_lds((const unsigned*)((const char*)(gbase) + (voff)[_i]), (PG8_LAS unsigned*)(lds + (bufoff) + ldsw + _i * 8192), 16, 0, 0); } while (0)
; #define PG8_LDA(dst, b, h) do { _Pragma("unroll") for (int m = 0; m < 4; ++m) _Pragma("unroll") for (int k = 0; k < 2; ++k) dst[m][k] = *(const PG8_LAS bf16x8*)(lds + PG8_SA(b, h) + aoff + m * 2048 + k * 1024); } while (0)
; #define PG8_LDB(dst, b, h) do { _Pragma("unroll") for (int n = 0; n < 2; ++n) _Pragma("unroll") for (int k = 0; k < 2; ++k) dst[n][k] = *(const PG8_LAS bf16x8*)(lds + PG8_SB(b, h) + boff + n * 2048 + k * 1024); } while (0)
; #define PG8_MMA(ai, bj, At, Bt) do { __builtin_amdgcn_s_setprio(1); _Pragma("unroll") for (int m = 0; m < 4; ++m) _Pragma("unroll") for (int n = 0; n < 2; ++n) _Pragma("unroll") for (int k = 0; k < 2; ++k) \
;         acc[ai][bj][m][n] = __builtin_amdgcn_mfma_f32_16x16x32_bf16(Bt[n][k], At[m][k], acc[ai][bj][m][n], 0, 0, 0); __builtin_amdgcn_s_setprio(0); } while (0)
; #define PG8_WAIT_V(n) asm volatile("s_waitcnt vmcnt(" #n ")" ::: "memory")
; #define PG8_WAIT_L(n) asm volatile("s_waitcnt lgkmcnt(" #n ")" ::: "memory")
; #define PG8_BAR __builtin_amdgcn_s_barrier()
; #define PG8_SCHED __builtin_amdgcn_sched_barrier(0)
; template <class Epi, class Sched, bool ALIGN_EPI = false, bool SP2 = false>
; __device__ __forceinline__ void gemm_phase(PG8_LAS unsigned char* lds, const Gemm g, const Sched& S, const Epi& E) {
;     ...
;             PG8_LDB(B0, 0, 0); PG8_LDB(B1, 0, 1); PG8_SCHED; PG8_LDA(At, 0, 0); PG8_STAGE(PG8_SA(1, 1), a1 + hstep, voffA);
;             PG8_WAIT_V(8); PG8_WAIT_L(0); PG8_BAR; PG8_MMA(0, 0, At, B0); PG8_MMA(0, 1, At, B1); PG8_BAR; PG8_SCHED;
;             PG8_LDA(At, 0, 1); PG8_STAGE(PG8_SB(0, 0), b2, voffB); PG8_STAGE(PG8_SB(0, 1), b2 + hstep, voffB); PG8_STAGE(PG8_SA(0, 0), a2, voffA);
;             PG8_WAIT_V(8); PG8_WAIT_L(0); PG8_BAR; PG8_MMA(1, 0, At, B0); PG8_MMA(1, 1, At, B1); PG8_BAR; PG8_SCHED;
;     ...
;             PG8_LDA(At, 1, 1); PG8_STAGE(PG8_SB(1, 0), b3, voffB); PG8_STAGE(PG8_SB(1, 1), b3 + hstep, voffB); PG8_STAGE(PG8_SA(1, 0), a3, voffA);
;             PG8_WAIT_V(8); PG8_WAIT_L(0); PG8_BAR; PG8_MMA(1, 0, At, B0); PG8_MMA(1, 1, At, B1); PG8_BAR; PG8_SCHED;
	s_add_i32 s42, s62, s24
	s_add_u32 s86, s40, 0x80
	s_addc_u32 s87, s41, 0
	s_mov_b32 m0, s42
	ds_read_b128 v[184:187], v151 offset:49152
	ds_read_b128 v[188:191], v151 offset:50176
	ds_read_b128 v[192:195], v151 offset:51200
	ds_read_b128 v[196:199], v151 offset:52224
	ds_read_b128 v[200:203], v151 offset:53248
	ds_read_b128 v[204:207], v151 offset:54272
	ds_read_b128 v[208:211], v151 offset:55296
	ds_read_b128 v[214:217], v151 offset:56320
	global_load_lds_dwordx4 v132, s[86:87]
	s_add_i32 m0, s42, 0x2000
	s_add_u32 s40, s40, 0x80080
	s_addc_u32 s41, s41, 0
	s_add_i32 s42, s63, s24
	global_load_lds_dwordx4 v128, s[86:87]
	s_mov_b32 m0, s42
	s_nop 0
	global_load_lds_dwordx4 v132, s[40:41]
	s_add_i32 m0, s42, 0x2000
	s_nop 0
	global_load_lds_dwordx4 v128, s[40:41]
	s_mov_b32 m0, s49
	s_nop 0
	global_load_lds_dwordx4 v134, s[84:85]
	s_mov_b32 m0, s50
	s_nop 0
	global_load_lds_dwordx4 v130, s[84:85]
	s_waitcnt vmcnt(8) lgkmcnt(0)
	s_barrier
	v_mfma_f32_16x16x32_bf16 v[60:63], v[152:155], v[184:187], v[60:63]
	v_mfma_f32_16x16x32_bf16 v[56:59], v[160:163], v[184:187], v[56:59]
	v_mfma_f32_16x16x32_bf16 v[44:47], v[152:155], v[192:195], v[44:47]
	v_mfma_f32_16x16x32_bf16 v[40:43], v[160:163], v[192:195], v[40:43]
	v_mfma_f32_16x16x32_bf16 v[28:31], v[152:155], v[200:203], v[28:31]
	v_mfma_f32_16x16x32_bf16 v[24:27], v[160:163], v[200:203], v[24:27]
	v_mfma_f32_16x16x32_bf16 v[12:15], v[152:155], v[208:211], v[12:15]
	v_mfma_f32_16x16x32_bf16 v[8:11], v[160:163], v[208:211], v[8:11]
	v_mfma_f32_16x16x32_bf16 v[60:63], v[156:159], v[188:191], v[60:63]
	v_mfma_f32_16x16x32_bf16 v[56:59], v[164:167], v[188:191], v[56:59]
	v_mfma_f32_16x16x32_bf16 v[44:47], v[156:159], v[196:199], v[44:47]
	v_mfma_f32_16x16x32_bf16 v[40:43], v[164:167], v[196:199], v[40:43]
	v_mfma_f32_16x16x32_bf16 v[28:31], v[156:159], v[204:207], v[28:31]
	v_mfma_f32_16x16x32_bf16 v[24:27], v[164:167], v[204:207], v[24:27]
	v_mfma_f32_16x16x32_bf16 v[12:15], v[156:159], v[214:217], v[12:15]
	v_mfma_f32_16x16x32_bf16 v[8:11], v[164:167], v[214:217], v[8:11]
	v_mfma_f32_16x16x32_bf16 v[52:55], v[168:171], v[184:187], v[52:55]
	v_mfma_f32_16x16x32_bf16 v[48:51], v[176:179], v[184:187], v[48:51]
	v_mfma_f32_16x16x32_bf16 v[36:39], v[168:171], v[192:195], v[36:39]
	v_mfma_f32_16x16x32_bf16 v[32:35], v[176:179], v[192:195], v[32:35]
	v_mfma_f32_16x16x32_bf16 v[20:23], v[168:171], v[200:203], v[20:23]
	v_mfma_f32_16x16x32_bf16 v[16:19], v[176:179], v[200:203], v[16:19]
	v_mfma_f32_16x16x32_bf16 v[4:7], v[168:171], v[208:211], v[4:7]
	v_mfma_f32_16x16x32_bf16 v[0:3], v[176:179], v[208:211], v[0:3]
	v_mfma_f32_16x16x32_bf16 v[52:55], v[172:175], v[188:191], v[52:55]
	v_mfma_f32_16x16x32_bf16 v[48:51], v[180:183], v[188:191], v[48:51]
	v_mfma_f32_16x16x32_bf16 v[36:39], v[172:175], v[196:199], v[36:39]
	v_mfma_f32_16x16x32_bf16 v[32:35], v[180:183], v[196:199], v[32:35]
	v_mfma_f32_16x16x32_bf16 v[20:23], v[172:175], v[204:207], v[20:23]
	v_mfma_f32_16x16x32_bf16 v[16:19], v[180:183], v[204:207], v[16:19]
	v_mfma_f32_16x16x32_bf16 v[4:7], v[172:175], v[214:217], v[4:7]
	v_mfma_f32_16x16x32_bf16 v[0:3], v[180:183], v[214:217], v[0:3]
	s_barrier
	s_add_i32 s61, s61, 2
	s_add_u32 s38, s38, 0x100
	s_addc_u32 s39, s39, 0
	s_add_u32 s59, s59, 0x100
	s_addc_u32 s60, s60, 0
	s_cmp_gt_u32 s61, 29
.LBB0_169:
	ds_read_b128 v[152:155], v149
	ds_read_b128 v[156:159], v149 offset:1024
	ds_read_b128 v[160:163], v149 offset:2048
	ds_read_b128 v[164:167], v149 offset:3072
	ds_read_b128 v[168:171], v150
	ds_read_b128 v[172:175], v150 offset:1024
	ds_read_b128 v[176:179], v150 offset:2048
	ds_read_b128 v[180:183], v150 offset:3072
	s_add_u32 s40, s38, 0xfff80080
	s_addc_u32 s41, s39, -1
	s_cmp_eq_u32 s61, 28
	s_cselect_b32 s43, s29, s41
	s_cselect_b32 s42, s57, s40
	s_cselect_b32 s41, s27, s60
	s_cselect_b32 s40, s58, s59
	s_add_i32 m0, s37, 0xc000
	ds_read_b128 v[184:187], v151
	ds_read_b128 v[188:191], v151 offset:1024
	ds_read_b128 v[192:195], v151 offset:2048
	ds_read_b128 v[196:199], v151 offset:3072
	ds_read_b128 v[200:203], v151 offset:4096
	ds_read_b128 v[204:207], v151 offset:5120
	ds_read_b128 v[208:211], v151 offset:6144
	ds_read_b128 v[214:217], v151 offset:7168
	global_load_lds_dwordx4 v136, s[38:39]
	s_add_i32 m0, s37, 0xe000
	s_nop 0
	global_load_lds_dwordx4 v138, s[38:39]
	s_waitcnt vmcnt(8) lgkmcnt(0)
	s_barrier
	v_mfma_f32_16x16x32_bf16 v[124:127], v[152:155], v[184:187], v[124:127]
	v_mfma_f32_16x16x32_bf16 v[120:123], v[160:163], v[184:187], v[120:123]
	v_mfma_f32_16x16x32_bf16 v[108:111], v[152:155], v[192:195], v[108:111]
	v_mfma_f32_16x16x32_bf16 v[104:107], v[160:163], v[192:195], v[104:107]
	v_mfma_f32_16x16x32_bf16 v[92:95], v[152:155], v[200:203], v[92:95]
	v_mfma_f32_16x16x32_bf16 v[88:91], v[160:163], v[200:203], v[88:91]
	v_mfma_f32_16x16x32_bf16 v[76:79], v[152:155], v[208:211], v[76:79]
	v_mfma_f32_16x16x32_bf16 v[72:75], v[160:163], v[208:211], v[72:75]
	v_mfma_f32_16x16x32_bf16 v[124:127], v[156:159], v[188:191], v[124:127]
	v_mfma_f32_16x16x32_bf16 v[120:123], v[164:167], v[188:191], v[120:123]
	v_mfma_f32_16x16x32_bf16 v[108:111], v[156:159], v[196:199], v[108:111]
	v_mfma_f32_16x16x32_bf16 v[104:107], v[164:167], v[196:199], v[104:107]
	v_mfma_f32_16x16x32_bf16 v[92:95], v[156:159], v[204:207], v[92:95]
	v_mfma_f32_16x16x32_bf16 v[88:91], v[164:167], v[204:207], v[88:91]
	v_mfma_f32_16x16x32_bf16 v[76:79], v[156:159], v[214:217], v[76:79]
	v_mfma_f32_16x16x32_bf16 v[72:75], v[164:167], v[214:217], v[72:75]
	v_mfma_f32_16x16x32_bf16 v[116:119], v[168:171], v[184:187], v[116:119]
	v_mfma_f32_16x16x32_bf16 v[112:115], v[176:179], v[184:187], v[112:115]
	v_mfma_f32_16x16x32_bf16 v[100:103], v[168:171], v[192:195], v[100:103]
	v_mfma_f32_16x16x32_bf16 v[96:99], v[176:179], v[192:195], v[96:99]
	v_mfma_f32_16x16x32_bf16 v[84:87], v[168:171], v[200:203], v[84:87]
	v_mfma_f32_16x16x32_bf16 v[80:83], v[176:179], v[200:203], v[80:83]
	v_mfma_f32_16x16x32_bf16 v[68:71], v[168:171], v[208:211], v[68:71]
	v_mfma_f32_16x16x32_bf16 v[64:67], v[176:179], v[208:211], v[64:67]
	v_mfma_f32_16x16x32_bf16 v[116:119], v[172:175], v[188:191], v[116:119]
	v_mfma_f32_16x16x32_bf16 v[112:115], v[180:183], v[188:191], v[112:115]
	v_mfma_f32_16x16x32_bf16 v[100:103], v[172:175], v[196:199], v[100:103]
	v_mfma_f32_16x16x32_bf16 v[96:99], v[180:183], v[196:199], v[96:99]
	v_mfma_f32_16x16x32_bf16 v[84:87], v[172:175], v[204:207], v[84:87]
	v_mfma_f32_16x16x32_bf16 v[80:83], v[180:183], v[204:207], v[80:83]
	v_mfma_f32_16x16x32_bf16 v[68:71], v[172:175], v[214:217], v[68:71]
	v_mfma_f32_16x16x32_bf16 v[64:67], v[180:183], v[214:217], v[64:67]
	s_barrier
; #define PG8_STAGE(bufoff, gbase, voff) do { _Pragma("unroll") for (int _i = 0; _i < 2; ++_i) \
;         __builtin_amdgcn_global_load_lds((const unsigned*)((const char*)(gbase) + (voff)[_i]), (PG8_LAS unsigned*)(lds + (bufoff) + ldsw + _i * 8192), 16, 0, 0); } while (0)
; #define PG8_LDA(dst, b, h) do { _Pragma("unroll") for (int m = 0; m < 4; ++m) _Pragma("unroll") for (int k = 0; k < 2; ++k) dst[m][k] = *(const PG8_LAS bf16x8*)(lds + PG8_SA(b, h) + aoff + m * 2048 + k * 1024); } while (0)
; #define PG8_LDB(dst, b, h) do { _Pragma("unroll") for (int n = 0; n < 2; ++n) _Pragma("unroll") for (int k = 0; k < 2; ++k) dst[n][k] = *(const PG8_LAS bf16x8*)(lds + PG8_SB(b, h) + boff + n * 2048 + k * 1024); } while (0)
; #define PG8_MMA(ai, bj, At, Bt) do { __builtin_amdgcn_s_setprio(1); _Pragma("unroll") for (int m = 0; m < 4; ++m) _Pragma("unroll") for (int n = 0; n < 2; ++n) _Pragma("unroll") for (int k = 0; k < 2; ++k) \
;         acc[ai][bj][m][n] = __builtin_amdgcn_mfma_f32_16x16x32_bf16(Bt[n][k], At[m][k], acc[ai][bj][m][n], 0, 0, 0); __builtin_amdgcn_s_setprio(0); } while (0)
; #define PG8_WAIT_V(n) asm volatile("s_waitcnt vmcnt(" #n ")" ::: "memory")
; #define PG8_WAIT_L(n) asm volatile("s_waitcnt lgkmcnt(" #n ")" ::: "memory")
; #define PG8_BAR __builtin_amdgcn_s_barrier()
; #define PG8_SCHED __builtin_amdgcn_sched_barrier(0)
; template <class Epi, class Sched, bool ALIGN_EPI = false, bool SP2 = false>
; __device__ __forceinline__ void gemm_phase(PG8_LAS unsigned char* lds, const Gemm g, const Sched& S, const Epi& E) {
;     ...
;             PG8_WAIT_V(8); PG8_WAIT_L(0); PG8_BAR; PG8_MMA(0, 0, At, B0); PG8_MMA(0, 1, At, B1); PG8_BAR; PG8_SCHED;
;             PG8_LDA(At, 0, 1); PG8_STAGE(PG8_SB(0, 0), b2, voffB); PG8_STAGE(PG8_SB(0, 1), b2 + hstep, voffB); PG8_STAGE(PG8_SA(0, 0), a2, voffA);
;             PG8_WAIT_V(8); PG8_WAIT_L(0); PG8_BAR; PG8_MMA(1, 0, At, B0); PG8_MMA(1, 1, At, B1); PG8_BAR; PG8_SCHED;
;             PG8_LDB(B0, 1, 0); PG8_LDB(B1, 1, 1); PG8_SCHED; PG8_LDA(At, 1, 0); PG8_STAGE(PG8_SA(0, 1), a2 + hstep, voffA);
;             PG8_WAIT_V(8); PG8_WAIT_L(0); PG8_BAR; PG8_MMA(0, 0, At, B0); PG8_MMA(0, 1, At, B1); PG8_BAR; PG8_SCHED;
	s_add_i32 s62, s53, s24
	s_mov_b32 m0, s62
	ds_read_b128 v[184:187], v151 offset:16384
	ds_read_b128 v[188:191], v151 offset:17408
	ds_read_b128 v[192:195], v151 offset:18432
	ds_read_b128 v[196:199], v151 offset:19456
	ds_read_b128 v[200:203], v151 offset:20480
	ds_read_b128 v[204:207], v151 offset:21504
	ds_read_b128 v[208:211], v151 offset:22528
	ds_read_b128 v[214:217], v151 offset:23552
	global_load_lds_dwordx4 v132, s[40:41]
	s_add_i32 m0, s62, 0x2000
	s_add_u32 s62, s40, 0x80000
	s_addc_u32 s63, s41, 0
	s_add_i32 s64, s54, s24
	global_load_lds_dwordx4 v128, s[40:41]
	s_mov_b32 m0, s64
	s_nop 0
	global_load_lds_dwordx4 v132, s[62:63]
	s_add_i32 m0, s64, 0x2000
	s_nop 0
	global_load_lds_dwordx4 v128, s[62:63]
	s_mov_b32 m0, s37
	s_nop 0
	global_load_lds_dwordx4 v134, s[42:43]
	s_mov_b32 m0, s45
	s_nop 0
	global_load_lds_dwordx4 v130, s[42:43]
	s_waitcnt vmcnt(8) lgkmcnt(0)
	s_barrier
	v_mfma_f32_16x16x32_bf16 v[60:63], v[152:155], v[184:187], v[60:63]
	v_mfma_f32_16x16x32_bf16 v[56:59], v[160:163], v[184:187], v[56:59]
	v_mfma_f32_16x16x32_bf16 v[44:47], v[152:155], v[192:195], v[44:47]
	v_mfma_f32_16x16x32_bf16 v[40:43], v[160:163], v[192:195], v[40:43]
	v_mfma_f32_16x16x32_bf16 v[28:31], v[152:155], v[200:203], v[28:31]
	v_mfma_f32_16x16x32_bf16 v[24:27], v[160:163], v[200:203], v[24:27]
	v_mfma_f32_16x16x32_bf16 v[12:15], v[152:155], v[208:211], v[12:15]
	v_mfma_f32_16x16x32_bf16 v[8:11], v[160:163], v[208:211], v[8:11]
	v_mfma_f32_16x16x32_bf16 v[60:63], v[156:159], v[188:191], v[60:63]
	v_mfma_f32_16x16x32_bf16 v[56:59], v[164:167], v[188:191], v[56:59]
	v_mfma_f32_16x16x32_bf16 v[44:47], v[156:159], v[196:199], v[44:47]
	v_mfma_f32_16x16x32_bf16 v[40:43], v[164:167], v[196:199], v[40:43]
	v_mfma_f32_16x16x32_bf16 v[28:31], v[156:159], v[204:207], v[28:31]
	v_mfma_f32_16x16x32_bf16 v[24:27], v[164:167], v[204:207], v[24:27]
	v_mfma_f32_16x16x32_bf16 v[12:15], v[156:159], v[214:217], v[12:15]
	v_mfma_f32_16x16x32_bf16 v[8:11], v[164:167], v[214:217], v[8:11]
	v_mfma_f32_16x16x32_bf16 v[52:55], v[168:171], v[184:187], v[52:55]
	v_mfma_f32_16x16x32_bf16 v[48:51], v[176:179], v[184:187], v[48:51]
	v_mfma_f32_16x16x32_bf16 v[36:39], v[168:171], v[192:195], v[36:39]
	v_mfma_f32_16x16x32_bf16 v[32:35], v[176:179], v[192:195], v[32:35]
	v_mfma_f32_16x16x32_bf16 v[20:23], v[168:171], v[200:203], v[20:23]
	v_mfma_f32_16x16x32_bf16 v[16:19], v[176:179], v[200:203], v[16:19]
	v_mfma_f32_16x16x32_bf16 v[4:7], v[168:171], v[208:211], v[4:7]
	v_mfma_f32_16x16x32_bf16 v[0:3], v[176:179], v[208:211], v[0:3]
	v_mfma_f32_16x16x32_bf16 v[52:55], v[172:175], v[188:191], v[52:55]
	v_mfma_f32_16x16x32_bf16 v[48:51], v[180:183], v[188:191], v[48:51]
	v_mfma_f32_16x16x32_bf16 v[36:39], v[172:175], v[196:199], v[36:39]
	v_mfma_f32_16x16x32_bf16 v[32:35], v[180:183], v[196:199], v[32:35]
	v_mfma_f32_16x16x32_bf16 v[20:23], v[172:175], v[204:207], v[20:23]
	v_mfma_f32_16x16x32_bf16 v[16:19], v[180:183], v[204:207], v[16:19]
	v_mfma_f32_16x16x32_bf16 v[4:7], v[172:175], v[214:217], v[4:7]
	v_mfma_f32_16x16x32_bf16 v[0:3], v[180:183], v[214:217], v[0:3]
	s_barrier
	s_add_i32 s62, 0, 0x18000
	s_add_i32 s63, 0, 0x1c000
	v_add_u32_e32 v164, s62, v147
	v_add_u32_e32 v180, s63, v147
	ds_read_b128 v[152:155], v164
	ds_read_b128 v[156:159], v164 offset:1024
	ds_read_b128 v[160:163], v164 offset:2048
	ds_read_b128 v[164:167], v164 offset:3072
	ds_read_b128 v[168:171], v180
	ds_read_b128 v[172:175], v180 offset:1024
	ds_read_b128 v[176:179], v180 offset:2048
	ds_read_b128 v[180:183], v180 offset:3072
	s_add_u32 s84, s42, 0x80
	s_addc_u32 s85, s43, 0
	s_add_u32 s42, s42, 0x80000
	s_addc_u32 s43, s43, 0
	s_mov_b32 m0, s46
	ds_read_b128 v[184:187], v151 offset:32768
	ds_read_b128 v[188:191], v151 offset:33792
	ds_read_b128 v[192:195], v151 offset:34816
	ds_read_b128 v[196:199], v151 offset:35840
	ds_read_b128 v[200:203], v151 offset:36864
	ds_read_b128 v[204:207], v151 offset:37888
	ds_read_b128 v[208:211], v151 offset:38912
	ds_read_b128 v[214:217], v151 offset:39936
	global_load_lds_dwordx4 v134, s[42:43]
	s_mov_b32 m0, s47
	s_nop 0
	global_load_lds_dwordx4 v130, s[42:43]
	s_waitcnt vmcnt(8) lgkmcnt(0)
	s_barrier
	v_mfma_f32_16x16x32_bf16 v[124:127], v[152:155], v[184:187], v[124:127]
	v_mfma_f32_16x16x32_bf16 v[120:123], v[160:163], v[184:187], v[120:123]
	v_mfma_f32_16x16x32_bf16 v[108:111], v[152:155], v[192:195], v[108:111]
	v_mfma_f32_16x16x32_bf16 v[104:107], v[160:163], v[192:195], v[104:107]
	v_mfma_f32_16x16x32_bf16 v[92:95], v[152:155], v[200:203], v[92:95]
	v_mfma_f32_16x16x32_bf16 v[88:91], v[160:163], v[200:203], v[88:91]
	v_mfma_f32_16x16x32_bf16 v[76:79], v[152:155], v[208:211], v[76:79]
	v_mfma_f32_16x16x32_bf16 v[72:75], v[160:163], v[208:211], v[72:75]
	v_mfma_f32_16x16x32_bf16 v[124:127], v[156:159], v[188:191], v[124:127]
	v_mfma_f32_16x16x32_bf16 v[120:123], v[164:167], v[188:191], v[120:123]
	v_mfma_f32_16x16x32_bf16 v[108:111], v[156:159], v[196:199], v[108:111]
	v_mfma_f32_16x16x32_bf16 v[104:107], v[164:167], v[196:199], v[104:107]
	v_mfma_f32_16x16x32_bf16 v[92:95], v[156:159], v[204:207], v[92:95]
	v_mfma_f32_16x16x32_bf16 v[88:91], v[164:167], v[204:207], v[88:91]
	v_mfma_f32_16x16x32_bf16 v[76:79], v[156:159], v[214:217], v[76:79]
	v_mfma_f32_16x16x32_bf16 v[72:75], v[164:167], v[214:217], v[72:75]
	v_mfma_f32_16x16x32_bf16 v[116:119], v[168:171], v[184:187], v[116:119]
	v_mfma_f32_16x16x32_bf16 v[112:115], v[176:179], v[184:187], v[112:115]
	v_mfma_f32_16x16x32_bf16 v[100:103], v[168:171], v[192:195], v[100:103]
	v_mfma_f32_16x16x32_bf16 v[96:99], v[176:179], v[192:195], v[96:99]
	v_mfma_f32_16x16x32_bf16 v[84:87], v[168:171], v[200:203], v[84:87]
	v_mfma_f32_16x16x32_bf16 v[80:83], v[176:179], v[200:203], v[80:83]
	v_mfma_f32_16x16x32_bf16 v[68:71], v[168:171], v[208:211], v[68:71]
	v_mfma_f32_16x16x32_bf16 v[64:67], v[176:179], v[208:211], v[64:67]
	v_mfma_f32_16x16x32_bf16 v[116:119], v[172:175], v[188:191], v[116:119]
	v_mfma_f32_16x16x32_bf16 v[112:115], v[180:183], v[188:191], v[112:115]
	v_mfma_f32_16x16x32_bf16 v[100:103], v[172:175], v[196:199], v[100:103]
	v_mfma_f32_16x16x32_bf16 v[96:99], v[180:183], v[196:199], v[96:99]
	v_mfma_f32_16x16x32_bf16 v[84:87], v[172:175], v[204:207], v[84:87]
	v_mfma_f32_16x16x32_bf16 v[80:83], v[180:183], v[204:207], v[80:83]
	v_mfma_f32_16x16x32_bf16 v[68:71], v[172:175], v[214:217], v[68:71]
	v_mfma_f32_16x16x32_bf16 v[64:67], v[180:183], v[214:217], v[64:67]
	s_barrier
; __device__ __forceinline__ float fsilu(float v) { return v * fsigmoid(v); }
; __device__ __forceinline__ u32x4 pack8(const f32x4 a, const f32x4 b) { u32x4 w; w.x = cvt_pk_bf16(a[0], a[1]); w.y = cvt_pk_bf16(a[2], a[3]); w.z = cvt_pk_bf16(b[0], b[1]); w.w = cvt_pk_bf16(b[2], b[3]); return w; }
; #define PG8_STAGE(bufoff, gbase, voff) do { _Pragma("unroll") for (int _i = 0; _i < 2; ++_i) \
;         __builtin_amdgcn_global_load_lds((const unsigned*)((const char*)(gbase) + (voff)[_i]), (PG8_LAS unsigned*)(lds + (bufoff) + ldsw + _i * 8192), 16, 0, 0); } while (0)
; #define PG8_LDA(dst, b, h) do { _Pragma("unroll") for (int m = 0; m < 4; ++m) _Pragma("unroll") for (int k = 0; k < 2; ++k) dst[m][k] = *(const PG8_LAS bf16x8*)(lds + PG8_SA(b, h) + aoff + m * 2048 + k * 1024); } while (0)
; #define PG8_MMA(ai, bj, At, Bt) do { __builtin_amdgcn_s_setprio(1); _Pragma("unroll") for (int m = 0; m < 4; ++m) _Pragma("unroll") for (int n = 0; n < 2; ++n) _Pragma("unroll") for (int k = 0; k < 2; ++k) \
;         acc[ai][bj][m][n] = __builtin_amdgcn_mfma_f32_16x16x32_bf16(Bt[n][k], At[m][k], acc[ai][bj][m][n], 0, 0, 0); __builtin_amdgcn_s_setprio(0); } while (0)
; #define PG8_BAR __builtin_amdgcn_s_barrier()
;     __device__ __forceinline__ void operator()(const f32x4 (&acc)[2][2][4][2], const Unit& u, int wr, int wc, int fr, int fq) const {
;         const int row0 = u.pm * BM + wr * 64 + fr, col0 = u.pn * 128 + wc * 32 + 8 * fq;
; #pragma unroll
;         for (int ai = 0; ai < 2; ++ai)
; #pragma unroll
;             for (int m = 0; m < 4; ++m) {
;                 bf16_t* rowp = O + (size_t)(row0 + ai * HALF + m * 16) * ldc + col0;
;                 f32x4 h0, h1;
; #pragma unroll
;                 for (int j = 0; j < 4; ++j) { h0[j] = fsilu(acc[ai][0][m][0][j]) * acc[ai][1][m][0][j]; h1[j] = fsilu(acc[ai][0][m][1][j]) * acc[ai][1][m][1][j]; }
;                 *(u32x4*)rowp = pack8(h0, h1);
; template <class Epi, class Sched, bool ALIGN_EPI = false, bool SP2 = false>
; __device__ __forceinline__ void gemm_phase(PG8_LAS unsigned char* lds, const Gemm g, const Sched& S, const Epi& E) {
;     ...
;             PG8_LDA(At, 1, 1); PG8_STAGE(PG8_SB(1, 0), b3, voffB); PG8_STAGE(PG8_SB(1, 1), b3 + hstep, voffB); PG8_STAGE(PG8_SA(1, 0), a3, voffA);
;             PG8_WAIT_V(8); PG8_WAIT_L(0); PG8_BAR; PG8_MMA(1, 0, At, B0); PG8_MMA(1, 1, At, B1); PG8_BAR; PG8_SCHED;
	s_add_i32 s42, s62, s24
	s_add_u32 s86, s40, 0x80
	s_addc_u32 s87, s41, 0
	s_mov_b32 m0, s42
	ds_read_b128 v[184:187], v151 offset:49152
	ds_read_b128 v[188:191], v151 offset:50176
	ds_read_b128 v[192:195], v151 offset:51200
	ds_read_b128 v[196:199], v151 offset:52224
	ds_read_b128 v[200:203], v151 offset:53248
	ds_read_b128 v[204:207], v151 offset:54272
	ds_read_b128 v[208:211], v151 offset:55296
	ds_read_b128 v[214:217], v151 offset:56320
	global_load_lds_dwordx4 v132, s[86:87]
	s_add_i32 m0, s42, 0x2000
	s_add_u32 s40, s40, 0x80080
	s_addc_u32 s41, s41, 0
	s_add_i32 s42, s63, s24
	global_load_lds_dwordx4 v128, s[86:87]
	s_mov_b32 m0, s42
	s_nop 0
	global_load_lds_dwordx4 v132, s[40:41]
	s_add_i32 m0, s42, 0x2000
	s_nop 0
	global_load_lds_dwordx4 v128, s[40:41]
	s_mov_b32 m0, s49
	s_nop 0
	global_load_lds_dwordx4 v134, s[84:85]
	s_mov_b32 m0, s50
	s_nop 0
	global_load_lds_dwordx4 v130, s[84:85]
	s_waitcnt vmcnt(8) lgkmcnt(0)
	s_barrier
	v_mfma_f32_16x16x32_bf16 v[60:63], v[152:155], v[184:187], v[60:63]
	v_mfma_f32_16x16x32_bf16 v[56:59], v[160:163], v[184:187], v[56:59]
	v_mfma_f32_16x16x32_bf16 v[44:47], v[152:155], v[192:195], v[44:47]
	v_mfma_f32_16x16x32_bf16 v[40:43], v[160:163], v[192:195], v[40:43]
	v_mfma_f32_16x16x32_bf16 v[28:31], v[152:155], v[200:203], v[28:31]
	v_mfma_f32_16x16x32_bf16 v[24:27], v[160:163], v[200:203], v[24:27]
	v_mfma_f32_16x16x32_bf16 v[12:15], v[152:155], v[208:211], v[12:15]
	v_mfma_f32_16x16x32_bf16 v[8:11], v[160:163], v[208:211], v[8:11]
	v_mfma_f32_16x16x32_bf16 v[60:63], v[156:159], v[188:191], v[60:63]
	v_mfma_f32_16x16x32_bf16 v[56:59], v[164:167], v[188:191], v[56:59]
	v_mfma_f32_16x16x32_bf16 v[44:47], v[156:159], v[196:199], v[44:47]
	v_mfma_f32_16x16x32_bf16 v[40:43], v[164:167], v[196:199], v[40:43]
	v_mfma_f32_16x16x32_bf16 v[28:31], v[156:159], v[204:207], v[28:31]
	v_mfma_f32_16x16x32_bf16 v[24:27], v[164:167], v[204:207], v[24:27]
	v_mfma_f32_16x16x32_bf16 v[12:15], v[156:159], v[214:217], v[12:15]
	v_mfma_f32_16x16x32_bf16 v[8:11], v[164:167], v[214:217], v[8:11]
	v_mfma_f32_16x16x32_bf16 v[52:55], v[168:171], v[184:187], v[52:55]
	v_mfma_f32_16x16x32_bf16 v[48:51], v[176:179], v[184:187], v[48:51]
	v_mfma_f32_16x16x32_bf16 v[36:39], v[168:171], v[192:195], v[36:39]
	v_mfma_f32_16x16x32_bf16 v[32:35], v[176:179], v[192:195], v[32:35]
	v_mfma_f32_16x16x32_bf16 v[20:23], v[168:171], v[200:203], v[20:23]
	v_mfma_f32_16x16x32_bf16 v[16:19], v[176:179], v[200:203], v[16:19]
	v_mfma_f32_16x16x32_bf16 v[4:7], v[168:171], v[208:211], v[4:7]
	v_mfma_f32_16x16x32_bf16 v[0:3], v[176:179], v[208:211], v[0:3]
	v_mfma_f32_16x16x32_bf16 v[52:55], v[172:175], v[188:191], v[52:55]
	v_mfma_f32_16x16x32_bf16 v[48:51], v[180:183], v[188:191], v[48:51]
	v_mfma_f32_16x16x32_bf16 v[36:39], v[172:175], v[196:199], v[36:39]
	v_mfma_f32_16x16x32_bf16 v[32:35], v[180:183], v[196:199], v[32:35]
	v_mfma_f32_16x16x32_bf16 v[20:23], v[172:175], v[204:207], v[20:23]
	v_mfma_f32_16x16x32_bf16 v[16:19], v[180:183], v[204:207], v[16:19]
	v_mfma_f32_16x16x32_bf16 v[4:7], v[172:175], v[214:217], v[4:7]
	v_mfma_f32_16x16x32_bf16 v[0:3], v[180:183], v[214:217], v[0:3]
	s_barrier
	s_add_i32 s61, s61, 2
	s_add_u32 s38, s38, 0x100
	s_addc_u32 s39, s39, 0
	s_add_u32 s59, s59, 0x100
	s_addc_u32 s60, s60, 0
	s_cmp_gt_u32 s61, 29
	s_cbranch_scc0 .LBB0_169
	v_mul_f32_e32 v153, 0xbfb8aa3b, v124
	v_mul_f32_e32 v158, 0xbfb8aa3b, v120
	v_exp_f32_e32 v153, v153
	v_exp_f32_e32 v159, v158
	v_mul_f32_e32 v158, 0xbfb8aa3b, v125
	v_exp_f32_e32 v160, v158
	v_add_f32_e32 v153, 1.0, v153
	v_rcp_f32_e32 v158, v153
	v_add_f32_e32 v153, 1.0, v159
	v_add_f32_e32 v159, 1.0, v160
	v_rcp_f32_e32 v159, v159
	v_mul_f32_e32 v160, 0xbfb8aa3b, v121
	v_exp_f32_e32 v161, v160
	v_rcp_f32_e32 v160, v153
	v_pk_mul_f32 v[124:125], v[124:125], v[158:159]
	v_mul_f32_e32 v153, 0xbfb8aa3b, v127
	v_pk_mul_f32 v[116:117], v[124:125], v[116:117]
	v_add_f32_e32 v124, 1.0, v161
	v_mul_f32_e32 v125, 0xbfb8aa3b, v122
	v_rcp_f32_e32 v161, v124
	v_mul_f32_e32 v124, 0xbfb8aa3b, v126
	v_exp_f32_e32 v125, v125
	v_exp_f32_e32 v124, v124
	v_exp_f32_e32 v153, v153
	v_mul_f32_e32 v158, 0xbfb8aa3b, v123
	v_exp_f32_e32 v159, v158
	v_add_f32_e32 v125, 1.0, v125
	v_add_f32_e32 v124, 1.0, v124
	v_rcp_f32_e32 v158, v125
	v_add_f32_e32 v125, 1.0, v153
	v_rcp_f32_e32 v124, v124
	v_rcp_f32_e32 v125, v125
	v_add_f32_e32 v153, 1.0, v159
	v_rcp_f32_e32 v159, v153
	v_pk_mul_f32 v[120:121], v[120:121], v[160:161]
	v_lshl_or_b32 v154, s56, 7, v148
	v_pk_mul_f32 v[120:121], v[120:121], v[112:113]
	v_pk_mul_f32 v[112:113], v[126:127], v[124:125]
	v_lshl_add_u32 v152, s36, 8, v146
	v_ashrrev_i32_e32 v155, 31, v154
	v_mov_b64_e32 v[144:145], s[10:11]
	v_pk_mul_f32 v[118:119], v[112:113], v[118:119]
	v_pk_mul_f32 v[112:113], v[122:123], v[158:159]
	v_mad_i64_i32 v[156:157], s[38:39], v152, s55, v[144:145]
	v_pk_mul_f32 v[122:123], v[112:113], v[114:115]
	v_lshlrev_b64 v[112:113], 1, v[154:155]
	v_lshl_add_u64 v[124:125], v[156:157], 0, v[112:113]
	v_cvt_pk_bf16_f32 v114, v116, v117
	v_cvt_pk_bf16_f32 v115, v118, v119
	v_cvt_pk_bf16_f32 v116, v120, v121
	v_cvt_pk_bf16_f32 v117, v122, v123
	global_store_dwordx4 v[124:125], v[114:117], off
	v_mul_f32_e32 v118, 0xbfb8aa3b, v109
	v_exp_f32_e32 v118, v118
	v_mul_f32_e32 v116, 0xbfb8aa3b, v108
	v_mul_f32_e32 v117, 0xbfb8aa3b, v104
	v_exp_f32_e32 v116, v116
	v_exp_f32_e32 v117, v117
	v_or_b32_e32 v114, 16, v152
	v_mad_i64_i32 v[114:115], s[38:39], v114, s55, v[144:145]
	v_add_f32_e32 v116, 1.0, v116
	v_add_f32_e32 v119, 1.0, v117
	v_add_f32_e32 v117, 1.0, v118
	v_rcp_f32_e32 v116, v116
	v_rcp_f32_e32 v117, v117
	v_mul_f32_e32 v118, 0xbfb8aa3b, v105
; __device__ __forceinline__ float fsilu(float v) { return v * fsigmoid(v); }
; __device__ __forceinline__ u32x4 pack8(const f32x4 a, const f32x4 b) { u32x4 w; w.x = cvt_pk_bf16(a[0], a[1]); w.y = cvt_pk_bf16(a[2], a[3]); w.z = cvt_pk_bf16(b[0], b[1]); w.w = cvt_pk_bf16(b[2], b[3]); return w; }
;     __device__ __forceinline__ void operator()(const f32x4 (&acc)[2][2][4][2], const Unit& u, int wr, int wc, int fr, int fq) const {
;         const int row0 = u.pm * BM + wr * 64 + fr, col0 = u.pn * 128 + wc * 32 + 8 * fq;
; #pragma unroll
;         for (int ai = 0; ai < 2; ++ai)
; #pragma unroll
;             for (int m = 0; m < 4; ++m) {
;                 bf16_t* rowp = O + (size_t)(row0 + ai * HALF + m * 16) * ldc + col0;
;                 f32x4 h0, h1;
; #pragma unroll
;                 for (int j = 0; j < 4; ++j) { h0[j] = fsilu(acc[ai][0][m][0][j]) * acc[ai][1][m][0][j]; h1[j] = fsilu(acc[ai][0][m][1][j]) * acc[ai][1][m][1][j]; }
;                 *(u32x4*)rowp = pack8(h0, h1);
	v_exp_f32_e32 v120, v118
	v_rcp_f32_e32 v118, v119
	v_pk_mul_f32 v[108:109], v[108:109], v[116:117]
	v_mul_f32_e32 v116, 0xbfb8aa3b, v111
	v_pk_mul_f32 v[100:101], v[108:109], v[100:101]
	v_add_f32_e32 v108, 1.0, v120
	v_rcp_f32_e32 v119, v108
	v_mul_f32_e32 v109, 0xbfb8aa3b, v106
	v_mul_f32_e32 v108, 0xbfb8aa3b, v110
	v_exp_f32_e32 v109, v109
	v_exp_f32_e32 v108, v108
	v_exp_f32_e32 v117, v116
	v_mul_f32_e32 v116, 0xbfb8aa3b, v107
	v_pk_mul_f32 v[104:105], v[104:105], v[118:119]
	v_exp_f32_e32 v118, v116
	v_add_f32_e32 v109, 1.0, v109
	v_add_f32_e32 v108, 1.0, v108
	v_rcp_f32_e32 v116, v109
	v_add_f32_e32 v109, 1.0, v117
	v_rcp_f32_e32 v108, v108
	v_rcp_f32_e32 v109, v109
	v_add_f32_e32 v117, 1.0, v118
	v_rcp_f32_e32 v117, v117
	v_pk_mul_f32 v[104:105], v[104:105], v[96:97]
	v_pk_mul_f32 v[96:97], v[110:111], v[108:109]
	v_lshl_add_u64 v[108:109], v[114:115], 0, v[112:113]
	v_pk_mul_f32 v[102:103], v[96:97], v[102:103]
	v_pk_mul_f32 v[96:97], v[106:107], v[116:117]
	s_and_b64 vcc, exec, s[8:9]
	v_pk_mul_f32 v[106:107], v[96:97], v[98:99]
	v_cvt_pk_bf16_f32 v96, v100, v101
	v_cvt_pk_bf16_f32 v97, v102, v103
	v_cvt_pk_bf16_f32 v98, v104, v105
	v_cvt_pk_bf16_f32 v99, v106, v107
	global_store_dwordx4 v[108:109], v[96:99], off
	v_mul_f32_e32 v100, 0xbfb8aa3b, v93
	v_exp_f32_e32 v100, v100
	v_mul_f32_e32 v98, 0xbfb8aa3b, v92
	v_mul_f32_e32 v99, 0xbfb8aa3b, v88
	v_exp_f32_e32 v98, v98
	v_exp_f32_e32 v99, v99
	v_or_b32_e32 v96, 32, v152
	v_mad_i64_i32 v[96:97], s[38:39], v96, s55, v[144:145]
	v_add_f32_e32 v98, 1.0, v98
	v_add_f32_e32 v101, 1.0, v99
	v_add_f32_e32 v99, 1.0, v100
	v_rcp_f32_e32 v98, v98
	v_rcp_f32_e32 v99, v99
	v_mul_f32_e32 v100, 0xbfb8aa3b, v89
	v_exp_f32_e32 v102, v100
	v_rcp_f32_e32 v100, v101
	v_pk_mul_f32 v[92:93], v[92:93], v[98:99]
	v_mul_f32_e32 v98, 0xbfb8aa3b, v95
	v_pk_mul_f32 v[84:85], v[92:93], v[84:85]
	v_add_f32_e32 v92, 1.0, v102
	v_rcp_f32_e32 v101, v92
	v_mul_f32_e32 v93, 0xbfb8aa3b, v90
	v_mul_f32_e32 v92, 0xbfb8aa3b, v94
	v_exp_f32_e32 v93, v93
	v_exp_f32_e32 v92, v92
	v_exp_f32_e32 v99, v98
	v_mul_f32_e32 v98, 0xbfb8aa3b, v91
	v_pk_mul_f32 v[88:89], v[88:89], v[100:101]
	v_exp_f32_e32 v100, v98
	v_add_f32_e32 v93, 1.0, v93
	v_add_f32_e32 v92, 1.0, v92
	v_rcp_f32_e32 v98, v93
	v_add_f32_e32 v93, 1.0, v99
	v_rcp_f32_e32 v92, v92
	v_rcp_f32_e32 v93, v93
	v_add_f32_e32 v99, 1.0, v100
	v_rcp_f32_e32 v99, v99
	v_pk_mul_f32 v[88:89], v[88:89], v[80:81]
	v_pk_mul_f32 v[80:81], v[94:95], v[92:93]
	v_lshl_add_u64 v[92:93], v[96:97], 0, v[112:113]
	v_pk_mul_f32 v[86:87], v[80:81], v[86:87]
	v_pk_mul_f32 v[80:81], v[90:91], v[98:99]
	s_mov_b32 s56, s26
	v_pk_mul_f32 v[90:91], v[80:81], v[82:83]
	v_cvt_pk_bf16_f32 v80, v84, v85
	v_cvt_pk_bf16_f32 v81, v86, v87
	v_cvt_pk_bf16_f32 v82, v88, v89
	v_cvt_pk_bf16_f32 v83, v90, v91
	global_store_dwordx4 v[92:93], v[80:83], off
	v_mul_f32_e32 v84, 0xbfb8aa3b, v77
	v_exp_f32_e32 v84, v84
	v_mul_f32_e32 v82, 0xbfb8aa3b, v76
	v_mul_f32_e32 v83, 0xbfb8aa3b, v72
	v_exp_f32_e32 v82, v82
	v_exp_f32_e32 v83, v83
	v_or_b32_e32 v80, 48, v152
	v_mad_i64_i32 v[80:81], s[38:39], v80, s55, v[144:145]
	v_add_f32_e32 v82, 1.0, v82
	v_add_f32_e32 v85, 1.0, v83
	v_add_f32_e32 v83, 1.0, v84
	v_rcp_f32_e32 v82, v82
	v_rcp_f32_e32 v83, v83
	v_mul_f32_e32 v84, 0xbfb8aa3b, v73
	v_exp_f32_e32 v86, v84
	v_rcp_f32_e32 v84, v85
	v_pk_mul_f32 v[76:77], v[76:77], v[82:83]
	v_mul_f32_e32 v82, 0xbfb8aa3b, v79
	v_pk_mul_f32 v[68:69], v[76:77], v[68:69]
	v_add_f32_e32 v76, 1.0, v86
	v_rcp_f32_e32 v85, v76
	v_mul_f32_e32 v77, 0xbfb8aa3b, v74
	v_mul_f32_e32 v76, 0xbfb8aa3b, v78
	v_exp_f32_e32 v77, v77
	v_exp_f32_e32 v76, v76
	v_exp_f32_e32 v83, v82
	v_mul_f32_e32 v82, 0xbfb8aa3b, v75
	v_pk_mul_f32 v[72:73], v[72:73], v[84:85]
	v_exp_f32_e32 v84, v82
	v_add_f32_e32 v77, 1.0, v77
	v_add_f32_e32 v76, 1.0, v76
	v_rcp_f32_e32 v82, v77
	v_add_f32_e32 v77, 1.0, v83
	v_rcp_f32_e32 v76, v76
	v_rcp_f32_e32 v77, v77
	v_add_f32_e32 v83, 1.0, v84
	v_rcp_f32_e32 v83, v83
	v_pk_mul_f32 v[72:73], v[72:73], v[64:65]
	v_pk_mul_f32 v[64:65], v[78:79], v[76:77]
	v_lshl_add_u64 v[76:77], v[80:81], 0, v[112:113]
	v_pk_mul_f32 v[70:71], v[64:65], v[70:71]
	v_pk_mul_f32 v[64:65], v[74:75], v[82:83]
	s_mov_b32 s36, s28
	v_pk_mul_f32 v[74:75], v[64:65], v[66:67]
	v_cvt_pk_bf16_f32 v64, v68, v69
	v_cvt_pk_bf16_f32 v65, v70, v71
	v_cvt_pk_bf16_f32 v66, v72, v73
	v_cvt_pk_bf16_f32 v67, v74, v75
	global_store_dwordx4 v[76:77], v[64:67], off
	v_mul_f32_e32 v68, 0xbfb8aa3b, v61
	v_exp_f32_e32 v68, v68
	v_mul_f32_e32 v66, 0xbfb8aa3b, v60
	v_mul_f32_e32 v67, 0xbfb8aa3b, v56
	v_exp_f32_e32 v66, v66
	v_exp_f32_e32 v67, v67
	v_add_u32_e32 v64, 0x80, v152
	v_mad_i64_i32 v[64:65], s[38:39], v64, s55, v[144:145]
	v_add_f32_e32 v66, 1.0, v66
	v_add_f32_e32 v69, 1.0, v67
	v_add_f32_e32 v67, 1.0, v68
	v_rcp_f32_e32 v66, v66
	v_rcp_f32_e32 v67, v67
	v_mul_f32_e32 v68, 0xbfb8aa3b, v57
	v_exp_f32_e32 v70, v68
	v_rcp_f32_e32 v68, v69
	v_pk_mul_f32 v[60:61], v[60:61], v[66:67]
	v_mul_f32_e32 v66, 0xbfb8aa3b, v63
	v_pk_mul_f32 v[52:53], v[60:61], v[52:53]
	v_add_f32_e32 v60, 1.0, v70
	v_rcp_f32_e32 v69, v60
	v_mul_f32_e32 v61, 0xbfb8aa3b, v58
	v_mul_f32_e32 v60, 0xbfb8aa3b, v62
	v_exp_f32_e32 v61, v61
	v_exp_f32_e32 v60, v60
	v_exp_f32_e32 v67, v66
	v_mul_f32_e32 v66, 0xbfb8aa3b, v59
	v_pk_mul_f32 v[56:57], v[56:57], v[68:69]
	v_exp_f32_e32 v68, v66
	v_add_f32_e32 v61, 1.0, v61
	v_add_f32_e32 v60, 1.0, v60
	v_rcp_f32_e32 v66, v61
; __device__ __forceinline__ float fsilu(float v) { return v * fsigmoid(v); }
; __device__ __forceinline__ u32x4 pack8(const f32x4 a, const f32x4 b) { u32x4 w; w.x = cvt_pk_bf16(a[0], a[1]); w.y = cvt_pk_bf16(a[2], a[3]); w.z = cvt_pk_bf16(b[0], b[1]); w.w = cvt_pk_bf16(b[2], b[3]); return w; }
; #define PG8_WAIT_V(n) asm volatile("s_waitcnt vmcnt(" #n ")" ::: "memory")
; #define PG8_BAR __builtin_amdgcn_s_barrier()
;     __device__ __forceinline__ void operator()(const f32x4 (&acc)[2][2][4][2], const Unit& u, int wr, int wc, int fr, int fq) const {
;         const int row0 = u.pm * BM + wr * 64 + fr, col0 = u.pn * 128 + wc * 32 + 8 * fq;
; #pragma unroll
;         for (int ai = 0; ai < 2; ++ai)
; #pragma unroll
;             for (int m = 0; m < 4; ++m) {
;                 bf16_t* rowp = O + (size_t)(row0 + ai * HALF + m * 16) * ldc + col0;
;                 f32x4 h0, h1;
; #pragma unroll
;                 for (int j = 0; j < 4; ++j) { h0[j] = fsilu(acc[ai][0][m][0][j]) * acc[ai][1][m][0][j]; h1[j] = fsilu(acc[ai][0][m][1][j]) * acc[ai][1][m][1][j]; }
;                 *(u32x4*)rowp = pack8(h0, h1);
; template <class Epi, class Sched, bool ALIGN_EPI = false, bool SP2 = false>
; __device__ __forceinline__ void gemm_phase(PG8_LAS unsigned char* lds, const Gemm g, const Sched& S, const Epi& E) {
;     ...
;         if constexpr (!Epi::AFTER_DRAIN) { E(acc, cur, wr, wc, fr, fq); S.done(cur); }
;         if (!has_next) break;
; #pragma unroll
;         for (int a = 0; a < 2; ++a)
; #pragma unroll
;             for (int b = 0; b < 2; ++b)
; #pragma unroll
;                 for (int m = 0; m < 4; ++m)
; #pragma unroll
;                     for (int n = 0; n < 2; ++n) acc[a][b][m][n] = (f32x4){0.f, 0.f, 0.f, 0.f};
;         cur = nxt; cA = nA; cB = nB; ++ui;
;         if constexpr (ALIGN_EPI) { if (wr == 1) PG8_BAR; }
;     }
;     PG8_WAIT_V(0);
;     if constexpr (!ALIGN_EPI) { if (wr == 0) PG8_BAR; }
;     PG8_BAR;
	v_add_f32_e32 v61, 1.0, v67
	v_rcp_f32_e32 v60, v60
	v_rcp_f32_e32 v61, v61
	v_add_f32_e32 v67, 1.0, v68
	v_rcp_f32_e32 v67, v67
	v_pk_mul_f32 v[56:57], v[56:57], v[48:49]
	v_pk_mul_f32 v[48:49], v[62:63], v[60:61]
	v_lshl_add_u64 v[60:61], v[64:65], 0, v[112:113]
	v_pk_mul_f32 v[54:55], v[48:49], v[54:55]
	v_pk_mul_f32 v[48:49], v[58:59], v[66:67]
	s_mov_b64 s[40:41], s[34:35]
	v_pk_mul_f32 v[58:59], v[48:49], v[50:51]
	v_cvt_pk_bf16_f32 v48, v52, v53
	v_cvt_pk_bf16_f32 v49, v54, v55
	v_cvt_pk_bf16_f32 v50, v56, v57
	v_cvt_pk_bf16_f32 v51, v58, v59
	global_store_dwordx4 v[60:61], v[48:51], off
	v_mul_f32_e32 v52, 0xbfb8aa3b, v45
	v_exp_f32_e32 v52, v52
	v_mul_f32_e32 v50, 0xbfb8aa3b, v44
	v_mul_f32_e32 v51, 0xbfb8aa3b, v40
	v_exp_f32_e32 v50, v50
	v_exp_f32_e32 v51, v51
	v_add_u32_e32 v48, 0x90, v152
	v_mad_i64_i32 v[48:49], s[38:39], v48, s55, v[144:145]
	v_add_f32_e32 v50, 1.0, v50
	v_add_f32_e32 v53, 1.0, v51
	v_add_f32_e32 v51, 1.0, v52
	v_rcp_f32_e32 v50, v50
	v_rcp_f32_e32 v51, v51
	v_mul_f32_e32 v52, 0xbfb8aa3b, v41
	v_exp_f32_e32 v54, v52
	v_rcp_f32_e32 v52, v53
	v_pk_mul_f32 v[44:45], v[44:45], v[50:51]
	v_mul_f32_e32 v50, 0xbfb8aa3b, v47
	v_pk_mul_f32 v[36:37], v[44:45], v[36:37]
	v_add_f32_e32 v44, 1.0, v54
	v_rcp_f32_e32 v53, v44
	v_mul_f32_e32 v45, 0xbfb8aa3b, v42
	v_mul_f32_e32 v44, 0xbfb8aa3b, v46
	v_exp_f32_e32 v45, v45
	v_exp_f32_e32 v44, v44
	v_exp_f32_e32 v51, v50
	v_mul_f32_e32 v50, 0xbfb8aa3b, v43
	v_pk_mul_f32 v[40:41], v[40:41], v[52:53]
	v_exp_f32_e32 v52, v50
	v_add_f32_e32 v45, 1.0, v45
	v_add_f32_e32 v44, 1.0, v44
	v_rcp_f32_e32 v50, v45
	v_add_f32_e32 v45, 1.0, v51
	v_rcp_f32_e32 v44, v44
	v_rcp_f32_e32 v45, v45
	v_add_f32_e32 v51, 1.0, v52
	v_rcp_f32_e32 v51, v51
	v_pk_mul_f32 v[40:41], v[40:41], v[32:33]
	v_pk_mul_f32 v[32:33], v[46:47], v[44:45]
	v_lshl_add_u64 v[44:45], v[48:49], 0, v[112:113]
	v_pk_mul_f32 v[38:39], v[32:33], v[38:39]
	v_pk_mul_f32 v[32:33], v[42:43], v[50:51]
	s_nop 0
	v_pk_mul_f32 v[42:43], v[32:33], v[34:35]
	v_cvt_pk_bf16_f32 v32, v36, v37
	v_cvt_pk_bf16_f32 v33, v38, v39
	v_cvt_pk_bf16_f32 v34, v40, v41
	v_cvt_pk_bf16_f32 v35, v42, v43
	global_store_dwordx4 v[44:45], v[32:35], off
	v_mul_f32_e32 v36, 0xbfb8aa3b, v29
	v_exp_f32_e32 v36, v36
	v_mul_f32_e32 v34, 0xbfb8aa3b, v28
	v_mul_f32_e32 v35, 0xbfb8aa3b, v24
	v_exp_f32_e32 v34, v34
	v_exp_f32_e32 v35, v35
	v_add_u32_e32 v32, 0xa0, v152
	v_mad_i64_i32 v[32:33], s[38:39], v32, s55, v[144:145]
	v_add_f32_e32 v34, 1.0, v34
	v_add_f32_e32 v37, 1.0, v35
	v_add_f32_e32 v35, 1.0, v36
	v_rcp_f32_e32 v34, v34
	v_rcp_f32_e32 v35, v35
	v_mul_f32_e32 v36, 0xbfb8aa3b, v25
	v_exp_f32_e32 v38, v36
	v_rcp_f32_e32 v36, v37
	v_pk_mul_f32 v[28:29], v[28:29], v[34:35]
	v_mul_f32_e32 v34, 0xbfb8aa3b, v31
	v_pk_mul_f32 v[20:21], v[28:29], v[20:21]
	v_add_f32_e32 v28, 1.0, v38
	v_rcp_f32_e32 v37, v28
	v_mul_f32_e32 v29, 0xbfb8aa3b, v26
	v_mul_f32_e32 v28, 0xbfb8aa3b, v30
	v_exp_f32_e32 v29, v29
	v_exp_f32_e32 v28, v28
	v_exp_f32_e32 v35, v34
	v_mul_f32_e32 v34, 0xbfb8aa3b, v27
	v_pk_mul_f32 v[24:25], v[24:25], v[36:37]
	v_exp_f32_e32 v36, v34
	v_add_f32_e32 v29, 1.0, v29
	v_add_f32_e32 v28, 1.0, v28
	v_rcp_f32_e32 v34, v29
	v_add_f32_e32 v29, 1.0, v35
	v_rcp_f32_e32 v28, v28
	v_rcp_f32_e32 v29, v29
	v_add_f32_e32 v35, 1.0, v36
	v_rcp_f32_e32 v35, v35
	v_pk_mul_f32 v[24:25], v[24:25], v[16:17]
	v_pk_mul_f32 v[16:17], v[30:31], v[28:29]
	v_lshl_add_u64 v[28:29], v[32:33], 0, v[112:113]
	v_pk_mul_f32 v[22:23], v[16:17], v[22:23]
	v_pk_mul_f32 v[16:17], v[26:27], v[34:35]
	s_nop 0
	v_pk_mul_f32 v[26:27], v[16:17], v[18:19]
	v_cvt_pk_bf16_f32 v16, v20, v21
	v_cvt_pk_bf16_f32 v17, v22, v23
	v_cvt_pk_bf16_f32 v18, v24, v25
	v_cvt_pk_bf16_f32 v19, v26, v27
	global_store_dwordx4 v[28:29], v[16:19], off
	v_mul_f32_e32 v20, 0xbfb8aa3b, v13
	v_exp_f32_e32 v20, v20
	v_mul_f32_e32 v18, 0xbfb8aa3b, v12
	v_mul_f32_e32 v19, 0xbfb8aa3b, v8
	v_exp_f32_e32 v18, v18
	v_exp_f32_e32 v19, v19
	v_add_u32_e32 v16, 0xb0, v152
	v_mad_i64_i32 v[16:17], s[38:39], v16, s55, v[144:145]
	v_add_f32_e32 v18, 1.0, v18
	v_add_f32_e32 v21, 1.0, v19
	v_add_f32_e32 v19, 1.0, v20
	v_rcp_f32_e32 v18, v18
	v_rcp_f32_e32 v19, v19
	v_mul_f32_e32 v20, 0xbfb8aa3b, v9
	v_exp_f32_e32 v22, v20
	v_rcp_f32_e32 v20, v21
	v_pk_mul_f32 v[12:13], v[12:13], v[18:19]
	v_mul_f32_e32 v18, 0xbfb8aa3b, v15
	v_pk_mul_f32 v[4:5], v[12:13], v[4:5]
	v_add_f32_e32 v12, 1.0, v22
	v_rcp_f32_e32 v21, v12
	v_mul_f32_e32 v13, 0xbfb8aa3b, v10
	v_mul_f32_e32 v12, 0xbfb8aa3b, v14
	v_exp_f32_e32 v13, v13
	v_exp_f32_e32 v12, v12
	v_exp_f32_e32 v19, v18
	v_mul_f32_e32 v18, 0xbfb8aa3b, v11
	v_pk_mul_f32 v[8:9], v[8:9], v[20:21]
	v_exp_f32_e32 v20, v18
	v_add_f32_e32 v13, 1.0, v13
	v_add_f32_e32 v12, 1.0, v12
	v_rcp_f32_e32 v18, v13
	v_add_f32_e32 v13, 1.0, v19
	v_rcp_f32_e32 v12, v12
	v_rcp_f32_e32 v13, v13
	v_add_f32_e32 v19, 1.0, v20
	v_rcp_f32_e32 v19, v19
	v_pk_mul_f32 v[8:9], v[8:9], v[0:1]
	v_pk_mul_f32 v[0:1], v[14:15], v[12:13]
	v_lshl_add_u64 v[12:13], v[16:17], 0, v[112:113]
	v_pk_mul_f32 v[6:7], v[0:1], v[6:7]
	v_pk_mul_f32 v[0:1], v[10:11], v[18:19]
	s_mov_b64 s[38:39], s[30:31]
	v_pk_mul_f32 v[10:11], v[0:1], v[2:3]
	v_cvt_pk_bf16_f32 v0, v4, v5
	v_cvt_pk_bf16_f32 v1, v6, v7
	v_cvt_pk_bf16_f32 v2, v8, v9
	v_cvt_pk_bf16_f32 v3, v10, v11
	global_store_dwordx4 v[12:13], v[0:3], off
	s_cbranch_vccz .LBB0_166
	s_waitcnt vmcnt(0)
	s_cmpk_gt_u32 s3, 0xff
	s_cbranch_scc1 .LBB0_173
	s_barrier

; #define PG8_STAGE(bufoff, gbase, voff) do { _Pragma("unroll") for (int _i = 0; _i < 2; ++_i) \
;         __builtin_amdgcn_global_load_lds((const unsigned*)((const char*)(gbase) + (voff)[_i]), (PG8_LAS unsigned*)(lds + (bufoff) + ldsw + _i * 8192), 16, 0, 0); } while (0)
; #define PG8_LDA(dst, b, h) do { _Pragma("unroll") for (int m = 0; m < 4; ++m) _Pragma("unroll") for (int k = 0; k < 2; ++k) dst[m][k] = *(const PG8_LAS bf16x8*)(lds + PG8_SA(b, h) + aoff + m * 2048 + k * 1024); } while (0)
; #define PG8_LDB(dst, b, h) do { _Pragma("unroll") for (int n = 0; n < 2; ++n) _Pragma("unroll") for (int k = 0; k < 2; ++k) dst[n][k] = *(const PG8_LAS bf16x8*)(lds + PG8_SB(b, h) + boff + n * 2048 + k * 1024); } while (0)
; #define PG8_WAIT_V(n) asm volatile("s_waitcnt vmcnt(" #n ")" ::: "memory")
; #define PG8_WAIT_L(n) asm volatile("s_waitcnt lgkmcnt(" #n ")" ::: "memory")
; #define PG8_BAR __builtin_amdgcn_s_barrier()
; #define PG8_SCHED __builtin_amdgcn_sched_barrier(0)
; template <class Epi, class Sched, bool ALIGN_EPI = false, bool SP2 = false>
; __device__ __forceinline__ void gemm_phase(PG8_LAS unsigned char* lds, const Gemm g, const Sched& S, const Epi& E) {
;     ...
;         const bool has_next = S.next(ui + 1, nxt);
;         const char* nA = has_next ? (const char*)g.A + (size_t)nxt.pm * tstep : cA; const char* nB = has_next ? (const char*)g.Bt + (size_t)nxt.pn * tstep : cB;
;         for (int t = 0; t < nt; t += 2) {
;             const bool last = (t == nt - 2);
;             const char* a1 = cA + (size_t)(t + 1) * kstep;
;             const char* a2 = last ? nA : cA + (size_t)(t + 2) * kstep; const char* b2 = last ? nB : cB + (size_t)(t + 2) * kstep;
;             const char* a3 = a2 + kstep; const char* b3 = b2 + kstep;
;             if (last && has_next) S.a_ready(nxt);
;             if constexpr (SP2) {
;             PG8_LDB(B0, 0, 0); PG8_LDB(B1, 0, 1); PG8_SCHED; PG8_LDA(At, 0, 0); PG8_STAGE(PG8_SA(1, 1), a1 + hstep, voffA);
;             PG8_WAIT_V(8); PG8_WAIT_L(0); PG8_BAR; PG8_MMA(0, 0, At, B0); PG8_MMA(0, 1, At, B1); PG8_BAR; PG8_SCHED;
;             PG8_LDA(At, 0, 1); PG8_STAGE(PG8_SB(0, 0), b2, voffB); PG8_STAGE(PG8_SB(0, 1), b2 + hstep, voffB); PG8_STAGE(PG8_SA(0, 0), a2, voffA);
;             PG8_WAIT_V(8); PG8_WAIT_L(0); PG8_BAR; PG8_MMA(1, 0, At, B0); PG8_MMA(1, 1, At, B1); PG8_BAR; PG8_SCHED;
.LBB0_244:
	s_add_u32 s67, s46, 0x100
	v_mov_b32_e32 v220, v251
	s_addc_u32 s68, s47, 0
	s_mov_b32 s69, -2
	ds_read_b128 v[140:143], v169
	ds_read_b128 v[144:147], v169 offset:1024
	ds_read_b128 v[148:151], v169 offset:2048
	ds_read_b128 v[152:155], v169 offset:3072
	ds_read_b128 v[156:159], v170
	ds_read_b128 v[160:163], v170 offset:1024
	ds_read_b128 v[172:175], v170 offset:2048
	ds_read_b128 v[176:179], v170 offset:3072
	s_add_u32 s46, s44, 0x100
	s_addc_u32 s47, s45, 0
	s_cmpk_eq_i32 s69, 0x54
	s_cselect_b32 s51, s11, s47
	s_cselect_b32 s50, s10, s46
	s_cselect_b32 s49, s13, s68
	s_cselect_b32 s48, s12, s67
	s_add_i32 m0, s26, 0xc000
	ds_read_b128 v[180:183], v171
	ds_read_b128 v[184:187], v171 offset:1024
	ds_read_b128 v[188:191], v171 offset:2048
	ds_read_b128 v[192:195], v171 offset:3072
	ds_read_b128 v[196:199], v171 offset:4096
	ds_read_b128 v[200:203], v171 offset:5120
	ds_read_b128 v[204:207], v171 offset:6144
	ds_read_b128 v[208:211], v171 offset:7168
	global_load_lds_dwordx4 v136, s[44:45]
	s_add_i32 m0, s26, 0xe000
	s_nop 0
	global_load_lds_dwordx4 v138, s[44:45]
	s_waitcnt vmcnt(8) lgkmcnt(0)
	s_barrier
	v_mfma_f32_16x16x32_bf16 v[124:127], v[140:143], v[180:183], 0
	v_mfma_f32_16x16x32_bf16 v[120:123], v[148:151], v[180:183], 0
	v_mfma_f32_16x16x32_bf16 v[116:119], v[140:143], v[188:191], 0
	v_mfma_f32_16x16x32_bf16 v[112:115], v[148:151], v[188:191], 0
	v_mfma_f32_16x16x32_bf16 v[108:111], v[140:143], v[196:199], 0
	v_mfma_f32_16x16x32_bf16 v[96:99], v[148:151], v[196:199], 0
	v_mfma_f32_16x16x32_bf16 v[84:87], v[140:143], v[204:207], 0
	v_mfma_f32_16x16x32_bf16 v[76:79], v[148:151], v[204:207], 0
	v_mfma_f32_16x16x32_bf16 v[124:127], v[144:147], v[184:187], v[124:127]
	v_mfma_f32_16x16x32_bf16 v[120:123], v[152:155], v[184:187], v[120:123]
	v_mfma_f32_16x16x32_bf16 v[116:119], v[144:147], v[192:195], v[116:119]
	v_mfma_f32_16x16x32_bf16 v[112:115], v[152:155], v[192:195], v[112:115]
	v_mfma_f32_16x16x32_bf16 v[108:111], v[144:147], v[200:203], v[108:111]
	v_mfma_f32_16x16x32_bf16 v[96:99], v[152:155], v[200:203], v[96:99]
	v_mfma_f32_16x16x32_bf16 v[84:87], v[144:147], v[208:211], v[84:87]
	v_mfma_f32_16x16x32_bf16 v[76:79], v[152:155], v[208:211], v[76:79]
	v_mfma_f32_16x16x32_bf16 v[104:107], v[156:159], v[180:183], 0
	v_mfma_f32_16x16x32_bf16 v[100:103], v[172:175], v[180:183], 0
	v_mfma_f32_16x16x32_bf16 v[92:95], v[156:159], v[188:191], 0
	v_mfma_f32_16x16x32_bf16 v[88:91], v[172:175], v[188:191], 0
	v_mfma_f32_16x16x32_bf16 v[80:83], v[156:159], v[196:199], 0
	v_mfma_f32_16x16x32_bf16 v[72:75], v[172:175], v[196:199], 0
	v_mfma_f32_16x16x32_bf16 v[68:71], v[156:159], v[204:207], 0
	v_mfma_f32_16x16x32_bf16 v[64:67], v[172:175], v[204:207], 0
	v_mfma_f32_16x16x32_bf16 v[104:107], v[160:163], v[184:187], v[104:107]
	v_mfma_f32_16x16x32_bf16 v[100:103], v[176:179], v[184:187], v[100:103]
	v_mfma_f32_16x16x32_bf16 v[92:95], v[160:163], v[192:195], v[92:95]
	v_mfma_f32_16x16x32_bf16 v[88:91], v[176:179], v[192:195], v[88:91]
	v_mfma_f32_16x16x32_bf16 v[80:83], v[160:163], v[200:203], v[80:83]
	v_mfma_f32_16x16x32_bf16 v[72:75], v[176:179], v[200:203], v[72:75]
	v_mfma_f32_16x16x32_bf16 v[68:71], v[160:163], v[208:211], v[68:71]
	v_mfma_f32_16x16x32_bf16 v[64:67], v[176:179], v[208:211], v[64:67]
	s_barrier
	s_add_i32 s44, s61, s25
	s_mov_b32 m0, s44
	ds_read_b128 v[180:183], v171 offset:16384
	ds_read_b128 v[184:187], v171 offset:17408
	ds_read_b128 v[188:191], v171 offset:18432
	ds_read_b128 v[192:195], v171 offset:19456
	ds_read_b128 v[196:199], v171 offset:20480
	ds_read_b128 v[200:203], v171 offset:21504
	ds_read_b128 v[204:207], v171 offset:22528
	ds_read_b128 v[208:211], v171 offset:23552
	global_load_lds_dwordx4 v130, s[48:49]
	s_add_i32 m0, s44, 0x2000
	s_add_u32 s44, s48, 0x160000
	s_addc_u32 s45, s49, 0
	s_add_i32 s70, s62, s25
	global_load_lds_dwordx4 v134, s[48:49]
	s_mov_b32 m0, s70
	s_nop 0
	global_load_lds_dwordx4 v130, s[44:45]
	s_add_i32 m0, s70, 0x2000
	s_nop 0
	global_load_lds_dwordx4 v134, s[44:45]
	s_mov_b32 m0, s26
	s_nop 0
	global_load_lds_dwordx4 v128, s[50:51]
	s_mov_b32 m0, s27
	s_nop 0
	global_load_lds_dwordx4 v132, s[50:51]
	s_waitcnt vmcnt(8) lgkmcnt(0)
	s_barrier
	v_mfma_f32_16x16x32_bf16 v[60:63], v[140:143], v[180:183], 0
	v_mfma_f32_16x16x32_bf16 v[56:59], v[148:151], v[180:183], 0
	v_mfma_f32_16x16x32_bf16 v[52:55], v[140:143], v[188:191], 0
	v_mfma_f32_16x16x32_bf16 v[48:51], v[148:151], v[188:191], 0
	v_mfma_f32_16x16x32_bf16 v[44:47], v[140:143], v[196:199], 0
	v_mfma_f32_16x16x32_bf16 v[32:35], v[148:151], v[196:199], 0
	v_mfma_f32_16x16x32_bf16 v[20:23], v[140:143], v[204:207], 0
	v_mfma_f32_16x16x32_bf16 v[12:15], v[148:151], v[204:207], 0
	v_mfma_f32_16x16x32_bf16 v[60:63], v[144:147], v[184:187], v[60:63]
	v_mfma_f32_16x16x32_bf16 v[56:59], v[152:155], v[184:187], v[56:59]
	v_mfma_f32_16x16x32_bf16 v[52:55], v[144:147], v[192:195], v[52:55]
	v_mfma_f32_16x16x32_bf16 v[48:51], v[152:155], v[192:195], v[48:51]
	v_mfma_f32_16x16x32_bf16 v[44:47], v[144:147], v[200:203], v[44:47]
	v_mfma_f32_16x16x32_bf16 v[32:35], v[152:155], v[200:203], v[32:35]
	v_mfma_f32_16x16x32_bf16 v[20:23], v[144:147], v[208:211], v[20:23]
	v_mfma_f32_16x16x32_bf16 v[12:15], v[152:155], v[208:211], v[12:15]
	v_mfma_f32_16x16x32_bf16 v[40:43], v[156:159], v[180:183], 0
	v_mfma_f32_16x16x32_bf16 v[36:39], v[172:175], v[180:183], 0
	v_mfma_f32_16x16x32_bf16 v[28:31], v[156:159], v[188:191], 0
	v_mfma_f32_16x16x32_bf16 v[24:27], v[172:175], v[188:191], 0
	v_mfma_f32_16x16x32_bf16 v[16:19], v[156:159], v[196:199], 0
	v_mfma_f32_16x16x32_bf16 v[8:11], v[172:175], v[196:199], 0
	v_mfma_f32_16x16x32_bf16 v[4:7], v[156:159], v[204:207], 0
	v_mfma_f32_16x16x32_bf16 v[0:3], v[172:175], v[204:207], 0
	v_mfma_f32_16x16x32_bf16 v[40:43], v[160:163], v[184:187], v[40:43]
	v_mfma_f32_16x16x32_bf16 v[36:39], v[176:179], v[184:187], v[36:39]
	v_mfma_f32_16x16x32_bf16 v[28:31], v[160:163], v[192:195], v[28:31]
	v_mfma_f32_16x16x32_bf16 v[24:27], v[176:179], v[192:195], v[24:27]
	v_mfma_f32_16x16x32_bf16 v[16:19], v[160:163], v[200:203], v[16:19]
	v_mfma_f32_16x16x32_bf16 v[8:11], v[176:179], v[200:203], v[8:11]
	v_mfma_f32_16x16x32_bf16 v[4:7], v[160:163], v[208:211], v[4:7]
	v_mfma_f32_16x16x32_bf16 v[0:3], v[176:179], v[208:211], v[0:3]
	s_barrier
; #define PG8_STAGE(bufoff, gbase, voff) do { _Pragma("unroll") for (int _i = 0; _i < 2; ++_i) \
;         __builtin_amdgcn_global_load_lds((const unsigned*)((const char*)(gbase) + (voff)[_i]), (PG8_LAS unsigned*)(lds + (bufoff) + ldsw + _i * 8192), 16, 0, 0); } while (0)
; #define PG8_LDA(dst, b, h) do { _Pragma("unroll") for (int m = 0; m < 4; ++m) _Pragma("unroll") for (int k = 0; k < 2; ++k) dst[m][k] = *(const PG8_LAS bf16x8*)(lds + PG8_SA(b, h) + aoff + m * 2048 + k * 1024); } while (0)
; #define PG8_LDB(dst, b, h) do { _Pragma("unroll") for (int n = 0; n < 2; ++n) _Pragma("unroll") for (int k = 0; k < 2; ++k) dst[n][k] = *(const PG8_LAS bf16x8*)(lds + PG8_SB(b, h) + boff + n * 2048 + k * 1024); } while (0)
; #define PG8_MMA(ai, bj, At, Bt) do { __builtin_amdgcn_s_setprio(1); _Pragma("unroll") for (int m = 0; m < 4; ++m) _Pragma("unroll") for (int n = 0; n < 2; ++n) _Pragma("unroll") for (int k = 0; k < 2; ++k) \
;         acc[ai][bj][m][n] = __builtin_amdgcn_mfma_f32_16x16x32_bf16(Bt[n][k], At[m][k], acc[ai][bj][m][n], 0, 0, 0); __builtin_amdgcn_s_setprio(0); } while (0)
; #define PG8_WAIT_V(n) asm volatile("s_waitcnt vmcnt(" #n ")" ::: "memory")
; #define PG8_WAIT_L(n) asm volatile("s_waitcnt lgkmcnt(" #n ")" ::: "memory")
; #define PG8_BAR __builtin_amdgcn_s_barrier()
; #define PG8_SCHED __builtin_amdgcn_sched_barrier(0)
; template <class Epi, class Sched, bool ALIGN_EPI = false, bool SP2 = false>
; __device__ __forceinline__ void gemm_phase(PG8_LAS unsigned char* lds, const Gemm g, const Sched& S, const Epi& E) {
;     ...
;             PG8_LDB(B0, 1, 0); PG8_LDB(B1, 1, 1); PG8_SCHED; PG8_LDA(At, 1, 0); PG8_STAGE(PG8_SA(0, 1), a2 + hstep, voffA);
;             PG8_WAIT_V(8); PG8_WAIT_L(0); PG8_BAR; PG8_MMA(0, 0, At, B0); PG8_MMA(0, 1, At, B1); PG8_BAR; PG8_SCHED;
;             PG8_LDA(At, 1, 1); PG8_STAGE(PG8_SB(1, 0), b3, voffB); PG8_STAGE(PG8_SB(1, 1), b3 + hstep, voffB); PG8_STAGE(PG8_SA(1, 0), a3, voffA);
;             PG8_WAIT_V(8); PG8_WAIT_L(0); PG8_BAR; PG8_MMA(1, 0, At, B0); PG8_MMA(1, 1, At, B1); PG8_BAR; PG8_SCHED;
	s_add_i32 s70, 0, 0x18000
	s_add_i32 s71, 0, 0x1c000
	v_add_u32_e32 v152, s70, v167
	v_add_u32_e32 v176, s71, v167
	ds_read_b128 v[140:143], v152
	ds_read_b128 v[144:147], v152 offset:1024
	ds_read_b128 v[148:151], v152 offset:2048
	ds_read_b128 v[152:155], v152 offset:3072
	ds_read_b128 v[156:159], v176
	ds_read_b128 v[160:163], v176 offset:1024
	ds_read_b128 v[172:175], v176 offset:2048
	ds_read_b128 v[176:179], v176 offset:3072
	s_add_u32 s44, s50, 0x160000
	s_addc_u32 s45, s51, 0
	s_mov_b32 m0, s52
	ds_read_b128 v[180:183], v171 offset:32768
	ds_read_b128 v[184:187], v171 offset:33792
	ds_read_b128 v[188:191], v171 offset:34816
	ds_read_b128 v[192:195], v171 offset:35840
	ds_read_b128 v[196:199], v171 offset:36864
	ds_read_b128 v[200:203], v171 offset:37888
	ds_read_b128 v[204:207], v171 offset:38912
	ds_read_b128 v[208:211], v171 offset:39936
	global_load_lds_dwordx4 v128, s[44:45]
	s_mov_b32 m0, s53
	s_nop 0
	global_load_lds_dwordx4 v132, s[44:45]
	s_waitcnt vmcnt(8) lgkmcnt(0)
	s_barrier
	v_mfma_f32_16x16x32_bf16 v[124:127], v[140:143], v[180:183], v[124:127]
	v_mfma_f32_16x16x32_bf16 v[120:123], v[148:151], v[180:183], v[120:123]
	v_mfma_f32_16x16x32_bf16 v[116:119], v[140:143], v[188:191], v[116:119]
	v_mfma_f32_16x16x32_bf16 v[112:115], v[148:151], v[188:191], v[112:115]
	v_mfma_f32_16x16x32_bf16 v[108:111], v[140:143], v[196:199], v[108:111]
	v_mfma_f32_16x16x32_bf16 v[96:99], v[148:151], v[196:199], v[96:99]
	v_mfma_f32_16x16x32_bf16 v[84:87], v[140:143], v[204:207], v[84:87]
	v_mfma_f32_16x16x32_bf16 v[76:79], v[148:151], v[204:207], v[76:79]
	v_mfma_f32_16x16x32_bf16 v[124:127], v[144:147], v[184:187], v[124:127]
	v_mfma_f32_16x16x32_bf16 v[120:123], v[152:155], v[184:187], v[120:123]
	v_mfma_f32_16x16x32_bf16 v[116:119], v[144:147], v[192:195], v[116:119]
	v_mfma_f32_16x16x32_bf16 v[112:115], v[152:155], v[192:195], v[112:115]
	v_mfma_f32_16x16x32_bf16 v[108:111], v[144:147], v[200:203], v[108:111]
	v_mfma_f32_16x16x32_bf16 v[96:99], v[152:155], v[200:203], v[96:99]
	v_mfma_f32_16x16x32_bf16 v[84:87], v[144:147], v[208:211], v[84:87]
	v_mfma_f32_16x16x32_bf16 v[76:79], v[152:155], v[208:211], v[76:79]
	v_mfma_f32_16x16x32_bf16 v[104:107], v[156:159], v[180:183], v[104:107]
	v_mfma_f32_16x16x32_bf16 v[100:103], v[172:175], v[180:183], v[100:103]
	v_mfma_f32_16x16x32_bf16 v[92:95], v[156:159], v[188:191], v[92:95]
	v_mfma_f32_16x16x32_bf16 v[88:91], v[172:175], v[188:191], v[88:91]
	v_mfma_f32_16x16x32_bf16 v[80:83], v[156:159], v[196:199], v[80:83]
	v_mfma_f32_16x16x32_bf16 v[72:75], v[172:175], v[196:199], v[72:75]
	v_mfma_f32_16x16x32_bf16 v[68:71], v[156:159], v[204:207], v[68:71]
	v_mfma_f32_16x16x32_bf16 v[64:67], v[172:175], v[204:207], v[64:67]
	v_mfma_f32_16x16x32_bf16 v[104:107], v[160:163], v[184:187], v[104:107]
	v_mfma_f32_16x16x32_bf16 v[100:103], v[176:179], v[184:187], v[100:103]
	v_mfma_f32_16x16x32_bf16 v[92:95], v[160:163], v[192:195], v[92:95]
	v_mfma_f32_16x16x32_bf16 v[88:91], v[176:179], v[192:195], v[88:91]
	v_mfma_f32_16x16x32_bf16 v[80:83], v[160:163], v[200:203], v[80:83]
	v_mfma_f32_16x16x32_bf16 v[72:75], v[176:179], v[200:203], v[72:75]
	v_mfma_f32_16x16x32_bf16 v[68:71], v[160:163], v[208:211], v[68:71]
	v_mfma_f32_16x16x32_bf16 v[64:67], v[176:179], v[208:211], v[64:67]
	s_barrier
	s_add_i32 s44, s70, s25
	s_add_u32 s86, s48, 0x80
	s_addc_u32 s87, s49, 0
	s_mov_b32 m0, s44
	ds_read_b128 v[180:183], v171 offset:49152
	ds_read_b128 v[184:187], v171 offset:50176
	ds_read_b128 v[188:191], v171 offset:51200
	ds_read_b128 v[192:195], v171 offset:52224
	ds_read_b128 v[196:199], v171 offset:53248
	ds_read_b128 v[200:203], v171 offset:54272
	ds_read_b128 v[204:207], v171 offset:55296
	ds_read_b128 v[208:211], v171 offset:56320
	global_load_lds_dwordx4 v130, s[86:87]
	s_add_i32 m0, s44, 0x2000
	s_add_u32 s44, s48, 0x160080
	s_addc_u32 s45, s49, 0
	s_add_i32 s48, s71, s25
	global_load_lds_dwordx4 v134, s[86:87]
	s_mov_b32 m0, s48
	s_nop 0
	global_load_lds_dwordx4 v130, s[44:45]
	s_add_i32 m0, s48, 0x2000
	s_nop 0
	global_load_lds_dwordx4 v134, s[44:45]
	s_add_u32 s84, s50, 0x80
	s_addc_u32 s85, s51, 0
	s_mov_b32 m0, s57
	s_nop 0
	global_load_lds_dwordx4 v128, s[84:85]
	s_mov_b32 m0, s58
	s_nop 0
	global_load_lds_dwordx4 v132, s[84:85]
	s_waitcnt vmcnt(8) lgkmcnt(0)
	s_barrier
	v_mfma_f32_16x16x32_bf16 v[60:63], v[140:143], v[180:183], v[60:63]
	v_mfma_f32_16x16x32_bf16 v[56:59], v[148:151], v[180:183], v[56:59]
	v_mfma_f32_16x16x32_bf16 v[52:55], v[140:143], v[188:191], v[52:55]
	v_mfma_f32_16x16x32_bf16 v[48:51], v[148:151], v[188:191], v[48:51]
	v_mfma_f32_16x16x32_bf16 v[44:47], v[140:143], v[196:199], v[44:47]
	v_mfma_f32_16x16x32_bf16 v[32:35], v[148:151], v[196:199], v[32:35]
	v_mfma_f32_16x16x32_bf16 v[20:23], v[140:143], v[204:207], v[20:23]
	v_mfma_f32_16x16x32_bf16 v[12:15], v[148:151], v[204:207], v[12:15]
	v_mfma_f32_16x16x32_bf16 v[60:63], v[144:147], v[184:187], v[60:63]
	v_mfma_f32_16x16x32_bf16 v[56:59], v[152:155], v[184:187], v[56:59]
	v_mfma_f32_16x16x32_bf16 v[52:55], v[144:147], v[192:195], v[52:55]
	v_mfma_f32_16x16x32_bf16 v[48:51], v[152:155], v[192:195], v[48:51]
	v_mfma_f32_16x16x32_bf16 v[44:47], v[144:147], v[200:203], v[44:47]
	v_mfma_f32_16x16x32_bf16 v[32:35], v[152:155], v[200:203], v[32:35]
	v_mfma_f32_16x16x32_bf16 v[20:23], v[144:147], v[208:211], v[20:23]
	v_mfma_f32_16x16x32_bf16 v[12:15], v[152:155], v[208:211], v[12:15]
	v_mfma_f32_16x16x32_bf16 v[40:43], v[156:159], v[180:183], v[40:43]
	v_mfma_f32_16x16x32_bf16 v[36:39], v[172:175], v[180:183], v[36:39]
	v_mfma_f32_16x16x32_bf16 v[28:31], v[156:159], v[188:191], v[28:31]
	v_mfma_f32_16x16x32_bf16 v[24:27], v[172:175], v[188:191], v[24:27]
	v_mfma_f32_16x16x32_bf16 v[16:19], v[156:159], v[196:199], v[16:19]
	v_mfma_f32_16x16x32_bf16 v[8:11], v[172:175], v[196:199], v[8:11]
	v_mfma_f32_16x16x32_bf16 v[4:7], v[156:159], v[204:207], v[4:7]
	v_mfma_f32_16x16x32_bf16 v[0:3], v[172:175], v[204:207], v[0:3]
	v_mfma_f32_16x16x32_bf16 v[40:43], v[160:163], v[184:187], v[40:43]
	v_mfma_f32_16x16x32_bf16 v[36:39], v[176:179], v[184:187], v[36:39]
	v_mfma_f32_16x16x32_bf16 v[28:31], v[160:163], v[192:195], v[28:31]
	v_mfma_f32_16x16x32_bf16 v[24:27], v[176:179], v[192:195], v[24:27]
	v_mfma_f32_16x16x32_bf16 v[16:19], v[160:163], v[200:203], v[16:19]
	v_mfma_f32_16x16x32_bf16 v[8:11], v[176:179], v[200:203], v[8:11]
	v_mfma_f32_16x16x32_bf16 v[4:7], v[160:163], v[208:211], v[4:7]
	v_mfma_f32_16x16x32_bf16 v[0:3], v[176:179], v[208:211], v[0:3]
	s_barrier
	s_add_i32 s69, s69, 2
	s_add_u32 s67, s67, 0x100
	s_addc_u32 s68, s68, 0
	s_cmpk_gt_u32 s69, 0x55
	s_mov_b64 s[44:45], s[46:47]
; #define PG8_STAGE(bufoff, gbase, voff) do { _Pragma("unroll") for (int _i = 0; _i < 2; ++_i) \
;         __builtin_amdgcn_global_load_lds((const unsigned*)((const char*)(gbase) + (voff)[_i]), (PG8_LAS unsigned*)(lds + (bufoff) + ldsw + _i * 8192), 16, 0, 0); } while (0)
; #define PG8_LDA(dst, b, h) do { _Pragma("unroll") for (int m = 0; m < 4; ++m) _Pragma("unroll") for (int k = 0; k < 2; ++k) dst[m][k] = *(const PG8_LAS bf16x8*)(lds + PG8_SA(b, h) + aoff + m * 2048 + k * 1024); } while (0)
; #define PG8_LDB(dst, b, h) do { _Pragma("unroll") for (int n = 0; n < 2; ++n) _Pragma("unroll") for (int k = 0; k < 2; ++k) dst[n][k] = *(const PG8_LAS bf16x8*)(lds + PG8_SB(b, h) + boff + n * 2048 + k * 1024); } while (0)
; #define PG8_MMA(ai, bj, At, Bt) do { __builtin_amdgcn_s_setprio(1); _Pragma("unroll") for (int m = 0; m < 4; ++m) _Pragma("unroll") for (int n = 0; n < 2; ++n) _Pragma("unroll") for (int k = 0; k < 2; ++k) \
;         acc[ai][bj][m][n] = __builtin_amdgcn_mfma_f32_16x16x32_bf16(Bt[n][k], At[m][k], acc[ai][bj][m][n], 0, 0, 0); __builtin_amdgcn_s_setprio(0); } while (0)
; #define PG8_WAIT_V(n) asm volatile("s_waitcnt vmcnt(" #n ")" ::: "memory")
; #define PG8_WAIT_L(n) asm volatile("s_waitcnt lgkmcnt(" #n ")" ::: "memory")
; #define PG8_BAR __builtin_amdgcn_s_barrier()
; #define PG8_SCHED __builtin_amdgcn_sched_barrier(0)
; template <class Epi, class Sched, bool ALIGN_EPI = false, bool SP2 = false>
; __device__ __forceinline__ void gemm_phase(PG8_LAS unsigned char* lds, const Gemm g, const Sched& S, const Epi& E) {
;     ...
;             PG8_LDB(B0, 0, 0); PG8_LDB(B1, 0, 1); PG8_SCHED; PG8_LDA(At, 0, 0); PG8_STAGE(PG8_SA(1, 1), a1 + hstep, voffA);
;             PG8_WAIT_V(8); PG8_WAIT_L(0); PG8_BAR; PG8_MMA(0, 0, At, B0); PG8_MMA(0, 1, At, B1); PG8_BAR; PG8_SCHED;
;             PG8_LDA(At, 0, 1); PG8_STAGE(PG8_SB(0, 0), b2, voffB); PG8_STAGE(PG8_SB(0, 1), b2 + hstep, voffB); PG8_STAGE(PG8_SA(0, 0), a2, voffA);
;             PG8_WAIT_V(8); PG8_WAIT_L(0); PG8_BAR; PG8_MMA(1, 0, At, B0); PG8_MMA(1, 1, At, B1); PG8_BAR; PG8_SCHED;
.LBB0_245:
	ds_read_b128 v[140:143], v169
	ds_read_b128 v[144:147], v169 offset:1024
	ds_read_b128 v[148:151], v169 offset:2048
	ds_read_b128 v[152:155], v169 offset:3072
	ds_read_b128 v[156:159], v170
	ds_read_b128 v[160:163], v170 offset:1024
	ds_read_b128 v[172:175], v170 offset:2048
	ds_read_b128 v[176:179], v170 offset:3072
	s_add_u32 s46, s44, 0x100
	s_addc_u32 s47, s45, 0
	s_cmpk_eq_i32 s69, 0x54
	s_cselect_b32 s51, s11, s47
	s_cselect_b32 s50, s10, s46
	s_cselect_b32 s49, s13, s68
	s_cselect_b32 s48, s12, s67
	s_add_i32 m0, s26, 0xc000
	ds_read_b128 v[180:183], v171
	ds_read_b128 v[184:187], v171 offset:1024
	ds_read_b128 v[188:191], v171 offset:2048
	ds_read_b128 v[192:195], v171 offset:3072
	ds_read_b128 v[196:199], v171 offset:4096
	ds_read_b128 v[200:203], v171 offset:5120
	ds_read_b128 v[204:207], v171 offset:6144
	ds_read_b128 v[208:211], v171 offset:7168
	global_load_lds_dwordx4 v136, s[44:45]
	s_add_i32 m0, s26, 0xe000
	s_nop 0
	global_load_lds_dwordx4 v138, s[44:45]
	s_waitcnt vmcnt(8) lgkmcnt(0)
	s_barrier
	v_mfma_f32_16x16x32_bf16 v[124:127], v[140:143], v[180:183], v[124:127]
	v_mfma_f32_16x16x32_bf16 v[120:123], v[148:151], v[180:183], v[120:123]
	v_mfma_f32_16x16x32_bf16 v[116:119], v[140:143], v[188:191], v[116:119]
	v_mfma_f32_16x16x32_bf16 v[112:115], v[148:151], v[188:191], v[112:115]
	v_mfma_f32_16x16x32_bf16 v[108:111], v[140:143], v[196:199], v[108:111]
	v_mfma_f32_16x16x32_bf16 v[96:99], v[148:151], v[196:199], v[96:99]
	v_mfma_f32_16x16x32_bf16 v[84:87], v[140:143], v[204:207], v[84:87]
	v_mfma_f32_16x16x32_bf16 v[76:79], v[148:151], v[204:207], v[76:79]
	v_mfma_f32_16x16x32_bf16 v[124:127], v[144:147], v[184:187], v[124:127]
	v_mfma_f32_16x16x32_bf16 v[120:123], v[152:155], v[184:187], v[120:123]
	v_mfma_f32_16x16x32_bf16 v[116:119], v[144:147], v[192:195], v[116:119]
	v_mfma_f32_16x16x32_bf16 v[112:115], v[152:155], v[192:195], v[112:115]
	v_mfma_f32_16x16x32_bf16 v[108:111], v[144:147], v[200:203], v[108:111]
	v_mfma_f32_16x16x32_bf16 v[96:99], v[152:155], v[200:203], v[96:99]
	v_mfma_f32_16x16x32_bf16 v[84:87], v[144:147], v[208:211], v[84:87]
	v_mfma_f32_16x16x32_bf16 v[76:79], v[152:155], v[208:211], v[76:79]
	v_mfma_f32_16x16x32_bf16 v[104:107], v[156:159], v[180:183], v[104:107]
	v_mfma_f32_16x16x32_bf16 v[100:103], v[172:175], v[180:183], v[100:103]
	v_mfma_f32_16x16x32_bf16 v[92:95], v[156:159], v[188:191], v[92:95]
	v_mfma_f32_16x16x32_bf16 v[88:91], v[172:175], v[188:191], v[88:91]
	v_mfma_f32_16x16x32_bf16 v[80:83], v[156:159], v[196:199], v[80:83]
	v_mfma_f32_16x16x32_bf16 v[72:75], v[172:175], v[196:199], v[72:75]
	v_mfma_f32_16x16x32_bf16 v[68:71], v[156:159], v[204:207], v[68:71]
	v_mfma_f32_16x16x32_bf16 v[64:67], v[172:175], v[204:207], v[64:67]
	v_mfma_f32_16x16x32_bf16 v[104:107], v[160:163], v[184:187], v[104:107]
	v_mfma_f32_16x16x32_bf16 v[100:103], v[176:179], v[184:187], v[100:103]
	v_mfma_f32_16x16x32_bf16 v[92:95], v[160:163], v[192:195], v[92:95]
	v_mfma_f32_16x16x32_bf16 v[88:91], v[176:179], v[192:195], v[88:91]
	v_mfma_f32_16x16x32_bf16 v[80:83], v[160:163], v[200:203], v[80:83]
	v_mfma_f32_16x16x32_bf16 v[72:75], v[176:179], v[200:203], v[72:75]
	v_mfma_f32_16x16x32_bf16 v[68:71], v[160:163], v[208:211], v[68:71]
	v_mfma_f32_16x16x32_bf16 v[64:67], v[176:179], v[208:211], v[64:67]
	s_barrier
	s_add_i32 s44, s61, s25
	s_mov_b32 m0, s44
	ds_read_b128 v[180:183], v171 offset:16384
	ds_read_b128 v[184:187], v171 offset:17408
	ds_read_b128 v[188:191], v171 offset:18432
	ds_read_b128 v[192:195], v171 offset:19456
	ds_read_b128 v[196:199], v171 offset:20480
	ds_read_b128 v[200:203], v171 offset:21504
	ds_read_b128 v[204:207], v171 offset:22528
	ds_read_b128 v[208:211], v171 offset:23552
	global_load_lds_dwordx4 v130, s[48:49]
	s_add_i32 m0, s44, 0x2000
	s_add_u32 s44, s48, 0x160000
	s_addc_u32 s45, s49, 0
	s_add_i32 s70, s62, s25
	global_load_lds_dwordx4 v134, s[48:49]
	s_mov_b32 m0, s70
	s_nop 0
	global_load_lds_dwordx4 v130, s[44:45]
	s_add_i32 m0, s70, 0x2000
	s_nop 0
	global_load_lds_dwordx4 v134, s[44:45]
	s_mov_b32 m0, s26
	s_nop 0
	global_load_lds_dwordx4 v128, s[50:51]
	s_mov_b32 m0, s27
	s_nop 0
	global_load_lds_dwordx4 v132, s[50:51]
	s_waitcnt vmcnt(8) lgkmcnt(0)
	s_barrier
	v_mfma_f32_16x16x32_bf16 v[60:63], v[140:143], v[180:183], v[60:63]
	v_mfma_f32_16x16x32_bf16 v[56:59], v[148:151], v[180:183], v[56:59]
	v_mfma_f32_16x16x32_bf16 v[52:55], v[140:143], v[188:191], v[52:55]
	v_mfma_f32_16x16x32_bf16 v[48:51], v[148:151], v[188:191], v[48:51]
	v_mfma_f32_16x16x32_bf16 v[44:47], v[140:143], v[196:199], v[44:47]
	v_mfma_f32_16x16x32_bf16 v[32:35], v[148:151], v[196:199], v[32:35]
	v_mfma_f32_16x16x32_bf16 v[20:23], v[140:143], v[204:207], v[20:23]
	v_mfma_f32_16x16x32_bf16 v[12:15], v[148:151], v[204:207], v[12:15]
	v_mfma_f32_16x16x32_bf16 v[60:63], v[144:147], v[184:187], v[60:63]
	v_mfma_f32_16x16x32_bf16 v[56:59], v[152:155], v[184:187], v[56:59]
	v_mfma_f32_16x16x32_bf16 v[52:55], v[144:147], v[192:195], v[52:55]
	v_mfma_f32_16x16x32_bf16 v[48:51], v[152:155], v[192:195], v[48:51]
	v_mfma_f32_16x16x32_bf16 v[44:47], v[144:147], v[200:203], v[44:47]
	v_mfma_f32_16x16x32_bf16 v[32:35], v[152:155], v[200:203], v[32:35]
	v_mfma_f32_16x16x32_bf16 v[20:23], v[144:147], v[208:211], v[20:23]
	v_mfma_f32_16x16x32_bf16 v[12:15], v[152:155], v[208:211], v[12:15]
	v_mfma_f32_16x16x32_bf16 v[40:43], v[156:159], v[180:183], v[40:43]
	v_mfma_f32_16x16x32_bf16 v[36:39], v[172:175], v[180:183], v[36:39]
	v_mfma_f32_16x16x32_bf16 v[28:31], v[156:159], v[188:191], v[28:31]
	v_mfma_f32_16x16x32_bf16 v[24:27], v[172:175], v[188:191], v[24:27]
	v_mfma_f32_16x16x32_bf16 v[16:19], v[156:159], v[196:199], v[16:19]
	v_mfma_f32_16x16x32_bf16 v[8:11], v[172:175], v[196:199], v[8:11]
	v_mfma_f32_16x16x32_bf16 v[4:7], v[156:159], v[204:207], v[4:7]
	v_mfma_f32_16x16x32_bf16 v[0:3], v[172:175], v[204:207], v[0:3]
	v_mfma_f32_16x16x32_bf16 v[40:43], v[160:163], v[184:187], v[40:43]
	v_mfma_f32_16x16x32_bf16 v[36:39], v[176:179], v[184:187], v[36:39]
	v_mfma_f32_16x16x32_bf16 v[28:31], v[160:163], v[192:195], v[28:31]
	v_mfma_f32_16x16x32_bf16 v[24:27], v[176:179], v[192:195], v[24:27]
	v_mfma_f32_16x16x32_bf16 v[16:19], v[160:163], v[200:203], v[16:19]
	v_mfma_f32_16x16x32_bf16 v[8:11], v[176:179], v[200:203], v[8:11]
	v_mfma_f32_16x16x32_bf16 v[4:7], v[160:163], v[208:211], v[4:7]
	v_mfma_f32_16x16x32_bf16 v[0:3], v[176:179], v[208:211], v[0:3]
	s_barrier
; #define PG8_STAGE(bufoff, gbase, voff) do { _Pragma("unroll") for (int _i = 0; _i < 2; ++_i) \
;         __builtin_amdgcn_global_load_lds((const unsigned*)((const char*)(gbase) + (voff)[_i]), (PG8_LAS unsigned*)(lds + (bufoff) + ldsw + _i * 8192), 16, 0, 0); } while (0)
; #define PG8_LDA(dst, b, h) do { _Pragma("unroll") for (int m = 0; m < 4; ++m) _Pragma("unroll") for (int k = 0; k < 2; ++k) dst[m][k] = *(const PG8_LAS bf16x8*)(lds + PG8_SA(b, h) + aoff + m * 2048 + k * 1024); } while (0)
; #define PG8_LDB(dst, b, h) do { _Pragma("unroll") for (int n = 0; n < 2; ++n) _Pragma("unroll") for (int k = 0; k < 2; ++k) dst[n][k] = *(const PG8_LAS bf16x8*)(lds + PG8_SB(b, h) + boff + n * 2048 + k * 1024); } while (0)
; #define PG8_MMA(ai, bj, At, Bt) do { __builtin_amdgcn_s_setprio(1); _Pragma("unroll") for (int m = 0; m < 4; ++m) _Pragma("unroll") for (int n = 0; n < 2; ++n) _Pragma("unroll") for (int k = 0; k < 2; ++k) \
;         acc[ai][bj][m][n] = __builtin_amdgcn_mfma_f32_16x16x32_bf16(Bt[n][k], At[m][k], acc[ai][bj][m][n], 0, 0, 0); __builtin_amdgcn_s_setprio(0); } while (0)
; #define PG8_WAIT_V(n) asm volatile("s_waitcnt vmcnt(" #n ")" ::: "memory")
; #define PG8_WAIT_L(n) asm volatile("s_waitcnt lgkmcnt(" #n ")" ::: "memory")
; #define PG8_BAR __builtin_amdgcn_s_barrier()
; #define PG8_SCHED __builtin_amdgcn_sched_barrier(0)
; template <class Epi, class Sched, bool ALIGN_EPI = false, bool SP2 = false>
; __device__ __forceinline__ void gemm_phase(PG8_LAS unsigned char* lds, const Gemm g, const Sched& S, const Epi& E) {
;     ...
;             PG8_LDB(B0, 1, 0); PG8_LDB(B1, 1, 1); PG8_SCHED; PG8_LDA(At, 1, 0); PG8_STAGE(PG8_SA(0, 1), a2 + hstep, voffA);
;             PG8_WAIT_V(8); PG8_WAIT_L(0); PG8_BAR; PG8_MMA(0, 0, At, B0); PG8_MMA(0, 1, At, B1); PG8_BAR; PG8_SCHED;
;             PG8_LDA(At, 1, 1); PG8_STAGE(PG8_SB(1, 0), b3, voffB); PG8_STAGE(PG8_SB(1, 1), b3 + hstep, voffB); PG8_STAGE(PG8_SA(1, 0), a3, voffA);
;             PG8_WAIT_V(8); PG8_WAIT_L(0); PG8_BAR; PG8_MMA(1, 0, At, B0); PG8_MMA(1, 1, At, B1); PG8_BAR; PG8_SCHED;
	s_add_i32 s70, 0, 0x18000
	s_add_i32 s71, 0, 0x1c000
	v_add_u32_e32 v152, s70, v167
	v_add_u32_e32 v176, s71, v167
	ds_read_b128 v[140:143], v152
	ds_read_b128 v[144:147], v152 offset:1024
	ds_read_b128 v[148:151], v152 offset:2048
	ds_read_b128 v[152:155], v152 offset:3072
	ds_read_b128 v[156:159], v176
	ds_read_b128 v[160:163], v176 offset:1024
	ds_read_b128 v[172:175], v176 offset:2048
	ds_read_b128 v[176:179], v176 offset:3072
	s_add_u32 s44, s50, 0x160000
	s_addc_u32 s45, s51, 0
	s_mov_b32 m0, s52
	ds_read_b128 v[180:183], v171 offset:32768
	ds_read_b128 v[184:187], v171 offset:33792
	ds_read_b128 v[188:191], v171 offset:34816
	ds_read_b128 v[192:195], v171 offset:35840
	ds_read_b128 v[196:199], v171 offset:36864
	ds_read_b128 v[200:203], v171 offset:37888
	ds_read_b128 v[204:207], v171 offset:38912
	ds_read_b128 v[208:211], v171 offset:39936
	global_load_lds_dwordx4 v128, s[44:45]
	s_mov_b32 m0, s53
	s_nop 0
	global_load_lds_dwordx4 v132, s[44:45]
	s_waitcnt vmcnt(8) lgkmcnt(0)
	s_barrier
	v_mfma_f32_16x16x32_bf16 v[124:127], v[140:143], v[180:183], v[124:127]
	v_mfma_f32_16x16x32_bf16 v[120:123], v[148:151], v[180:183], v[120:123]
	v_mfma_f32_16x16x32_bf16 v[116:119], v[140:143], v[188:191], v[116:119]
	v_mfma_f32_16x16x32_bf16 v[112:115], v[148:151], v[188:191], v[112:115]
	v_mfma_f32_16x16x32_bf16 v[108:111], v[140:143], v[196:199], v[108:111]
	v_mfma_f32_16x16x32_bf16 v[96:99], v[148:151], v[196:199], v[96:99]
	v_mfma_f32_16x16x32_bf16 v[84:87], v[140:143], v[204:207], v[84:87]
	v_mfma_f32_16x16x32_bf16 v[76:79], v[148:151], v[204:207], v[76:79]
	v_mfma_f32_16x16x32_bf16 v[124:127], v[144:147], v[184:187], v[124:127]
	v_mfma_f32_16x16x32_bf16 v[120:123], v[152:155], v[184:187], v[120:123]
	v_mfma_f32_16x16x32_bf16 v[116:119], v[144:147], v[192:195], v[116:119]
	v_mfma_f32_16x16x32_bf16 v[112:115], v[152:155], v[192:195], v[112:115]
	v_mfma_f32_16x16x32_bf16 v[108:111], v[144:147], v[200:203], v[108:111]
	v_mfma_f32_16x16x32_bf16 v[96:99], v[152:155], v[200:203], v[96:99]
	v_mfma_f32_16x16x32_bf16 v[84:87], v[144:147], v[208:211], v[84:87]
	v_mfma_f32_16x16x32_bf16 v[76:79], v[152:155], v[208:211], v[76:79]
	v_mfma_f32_16x16x32_bf16 v[104:107], v[156:159], v[180:183], v[104:107]
	v_mfma_f32_16x16x32_bf16 v[100:103], v[172:175], v[180:183], v[100:103]
	v_mfma_f32_16x16x32_bf16 v[92:95], v[156:159], v[188:191], v[92:95]
	v_mfma_f32_16x16x32_bf16 v[88:91], v[172:175], v[188:191], v[88:91]
	v_mfma_f32_16x16x32_bf16 v[80:83], v[156:159], v[196:199], v[80:83]
	v_mfma_f32_16x16x32_bf16 v[72:75], v[172:175], v[196:199], v[72:75]
	v_mfma_f32_16x16x32_bf16 v[68:71], v[156:159], v[204:207], v[68:71]
	v_mfma_f32_16x16x32_bf16 v[64:67], v[172:175], v[204:207], v[64:67]
	v_mfma_f32_16x16x32_bf16 v[104:107], v[160:163], v[184:187], v[104:107]
	v_mfma_f32_16x16x32_bf16 v[100:103], v[176:179], v[184:187], v[100:103]
	v_mfma_f32_16x16x32_bf16 v[92:95], v[160:163], v[192:195], v[92:95]
	v_mfma_f32_16x16x32_bf16 v[88:91], v[176:179], v[192:195], v[88:91]
	v_mfma_f32_16x16x32_bf16 v[80:83], v[160:163], v[200:203], v[80:83]
	v_mfma_f32_16x16x32_bf16 v[72:75], v[176:179], v[200:203], v[72:75]
	v_mfma_f32_16x16x32_bf16 v[68:71], v[160:163], v[208:211], v[68:71]
	v_mfma_f32_16x16x32_bf16 v[64:67], v[176:179], v[208:211], v[64:67]
	s_barrier
	s_add_i32 s44, s70, s25
	s_add_u32 s86, s48, 0x80
	s_addc_u32 s87, s49, 0
	s_mov_b32 m0, s44
	ds_read_b128 v[180:183], v171 offset:49152
	ds_read_b128 v[184:187], v171 offset:50176
	ds_read_b128 v[188:191], v171 offset:51200
	ds_read_b128 v[192:195], v171 offset:52224
	ds_read_b128 v[196:199], v171 offset:53248
	ds_read_b128 v[200:203], v171 offset:54272
	ds_read_b128 v[204:207], v171 offset:55296
	ds_read_b128 v[208:211], v171 offset:56320
	global_load_lds_dwordx4 v130, s[86:87]
	s_add_i32 m0, s44, 0x2000
	s_add_u32 s44, s48, 0x160080
	s_addc_u32 s45, s49, 0
	s_add_i32 s48, s71, s25
	global_load_lds_dwordx4 v134, s[86:87]
	s_mov_b32 m0, s48
	s_nop 0
	global_load_lds_dwordx4 v130, s[44:45]
	s_add_i32 m0, s48, 0x2000
	s_nop 0
	global_load_lds_dwordx4 v134, s[44:45]
	s_add_u32 s84, s50, 0x80
	s_addc_u32 s85, s51, 0
	s_mov_b32 m0, s57
	s_nop 0
	global_load_lds_dwordx4 v128, s[84:85]
	s_mov_b32 m0, s58
	s_nop 0
	global_load_lds_dwordx4 v132, s[84:85]
	s_waitcnt vmcnt(8) lgkmcnt(0)
	s_barrier
	v_mfma_f32_16x16x32_bf16 v[60:63], v[140:143], v[180:183], v[60:63]
	v_mfma_f32_16x16x32_bf16 v[56:59], v[148:151], v[180:183], v[56:59]
	v_mfma_f32_16x16x32_bf16 v[52:55], v[140:143], v[188:191], v[52:55]
	v_mfma_f32_16x16x32_bf16 v[48:51], v[148:151], v[188:191], v[48:51]
	v_mfma_f32_16x16x32_bf16 v[44:47], v[140:143], v[196:199], v[44:47]
	v_mfma_f32_16x16x32_bf16 v[32:35], v[148:151], v[196:199], v[32:35]
	v_mfma_f32_16x16x32_bf16 v[20:23], v[140:143], v[204:207], v[20:23]
	v_mfma_f32_16x16x32_bf16 v[12:15], v[148:151], v[204:207], v[12:15]
	v_mfma_f32_16x16x32_bf16 v[60:63], v[144:147], v[184:187], v[60:63]
	v_mfma_f32_16x16x32_bf16 v[56:59], v[152:155], v[184:187], v[56:59]
	v_mfma_f32_16x16x32_bf16 v[52:55], v[144:147], v[192:195], v[52:55]
	v_mfma_f32_16x16x32_bf16 v[48:51], v[152:155], v[192:195], v[48:51]
	v_mfma_f32_16x16x32_bf16 v[44:47], v[144:147], v[200:203], v[44:47]
	v_mfma_f32_16x16x32_bf16 v[32:35], v[152:155], v[200:203], v[32:35]
	v_mfma_f32_16x16x32_bf16 v[20:23], v[144:147], v[208:211], v[20:23]
	v_mfma_f32_16x16x32_bf16 v[12:15], v[152:155], v[208:211], v[12:15]
	v_mfma_f32_16x16x32_bf16 v[40:43], v[156:159], v[180:183], v[40:43]
	v_mfma_f32_16x16x32_bf16 v[36:39], v[172:175], v[180:183], v[36:39]
	v_mfma_f32_16x16x32_bf16 v[28:31], v[156:159], v[188:191], v[28:31]
	v_mfma_f32_16x16x32_bf16 v[24:27], v[172:175], v[188:191], v[24:27]
	v_mfma_f32_16x16x32_bf16 v[16:19], v[156:159], v[196:199], v[16:19]
	v_mfma_f32_16x16x32_bf16 v[8:11], v[172:175], v[196:199], v[8:11]
	v_mfma_f32_16x16x32_bf16 v[4:7], v[156:159], v[204:207], v[4:7]
	v_mfma_f32_16x16x32_bf16 v[0:3], v[172:175], v[204:207], v[0:3]
	v_mfma_f32_16x16x32_bf16 v[40:43], v[160:163], v[184:187], v[40:43]
	v_mfma_f32_16x16x32_bf16 v[36:39], v[176:179], v[184:187], v[36:39]
	v_mfma_f32_16x16x32_bf16 v[28:31], v[160:163], v[192:195], v[28:31]
	v_mfma_f32_16x16x32_bf16 v[24:27], v[176:179], v[192:195], v[24:27]
	v_mfma_f32_16x16x32_bf16 v[16:19], v[160:163], v[200:203], v[16:19]
	v_mfma_f32_16x16x32_bf16 v[8:11], v[176:179], v[200:203], v[8:11]
	v_mfma_f32_16x16x32_bf16 v[4:7], v[160:163], v[208:211], v[4:7]
	v_mfma_f32_16x16x32_bf16 v[0:3], v[176:179], v[208:211], v[0:3]
	s_barrier
;     __device__ __forceinline__ void operator()(const f32x4 (&acc)[2][2][4][2], const Unit& u, int wr, int wc, int fr, int fq) const {
;         const int row0 = u.pm * BM + wr * 64 + fr, col0 = u.pn * BM + wc * 32 + 8 * fq;
;         const float* gp = gate + (u.pm >> 5) * 18432 + col0;
;         f32x4 gv[2][2];
; #pragma unroll
;         for (int bj = 0; bj < 2; ++bj)
; #pragma unroll
;             for (int n = 0; n < 2; ++n) gv[bj][n] = *(const f32x4*)(gp + bj * HALF + 4 * n) * scale;
; #pragma unroll
;         for (int ai = 0; ai < 2; ++ai) { f32x4 r[4][2][2];
; #pragma unroll
;             for (int m = 0; m < 4; ++m) { const size_t off = (size_t)(row0 + ai * HALF + m * 16) * 2048 + col0;
; #pragma unroll
;                 for (int bj = 0; bj < 2; ++bj)
; #pragma unroll
;                     for (int n = 0; n < 2; ++n) r[m][bj][n] = *(const f32x4*)(res + off + bj * HALF + 4 * n); }
; #pragma unroll
;             for (int m = 0; m < 4; ++m) { const size_t off = (size_t)(row0 + ai * HALF + m * 16) * 2048 + col0;
; #pragma unroll
;                 for (int bj = 0; bj < 2; ++bj)
; #pragma unroll
;                     for (int n = 0; n < 2; ++n) *(f32x4*)(out + off + bj * HALF + 4 * n) = r[m][bj][n] + gv[bj][n] * acc[ai][bj][m][n]; } }
	s_add_i32 s69, s69, 2
	s_add_u32 s67, s67, 0x100
	s_addc_u32 s68, s68, 0
	s_cmpk_gt_u32 s69, 0x55
	s_mov_b64 s[44:45], s[46:47]
	s_cbranch_scc0 .LBB0_245
	s_lshr_b32 s44, s65, 5
	s_mulk_i32 s44, 0x4800
	s_ashr_i32 s45, s44, 31
	v_lshl_or_b32 v140, s66, 8, v168
	s_lshl_b64 s[44:45], s[44:45], 2
	s_add_u32 s44, s55, s44
	v_ashrrev_i32_e32 v141, 31, v140
	s_addc_u32 s45, s56, s45
	v_lshlrev_b64 v[144:145], 2, v[140:141]
	v_lshl_add_u64 v[140:141], s[44:45], 0, v[144:145]
	global_load_dwordx4 v[146:149], v[140:141], off offset:16
	global_load_dwordx4 v[150:153], v[140:141], off
	global_load_dwordx4 v[172:175], v[140:141], off offset:528
	global_load_dwordx4 v[176:179], v[140:141], off offset:512
	v_lshl_add_u32 v140, s65, 8, v166
	v_ashrrev_i32_e32 v141, 31, v140
	v_lshl_add_u64 v[162:163], s[28:29], 0, v[144:145]
	v_lshlrev_b64 v[164:165], 13, v[140:141]
	v_lshl_add_u64 v[142:143], v[162:163], 0, v[164:165]
	global_load_dwordx4 v[180:183], v[142:143], off
	global_load_dwordx4 v[184:187], v[142:143], off offset:16
	global_load_dwordx4 v[188:191], v[142:143], off offset:528
	global_load_dwordx4 v[192:195], v[142:143], off offset:512
	v_or_b32_e32 v142, 16, v140
	v_ashrrev_i32_e32 v143, 31, v142
	v_lshlrev_b64 v[154:155], 13, v[142:143]
	v_lshl_add_u64 v[142:143], v[162:163], 0, v[154:155]
	global_load_dwordx4 v[196:199], v[142:143], off
	global_load_dwordx4 v[200:203], v[142:143], off offset:16
	global_load_dwordx4 v[204:207], v[142:143], off offset:528
	global_load_dwordx4 v[208:211], v[142:143], off offset:512
	v_or_b32_e32 v142, 32, v140
	v_ashrrev_i32_e32 v143, 31, v142
	v_lshlrev_b64 v[156:157], 13, v[142:143]
	v_or_b32_e32 v140, 48, v140
	v_lshl_add_u64 v[142:143], v[162:163], 0, v[156:157]
	v_ashrrev_i32_e32 v141, 31, v140
	global_load_dwordx4 v[214:217], v[142:143], off
	global_load_dwordx4 v[222:225], v[142:143], off offset:16
	global_load_dwordx4 v[232:235], v[142:143], off offset:512
	global_load_dwordx4 v[236:239], v[142:143], off offset:528
	v_lshlrev_b64 v[212:213], 13, v[140:141]
	v_lshl_add_u64 v[140:141], v[162:163], 0, v[212:213]
	global_load_dwordx4 v[240:243], v[140:141], off
	global_load_dwordx4 v[244:247], v[140:141], off offset:16
	global_load_dwordx4 v[248:251], v[140:141], off offset:512
	s_nop 0
	global_load_dwordx4 v[140:143], v[140:141], off offset:528
	v_lshl_add_u64 v[158:159], s[30:31], 0, v[164:165]
	v_lshl_add_u64 v[230:231], v[158:159], 0, v[144:145]
	v_lshl_add_u64 v[154:155], s[30:31], 0, v[154:155]
	v_lshl_add_u64 v[156:157], s[30:31], 0, v[156:157]
	v_lshl_add_u64 v[218:219], v[154:155], 0, v[144:145]
	v_lshl_add_u64 v[252:253], v[156:157], 0, v[144:145]
	s_and_b64 vcc, exec, s[8:9]
	s_mov_b32 s66, s63
	s_mov_b32 s65, s64
	s_mov_b64 s[46:47], s[12:13]
	s_mov_b64 s[44:45], s[10:11]
	s_waitcnt vmcnt(0)
	v_pk_mul_f32 v[154:155], v[148:149], 0.5 op_sel_hi:[1,0]
	v_pk_mul_f32 v[158:159], v[152:153], 0.5 op_sel_hi:[1,0]
	v_pk_mul_f32 v[160:161], v[150:151], 0.5 op_sel_hi:[1,0]
	v_pk_mul_f32 v[150:151], v[178:179], 0.5 op_sel_hi:[1,0]
	v_pk_mul_f32 v[152:153], v[176:177], 0.5 op_sel_hi:[1,0]
	v_pk_mul_f32 v[156:157], v[146:147], 0.5 op_sel_hi:[1,0]
	v_pk_mul_f32 v[146:147], v[174:175], 0.5 op_sel_hi:[1,0]
	v_pk_mul_f32 v[148:149], v[172:173], 0.5 op_sel_hi:[1,0]
	v_pk_fma_f32 v[126:127], v[126:127], v[158:159], v[182:183]
	v_pk_fma_f32 v[124:125], v[124:125], v[160:161], v[180:181]
	v_pk_fma_f32 v[122:123], v[122:123], v[154:155], v[186:187]
	v_pk_fma_f32 v[120:121], v[120:121], v[156:157], v[184:185]
	v_pk_fma_f32 v[106:107], v[106:107], v[150:151], v[194:195]
	v_pk_fma_f32 v[104:105], v[104:105], v[152:153], v[192:193]
	v_pk_fma_f32 v[102:103], v[102:103], v[146:147], v[190:191]
	v_pk_fma_f32 v[100:101], v[100:101], v[148:149], v[188:189]
	v_pk_fma_f32 v[118:119], v[118:119], v[158:159], v[198:199]
	v_pk_fma_f32 v[116:117], v[116:117], v[160:161], v[196:197]
	v_pk_fma_f32 v[114:115], v[114:115], v[154:155], v[202:203]
	v_pk_fma_f32 v[112:113], v[112:113], v[156:157], v[200:201]
	v_pk_fma_f32 v[82:83], v[82:83], v[150:151], v[234:235]
	v_pk_fma_f32 v[80:81], v[80:81], v[152:153], v[232:233]
	v_pk_fma_f32 v[94:95], v[94:95], v[150:151], v[210:211]
	v_pk_fma_f32 v[92:93], v[92:93], v[152:153], v[208:209]
	v_pk_fma_f32 v[90:91], v[90:91], v[146:147], v[206:207]
	v_pk_fma_f32 v[88:89], v[88:89], v[148:149], v[204:205]
	v_pk_fma_f32 v[110:111], v[110:111], v[158:159], v[216:217]
	v_pk_fma_f32 v[108:109], v[108:109], v[160:161], v[214:215]
	v_pk_fma_f32 v[98:99], v[98:99], v[154:155], v[224:225]
	v_pk_fma_f32 v[96:97], v[96:97], v[156:157], v[222:223]
	global_store_dwordx4 v[230:231], v[124:127], off
	global_store_dwordx4 v[230:231], v[120:123], off offset:16
	global_store_dwordx4 v[230:231], v[104:107], off offset:512
	global_store_dwordx4 v[230:231], v[100:103], off offset:528
	global_store_dwordx4 v[218:219], v[116:119], off
	global_store_dwordx4 v[218:219], v[112:115], off offset:16
	global_store_dwordx4 v[218:219], v[92:95], off offset:512
	global_store_dwordx4 v[218:219], v[88:91], off offset:528
	global_store_dwordx4 v[252:253], v[108:111], off
	global_store_dwordx4 v[252:253], v[96:99], off offset:16
	global_store_dwordx4 v[252:253], v[80:83], off offset:512
	v_pk_fma_f32 v[74:75], v[74:75], v[146:147], v[238:239]
	v_pk_fma_f32 v[72:73], v[72:73], v[148:149], v[236:237]
	v_lshl_add_u64 v[80:81], s[30:31], 0, v[212:213]
	global_store_dwordx4 v[252:253], v[72:75], off offset:528
; #define PG8_WAIT_V(n) asm volatile("s_waitcnt vmcnt(" #n ")" ::: "memory")
; #define PG8_BAR __builtin_amdgcn_s_barrier()
;     __device__ __forceinline__ void operator()(const f32x4 (&acc)[2][2][4][2], const Unit& u, int wr, int wc, int fr, int fq) const {
;     ...
;         for (int ai = 0; ai < 2; ++ai) { f32x4 r[4][2][2];
; #pragma unroll
;             for (int m = 0; m < 4; ++m) { const size_t off = (size_t)(row0 + ai * HALF + m * 16) * 2048 + col0;
; #pragma unroll
;                 for (int bj = 0; bj < 2; ++bj)
; #pragma unroll
;                     for (int n = 0; n < 2; ++n) r[m][bj][n] = *(const f32x4*)(res + off + bj * HALF + 4 * n); }
; #pragma unroll
;             for (int m = 0; m < 4; ++m) { const size_t off = (size_t)(row0 + ai * HALF + m * 16) * 2048 + col0;
; #pragma unroll
;                 for (int bj = 0; bj < 2; ++bj)
; #pragma unroll
;                     for (int n = 0; n < 2; ++n) *(f32x4*)(out + off + bj * HALF + 4 * n) = r[m][bj][n] + gv[bj][n] * acc[ai][bj][m][n]; } }
; template <class Epi, class Sched, bool ALIGN_EPI = false, bool SP2 = false>
; __device__ __forceinline__ void gemm_phase(PG8_LAS unsigned char* lds, const Gemm g, const Sched& S, const Epi& E) {
;     ...
;         if (!has_next) break;
; #pragma unroll
;         for (int a = 0; a < 2; ++a)
; #pragma unroll
;             for (int b = 0; b < 2; ++b)
; #pragma unroll
;                 for (int m = 0; m < 4; ++m)
; #pragma unroll
;                     for (int n = 0; n < 2; ++n) acc[a][b][m][n] = (f32x4){0.f, 0.f, 0.f, 0.f};
;         cur = nxt; cA = nA; cB = nB; ++ui;
;         if constexpr (ALIGN_EPI) { if (wr == 1) PG8_BAR; }
;     }
;     PG8_WAIT_V(0);
;     if constexpr (!ALIGN_EPI) { if (wr == 0) PG8_BAR; }
;     PG8_BAR;
	v_lshl_add_u64 v[80:81], v[80:81], 0, v[144:145]
	v_pk_fma_f32 v[70:71], v[70:71], v[150:151], v[250:251]
	v_pk_fma_f32 v[74:75], v[86:87], v[158:159], v[242:243]
	v_pk_fma_f32 v[72:73], v[84:85], v[160:161], v[240:241]
	global_store_dwordx4 v[80:81], v[72:75], off
	v_pk_fma_f32 v[68:69], v[68:69], v[152:153], v[248:249]
	v_pk_fma_f32 v[66:67], v[66:67], v[146:147], v[142:143]
	v_pk_fma_f32 v[74:75], v[78:79], v[154:155], v[246:247]
	v_pk_fma_f32 v[72:73], v[76:77], v[156:157], v[244:245]
	v_pk_fma_f32 v[64:65], v[64:65], v[148:149], v[140:141]
	v_lshl_add_u64 v[140:141], v[164:165], 0, s[38:39]
	v_lshl_add_u64 v[142:143], v[164:165], 0, s[40:41]
	v_lshl_add_u64 v[172:173], v[164:165], 0, s[42:43]
	global_store_dwordx4 v[80:81], v[72:75], off offset:16
	global_store_dwordx4 v[80:81], v[68:71], off offset:512
	global_store_dwordx4 v[80:81], v[64:67], off offset:528
	v_lshl_add_u64 v[76:77], v[162:163], 0, v[140:141]
	v_lshl_add_u64 v[92:93], v[162:163], 0, v[142:143]
	v_lshl_add_u64 v[108:109], v[162:163], 0, v[172:173]
	global_load_dwordx4 v[64:67], v[76:77], off
	global_load_dwordx4 v[68:71], v[76:77], off offset:16
	global_load_dwordx4 v[72:75], v[76:77], off offset:512
	s_nop 0
	global_load_dwordx4 v[76:79], v[76:77], off offset:528
	s_nop 0
	global_load_dwordx4 v[80:83], v[92:93], off
	global_load_dwordx4 v[84:87], v[92:93], off offset:16
	global_load_dwordx4 v[88:91], v[92:93], off offset:512
	s_nop 0
	global_load_dwordx4 v[92:95], v[92:93], off offset:528
	s_nop 0
	global_load_dwordx4 v[96:99], v[108:109], off
	global_load_dwordx4 v[100:103], v[108:109], off offset:16
	global_load_dwordx4 v[104:107], v[108:109], off offset:512
	s_nop 0
	global_load_dwordx4 v[108:111], v[108:109], off offset:528
	v_lshl_add_u64 v[164:165], v[164:165], 0, s[34:35]
	v_lshl_add_u64 v[124:125], v[162:163], 0, v[164:165]
	global_load_dwordx4 v[112:115], v[124:125], off
	global_load_dwordx4 v[116:119], v[124:125], off offset:16
	global_load_dwordx4 v[120:123], v[124:125], off offset:512
	s_nop 0
	global_load_dwordx4 v[124:127], v[124:125], off offset:528
	v_lshl_add_u64 v[140:141], s[30:31], 0, v[140:141]
	v_lshl_add_u64 v[162:163], s[30:31], 0, v[172:173]
	v_lshl_add_u64 v[142:143], s[30:31], 0, v[142:143]
	v_lshl_add_u64 v[140:141], v[140:141], 0, v[144:145]
	v_lshl_add_u64 v[162:163], v[162:163], 0, v[144:145]
	v_lshl_add_u64 v[142:143], v[142:143], 0, v[144:145]
	v_mov_b32_e32 v251, v220
	s_waitcnt vmcnt(15)
	v_pk_fma_f32 v[62:63], v[62:63], v[158:159], v[66:67]
	v_pk_fma_f32 v[60:61], v[60:61], v[160:161], v[64:65]
	s_waitcnt vmcnt(14)
	v_pk_fma_f32 v[58:59], v[58:59], v[154:155], v[70:71]
	v_pk_fma_f32 v[56:57], v[56:57], v[156:157], v[68:69]
	s_waitcnt vmcnt(5)
	v_pk_fma_f32 v[18:19], v[18:19], v[150:151], v[106:107]
	v_pk_fma_f32 v[16:17], v[16:17], v[152:153], v[104:105]
	v_pk_fma_f32 v[42:43], v[42:43], v[150:151], v[74:75]
	v_pk_fma_f32 v[40:41], v[40:41], v[152:153], v[72:73]
	v_pk_fma_f32 v[38:39], v[38:39], v[146:147], v[78:79]
	v_pk_fma_f32 v[36:37], v[36:37], v[148:149], v[76:77]
	v_pk_fma_f32 v[54:55], v[54:55], v[158:159], v[82:83]
	v_pk_fma_f32 v[52:53], v[52:53], v[160:161], v[80:81]
	v_pk_fma_f32 v[50:51], v[50:51], v[154:155], v[86:87]
	v_pk_fma_f32 v[48:49], v[48:49], v[156:157], v[84:85]
	v_pk_fma_f32 v[30:31], v[30:31], v[150:151], v[90:91]
	v_pk_fma_f32 v[28:29], v[28:29], v[152:153], v[88:89]
	v_pk_fma_f32 v[26:27], v[26:27], v[146:147], v[94:95]
	v_pk_fma_f32 v[24:25], v[24:25], v[148:149], v[92:93]
	v_pk_fma_f32 v[46:47], v[46:47], v[158:159], v[98:99]
	v_pk_fma_f32 v[44:45], v[44:45], v[160:161], v[96:97]
	v_pk_fma_f32 v[34:35], v[34:35], v[154:155], v[102:103]
	v_pk_fma_f32 v[32:33], v[32:33], v[156:157], v[100:101]
	global_store_dwordx4 v[140:141], v[60:63], off
	global_store_dwordx4 v[140:141], v[56:59], off offset:16
	global_store_dwordx4 v[140:141], v[40:43], off offset:512
	global_store_dwordx4 v[140:141], v[36:39], off offset:528
	global_store_dwordx4 v[142:143], v[52:55], off
	global_store_dwordx4 v[142:143], v[48:51], off offset:16
	global_store_dwordx4 v[142:143], v[28:31], off offset:512
	global_store_dwordx4 v[142:143], v[24:27], off offset:528
	global_store_dwordx4 v[162:163], v[44:47], off
	global_store_dwordx4 v[162:163], v[32:35], off offset:16
	global_store_dwordx4 v[162:163], v[16:19], off offset:512
	s_waitcnt vmcnt(15)
	v_pk_fma_f32 v[10:11], v[10:11], v[146:147], v[110:111]
	v_pk_fma_f32 v[8:9], v[8:9], v[148:149], v[108:109]
	v_lshl_add_u64 v[16:17], s[30:31], 0, v[164:165]
	global_store_dwordx4 v[162:163], v[8:11], off offset:528
	v_lshl_add_u64 v[16:17], v[16:17], 0, v[144:145]
	s_waitcnt vmcnt(13)
	v_pk_fma_f32 v[6:7], v[6:7], v[150:151], v[122:123]
	v_pk_fma_f32 v[10:11], v[22:23], v[158:159], v[114:115]
	v_pk_fma_f32 v[8:9], v[20:21], v[160:161], v[112:113]
	global_store_dwordx4 v[16:17], v[8:11], off
	v_pk_fma_f32 v[4:5], v[4:5], v[152:153], v[120:121]
	s_waitcnt vmcnt(13)
	v_pk_fma_f32 v[2:3], v[2:3], v[146:147], v[126:127]
	v_pk_fma_f32 v[10:11], v[14:15], v[154:155], v[118:119]
	v_pk_fma_f32 v[8:9], v[12:13], v[156:157], v[116:117]
	v_pk_fma_f32 v[0:1], v[0:1], v[148:149], v[124:125]
	global_store_dwordx4 v[16:17], v[8:11], off offset:16
	global_store_dwordx4 v[16:17], v[4:7], off offset:512
	global_store_dwordx4 v[16:17], v[0:3], off offset:528
	s_cbranch_vccz .LBB0_234
	s_waitcnt vmcnt(0)
	s_cmpk_gt_u32 s3, 0xff
	s_cbranch_scc1 .LBB0_249
	s_barrier

; #define PG8_STAGE(bufoff, gbase, voff) do { _Pragma("unroll") for (int _i = 0; _i < 2; ++_i) \
;         __builtin_amdgcn_global_load_lds((const unsigned*)((const char*)(gbase) + (voff)[_i]), (PG8_LAS unsigned*)(lds + (bufoff) + ldsw + _i * 8192), 16, 0, 0); } while (0)
; #define PG8_LDA(dst, b, h) do { _Pragma("unroll") for (int m = 0; m < 4; ++m) _Pragma("unroll") for (int k = 0; k < 2; ++k) dst[m][k] = *(const PG8_LAS bf16x8*)(lds + PG8_SA(b, h) + aoff + m * 2048 + k * 1024); } while (0)
; #define PG8_LDB(dst, b, h) do { _Pragma("unroll") for (int n = 0; n < 2; ++n) _Pragma("unroll") for (int k = 0; k < 2; ++k) dst[n][k] = *(const PG8_LAS bf16x8*)(lds + PG8_SB(b, h) + boff + n * 2048 + k * 1024); } while (0)
; #define PG8_WAIT_V(n) asm volatile("s_waitcnt vmcnt(" #n ")" ::: "memory")
; #define PG8_WAIT_L(n) asm volatile("s_waitcnt lgkmcnt(" #n ")" ::: "memory")
; #define PG8_BAR __builtin_amdgcn_s_barrier()
; #define PG8_SCHED __builtin_amdgcn_sched_barrier(0)
; template <class Epi, class Sched, bool ALIGN_EPI = false, bool SP2 = false>
; __device__ __forceinline__ void gemm_phase(PG8_LAS unsigned char* lds, const Gemm g, const Sched& S, const Epi& E) {
;     ...
;         const bool has_next = S.next(ui + 1, nxt);
;         const char* nA = has_next ? (const char*)g.A + (size_t)nxt.pm * tstep : cA; const char* nB = has_next ? (const char*)g.Bt + (size_t)nxt.pn * tstep : cB;
;         for (int t = 0; t < nt; t += 2) {
;             const bool last = (t == nt - 2);
;             const char* a1 = cA + (size_t)(t + 1) * kstep;
;             const char* a2 = last ? nA : cA + (size_t)(t + 2) * kstep; const char* b2 = last ? nB : cB + (size_t)(t + 2) * kstep;
;             const char* a3 = a2 + kstep; const char* b3 = b2 + kstep;
;             if (last && has_next) S.a_ready(nxt);
;             if constexpr (SP2) {
;             PG8_LDB(B0, 0, 0); PG8_LDB(B1, 0, 1); PG8_SCHED; PG8_LDA(At, 0, 0); PG8_STAGE(PG8_SA(1, 1), a1 + hstep, voffA);
;             PG8_WAIT_V(8); PG8_WAIT_L(0); PG8_BAR; PG8_MMA(0, 0, At, B0); PG8_MMA(0, 1, At, B1); PG8_BAR; PG8_SCHED;
;             PG8_LDA(At, 0, 1); PG8_STAGE(PG8_SB(0, 0), b2, voffB); PG8_STAGE(PG8_SB(0, 1), b2 + hstep, voffB); PG8_STAGE(PG8_SA(0, 0), a2, voffA);
;             PG8_WAIT_V(8); PG8_WAIT_L(0); PG8_BAR; PG8_MMA(1, 0, At, B0); PG8_MMA(1, 1, At, B1); PG8_BAR; PG8_SCHED;
.LBB0_363:
	s_ashr_i32 s77, s76, 31
	s_lshl_b64 s[38:39], s[76:77], 20
	v_cmp_lt_i64_e32 vcc, s[78:79], v[178:179]
	s_add_u32 s78, s73, s38
	s_addc_u32 s79, s96, s39
	s_and_b64 s[38:39], vcc, exec
	s_cselect_b32 s77, s79, s85
	s_cselect_b32 s83, s78, s84
	s_ashr_i32 s75, s74, 31
	s_lshl_b64 s[38:39], s[74:75], 20
	s_add_u32 s80, s97, s38
	s_addc_u32 s81, s90, s39
	s_and_b64 s[38:39], vcc, exec
	s_cselect_b32 s75, s81, s87
	s_cselect_b32 vcc_lo, s80, s86
	s_add_u32 s84, s84, 0x80080
	s_addc_u32 s85, s85, 0
	s_add_u32 vcc_hi, s86, 0x100
	s_addc_u32 s38, s87, 0
	s_mov_b32 s39, -2
	ds_read_b128 v[128:131], v214
	ds_read_b128 v[132:135], v214 offset:1024
	ds_read_b128 v[136:139], v214 offset:2048
	ds_read_b128 v[140:143], v214 offset:3072
	ds_read_b128 v[144:147], v215
	ds_read_b128 v[148:151], v215 offset:1024
	ds_read_b128 v[152:155], v215 offset:2048
	ds_read_b128 v[156:159], v215 offset:3072
	s_add_u32 s58, s84, 0xfff80080
	s_addc_u32 s59, s85, -1
	s_cmp_eq_u32 s39, 28
	s_cselect_b32 s89, s77, s59
	s_cselect_b32 s88, s83, s58
	s_cselect_b32 s87, s75, s38
	s_cselect_b32 s86, vcc_lo, vcc_hi
	s_add_i32 m0, s7, 0xc000
	ds_read_b128 v[160:163], v216
	ds_read_b128 v[182:185], v216 offset:1024
	ds_read_b128 v[186:189], v216 offset:2048
	ds_read_b128 v[190:193], v216 offset:3072
	ds_read_b128 v[222:225], v216 offset:4096
	ds_read_b128 v[232:235], v216 offset:5120
	ds_read_b128 v[236:239], v216 offset:6144
	ds_read_b128 v[240:243], v216 offset:7168
	global_load_lds_dwordx4 v174, s[84:85]
	s_add_i32 m0, s7, 0xe000
	s_nop 0
	global_load_lds_dwordx4 v176, s[84:85]
	s_waitcnt vmcnt(8) lgkmcnt(0)
	s_barrier
	v_mfma_f32_16x16x32_bf16 v[124:127], v[128:131], v[160:163], 0
	v_mfma_f32_16x16x32_bf16 v[120:123], v[136:139], v[160:163], 0
	v_mfma_f32_16x16x32_bf16 v[116:119], v[128:131], v[186:189], 0
	v_mfma_f32_16x16x32_bf16 v[112:115], v[136:139], v[186:189], 0
	v_mfma_f32_16x16x32_bf16 v[100:103], v[128:131], v[222:225], 0
	v_mfma_f32_16x16x32_bf16 v[96:99], v[136:139], v[222:225], 0
	v_mfma_f32_16x16x32_bf16 v[84:87], v[128:131], v[236:239], 0
	v_mfma_f32_16x16x32_bf16 v[80:83], v[136:139], v[236:239], 0
	v_mfma_f32_16x16x32_bf16 v[124:127], v[132:135], v[182:185], v[124:127]
	v_mfma_f32_16x16x32_bf16 v[120:123], v[140:143], v[182:185], v[120:123]
	v_mfma_f32_16x16x32_bf16 v[116:119], v[132:135], v[190:193], v[116:119]
	v_mfma_f32_16x16x32_bf16 v[112:115], v[140:143], v[190:193], v[112:115]
	v_mfma_f32_16x16x32_bf16 v[100:103], v[132:135], v[232:235], v[100:103]
	v_mfma_f32_16x16x32_bf16 v[96:99], v[140:143], v[232:235], v[96:99]
	v_mfma_f32_16x16x32_bf16 v[84:87], v[132:135], v[240:243], v[84:87]
	v_mfma_f32_16x16x32_bf16 v[80:83], v[140:143], v[240:243], v[80:83]
	v_mfma_f32_16x16x32_bf16 v[108:111], v[144:147], v[160:163], 0
	v_mfma_f32_16x16x32_bf16 v[104:107], v[152:155], v[160:163], 0
	v_mfma_f32_16x16x32_bf16 v[92:95], v[144:147], v[186:189], 0
	v_mfma_f32_16x16x32_bf16 v[88:91], v[152:155], v[186:189], 0
	v_mfma_f32_16x16x32_bf16 v[76:79], v[144:147], v[222:225], 0
	v_mfma_f32_16x16x32_bf16 v[72:75], v[152:155], v[222:225], 0
	v_mfma_f32_16x16x32_bf16 v[68:71], v[144:147], v[236:239], 0
	v_mfma_f32_16x16x32_bf16 v[64:67], v[152:155], v[236:239], 0
	v_mfma_f32_16x16x32_bf16 v[108:111], v[148:151], v[182:185], v[108:111]
	v_mfma_f32_16x16x32_bf16 v[104:107], v[156:159], v[182:185], v[104:107]
	v_mfma_f32_16x16x32_bf16 v[92:95], v[148:151], v[190:193], v[92:95]
	v_mfma_f32_16x16x32_bf16 v[88:91], v[156:159], v[190:193], v[88:91]
	v_mfma_f32_16x16x32_bf16 v[76:79], v[148:151], v[232:235], v[76:79]
	v_mfma_f32_16x16x32_bf16 v[72:75], v[156:159], v[232:235], v[72:75]
	v_mfma_f32_16x16x32_bf16 v[68:71], v[148:151], v[240:243], v[68:71]
	v_mfma_f32_16x16x32_bf16 v[64:67], v[156:159], v[240:243], v[64:67]
	s_barrier
	s_add_i32 s58, s34, s24
	v_lshl_add_u64 v[194:195], s[86:87], 0, v[168:169]
	s_mov_b32 m0, s58
	ds_read_b128 v[160:163], v216 offset:16384
	ds_read_b128 v[182:185], v216 offset:17408
	ds_read_b128 v[186:189], v216 offset:18432
	ds_read_b128 v[190:193], v216 offset:19456
	ds_read_b128 v[222:225], v216 offset:20480
	ds_read_b128 v[232:235], v216 offset:21504
	ds_read_b128 v[236:239], v216 offset:22528
	ds_read_b128 v[240:243], v216 offset:23552
	global_load_lds_dwordx4 v168, s[86:87]
	s_add_i32 m0, s58, 0x2000
	s_add_u32 s58, s86, 0x80000
	v_lshl_add_u64 v[230:231], s[86:87], 0, v[164:165]
	s_addc_u32 s59, s87, 0
	s_add_i32 s48, s35, s24
	global_load_lds_dwordx4 v164, s[86:87]
	s_mov_b32 m0, s48
	v_lshl_add_u64 v[246:247], s[88:89], 0, v[166:167]
	global_load_lds_dwordx4 v168, s[58:59]
	s_add_i32 m0, s48, 0x2000
	s_nop 0
	global_load_lds_dwordx4 v164, s[58:59]
	v_lshl_add_u64 v[244:245], s[88:89], 0, v[170:171]
	s_mov_b32 m0, s7
	s_nop 0
	global_load_lds_dwordx4 v170, s[88:89]
	s_mov_b32 m0, s8
	s_nop 0
	global_load_lds_dwordx4 v166, s[88:89]
	s_waitcnt vmcnt(8) lgkmcnt(0)
	s_barrier
; #define PG8_STAGE(bufoff, gbase, voff) do { _Pragma("unroll") for (int _i = 0; _i < 2; ++_i) \
;         __builtin_amdgcn_global_load_lds((const unsigned*)((const char*)(gbase) + (voff)[_i]), (PG8_LAS unsigned*)(lds + (bufoff) + ldsw + _i * 8192), 16, 0, 0); } while (0)
; #define PG8_LDA(dst, b, h) do { _Pragma("unroll") for (int m = 0; m < 4; ++m) _Pragma("unroll") for (int k = 0; k < 2; ++k) dst[m][k] = *(const PG8_LAS bf16x8*)(lds + PG8_SA(b, h) + aoff + m * 2048 + k * 1024); } while (0)
; #define PG8_LDB(dst, b, h) do { _Pragma("unroll") for (int n = 0; n < 2; ++n) _Pragma("unroll") for (int k = 0; k < 2; ++k) dst[n][k] = *(const PG8_LAS bf16x8*)(lds + PG8_SB(b, h) + boff + n * 2048 + k * 1024); } while (0)
; #define PG8_MMA(ai, bj, At, Bt) do { __builtin_amdgcn_s_setprio(1); _Pragma("unroll") for (int m = 0; m < 4; ++m) _Pragma("unroll") for (int n = 0; n < 2; ++n) _Pragma("unroll") for (int k = 0; k < 2; ++k) \
;         acc[ai][bj][m][n] = __builtin_amdgcn_mfma_f32_16x16x32_bf16(Bt[n][k], At[m][k], acc[ai][bj][m][n], 0, 0, 0); __builtin_amdgcn_s_setprio(0); } while (0)
; #define PG8_WAIT_V(n) asm volatile("s_waitcnt vmcnt(" #n ")" ::: "memory")
; #define PG8_WAIT_L(n) asm volatile("s_waitcnt lgkmcnt(" #n ")" ::: "memory")
; #define PG8_BAR __builtin_amdgcn_s_barrier()
; #define PG8_SCHED __builtin_amdgcn_sched_barrier(0)
; template <class Epi, class Sched, bool ALIGN_EPI = false, bool SP2 = false>
; __device__ __forceinline__ void gemm_phase(PG8_LAS unsigned char* lds, const Gemm g, const Sched& S, const Epi& E) {
;     ...
;             PG8_WAIT_V(8); PG8_WAIT_L(0); PG8_BAR; PG8_MMA(1, 0, At, B0); PG8_MMA(1, 1, At, B1); PG8_BAR; PG8_SCHED;
;             PG8_LDB(B0, 1, 0); PG8_LDB(B1, 1, 1); PG8_SCHED; PG8_LDA(At, 1, 0); PG8_STAGE(PG8_SA(0, 1), a2 + hstep, voffA);
;             PG8_WAIT_V(8); PG8_WAIT_L(0); PG8_BAR; PG8_MMA(0, 0, At, B0); PG8_MMA(0, 1, At, B1); PG8_BAR; PG8_SCHED;
	v_mfma_f32_16x16x32_bf16 v[60:63], v[128:131], v[160:163], 0
	v_mfma_f32_16x16x32_bf16 v[56:59], v[136:139], v[160:163], 0
	v_mfma_f32_16x16x32_bf16 v[52:55], v[128:131], v[186:189], 0
	v_mfma_f32_16x16x32_bf16 v[48:51], v[136:139], v[186:189], 0
	v_mfma_f32_16x16x32_bf16 v[36:39], v[128:131], v[222:225], 0
	v_mfma_f32_16x16x32_bf16 v[32:35], v[136:139], v[222:225], 0
	v_mfma_f32_16x16x32_bf16 v[20:23], v[128:131], v[236:239], 0
	v_mfma_f32_16x16x32_bf16 v[16:19], v[136:139], v[236:239], 0
	v_mfma_f32_16x16x32_bf16 v[60:63], v[132:135], v[182:185], v[60:63]
	v_mfma_f32_16x16x32_bf16 v[56:59], v[140:143], v[182:185], v[56:59]
	v_mfma_f32_16x16x32_bf16 v[52:55], v[132:135], v[190:193], v[52:55]
	v_mfma_f32_16x16x32_bf16 v[48:51], v[140:143], v[190:193], v[48:51]
	v_mfma_f32_16x16x32_bf16 v[36:39], v[132:135], v[232:235], v[36:39]
	v_mfma_f32_16x16x32_bf16 v[32:35], v[140:143], v[232:235], v[32:35]
	v_mfma_f32_16x16x32_bf16 v[20:23], v[132:135], v[240:243], v[20:23]
	v_mfma_f32_16x16x32_bf16 v[16:19], v[140:143], v[240:243], v[16:19]
	v_mfma_f32_16x16x32_bf16 v[44:47], v[144:147], v[160:163], 0
	v_mfma_f32_16x16x32_bf16 v[40:43], v[152:155], v[160:163], 0
	v_mfma_f32_16x16x32_bf16 v[28:31], v[144:147], v[186:189], 0
	v_mfma_f32_16x16x32_bf16 v[24:27], v[152:155], v[186:189], 0
	v_mfma_f32_16x16x32_bf16 v[12:15], v[144:147], v[222:225], 0
	v_mfma_f32_16x16x32_bf16 v[8:11], v[152:155], v[222:225], 0
	v_mfma_f32_16x16x32_bf16 v[4:7], v[144:147], v[236:239], 0
	v_mfma_f32_16x16x32_bf16 v[0:3], v[152:155], v[236:239], 0
	v_mfma_f32_16x16x32_bf16 v[44:47], v[148:151], v[182:185], v[44:47]
	v_mfma_f32_16x16x32_bf16 v[40:43], v[156:159], v[182:185], v[40:43]
	v_mfma_f32_16x16x32_bf16 v[28:31], v[148:151], v[190:193], v[28:31]
	v_mfma_f32_16x16x32_bf16 v[24:27], v[156:159], v[190:193], v[24:27]
	v_mfma_f32_16x16x32_bf16 v[12:15], v[148:151], v[232:235], v[12:15]
	v_mfma_f32_16x16x32_bf16 v[8:11], v[156:159], v[232:235], v[8:11]
	v_mfma_f32_16x16x32_bf16 v[4:7], v[148:151], v[240:243], v[4:7]
	v_mfma_f32_16x16x32_bf16 v[0:3], v[156:159], v[240:243], v[0:3]
	s_barrier
	s_add_i32 s48, 0, 0x18000
	s_add_i32 s60, 0, 0x1c000
	v_add_u32_e32 v140, s48, v197
	v_add_u32_e32 v156, s60, v197
	ds_read_b128 v[128:131], v140
	ds_read_b128 v[132:135], v140 offset:1024
	ds_read_b128 v[136:139], v140 offset:2048
	ds_read_b128 v[140:143], v140 offset:3072
	ds_read_b128 v[144:147], v156
	ds_read_b128 v[148:151], v156 offset:1024
	ds_read_b128 v[152:155], v156 offset:2048
	ds_read_b128 v[156:159], v156 offset:3072
	s_add_u32 s58, s88, 0x80000
	s_addc_u32 s59, s89, 0
	s_mov_b32 m0, s9
	ds_read_b128 v[160:163], v216 offset:32768
	ds_read_b128 v[182:185], v216 offset:33792
	ds_read_b128 v[186:189], v216 offset:34816
	ds_read_b128 v[190:193], v216 offset:35840
	ds_read_b128 v[222:225], v216 offset:36864
	ds_read_b128 v[232:235], v216 offset:37888
	ds_read_b128 v[236:239], v216 offset:38912
	ds_read_b128 v[240:243], v216 offset:39936
	global_load_lds_dwordx4 v170, s[58:59]
	s_mov_b32 m0, s26
	s_nop 0
	global_load_lds_dwordx4 v166, s[58:59]
	s_waitcnt vmcnt(8) lgkmcnt(0)
	s_barrier
	v_mfma_f32_16x16x32_bf16 v[124:127], v[128:131], v[160:163], v[124:127]
	v_mfma_f32_16x16x32_bf16 v[120:123], v[136:139], v[160:163], v[120:123]
	v_mfma_f32_16x16x32_bf16 v[116:119], v[128:131], v[186:189], v[116:119]
	v_mfma_f32_16x16x32_bf16 v[112:115], v[136:139], v[186:189], v[112:115]
	v_mfma_f32_16x16x32_bf16 v[100:103], v[128:131], v[222:225], v[100:103]
	v_mfma_f32_16x16x32_bf16 v[96:99], v[136:139], v[222:225], v[96:99]
	v_mfma_f32_16x16x32_bf16 v[84:87], v[128:131], v[236:239], v[84:87]
	v_mfma_f32_16x16x32_bf16 v[80:83], v[136:139], v[236:239], v[80:83]
	v_mfma_f32_16x16x32_bf16 v[124:127], v[132:135], v[182:185], v[124:127]
	v_mfma_f32_16x16x32_bf16 v[120:123], v[140:143], v[182:185], v[120:123]
	v_mfma_f32_16x16x32_bf16 v[116:119], v[132:135], v[190:193], v[116:119]
	v_mfma_f32_16x16x32_bf16 v[112:115], v[140:143], v[190:193], v[112:115]
	v_mfma_f32_16x16x32_bf16 v[100:103], v[132:135], v[232:235], v[100:103]
	v_mfma_f32_16x16x32_bf16 v[96:99], v[140:143], v[232:235], v[96:99]
	v_mfma_f32_16x16x32_bf16 v[84:87], v[132:135], v[240:243], v[84:87]
	v_mfma_f32_16x16x32_bf16 v[80:83], v[140:143], v[240:243], v[80:83]
	v_mfma_f32_16x16x32_bf16 v[108:111], v[144:147], v[160:163], v[108:111]
	v_mfma_f32_16x16x32_bf16 v[104:107], v[152:155], v[160:163], v[104:107]
	v_mfma_f32_16x16x32_bf16 v[92:95], v[144:147], v[186:189], v[92:95]
	v_mfma_f32_16x16x32_bf16 v[88:91], v[152:155], v[186:189], v[88:91]
	v_mfma_f32_16x16x32_bf16 v[76:79], v[144:147], v[222:225], v[76:79]
	v_mfma_f32_16x16x32_bf16 v[72:75], v[152:155], v[222:225], v[72:75]
	v_mfma_f32_16x16x32_bf16 v[68:71], v[144:147], v[236:239], v[68:71]
	v_mfma_f32_16x16x32_bf16 v[64:67], v[152:155], v[236:239], v[64:67]
	v_mfma_f32_16x16x32_bf16 v[108:111], v[148:151], v[182:185], v[108:111]
	v_mfma_f32_16x16x32_bf16 v[104:107], v[156:159], v[182:185], v[104:107]
	v_mfma_f32_16x16x32_bf16 v[92:95], v[148:151], v[190:193], v[92:95]
	v_mfma_f32_16x16x32_bf16 v[88:91], v[156:159], v[190:193], v[88:91]
	v_mfma_f32_16x16x32_bf16 v[76:79], v[148:151], v[232:235], v[76:79]
	v_mfma_f32_16x16x32_bf16 v[72:75], v[156:159], v[232:235], v[72:75]
	v_mfma_f32_16x16x32_bf16 v[68:71], v[148:151], v[240:243], v[68:71]
	v_mfma_f32_16x16x32_bf16 v[64:67], v[156:159], v[240:243], v[64:67]
	s_barrier
; #define PG8_STAGE(bufoff, gbase, voff) do { _Pragma("unroll") for (int _i = 0; _i < 2; ++_i) \
;         __builtin_amdgcn_global_load_lds((const unsigned*)((const char*)(gbase) + (voff)[_i]), (PG8_LAS unsigned*)(lds + (bufoff) + ldsw + _i * 8192), 16, 0, 0); } while (0)
; #define PG8_LDA(dst, b, h) do { _Pragma("unroll") for (int m = 0; m < 4; ++m) _Pragma("unroll") for (int k = 0; k < 2; ++k) dst[m][k] = *(const PG8_LAS bf16x8*)(lds + PG8_SA(b, h) + aoff + m * 2048 + k * 1024); } while (0)
; #define PG8_LDB(dst, b, h) do { _Pragma("unroll") for (int n = 0; n < 2; ++n) _Pragma("unroll") for (int k = 0; k < 2; ++k) dst[n][k] = *(const PG8_LAS bf16x8*)(lds + PG8_SB(b, h) + boff + n * 2048 + k * 1024); } while (0)
; #define PG8_MMA(ai, bj, At, Bt) do { __builtin_amdgcn_s_setprio(1); _Pragma("unroll") for (int m = 0; m < 4; ++m) _Pragma("unroll") for (int n = 0; n < 2; ++n) _Pragma("unroll") for (int k = 0; k < 2; ++k) \
;         acc[ai][bj][m][n] = __builtin_amdgcn_mfma_f32_16x16x32_bf16(Bt[n][k], At[m][k], acc[ai][bj][m][n], 0, 0, 0); __builtin_amdgcn_s_setprio(0); } while (0)
; #define PG8_WAIT_V(n) asm volatile("s_waitcnt vmcnt(" #n ")" ::: "memory")
; #define PG8_WAIT_L(n) asm volatile("s_waitcnt lgkmcnt(" #n ")" ::: "memory")
; #define PG8_BAR __builtin_amdgcn_s_barrier()
; #define PG8_SCHED __builtin_amdgcn_sched_barrier(0)
; template <class Epi, class Sched, bool ALIGN_EPI = false, bool SP2 = false>
; __device__ __forceinline__ void gemm_phase(PG8_LAS unsigned char* lds, const Gemm g, const Sched& S, const Epi& E) {
;     ...
;             PG8_LDB(B0, 0, 0); PG8_LDB(B1, 0, 1); PG8_SCHED; PG8_LDA(At, 0, 0); PG8_STAGE(PG8_SA(1, 1), a1 + hstep, voffA);
;             PG8_WAIT_V(8); PG8_WAIT_L(0); PG8_BAR; PG8_MMA(0, 0, At, B0); PG8_MMA(0, 1, At, B1); PG8_BAR; PG8_SCHED;
;             PG8_LDA(At, 0, 1); PG8_STAGE(PG8_SB(0, 0), b2, voffB); PG8_STAGE(PG8_SB(0, 1), b2 + hstep, voffB); PG8_STAGE(PG8_SA(0, 0), a2, voffA);
;             PG8_WAIT_V(8); PG8_WAIT_L(0); PG8_BAR; PG8_MMA(1, 0, At, B0); PG8_MMA(1, 1, At, B1); PG8_BAR; PG8_SCHED;
;     ...
;             PG8_LDA(At, 1, 1); PG8_STAGE(PG8_SB(1, 0), b3, voffB); PG8_STAGE(PG8_SB(1, 1), b3 + hstep, voffB); PG8_STAGE(PG8_SA(1, 0), a3, voffA);
;             PG8_WAIT_V(8); PG8_WAIT_L(0); PG8_BAR; PG8_MMA(1, 0, At, B0); PG8_MMA(1, 1, At, B1); PG8_BAR; PG8_SCHED;
	s_add_i32 s48, s48, s24
	v_lshl_add_u64 v[194:195], v[194:195], 0, s[54:55]
	s_mov_b32 m0, s48
	ds_read_b128 v[160:163], v216 offset:49152
	ds_read_b128 v[182:185], v216 offset:50176
	ds_read_b128 v[186:189], v216 offset:51200
	ds_read_b128 v[190:193], v216 offset:52224
	ds_read_b128 v[222:225], v216 offset:53248
	ds_read_b128 v[232:235], v216 offset:54272
	ds_read_b128 v[236:239], v216 offset:55296
	ds_read_b128 v[240:243], v216 offset:56320
	global_load_lds_dwordx4 v[194:195], off
	s_add_i32 m0, s48, 0x2000
	s_add_u32 s58, s86, 0x80080
	v_lshl_add_u64 v[194:195], v[230:231], 0, s[54:55]
	s_addc_u32 s59, s87, 0
	s_add_i32 s48, s60, s24
	global_load_lds_dwordx4 v[194:195], off
	s_mov_b32 m0, s48
	s_nop 0
	global_load_lds_dwordx4 v168, s[58:59]
	s_add_i32 m0, s48, 0x2000
	s_nop 0
	global_load_lds_dwordx4 v164, s[58:59]
	v_lshl_add_u64 v[194:195], v[244:245], 0, s[54:55]
	s_mov_b32 m0, s36
	s_nop 0
	global_load_lds_dwordx4 v[194:195], off
	v_lshl_add_u64 v[194:195], v[246:247], 0, s[54:55]
	s_mov_b32 m0, s37
	s_nop 0
	global_load_lds_dwordx4 v[194:195], off
	s_waitcnt vmcnt(8) lgkmcnt(0)
	s_barrier
	v_mfma_f32_16x16x32_bf16 v[60:63], v[128:131], v[160:163], v[60:63]
	v_mfma_f32_16x16x32_bf16 v[56:59], v[136:139], v[160:163], v[56:59]
	v_mfma_f32_16x16x32_bf16 v[52:55], v[128:131], v[186:189], v[52:55]
	v_mfma_f32_16x16x32_bf16 v[48:51], v[136:139], v[186:189], v[48:51]
	v_mfma_f32_16x16x32_bf16 v[36:39], v[128:131], v[222:225], v[36:39]
	v_mfma_f32_16x16x32_bf16 v[32:35], v[136:139], v[222:225], v[32:35]
	v_mfma_f32_16x16x32_bf16 v[20:23], v[128:131], v[236:239], v[20:23]
	v_mfma_f32_16x16x32_bf16 v[16:19], v[136:139], v[236:239], v[16:19]
	v_mfma_f32_16x16x32_bf16 v[60:63], v[132:135], v[182:185], v[60:63]
	v_mfma_f32_16x16x32_bf16 v[56:59], v[140:143], v[182:185], v[56:59]
	v_mfma_f32_16x16x32_bf16 v[52:55], v[132:135], v[190:193], v[52:55]
	v_mfma_f32_16x16x32_bf16 v[48:51], v[140:143], v[190:193], v[48:51]
	v_mfma_f32_16x16x32_bf16 v[36:39], v[132:135], v[232:235], v[36:39]
	v_mfma_f32_16x16x32_bf16 v[32:35], v[140:143], v[232:235], v[32:35]
	v_mfma_f32_16x16x32_bf16 v[20:23], v[132:135], v[240:243], v[20:23]
	v_mfma_f32_16x16x32_bf16 v[16:19], v[140:143], v[240:243], v[16:19]
	v_mfma_f32_16x16x32_bf16 v[44:47], v[144:147], v[160:163], v[44:47]
	v_mfma_f32_16x16x32_bf16 v[40:43], v[152:155], v[160:163], v[40:43]
	v_mfma_f32_16x16x32_bf16 v[28:31], v[144:147], v[186:189], v[28:31]
	v_mfma_f32_16x16x32_bf16 v[24:27], v[152:155], v[186:189], v[24:27]
	v_mfma_f32_16x16x32_bf16 v[12:15], v[144:147], v[222:225], v[12:15]
	v_mfma_f32_16x16x32_bf16 v[8:11], v[152:155], v[222:225], v[8:11]
	v_mfma_f32_16x16x32_bf16 v[4:7], v[144:147], v[236:239], v[4:7]
	v_mfma_f32_16x16x32_bf16 v[0:3], v[152:155], v[236:239], v[0:3]
	v_mfma_f32_16x16x32_bf16 v[44:47], v[148:151], v[182:185], v[44:47]
	v_mfma_f32_16x16x32_bf16 v[40:43], v[156:159], v[182:185], v[40:43]
	v_mfma_f32_16x16x32_bf16 v[28:31], v[148:151], v[190:193], v[28:31]
	v_mfma_f32_16x16x32_bf16 v[24:27], v[156:159], v[190:193], v[24:27]
	v_mfma_f32_16x16x32_bf16 v[12:15], v[148:151], v[232:235], v[12:15]
	v_mfma_f32_16x16x32_bf16 v[8:11], v[156:159], v[232:235], v[8:11]
	v_mfma_f32_16x16x32_bf16 v[4:7], v[148:151], v[240:243], v[4:7]
	v_mfma_f32_16x16x32_bf16 v[0:3], v[156:159], v[240:243], v[0:3]
	s_barrier
	s_add_i32 s39, s39, 2
	s_add_u32 s84, s84, 0x100
	s_addc_u32 s85, s85, 0
	s_add_u32 vcc_hi, vcc_hi, 0x100
	s_addc_u32 s38, s38, 0
	s_cmp_gt_u32 s39, 29
.LBB0_364:
	ds_read_b128 v[128:131], v214
	ds_read_b128 v[132:135], v214 offset:1024
	ds_read_b128 v[136:139], v214 offset:2048
	ds_read_b128 v[140:143], v214 offset:3072
	ds_read_b128 v[144:147], v215
	ds_read_b128 v[148:151], v215 offset:1024
	ds_read_b128 v[152:155], v215 offset:2048
	ds_read_b128 v[156:159], v215 offset:3072
	s_add_u32 s58, s84, 0xfff80080
	s_addc_u32 s59, s85, -1
	s_cmp_eq_u32 s39, 28
	s_cselect_b32 s89, s77, s59
	s_cselect_b32 s88, s83, s58
	s_cselect_b32 s87, s75, s38
	s_cselect_b32 s86, vcc_lo, vcc_hi
	s_add_i32 m0, s7, 0xc000
	ds_read_b128 v[160:163], v216
	ds_read_b128 v[182:185], v216 offset:1024
	ds_read_b128 v[186:189], v216 offset:2048
	ds_read_b128 v[190:193], v216 offset:3072
	ds_read_b128 v[222:225], v216 offset:4096
	ds_read_b128 v[232:235], v216 offset:5120
	ds_read_b128 v[236:239], v216 offset:6144
	ds_read_b128 v[240:243], v216 offset:7168
	global_load_lds_dwordx4 v174, s[84:85]
	s_add_i32 m0, s7, 0xe000
	s_nop 0
	global_load_lds_dwordx4 v176, s[84:85]
	s_waitcnt vmcnt(8) lgkmcnt(0)
	s_barrier
; #define PG8_STAGE(bufoff, gbase, voff) do { _Pragma("unroll") for (int _i = 0; _i < 2; ++_i) \
;         __builtin_amdgcn_global_load_lds((const unsigned*)((const char*)(gbase) + (voff)[_i]), (PG8_LAS unsigned*)(lds + (bufoff) + ldsw + _i * 8192), 16, 0, 0); } while (0)
; #define PG8_LDA(dst, b, h) do { _Pragma("unroll") for (int m = 0; m < 4; ++m) _Pragma("unroll") for (int k = 0; k < 2; ++k) dst[m][k] = *(const PG8_LAS bf16x8*)(lds + PG8_SA(b, h) + aoff + m * 2048 + k * 1024); } while (0)
; #define PG8_LDB(dst, b, h) do { _Pragma("unroll") for (int n = 0; n < 2; ++n) _Pragma("unroll") for (int k = 0; k < 2; ++k) dst[n][k] = *(const PG8_LAS bf16x8*)(lds + PG8_SB(b, h) + boff + n * 2048 + k * 1024); } while (0)
; #define PG8_MMA(ai, bj, At, Bt) do { __builtin_amdgcn_s_setprio(1); _Pragma("unroll") for (int m = 0; m < 4; ++m) _Pragma("unroll") for (int n = 0; n < 2; ++n) _Pragma("unroll") for (int k = 0; k < 2; ++k) \
;         acc[ai][bj][m][n] = __builtin_amdgcn_mfma_f32_16x16x32_bf16(Bt[n][k], At[m][k], acc[ai][bj][m][n], 0, 0, 0); __builtin_amdgcn_s_setprio(0); } while (0)
; #define PG8_WAIT_V(n) asm volatile("s_waitcnt vmcnt(" #n ")" ::: "memory")
; #define PG8_WAIT_L(n) asm volatile("s_waitcnt lgkmcnt(" #n ")" ::: "memory")
; #define PG8_BAR __builtin_amdgcn_s_barrier()
; #define PG8_SCHED __builtin_amdgcn_sched_barrier(0)
; template <class Epi, class Sched, bool ALIGN_EPI = false, bool SP2 = false>
; __device__ __forceinline__ void gemm_phase(PG8_LAS unsigned char* lds, const Gemm g, const Sched& S, const Epi& E) {
;     ...
;             PG8_WAIT_V(8); PG8_WAIT_L(0); PG8_BAR; PG8_MMA(0, 0, At, B0); PG8_MMA(0, 1, At, B1); PG8_BAR; PG8_SCHED;
;             PG8_LDA(At, 0, 1); PG8_STAGE(PG8_SB(0, 0), b2, voffB); PG8_STAGE(PG8_SB(0, 1), b2 + hstep, voffB); PG8_STAGE(PG8_SA(0, 0), a2, voffA);
;             PG8_WAIT_V(8); PG8_WAIT_L(0); PG8_BAR; PG8_MMA(1, 0, At, B0); PG8_MMA(1, 1, At, B1); PG8_BAR; PG8_SCHED;
;             PG8_LDB(B0, 1, 0); PG8_LDB(B1, 1, 1); PG8_SCHED; PG8_LDA(At, 1, 0); PG8_STAGE(PG8_SA(0, 1), a2 + hstep, voffA);
;             PG8_WAIT_V(8); PG8_WAIT_L(0); PG8_BAR; PG8_MMA(0, 0, At, B0); PG8_MMA(0, 1, At, B1); PG8_BAR; PG8_SCHED;
	v_mfma_f32_16x16x32_bf16 v[124:127], v[128:131], v[160:163], v[124:127]
	v_mfma_f32_16x16x32_bf16 v[120:123], v[136:139], v[160:163], v[120:123]
	v_mfma_f32_16x16x32_bf16 v[116:119], v[128:131], v[186:189], v[116:119]
	v_mfma_f32_16x16x32_bf16 v[112:115], v[136:139], v[186:189], v[112:115]
	v_mfma_f32_16x16x32_bf16 v[100:103], v[128:131], v[222:225], v[100:103]
	v_mfma_f32_16x16x32_bf16 v[96:99], v[136:139], v[222:225], v[96:99]
	v_mfma_f32_16x16x32_bf16 v[84:87], v[128:131], v[236:239], v[84:87]
	v_mfma_f32_16x16x32_bf16 v[80:83], v[136:139], v[236:239], v[80:83]
	v_mfma_f32_16x16x32_bf16 v[124:127], v[132:135], v[182:185], v[124:127]
	v_mfma_f32_16x16x32_bf16 v[120:123], v[140:143], v[182:185], v[120:123]
	v_mfma_f32_16x16x32_bf16 v[116:119], v[132:135], v[190:193], v[116:119]
	v_mfma_f32_16x16x32_bf16 v[112:115], v[140:143], v[190:193], v[112:115]
	v_mfma_f32_16x16x32_bf16 v[100:103], v[132:135], v[232:235], v[100:103]
	v_mfma_f32_16x16x32_bf16 v[96:99], v[140:143], v[232:235], v[96:99]
	v_mfma_f32_16x16x32_bf16 v[84:87], v[132:135], v[240:243], v[84:87]
	v_mfma_f32_16x16x32_bf16 v[80:83], v[140:143], v[240:243], v[80:83]
	v_mfma_f32_16x16x32_bf16 v[108:111], v[144:147], v[160:163], v[108:111]
	v_mfma_f32_16x16x32_bf16 v[104:107], v[152:155], v[160:163], v[104:107]
	v_mfma_f32_16x16x32_bf16 v[92:95], v[144:147], v[186:189], v[92:95]
	v_mfma_f32_16x16x32_bf16 v[88:91], v[152:155], v[186:189], v[88:91]
	v_mfma_f32_16x16x32_bf16 v[76:79], v[144:147], v[222:225], v[76:79]
	v_mfma_f32_16x16x32_bf16 v[72:75], v[152:155], v[222:225], v[72:75]
	v_mfma_f32_16x16x32_bf16 v[68:71], v[144:147], v[236:239], v[68:71]
	v_mfma_f32_16x16x32_bf16 v[64:67], v[152:155], v[236:239], v[64:67]
	v_mfma_f32_16x16x32_bf16 v[108:111], v[148:151], v[182:185], v[108:111]
	v_mfma_f32_16x16x32_bf16 v[104:107], v[156:159], v[182:185], v[104:107]
	v_mfma_f32_16x16x32_bf16 v[92:95], v[148:151], v[190:193], v[92:95]
	v_mfma_f32_16x16x32_bf16 v[88:91], v[156:159], v[190:193], v[88:91]
	v_mfma_f32_16x16x32_bf16 v[76:79], v[148:151], v[232:235], v[76:79]
	v_mfma_f32_16x16x32_bf16 v[72:75], v[156:159], v[232:235], v[72:75]
	v_mfma_f32_16x16x32_bf16 v[68:71], v[148:151], v[240:243], v[68:71]
	v_mfma_f32_16x16x32_bf16 v[64:67], v[156:159], v[240:243], v[64:67]
	s_barrier
	s_add_i32 s58, s34, s24
	v_lshl_add_u64 v[194:195], s[86:87], 0, v[168:169]
	s_mov_b32 m0, s58
	ds_read_b128 v[160:163], v216 offset:16384
	ds_read_b128 v[182:185], v216 offset:17408
	ds_read_b128 v[186:189], v216 offset:18432
	ds_read_b128 v[190:193], v216 offset:19456
	ds_read_b128 v[222:225], v216 offset:20480
	ds_read_b128 v[232:235], v216 offset:21504
	ds_read_b128 v[236:239], v216 offset:22528
	ds_read_b128 v[240:243], v216 offset:23552
	global_load_lds_dwordx4 v168, s[86:87]
	s_add_i32 m0, s58, 0x2000
	s_add_u32 s58, s86, 0x80000
	v_lshl_add_u64 v[230:231], s[86:87], 0, v[164:165]
	s_addc_u32 s59, s87, 0
	s_add_i32 s48, s35, s24
	global_load_lds_dwordx4 v164, s[86:87]
	s_mov_b32 m0, s48
	v_lshl_add_u64 v[246:247], s[88:89], 0, v[166:167]
	global_load_lds_dwordx4 v168, s[58:59]
	s_add_i32 m0, s48, 0x2000
	s_nop 0
	global_load_lds_dwordx4 v164, s[58:59]
	v_lshl_add_u64 v[244:245], s[88:89], 0, v[170:171]
	s_mov_b32 m0, s7
	s_nop 0
	global_load_lds_dwordx4 v170, s[88:89]
	s_mov_b32 m0, s8
	s_nop 0
	global_load_lds_dwordx4 v166, s[88:89]
	s_waitcnt vmcnt(8) lgkmcnt(0)
	s_barrier
	v_mfma_f32_16x16x32_bf16 v[60:63], v[128:131], v[160:163], v[60:63]
	v_mfma_f32_16x16x32_bf16 v[56:59], v[136:139], v[160:163], v[56:59]
	v_mfma_f32_16x16x32_bf16 v[52:55], v[128:131], v[186:189], v[52:55]
	v_mfma_f32_16x16x32_bf16 v[48:51], v[136:139], v[186:189], v[48:51]
	v_mfma_f32_16x16x32_bf16 v[36:39], v[128:131], v[222:225], v[36:39]
	v_mfma_f32_16x16x32_bf16 v[32:35], v[136:139], v[222:225], v[32:35]
	v_mfma_f32_16x16x32_bf16 v[20:23], v[128:131], v[236:239], v[20:23]
	v_mfma_f32_16x16x32_bf16 v[16:19], v[136:139], v[236:239], v[16:19]
	v_mfma_f32_16x16x32_bf16 v[60:63], v[132:135], v[182:185], v[60:63]
	v_mfma_f32_16x16x32_bf16 v[56:59], v[140:143], v[182:185], v[56:59]
	v_mfma_f32_16x16x32_bf16 v[52:55], v[132:135], v[190:193], v[52:55]
	v_mfma_f32_16x16x32_bf16 v[48:51], v[140:143], v[190:193], v[48:51]
	v_mfma_f32_16x16x32_bf16 v[36:39], v[132:135], v[232:235], v[36:39]
	v_mfma_f32_16x16x32_bf16 v[32:35], v[140:143], v[232:235], v[32:35]
	v_mfma_f32_16x16x32_bf16 v[20:23], v[132:135], v[240:243], v[20:23]
	v_mfma_f32_16x16x32_bf16 v[16:19], v[140:143], v[240:243], v[16:19]
	v_mfma_f32_16x16x32_bf16 v[44:47], v[144:147], v[160:163], v[44:47]
	v_mfma_f32_16x16x32_bf16 v[40:43], v[152:155], v[160:163], v[40:43]
	v_mfma_f32_16x16x32_bf16 v[28:31], v[144:147], v[186:189], v[28:31]
	v_mfma_f32_16x16x32_bf16 v[24:27], v[152:155], v[186:189], v[24:27]
	v_mfma_f32_16x16x32_bf16 v[12:15], v[144:147], v[222:225], v[12:15]
	v_mfma_f32_16x16x32_bf16 v[8:11], v[152:155], v[222:225], v[8:11]
	v_mfma_f32_16x16x32_bf16 v[4:7], v[144:147], v[236:239], v[4:7]
	v_mfma_f32_16x16x32_bf16 v[0:3], v[152:155], v[236:239], v[0:3]
	v_mfma_f32_16x16x32_bf16 v[44:47], v[148:151], v[182:185], v[44:47]
	v_mfma_f32_16x16x32_bf16 v[40:43], v[156:159], v[182:185], v[40:43]
	v_mfma_f32_16x16x32_bf16 v[28:31], v[148:151], v[190:193], v[28:31]
	v_mfma_f32_16x16x32_bf16 v[24:27], v[156:159], v[190:193], v[24:27]
	v_mfma_f32_16x16x32_bf16 v[12:15], v[148:151], v[232:235], v[12:15]
	v_mfma_f32_16x16x32_bf16 v[8:11], v[156:159], v[232:235], v[8:11]
	v_mfma_f32_16x16x32_bf16 v[4:7], v[148:151], v[240:243], v[4:7]
	v_mfma_f32_16x16x32_bf16 v[0:3], v[156:159], v[240:243], v[0:3]
	s_barrier
; #define PG8_STAGE(bufoff, gbase, voff) do { _Pragma("unroll") for (int _i = 0; _i < 2; ++_i) \
;         __builtin_amdgcn_global_load_lds((const unsigned*)((const char*)(gbase) + (voff)[_i]), (PG8_LAS unsigned*)(lds + (bufoff) + ldsw + _i * 8192), 16, 0, 0); } while (0)
; #define PG8_LDA(dst, b, h) do { _Pragma("unroll") for (int m = 0; m < 4; ++m) _Pragma("unroll") for (int k = 0; k < 2; ++k) dst[m][k] = *(const PG8_LAS bf16x8*)(lds + PG8_SA(b, h) + aoff + m * 2048 + k * 1024); } while (0)
; #define PG8_LDB(dst, b, h) do { _Pragma("unroll") for (int n = 0; n < 2; ++n) _Pragma("unroll") for (int k = 0; k < 2; ++k) dst[n][k] = *(const PG8_LAS bf16x8*)(lds + PG8_SB(b, h) + boff + n * 2048 + k * 1024); } while (0)
; #define PG8_MMA(ai, bj, At, Bt) do { __builtin_amdgcn_s_setprio(1); _Pragma("unroll") for (int m = 0; m < 4; ++m) _Pragma("unroll") for (int n = 0; n < 2; ++n) _Pragma("unroll") for (int k = 0; k < 2; ++k) \
;         acc[ai][bj][m][n] = __builtin_amdgcn_mfma_f32_16x16x32_bf16(Bt[n][k], At[m][k], acc[ai][bj][m][n], 0, 0, 0); __builtin_amdgcn_s_setprio(0); } while (0)
; #define PG8_WAIT_V(n) asm volatile("s_waitcnt vmcnt(" #n ")" ::: "memory")
; #define PG8_WAIT_L(n) asm volatile("s_waitcnt lgkmcnt(" #n ")" ::: "memory")
; #define PG8_BAR __builtin_amdgcn_s_barrier()
; #define PG8_SCHED __builtin_amdgcn_sched_barrier(0)
; template <class Epi, class Sched, bool ALIGN_EPI = false, bool SP2 = false>
; __device__ __forceinline__ void gemm_phase(PG8_LAS unsigned char* lds, const Gemm g, const Sched& S, const Epi& E) {
;     ...
;             PG8_LDB(B0, 1, 0); PG8_LDB(B1, 1, 1); PG8_SCHED; PG8_LDA(At, 1, 0); PG8_STAGE(PG8_SA(0, 1), a2 + hstep, voffA);
;             PG8_WAIT_V(8); PG8_WAIT_L(0); PG8_BAR; PG8_MMA(0, 0, At, B0); PG8_MMA(0, 1, At, B1); PG8_BAR; PG8_SCHED;
;             PG8_LDA(At, 1, 1); PG8_STAGE(PG8_SB(1, 0), b3, voffB); PG8_STAGE(PG8_SB(1, 1), b3 + hstep, voffB); PG8_STAGE(PG8_SA(1, 0), a3, voffA);
;             PG8_WAIT_V(8); PG8_WAIT_L(0); PG8_BAR; PG8_MMA(1, 0, At, B0); PG8_MMA(1, 1, At, B1); PG8_BAR; PG8_SCHED;
	s_add_i32 s48, 0, 0x18000
	s_add_i32 s60, 0, 0x1c000
	v_add_u32_e32 v140, s48, v197
	v_add_u32_e32 v156, s60, v197
	ds_read_b128 v[128:131], v140
	ds_read_b128 v[132:135], v140 offset:1024
	ds_read_b128 v[136:139], v140 offset:2048
	ds_read_b128 v[140:143], v140 offset:3072
	ds_read_b128 v[144:147], v156
	ds_read_b128 v[148:151], v156 offset:1024
	ds_read_b128 v[152:155], v156 offset:2048
	ds_read_b128 v[156:159], v156 offset:3072
	s_add_u32 s58, s88, 0x80000
	s_addc_u32 s59, s89, 0
	s_mov_b32 m0, s9
	ds_read_b128 v[160:163], v216 offset:32768
	ds_read_b128 v[182:185], v216 offset:33792
	ds_read_b128 v[186:189], v216 offset:34816
	ds_read_b128 v[190:193], v216 offset:35840
	ds_read_b128 v[222:225], v216 offset:36864
	ds_read_b128 v[232:235], v216 offset:37888
	ds_read_b128 v[236:239], v216 offset:38912
	ds_read_b128 v[240:243], v216 offset:39936
	global_load_lds_dwordx4 v170, s[58:59]
	s_mov_b32 m0, s26
	s_nop 0
	global_load_lds_dwordx4 v166, s[58:59]
	s_waitcnt vmcnt(8) lgkmcnt(0)
	s_barrier
	v_mfma_f32_16x16x32_bf16 v[124:127], v[128:131], v[160:163], v[124:127]
	v_mfma_f32_16x16x32_bf16 v[120:123], v[136:139], v[160:163], v[120:123]
	v_mfma_f32_16x16x32_bf16 v[116:119], v[128:131], v[186:189], v[116:119]
	v_mfma_f32_16x16x32_bf16 v[112:115], v[136:139], v[186:189], v[112:115]
	v_mfma_f32_16x16x32_bf16 v[100:103], v[128:131], v[222:225], v[100:103]
	v_mfma_f32_16x16x32_bf16 v[96:99], v[136:139], v[222:225], v[96:99]
	v_mfma_f32_16x16x32_bf16 v[84:87], v[128:131], v[236:239], v[84:87]
	v_mfma_f32_16x16x32_bf16 v[80:83], v[136:139], v[236:239], v[80:83]
	v_mfma_f32_16x16x32_bf16 v[124:127], v[132:135], v[182:185], v[124:127]
	v_mfma_f32_16x16x32_bf16 v[120:123], v[140:143], v[182:185], v[120:123]
	v_mfma_f32_16x16x32_bf16 v[116:119], v[132:135], v[190:193], v[116:119]
	v_mfma_f32_16x16x32_bf16 v[112:115], v[140:143], v[190:193], v[112:115]
	v_mfma_f32_16x16x32_bf16 v[100:103], v[132:135], v[232:235], v[100:103]
	v_mfma_f32_16x16x32_bf16 v[96:99], v[140:143], v[232:235], v[96:99]
	v_mfma_f32_16x16x32_bf16 v[84:87], v[132:135], v[240:243], v[84:87]
	v_mfma_f32_16x16x32_bf16 v[80:83], v[140:143], v[240:243], v[80:83]
	v_mfma_f32_16x16x32_bf16 v[108:111], v[144:147], v[160:163], v[108:111]
	v_mfma_f32_16x16x32_bf16 v[104:107], v[152:155], v[160:163], v[104:107]
	v_mfma_f32_16x16x32_bf16 v[92:95], v[144:147], v[186:189], v[92:95]
	v_mfma_f32_16x16x32_bf16 v[88:91], v[152:155], v[186:189], v[88:91]
	v_mfma_f32_16x16x32_bf16 v[76:79], v[144:147], v[222:225], v[76:79]
	v_mfma_f32_16x16x32_bf16 v[72:75], v[152:155], v[222:225], v[72:75]
	v_mfma_f32_16x16x32_bf16 v[68:71], v[144:147], v[236:239], v[68:71]
	v_mfma_f32_16x16x32_bf16 v[64:67], v[152:155], v[236:239], v[64:67]
	v_mfma_f32_16x16x32_bf16 v[108:111], v[148:151], v[182:185], v[108:111]
	v_mfma_f32_16x16x32_bf16 v[104:107], v[156:159], v[182:185], v[104:107]
	v_mfma_f32_16x16x32_bf16 v[92:95], v[148:151], v[190:193], v[92:95]
	v_mfma_f32_16x16x32_bf16 v[88:91], v[156:159], v[190:193], v[88:91]
	v_mfma_f32_16x16x32_bf16 v[76:79], v[148:151], v[232:235], v[76:79]
	v_mfma_f32_16x16x32_bf16 v[72:75], v[156:159], v[232:235], v[72:75]
	v_mfma_f32_16x16x32_bf16 v[68:71], v[148:151], v[240:243], v[68:71]
	v_mfma_f32_16x16x32_bf16 v[64:67], v[156:159], v[240:243], v[64:67]
	s_barrier
	s_add_i32 s48, s48, s24
	v_lshl_add_u64 v[194:195], v[194:195], 0, s[54:55]
	s_mov_b32 m0, s48
	ds_read_b128 v[160:163], v216 offset:49152
	ds_read_b128 v[182:185], v216 offset:50176
	ds_read_b128 v[186:189], v216 offset:51200
	ds_read_b128 v[190:193], v216 offset:52224
	ds_read_b128 v[222:225], v216 offset:53248
	ds_read_b128 v[232:235], v216 offset:54272
	ds_read_b128 v[236:239], v216 offset:55296
	ds_read_b128 v[240:243], v216 offset:56320
	global_load_lds_dwordx4 v[194:195], off
	s_add_i32 m0, s48, 0x2000
	s_add_u32 s58, s86, 0x80080
	v_lshl_add_u64 v[194:195], v[230:231], 0, s[54:55]
	s_addc_u32 s59, s87, 0
	s_add_i32 s48, s60, s24
	global_load_lds_dwordx4 v[194:195], off
	s_mov_b32 m0, s48
	s_nop 0
	global_load_lds_dwordx4 v168, s[58:59]
	s_add_i32 m0, s48, 0x2000
	s_nop 0
	global_load_lds_dwordx4 v164, s[58:59]
	v_lshl_add_u64 v[194:195], v[244:245], 0, s[54:55]
	s_mov_b32 m0, s36
	s_nop 0
	global_load_lds_dwordx4 v[194:195], off
	v_lshl_add_u64 v[194:195], v[246:247], 0, s[54:55]
	s_mov_b32 m0, s37
	s_nop 0
	global_load_lds_dwordx4 v[194:195], off
	s_waitcnt vmcnt(8) lgkmcnt(0)
	s_barrier
	v_mfma_f32_16x16x32_bf16 v[60:63], v[128:131], v[160:163], v[60:63]
	v_mfma_f32_16x16x32_bf16 v[56:59], v[136:139], v[160:163], v[56:59]
	v_mfma_f32_16x16x32_bf16 v[52:55], v[128:131], v[186:189], v[52:55]
	v_mfma_f32_16x16x32_bf16 v[48:51], v[136:139], v[186:189], v[48:51]
	v_mfma_f32_16x16x32_bf16 v[36:39], v[128:131], v[222:225], v[36:39]
	v_mfma_f32_16x16x32_bf16 v[32:35], v[136:139], v[222:225], v[32:35]
	v_mfma_f32_16x16x32_bf16 v[20:23], v[128:131], v[236:239], v[20:23]
	v_mfma_f32_16x16x32_bf16 v[16:19], v[136:139], v[236:239], v[16:19]
	v_mfma_f32_16x16x32_bf16 v[60:63], v[132:135], v[182:185], v[60:63]
	v_mfma_f32_16x16x32_bf16 v[56:59], v[140:143], v[182:185], v[56:59]
	v_mfma_f32_16x16x32_bf16 v[52:55], v[132:135], v[190:193], v[52:55]
	v_mfma_f32_16x16x32_bf16 v[48:51], v[140:143], v[190:193], v[48:51]
	v_mfma_f32_16x16x32_bf16 v[36:39], v[132:135], v[232:235], v[36:39]
	v_mfma_f32_16x16x32_bf16 v[32:35], v[140:143], v[232:235], v[32:35]
	v_mfma_f32_16x16x32_bf16 v[20:23], v[132:135], v[240:243], v[20:23]
	v_mfma_f32_16x16x32_bf16 v[16:19], v[140:143], v[240:243], v[16:19]
	v_mfma_f32_16x16x32_bf16 v[44:47], v[144:147], v[160:163], v[44:47]
	v_mfma_f32_16x16x32_bf16 v[40:43], v[152:155], v[160:163], v[40:43]
	v_mfma_f32_16x16x32_bf16 v[28:31], v[144:147], v[186:189], v[28:31]
	v_mfma_f32_16x16x32_bf16 v[24:27], v[152:155], v[186:189], v[24:27]
	v_mfma_f32_16x16x32_bf16 v[12:15], v[144:147], v[222:225], v[12:15]
	v_mfma_f32_16x16x32_bf16 v[8:11], v[152:155], v[222:225], v[8:11]
	v_mfma_f32_16x16x32_bf16 v[4:7], v[144:147], v[236:239], v[4:7]
	v_mfma_f32_16x16x32_bf16 v[0:3], v[152:155], v[236:239], v[0:3]
	v_mfma_f32_16x16x32_bf16 v[44:47], v[148:151], v[182:185], v[44:47]
	v_mfma_f32_16x16x32_bf16 v[40:43], v[156:159], v[182:185], v[40:43]
	v_mfma_f32_16x16x32_bf16 v[28:31], v[148:151], v[190:193], v[28:31]
	v_mfma_f32_16x16x32_bf16 v[24:27], v[156:159], v[190:193], v[24:27]
	v_mfma_f32_16x16x32_bf16 v[12:15], v[148:151], v[232:235], v[12:15]
	v_mfma_f32_16x16x32_bf16 v[8:11], v[156:159], v[232:235], v[8:11]
	v_mfma_f32_16x16x32_bf16 v[4:7], v[148:151], v[240:243], v[4:7]
	v_mfma_f32_16x16x32_bf16 v[0:3], v[156:159], v[240:243], v[0:3]
	s_barrier
; __device__ __forceinline__ float fsigmoid(float v) { return __builtin_amdgcn_rcpf(1.0f + __builtin_amdgcn_exp2f(-LOG2E * v)); }
; __device__ __forceinline__ float fsilu(float v) { return v * fsigmoid(v); }
; __device__ __forceinline__ u32x4 pack8(const f32x4 a, const f32x4 b) { u32x4 w; w.x = cvt_pk_bf16(a[0], a[1]); w.y = cvt_pk_bf16(a[2], a[3]); w.z = cvt_pk_bf16(b[0], b[1]); w.w = cvt_pk_bf16(b[2], b[3]); return w; }
;     template <int ACT> __device__ __forceinline__ void ew(const f32x4 (&acc)[2][2][4][2], bf16_t* D, int ld, int row0, int col0) const {
; #pragma unroll
;         for (int ai = 0; ai < 2; ++ai)
; #pragma unroll
;             for (int m = 0; m < 4; ++m) { bf16_t* rowp = D + (size_t)(row0 + ai * HALF + m * 16) * ld + col0;
; #pragma unroll
;                 for (int bj = 0; bj < 2; ++bj) { f32x4 v0 = acc[ai][bj][m][0], v1 = acc[ai][bj][m][1];
;                     if (ACT == 1) {
; #pragma unroll
;                         for (int j = 0; j < 4; ++j) { v0[j] = fsilu(v0[j]); v1[j] = fsilu(v1[j]); } }
;                     if (ACT == 2) {
; #pragma unroll
;                         for (int j = 0; j < 4; ++j) { v0[j] = fsigmoid(v0[j]); v1[j] = fsigmoid(v1[j]); } }
;                     *(u32x4*)(rowp + bj * HALF) = pack8(v0, v1); } }
;     }
;     __device__ __forceinline__ void operator()(const f32x4 (&acc)[2][2][4][2], const Unit& u, int wr, int wc, int fr, int fq) const {
;         const int pn = u.pn, row0 = u.pm * BM + wr * 64 + fr, cl = wc * 32 + 8 * fq;
;         if (pn < 4) ew<0>(acc, HQ, 1024, row0, pn * 256 + cl);
;     ...
;         else if (pn < 36) ew<2>(acc, SGA, 2048, row0, (pn - 28) * 256 + cl);
;         else ew<2>(acc, SGB, 2048, row0, (pn - 36) * 256 + cl);
	s_add_i32 s39, s39, 2
	s_add_u32 s84, s84, 0x100
	s_addc_u32 s85, s85, 0
	s_add_u32 vcc_hi, vcc_hi, 0x100
	s_addc_u32 s38, s38, 0
	s_cmp_gt_u32 s39, 29
	s_cbranch_scc0 .LBB0_364
	v_lshl_add_u32 v182, s82, 8, v196
	s_cmp_gt_i32 s23, 3
	s_mov_b64 s[82:83], -1
	s_cbranch_scc0 .LBB0_391
	s_cmp_gt_u32 s23, 7
	s_cbranch_scc0 .LBB0_388
	s_cmp_gt_u32 s23, 11
	s_cbranch_scc0 .LBB0_385
	s_cmp_gt_u32 s23, 15
	s_cbranch_scc0 .LBB0_382
	s_cmp_gt_u32 s23, 23
	s_cbranch_scc0 .LBB0_379
	s_lshl_b32 s75, s23, 8
	s_cmp_gt_u32 s23, 27
	s_cbranch_scc0 .LBB0_376
	v_mul_f32_e32 v129, 0xbfb8aa3b, v120
	v_exp_f32_e32 v129, v129
	v_mul_f32_e32 v130, 0xbfb8aa3b, v125
	v_mul_f32_e32 v131, 0xbfb8aa3b, v121
	v_exp_f32_e32 v130, v130
	v_exp_f32_e32 v131, v131
	v_add_f32_e32 v129, 1.0, v129
	v_mul_f32_e32 v128, 0xbfb8aa3b, v124
	v_rcp_f32_e32 v132, v129
	v_add_f32_e32 v129, 1.0, v130
	v_add_f32_e32 v130, 1.0, v131
	v_mul_f32_e32 v131, 0xbfb8aa3b, v126
	v_mul_f32_e32 v134, 0xbfb8aa3b, v127
	v_exp_f32_e32 v128, v128
	v_exp_f32_e32 v131, v131
	v_exp_f32_e32 v134, v134
	v_rcp_f32_e32 v129, v129
	v_add_f32_e32 v128, 1.0, v128
	v_add_f32_e32 v131, 1.0, v131
	v_add_f32_e32 v134, 1.0, v134
	v_rcp_f32_e32 v128, v128
	v_mul_f32_e32 v133, 0xbfb8aa3b, v122
	v_rcp_f32_e32 v131, v131
	v_mul_f32_e32 v135, 0xbfb8aa3b, v123
	v_rcp_f32_e32 v134, v134
	v_exp_f32_e32 v133, v133
	v_rcp_f32_e32 v130, v130
	v_exp_f32_e32 v135, v135
	v_cvt_pk_bf16_f32 v128, v128, v129
	v_cvt_pk_bf16_f32 v129, v131, v134
	v_mul_f32_e32 v131, 0xbfb8aa3b, v108
	v_add_f32_e32 v133, 1.0, v133
	v_add_f32_e32 v135, 1.0, v135
	v_cvt_pk_bf16_f32 v130, v132, v130
	v_exp_f32_e32 v132, v131
	v_mul_f32_e32 v131, 0xbfb8aa3b, v104
	v_rcp_f32_e32 v133, v133
	v_rcp_f32_e32 v135, v135
	v_exp_f32_e32 v134, v131
	v_mul_f32_e32 v137, 0xbfb8aa3b, v106
	v_mul_f32_e32 v138, 0xbfb8aa3b, v111
	v_cvt_pk_bf16_f32 v131, v133, v135
	v_add_f32_e32 v133, 1.0, v134
	v_mul_f32_e32 v134, 0xbfb8aa3b, v109
	v_mul_f32_e32 v135, 0xbfb8aa3b, v105
	v_exp_f32_e32 v134, v134
	v_exp_f32_e32 v135, v135
	v_rcp_f32_e32 v136, v133
	v_mul_f32_e32 v139, 0xbfb8aa3b, v107
	v_add_f32_e32 v133, 1.0, v134
	v_add_f32_e32 v134, 1.0, v135
	v_mul_f32_e32 v135, 0xbfb8aa3b, v110
	v_exp_f32_e32 v135, v135
	v_exp_f32_e32 v137, v137
	v_exp_f32_e32 v138, v138
	v_exp_f32_e32 v139, v139
	v_add_f32_e32 v132, 1.0, v132
	v_add_f32_e32 v135, 1.0, v135
	v_add_f32_e32 v137, 1.0, v137
	v_add_f32_e32 v138, 1.0, v138
	v_add_f32_e32 v139, 1.0, v139
	v_rcp_f32_e32 v132, v132
	v_rcp_f32_e32 v133, v133
	v_rcp_f32_e32 v135, v135
	v_rcp_f32_e32 v137, v137
	v_rcp_f32_e32 v138, v138
	v_rcp_f32_e32 v139, v139
	v_rcp_f32_e32 v134, v134
	v_cvt_pk_bf16_f32 v132, v132, v133
	v_cvt_pk_bf16_f32 v133, v135, v138
	v_cvt_pk_bf16_f32 v135, v137, v139
	v_mul_f32_e32 v138, 0xbfb8aa3b, v116
	v_mul_f32_e32 v139, 0xbfb8aa3b, v112
	v_exp_f32_e32 v138, v138
	v_exp_f32_e32 v139, v139
	v_cvt_pk_bf16_f32 v134, v136, v134
	v_or_b32_e32 v136, 16, v182
	v_ashrrev_i32_e32 v137, 31, v136
	v_lshlrev_b64 v[186:187], 12, v[136:137]
	v_add_f32_e32 v136, 1.0, v138
	v_add_f32_e32 v137, 1.0, v139
	v_mul_f32_e32 v138, 0xbfb8aa3b, v117
	v_mul_f32_e32 v139, 0xbfb8aa3b, v113
	v_exp_f32_e32 v138, v138
	v_exp_f32_e32 v139, v139
	v_rcp_f32_e32 v140, v137
	v_mul_f32_e32 v142, 0xbfb8aa3b, v119
	v_add_f32_e32 v137, 1.0, v138
	v_add_f32_e32 v138, 1.0, v139
	v_mul_f32_e32 v139, 0xbfb8aa3b, v118
	v_exp_f32_e32 v139, v139
	v_exp_f32_e32 v142, v142
	v_rcp_f32_e32 v136, v136
	v_rcp_f32_e32 v137, v137
	v_add_f32_e32 v139, 1.0, v139
	v_add_f32_e32 v142, 1.0, v142
	v_mul_f32_e32 v141, 0xbfb8aa3b, v114
	v_rcp_f32_e32 v139, v139
	v_mul_f32_e32 v143, 0xbfb8aa3b, v115
	v_rcp_f32_e32 v142, v142
	v_exp_f32_e32 v141, v141
	v_rcp_f32_e32 v138, v138
	v_exp_f32_e32 v143, v143
	v_cvt_pk_bf16_f32 v136, v136, v137
	v_cvt_pk_bf16_f32 v137, v139, v142
	v_mul_f32_e32 v139, 0xbfb8aa3b, v92
	v_add_f32_e32 v141, 1.0, v141
	v_add_f32_e32 v143, 1.0, v143
	v_cvt_pk_bf16_f32 v138, v140, v138
	v_exp_f32_e32 v140, v139
	v_mul_f32_e32 v139, 0xbfb8aa3b, v88
	v_rcp_f32_e32 v141, v141
	v_rcp_f32_e32 v143, v143
	v_exp_f32_e32 v142, v139
	v_mul_f32_e32 v145, 0xbfb8aa3b, v90
	v_mul_f32_e32 v146, 0xbfb8aa3b, v95
	v_cvt_pk_bf16_f32 v139, v141, v143
	v_add_f32_e32 v141, 1.0, v142
	v_mul_f32_e32 v142, 0xbfb8aa3b, v93
	v_mul_f32_e32 v143, 0xbfb8aa3b, v89
	v_exp_f32_e32 v142, v142
	v_exp_f32_e32 v143, v143
	v_rcp_f32_e32 v144, v141
	v_mul_f32_e32 v147, 0xbfb8aa3b, v91
	v_add_f32_e32 v141, 1.0, v142
	v_add_f32_e32 v142, 1.0, v143
	v_mul_f32_e32 v143, 0xbfb8aa3b, v94
	v_exp_f32_e32 v143, v143
	v_exp_f32_e32 v145, v145
	v_exp_f32_e32 v146, v146
	v_exp_f32_e32 v147, v147
	v_add_f32_e32 v140, 1.0, v140
	v_add_f32_e32 v143, 1.0, v143
	v_add_f32_e32 v145, 1.0, v145
	v_add_f32_e32 v146, 1.0, v146
	v_add_f32_e32 v147, 1.0, v147
	v_rcp_f32_e32 v140, v140
	v_rcp_f32_e32 v141, v141
	v_rcp_f32_e32 v143, v143
	v_rcp_f32_e32 v145, v145
	v_rcp_f32_e32 v146, v146
	v_rcp_f32_e32 v147, v147
	v_rcp_f32_e32 v142, v142
	v_cvt_pk_bf16_f32 v140, v140, v141
	v_cvt_pk_bf16_f32 v141, v143, v146
	v_cvt_pk_bf16_f32 v143, v145, v147
	v_mul_f32_e32 v146, 0xbfb8aa3b, v100
	v_mul_f32_e32 v147, 0xbfb8aa3b, v96
	v_exp_f32_e32 v146, v146
	v_exp_f32_e32 v147, v147
	v_cvt_pk_bf16_f32 v142, v144, v142
	v_or_b32_e32 v144, 32, v182
	v_ashrrev_i32_e32 v145, 31, v144
	v_lshlrev_b64 v[188:189], 12, v[144:145]
	v_add_f32_e32 v144, 1.0, v146
	v_add_f32_e32 v145, 1.0, v147
	v_mul_f32_e32 v146, 0xbfb8aa3b, v101
	v_mul_f32_e32 v147, 0xbfb8aa3b, v97
	v_exp_f32_e32 v146, v146
	v_exp_f32_e32 v147, v147
	v_rcp_f32_e32 v148, v145
	v_mul_f32_e32 v150, 0xbfb8aa3b, v103
	v_add_f32_e32 v145, 1.0, v146
	v_add_f32_e32 v146, 1.0, v147
; __device__ __forceinline__ float fsigmoid(float v) { return __builtin_amdgcn_rcpf(1.0f + __builtin_amdgcn_exp2f(-LOG2E * v)); }
; __device__ __forceinline__ float fsilu(float v) { return v * fsigmoid(v); }
; __device__ __forceinline__ u32x4 pack8(const f32x4 a, const f32x4 b) { u32x4 w; w.x = cvt_pk_bf16(a[0], a[1]); w.y = cvt_pk_bf16(a[2], a[3]); w.z = cvt_pk_bf16(b[0], b[1]); w.w = cvt_pk_bf16(b[2], b[3]); return w; }
;     template <int ACT> __device__ __forceinline__ void ew(const f32x4 (&acc)[2][2][4][2], bf16_t* D, int ld, int row0, int col0) const {
; #pragma unroll
;         for (int ai = 0; ai < 2; ++ai)
; #pragma unroll
;             for (int m = 0; m < 4; ++m) { bf16_t* rowp = D + (size_t)(row0 + ai * HALF + m * 16) * ld + col0;
; #pragma unroll
;                 for (int bj = 0; bj < 2; ++bj) { f32x4 v0 = acc[ai][bj][m][0], v1 = acc[ai][bj][m][1];
;                     if (ACT == 1) {
; #pragma unroll
;                         for (int j = 0; j < 4; ++j) { v0[j] = fsilu(v0[j]); v1[j] = fsilu(v1[j]); } }
;                     if (ACT == 2) {
; #pragma unroll
;                         for (int j = 0; j < 4; ++j) { v0[j] = fsigmoid(v0[j]); v1[j] = fsigmoid(v1[j]); } }
;                     *(u32x4*)(rowp + bj * HALF) = pack8(v0, v1); } }
	v_mul_f32_e32 v147, 0xbfb8aa3b, v102
	v_exp_f32_e32 v147, v147
	v_exp_f32_e32 v150, v150
	v_rcp_f32_e32 v144, v144
	v_rcp_f32_e32 v145, v145
	v_add_f32_e32 v147, 1.0, v147
	v_add_f32_e32 v150, 1.0, v150
	v_mul_f32_e32 v149, 0xbfb8aa3b, v98
	v_rcp_f32_e32 v147, v147
	v_mul_f32_e32 v151, 0xbfb8aa3b, v99
	v_rcp_f32_e32 v150, v150
	v_exp_f32_e32 v149, v149
	v_rcp_f32_e32 v146, v146
	v_exp_f32_e32 v151, v151
	v_cvt_pk_bf16_f32 v144, v144, v145
	v_cvt_pk_bf16_f32 v145, v147, v150
	v_mul_f32_e32 v147, 0xbfb8aa3b, v76
	v_add_f32_e32 v149, 1.0, v149
	v_add_f32_e32 v151, 1.0, v151
	v_cvt_pk_bf16_f32 v146, v148, v146
	v_exp_f32_e32 v148, v147
	v_mul_f32_e32 v147, 0xbfb8aa3b, v72
	v_rcp_f32_e32 v149, v149
	v_rcp_f32_e32 v151, v151
	v_exp_f32_e32 v150, v147
	v_mul_f32_e32 v153, 0xbfb8aa3b, v74
	v_mul_f32_e32 v154, 0xbfb8aa3b, v79
	v_cvt_pk_bf16_f32 v147, v149, v151
	v_add_f32_e32 v149, 1.0, v150
	v_mul_f32_e32 v150, 0xbfb8aa3b, v77
	v_mul_f32_e32 v151, 0xbfb8aa3b, v73
	v_exp_f32_e32 v150, v150
	v_exp_f32_e32 v151, v151
	v_rcp_f32_e32 v152, v149
	v_mul_f32_e32 v155, 0xbfb8aa3b, v75
	v_add_f32_e32 v149, 1.0, v150
	v_add_f32_e32 v150, 1.0, v151
	v_mul_f32_e32 v151, 0xbfb8aa3b, v78
	v_exp_f32_e32 v151, v151
	v_exp_f32_e32 v153, v153
	v_exp_f32_e32 v154, v154
	v_exp_f32_e32 v155, v155
	v_add_f32_e32 v148, 1.0, v148
	v_add_f32_e32 v151, 1.0, v151
	v_add_f32_e32 v153, 1.0, v153
	v_add_f32_e32 v154, 1.0, v154
	v_add_f32_e32 v155, 1.0, v155
	v_rcp_f32_e32 v148, v148
	v_rcp_f32_e32 v149, v149
	v_rcp_f32_e32 v151, v151
	v_rcp_f32_e32 v153, v153
	v_rcp_f32_e32 v154, v154
	v_rcp_f32_e32 v155, v155
	v_rcp_f32_e32 v150, v150
	v_cvt_pk_bf16_f32 v148, v148, v149
	v_cvt_pk_bf16_f32 v149, v151, v154
	v_cvt_pk_bf16_f32 v151, v153, v155
	v_mul_f32_e32 v154, 0xbfb8aa3b, v84
	v_mul_f32_e32 v155, 0xbfb8aa3b, v80
	v_exp_f32_e32 v154, v154
	v_exp_f32_e32 v155, v155
	v_cvt_pk_bf16_f32 v150, v152, v150
	v_or_b32_e32 v152, 48, v182
	v_ashrrev_i32_e32 v153, 31, v152
	v_lshlrev_b64 v[190:191], 12, v[152:153]
	v_add_f32_e32 v152, 1.0, v154
	v_add_f32_e32 v153, 1.0, v155
	v_mul_f32_e32 v154, 0xbfb8aa3b, v85
	v_mul_f32_e32 v155, 0xbfb8aa3b, v81
	v_exp_f32_e32 v154, v154
	v_exp_f32_e32 v155, v155
	v_rcp_f32_e32 v156, v153
	v_mul_f32_e32 v158, 0xbfb8aa3b, v87
	v_add_f32_e32 v153, 1.0, v154
	v_add_f32_e32 v154, 1.0, v155
	v_mul_f32_e32 v155, 0xbfb8aa3b, v86
	v_exp_f32_e32 v155, v155
	v_exp_f32_e32 v158, v158
	v_rcp_f32_e32 v152, v152
	v_rcp_f32_e32 v153, v153
	v_add_f32_e32 v155, 1.0, v155
	v_add_f32_e32 v158, 1.0, v158
	v_mul_f32_e32 v157, 0xbfb8aa3b, v82
	v_rcp_f32_e32 v155, v155
	v_mul_f32_e32 v159, 0xbfb8aa3b, v83
	v_rcp_f32_e32 v158, v158
	v_exp_f32_e32 v157, v157
	v_rcp_f32_e32 v154, v154
	v_exp_f32_e32 v159, v159
	v_cvt_pk_bf16_f32 v152, v152, v153
	v_cvt_pk_bf16_f32 v153, v155, v158
	v_mul_f32_e32 v155, 0xbfb8aa3b, v68
	v_add_f32_e32 v157, 1.0, v157
	v_add_f32_e32 v159, 1.0, v159
	v_cvt_pk_bf16_f32 v154, v156, v154
	v_exp_f32_e32 v156, v155
	v_mul_f32_e32 v155, 0xbfb8aa3b, v64
	v_rcp_f32_e32 v157, v157
	v_rcp_f32_e32 v159, v159
	v_exp_f32_e32 v158, v155
	v_mul_f32_e32 v161, 0xbfb8aa3b, v66
	v_mul_f32_e32 v162, 0xbfb8aa3b, v71
	v_cvt_pk_bf16_f32 v155, v157, v159
	v_add_f32_e32 v157, 1.0, v158
	v_mul_f32_e32 v158, 0xbfb8aa3b, v69
	v_mul_f32_e32 v159, 0xbfb8aa3b, v65
	v_exp_f32_e32 v158, v158
	v_exp_f32_e32 v159, v159
	v_rcp_f32_e32 v160, v157
	v_mul_f32_e32 v163, 0xbfb8aa3b, v67
	v_add_f32_e32 v157, 1.0, v158
	v_add_f32_e32 v158, 1.0, v159
	v_mul_f32_e32 v159, 0xbfb8aa3b, v70
	v_exp_f32_e32 v159, v159
	v_exp_f32_e32 v161, v161
	v_exp_f32_e32 v162, v162
	v_exp_f32_e32 v163, v163
	v_add_f32_e32 v156, 1.0, v156
	v_add_f32_e32 v159, 1.0, v159
	v_add_f32_e32 v161, 1.0, v161
	v_add_f32_e32 v162, 1.0, v162
	v_add_f32_e32 v163, 1.0, v163
	v_rcp_f32_e32 v156, v156
	v_rcp_f32_e32 v157, v157
	v_rcp_f32_e32 v159, v159
	v_rcp_f32_e32 v161, v161
	v_rcp_f32_e32 v162, v162
	v_rcp_f32_e32 v163, v163
	v_cvt_pk_bf16_f32 v156, v156, v157
	v_rcp_f32_e32 v158, v158
	v_cvt_pk_bf16_f32 v157, v159, v162
	v_cvt_pk_bf16_f32 v159, v161, v163
	v_mul_f32_e32 v161, 0xbfb8aa3b, v56
	v_exp_f32_e32 v161, v161
	v_mul_f32_e32 v162, 0xbfb8aa3b, v61
	v_mul_f32_e32 v163, 0xbfb8aa3b, v57
	v_exp_f32_e32 v162, v162
	v_exp_f32_e32 v163, v163
	v_add_f32_e32 v161, 1.0, v161
	v_cvt_pk_bf16_f32 v158, v160, v158
	v_mul_f32_e32 v160, 0xbfb8aa3b, v60
	v_rcp_f32_e32 v172, v161
	v_add_f32_e32 v161, 1.0, v162
	v_add_f32_e32 v162, 1.0, v163
	v_mul_f32_e32 v163, 0xbfb8aa3b, v62
	v_mul_f32_e32 v194, 0xbfb8aa3b, v58
	v_mul_f32_e32 v195, 0xbfb8aa3b, v63
	v_mul_f32_e32 v212, 0xbfb8aa3b, v59
	v_exp_f32_e32 v160, v160
	v_exp_f32_e32 v163, v163
	v_exp_f32_e32 v194, v194
	v_exp_f32_e32 v195, v195
	v_exp_f32_e32 v212, v212
	v_add_f32_e32 v160, 1.0, v160
	v_add_f32_e32 v163, 1.0, v163
	v_add_f32_e32 v194, 1.0, v194
	v_add_f32_e32 v195, 1.0, v195
	v_add_f32_e32 v212, 1.0, v212
	v_rcp_f32_e32 v160, v160
	v_rcp_f32_e32 v161, v161
	v_rcp_f32_e32 v162, v162
	v_rcp_f32_e32 v163, v163
	v_rcp_f32_e32 v194, v194
	v_rcp_f32_e32 v195, v195
	v_rcp_f32_e32 v212, v212
	v_ashrrev_i32_e32 v183, 31, v182
	v_lshlrev_b64 v[184:185], 12, v[182:183]
	s_mov_b64 s[38:39], 0x80000
	s_cmp_gt_u32 s23, 35
	v_lshl_add_u64 v[192:193], v[184:185], 0, s[38:39]
	v_cvt_pk_bf16_f32 v160, v160, v161
	v_cvt_pk_bf16_f32 v161, v163, v195
	v_cvt_pk_bf16_f32 v162, v172, v162
	v_cvt_pk_bf16_f32 v163, v194, v212
	s_cbranch_scc0 .LBB0_373
; __device__ __forceinline__ float fsigmoid(float v) { return __builtin_amdgcn_rcpf(1.0f + __builtin_amdgcn_exp2f(-LOG2E * v)); }
; __device__ __forceinline__ float fsilu(float v) { return v * fsigmoid(v); }
; __device__ __forceinline__ u32x4 pack8(const f32x4 a, const f32x4 b) { u32x4 w; w.x = cvt_pk_bf16(a[0], a[1]); w.y = cvt_pk_bf16(a[2], a[3]); w.z = cvt_pk_bf16(b[0], b[1]); w.w = cvt_pk_bf16(b[2], b[3]); return w; }
;     template <int ACT> __device__ __forceinline__ void ew(const f32x4 (&acc)[2][2][4][2], bf16_t* D, int ld, int row0, int col0) const {
; #pragma unroll
;         for (int ai = 0; ai < 2; ++ai)
; #pragma unroll
;             for (int m = 0; m < 4; ++m) { bf16_t* rowp = D + (size_t)(row0 + ai * HALF + m * 16) * ld + col0;
; #pragma unroll
;                 for (int bj = 0; bj < 2; ++bj) { f32x4 v0 = acc[ai][bj][m][0], v1 = acc[ai][bj][m][1];
;                     if (ACT == 1) {
; #pragma unroll
;                         for (int j = 0; j < 4; ++j) { v0[j] = fsilu(v0[j]); v1[j] = fsilu(v1[j]); } }
;                     if (ACT == 2) {
; #pragma unroll
;                         for (int j = 0; j < 4; ++j) { v0[j] = fsigmoid(v0[j]); v1[j] = fsigmoid(v1[j]); } }
;                     *(u32x4*)(rowp + bj * HALF) = pack8(v0, v1); } }
;     __device__ __forceinline__ void operator()(const f32x4 (&acc)[2][2][4][2], const Unit& u, int wr, int wc, int fr, int fq) const {
;     ...
;         else if (pn < 36) ew<2>(acc, SGA, 2048, row0, (pn - 28) * 256 + cl);
;         else ew<2>(acc, SGB, 2048, row0, (pn - 36) * 256 + cl);
	v_readlane_b32 s38, v255, 23
	v_add_u32_e32 v172, s75, v199
	v_readlane_b32 s39, v255, 24
	v_mul_f32_e32 v212, 0xbfb8aa3b, v40
	v_mul_f32_e32 v220, 0xbfb8aa3b, v45
	v_lshl_add_u64 v[222:223], v[172:173], 1, s[38:39]
	v_lshl_add_u64 v[194:195], v[222:223], 0, v[184:185]
	v_lshl_add_u64 v[224:225], v[222:223], 0, v[186:187]
	global_store_dwordx4 v[194:195], v[128:131], off
	global_store_dwordx4 v[194:195], v[132:135], off offset:256
	global_store_dwordx4 v[224:225], v[136:139], off
	global_store_dwordx4 v[224:225], v[140:143], off offset:256
	v_lshl_add_u64 v[224:225], v[222:223], 0, v[188:189]
	global_store_dwordx4 v[224:225], v[144:147], off
	global_store_dwordx4 v[224:225], v[148:151], off offset:256
	v_lshl_add_u64 v[224:225], v[222:223], 0, v[190:191]
	v_lshl_add_u64 v[230:231], v[222:223], 0, v[192:193]
	v_mul_f32_e32 v222, 0xbfb8aa3b, v41
	v_exp_f32_e32 v222, v222
	v_mul_f32_e32 v223, 0xbfb8aa3b, v46
	global_store_dwordx4 v[224:225], v[152:155], off
	global_store_dwordx4 v[224:225], v[156:159], off offset:256
	v_exp_f32_e32 v223, v223
	v_mul_f32_e32 v224, 0xbfb8aa3b, v42
	v_exp_f32_e32 v224, v224
	v_add_f32_e32 v222, 1.0, v222
	v_rcp_f32_e32 v225, v222
	v_add_f32_e32 v222, 1.0, v223
	v_rcp_f32_e32 v223, v222
	v_add_f32_e32 v222, 1.0, v224
	v_mul_f32_e32 v224, 0xbfb8aa3b, v47
	v_mul_f32_e32 v172, 0xbfb8aa3b, v44
	v_exp_f32_e32 v224, v224
	v_mul_f32_e32 v232, 0xbfb8aa3b, v43
	v_exp_f32_e32 v172, v172
	v_exp_f32_e32 v212, v212
	v_exp_f32_e32 v220, v220
	v_exp_f32_e32 v232, v232
	v_rcp_f32_e32 v233, v222
	v_add_f32_e32 v222, 1.0, v224
	v_add_f32_e32 v172, 1.0, v172
	v_add_f32_e32 v212, 1.0, v212
	v_add_f32_e32 v220, 1.0, v220
	v_rcp_f32_e32 v224, v222
	v_add_f32_e32 v222, 1.0, v232
	v_rcp_f32_e32 v172, v172
	v_rcp_f32_e32 v212, v212
	v_rcp_f32_e32 v220, v220
	v_rcp_f32_e32 v232, v222
	v_cvt_pk_bf16_f32 v223, v223, v224
	v_cvt_pk_bf16_f32 v224, v212, v225
	v_cvt_pk_bf16_f32 v222, v172, v220
	v_cvt_pk_bf16_f32 v225, v233, v232
	global_store_dwordx4 v[230:231], v[222:225], off offset:256
	v_mul_f32_e32 v212, 0xbfb8aa3b, v48
	v_mul_f32_e32 v232, 0xbfb8aa3b, v51
	v_mul_f32_e32 v222, 0xbfb8aa3b, v49
	v_exp_f32_e32 v222, v222
	v_mul_f32_e32 v223, 0xbfb8aa3b, v54
	v_exp_f32_e32 v223, v223
	v_mul_f32_e32 v224, 0xbfb8aa3b, v50
	v_exp_f32_e32 v224, v224
	v_add_f32_e32 v222, 1.0, v222
	v_rcp_f32_e32 v225, v222
	v_add_f32_e32 v222, 1.0, v223
	v_rcp_f32_e32 v223, v222
	v_add_f32_e32 v222, 1.0, v224
	v_mul_f32_e32 v224, 0xbfb8aa3b, v55
	v_exp_f32_e32 v224, v224
	v_mul_f32_e32 v172, 0xbfb8aa3b, v52
	v_exp_f32_e32 v212, v212
	v_mul_f32_e32 v220, 0xbfb8aa3b, v53
	v_exp_f32_e32 v232, v232
	v_exp_f32_e32 v172, v172
	v_exp_f32_e32 v220, v220
	v_rcp_f32_e32 v233, v222
	v_add_f32_e32 v222, 1.0, v224
	v_add_f32_e32 v212, 1.0, v212
	v_rcp_f32_e32 v224, v222
	v_add_f32_e32 v222, 1.0, v232
	v_add_f32_e32 v172, 1.0, v172
	v_rcp_f32_e32 v212, v212
	v_add_f32_e32 v220, 1.0, v220
	v_rcp_f32_e32 v232, v222
	v_rcp_f32_e32 v172, v172
	v_rcp_f32_e32 v220, v220
	s_mov_b64 s[38:39], 0x90000
	global_store_dwordx4 v[230:231], v[160:163], off
	v_lshl_add_u64 v[230:231], v[194:195], 0, s[38:39]
	s_mov_b32 s38, 0x90000
	v_cvt_pk_bf16_f32 v223, v223, v224
	v_cvt_pk_bf16_f32 v224, v212, v225
	v_cvt_pk_bf16_f32 v225, v233, v232
	v_add_co_u32_e32 v232, vcc, s38, v194
	v_cvt_pk_bf16_f32 v222, v172, v220
	s_nop 0
	v_addc_co_u32_e32 v233, vcc, 0, v195, vcc
	global_store_dwordx4 v[232:233], v[222:225], off
	v_mul_f32_e32 v172, 0xbfb8aa3b, v28
	v_mul_f32_e32 v212, 0xbfb8aa3b, v24
	v_mul_f32_e32 v222, 0xbfb8aa3b, v25
	v_exp_f32_e32 v222, v222
	v_mul_f32_e32 v223, 0xbfb8aa3b, v30
	v_exp_f32_e32 v223, v223
	v_mul_f32_e32 v224, 0xbfb8aa3b, v26
	v_exp_f32_e32 v224, v224
	v_add_f32_e32 v222, 1.0, v222
	v_rcp_f32_e32 v225, v222
	v_add_f32_e32 v222, 1.0, v223
	v_rcp_f32_e32 v223, v222
	v_add_f32_e32 v222, 1.0, v224
	v_mul_f32_e32 v224, 0xbfb8aa3b, v31
	v_mul_f32_e32 v220, 0xbfb8aa3b, v29
	v_exp_f32_e32 v224, v224
	v_mul_f32_e32 v232, 0xbfb8aa3b, v27
	v_exp_f32_e32 v172, v172
	v_exp_f32_e32 v212, v212
	v_exp_f32_e32 v220, v220
	v_exp_f32_e32 v232, v232
	v_rcp_f32_e32 v233, v222
	v_add_f32_e32 v222, 1.0, v224
	v_add_f32_e32 v172, 1.0, v172
	v_add_f32_e32 v212, 1.0, v212
	v_add_f32_e32 v220, 1.0, v220
	v_rcp_f32_e32 v224, v222
	v_add_f32_e32 v222, 1.0, v232
	v_rcp_f32_e32 v172, v172
	v_rcp_f32_e32 v212, v212
	v_rcp_f32_e32 v220, v220
	v_rcp_f32_e32 v232, v222
	v_cvt_pk_bf16_f32 v223, v223, v224
	v_cvt_pk_bf16_f32 v224, v212, v225
	v_cvt_pk_bf16_f32 v222, v172, v220
	v_cvt_pk_bf16_f32 v225, v233, v232
	global_store_dwordx4 v[230:231], v[222:225], off offset:256
	v_mul_f32_e32 v212, 0xbfb8aa3b, v32
	v_mul_f32_e32 v232, 0xbfb8aa3b, v35
	v_mul_f32_e32 v222, 0xbfb8aa3b, v33
	v_exp_f32_e32 v222, v222
	v_mul_f32_e32 v223, 0xbfb8aa3b, v38
; __device__ __forceinline__ float fsigmoid(float v) { return __builtin_amdgcn_rcpf(1.0f + __builtin_amdgcn_exp2f(-LOG2E * v)); }
; __device__ __forceinline__ float fsilu(float v) { return v * fsigmoid(v); }
; __device__ __forceinline__ u32x4 pack8(const f32x4 a, const f32x4 b) { u32x4 w; w.x = cvt_pk_bf16(a[0], a[1]); w.y = cvt_pk_bf16(a[2], a[3]); w.z = cvt_pk_bf16(b[0], b[1]); w.w = cvt_pk_bf16(b[2], b[3]); return w; }
;     template <int ACT> __device__ __forceinline__ void ew(const f32x4 (&acc)[2][2][4][2], bf16_t* D, int ld, int row0, int col0) const {
; #pragma unroll
;         for (int ai = 0; ai < 2; ++ai)
; #pragma unroll
;             for (int m = 0; m < 4; ++m) { bf16_t* rowp = D + (size_t)(row0 + ai * HALF + m * 16) * ld + col0;
; #pragma unroll
;                 for (int bj = 0; bj < 2; ++bj) { f32x4 v0 = acc[ai][bj][m][0], v1 = acc[ai][bj][m][1];
;                     if (ACT == 1) {
; #pragma unroll
;                         for (int j = 0; j < 4; ++j) { v0[j] = fsilu(v0[j]); v1[j] = fsilu(v1[j]); } }
;                     if (ACT == 2) {
; #pragma unroll
;                         for (int j = 0; j < 4; ++j) { v0[j] = fsigmoid(v0[j]); v1[j] = fsigmoid(v1[j]); } }
;                     *(u32x4*)(rowp + bj * HALF) = pack8(v0, v1); } }
	v_exp_f32_e32 v223, v223
	v_mul_f32_e32 v224, 0xbfb8aa3b, v34
	v_exp_f32_e32 v224, v224
	v_add_f32_e32 v222, 1.0, v222
	v_rcp_f32_e32 v225, v222
	v_add_f32_e32 v222, 1.0, v223
	v_rcp_f32_e32 v223, v222
	v_add_f32_e32 v222, 1.0, v224
	v_mul_f32_e32 v224, 0xbfb8aa3b, v39
	v_exp_f32_e32 v224, v224
	v_mul_f32_e32 v172, 0xbfb8aa3b, v36
	v_exp_f32_e32 v212, v212
	v_mul_f32_e32 v220, 0xbfb8aa3b, v37
	v_exp_f32_e32 v232, v232
	v_exp_f32_e32 v172, v172
	v_exp_f32_e32 v220, v220
	v_rcp_f32_e32 v233, v222
	v_add_f32_e32 v222, 1.0, v224
	v_add_f32_e32 v212, 1.0, v212
	v_rcp_f32_e32 v224, v222
	v_add_f32_e32 v222, 1.0, v232
	v_add_f32_e32 v172, 1.0, v172
	v_rcp_f32_e32 v212, v212
	v_add_f32_e32 v220, 1.0, v220
	v_rcp_f32_e32 v232, v222
	v_rcp_f32_e32 v172, v172
	v_rcp_f32_e32 v220, v220
	v_cvt_pk_bf16_f32 v223, v223, v224
	v_cvt_pk_bf16_f32 v224, v212, v225
	v_cvt_pk_bf16_f32 v225, v233, v232
	v_add_co_u32_e32 v232, vcc, s49, v194
	v_cvt_pk_bf16_f32 v222, v172, v220
	s_nop 0
	v_addc_co_u32_e32 v233, vcc, 0, v195, vcc
	global_store_dwordx4 v[232:233], v[222:225], off
	v_mul_f32_e32 v172, 0xbfb8aa3b, v12
	v_mul_f32_e32 v212, 0xbfb8aa3b, v8
	v_mul_f32_e32 v222, 0xbfb8aa3b, v9
	v_exp_f32_e32 v222, v222
	v_mul_f32_e32 v223, 0xbfb8aa3b, v14
	v_exp_f32_e32 v223, v223
	v_mul_f32_e32 v224, 0xbfb8aa3b, v10
	v_exp_f32_e32 v224, v224
	v_add_f32_e32 v222, 1.0, v222
	v_rcp_f32_e32 v225, v222
	v_add_f32_e32 v222, 1.0, v223
	v_rcp_f32_e32 v223, v222
	v_add_f32_e32 v222, 1.0, v224
	v_mul_f32_e32 v224, 0xbfb8aa3b, v15
	v_mul_f32_e32 v220, 0xbfb8aa3b, v13
	v_exp_f32_e32 v224, v224
	v_mul_f32_e32 v232, 0xbfb8aa3b, v11
	v_exp_f32_e32 v172, v172
	v_exp_f32_e32 v212, v212
	v_exp_f32_e32 v220, v220
	v_exp_f32_e32 v232, v232
	v_rcp_f32_e32 v233, v222
	v_add_f32_e32 v222, 1.0, v224
	v_add_f32_e32 v172, 1.0, v172
	v_add_f32_e32 v212, 1.0, v212
	v_add_f32_e32 v220, 1.0, v220
	v_rcp_f32_e32 v224, v222
	v_add_f32_e32 v222, 1.0, v232
	v_rcp_f32_e32 v172, v172
	v_rcp_f32_e32 v212, v212
	v_rcp_f32_e32 v220, v220
	v_rcp_f32_e32 v232, v222
	s_mov_b64 s[38:39], 0xa0000
	v_lshl_add_u64 v[230:231], v[194:195], 0, s[38:39]
	v_cvt_pk_bf16_f32 v222, v172, v220
	v_cvt_pk_bf16_f32 v223, v223, v224
	v_cvt_pk_bf16_f32 v224, v212, v225
	v_cvt_pk_bf16_f32 v225, v233, v232
	global_store_dwordx4 v[230:231], v[222:225], off offset:256
	v_mul_f32_e32 v212, 0xbfb8aa3b, v16
	v_exp_f32_e32 v212, v212
	v_mul_f32_e32 v222, 0xbfb8aa3b, v17
	v_exp_f32_e32 v222, v222
	v_mul_f32_e32 v223, 0xbfb8aa3b, v22
	v_exp_f32_e32 v223, v223
	v_mul_f32_e32 v224, 0xbfb8aa3b, v18
	v_exp_f32_e32 v224, v224
	v_add_f32_e32 v222, 1.0, v222
	v_rcp_f32_e32 v225, v222
	v_add_f32_e32 v222, 1.0, v223
	v_rcp_f32_e32 v223, v222
	v_add_f32_e32 v222, 1.0, v224
	v_mul_f32_e32 v224, 0xbfb8aa3b, v23
	v_exp_f32_e32 v224, v224
	v_mul_f32_e32 v172, 0xbfb8aa3b, v20
	v_mul_f32_e32 v220, 0xbfb8aa3b, v21
	v_mul_f32_e32 v232, 0xbfb8aa3b, v19
	v_exp_f32_e32 v172, v172
	v_exp_f32_e32 v220, v220
	v_exp_f32_e32 v232, v232
	v_add_f32_e32 v212, 1.0, v212
	v_rcp_f32_e32 v233, v222
	v_add_f32_e32 v222, 1.0, v224
	v_rcp_f32_e32 v212, v212
	v_rcp_f32_e32 v224, v222
	v_add_f32_e32 v172, 1.0, v172
	v_add_f32_e32 v220, 1.0, v220
	v_add_f32_e32 v222, 1.0, v232
	v_rcp_f32_e32 v172, v172
	v_rcp_f32_e32 v220, v220
	v_rcp_f32_e32 v232, v222
	v_cvt_pk_bf16_f32 v223, v223, v224
	v_cvt_pk_bf16_f32 v224, v212, v225
	v_mul_f32_e32 v212, 0xbfb8aa3b, v0
	v_lshl_add_u64 v[230:231], v[194:195], 0, s[62:63]
	v_add_co_u32_e32 v194, vcc, s50, v194
	v_exp_f32_e32 v212, v212
	v_cvt_pk_bf16_f32 v222, v172, v220
	v_cvt_pk_bf16_f32 v225, v233, v232
	v_addc_co_u32_e32 v195, vcc, 0, v195, vcc
	global_store_dwordx4 v[194:195], v[222:225], off
	v_mul_f32_e32 v172, 0xbfb8aa3b, v4
	v_add_f32_e32 v194, 1.0, v212
	v_mul_f32_e32 v222, 0xbfb8aa3b, v2
	v_exp_f32_e32 v222, v222
	v_mul_f32_e32 v223, 0xbfb8aa3b, v7
	v_mul_f32_e32 v195, 0xbfb8aa3b, v5
	v_mul_f32_e32 v212, 0xbfb8aa3b, v1
	v_mul_f32_e32 v220, 0xbfb8aa3b, v6
	v_exp_f32_e32 v223, v223
	v_mul_f32_e32 v224, 0xbfb8aa3b, v3
	v_exp_f32_e32 v172, v172
	v_exp_f32_e32 v195, v195
	v_exp_f32_e32 v212, v212
	v_exp_f32_e32 v220, v220
	v_exp_f32_e32 v224, v224
	v_add_f32_e32 v222, 1.0, v222
	v_rcp_f32_e32 v225, v222
	v_add_f32_e32 v222, 1.0, v223
	v_add_f32_e32 v172, 1.0, v172
	v_add_f32_e32 v195, 1.0, v195
	v_add_f32_e32 v212, 1.0, v212
	v_add_f32_e32 v220, 1.0, v220
	v_rcp_f32_e32 v223, v222
	v_add_f32_e32 v222, 1.0, v224
	v_rcp_f32_e32 v172, v172
	v_rcp_f32_e32 v194, v194
	v_rcp_f32_e32 v195, v195
	v_rcp_f32_e32 v212, v212
	v_rcp_f32_e32 v220, v220
	v_rcp_f32_e32 v232, v222
	v_cvt_pk_bf16_f32 v222, v172, v195
	v_cvt_pk_bf16_f32 v224, v194, v212
	v_cvt_pk_bf16_f32 v223, v220, v223
	v_cvt_pk_bf16_f32 v225, v225, v232
	global_store_dwordx4 v[230:231], v[222:225], off offset:256
	s_mov_b64 s[82:83], 0

; #define PG8_STAGE(bufoff, gbase, voff) do { _Pragma("unroll") for (int _i = 0; _i < 2; ++_i) \
;         __builtin_amdgcn_global_load_lds((const unsigned*)((const char*)(gbase) + (voff)[_i]), (PG8_LAS unsigned*)(lds + (bufoff) + ldsw + _i * 8192), 16, 0, 0); } while (0)
; #define PG8_LDA(dst, b, h) do { _Pragma("unroll") for (int m = 0; m < 4; ++m) _Pragma("unroll") for (int k = 0; k < 2; ++k) dst[m][k] = *(const PG8_LAS bf16x8*)(lds + PG8_SA(b, h) + aoff + m * 2048 + k * 1024); } while (0)
; #define PG8_LDB(dst, b, h) do { _Pragma("unroll") for (int n = 0; n < 2; ++n) _Pragma("unroll") for (int k = 0; k < 2; ++k) dst[n][k] = *(const PG8_LAS bf16x8*)(lds + PG8_SB(b, h) + boff + n * 2048 + k * 1024); } while (0)
; #define PG8_WAIT_V(n) asm volatile("s_waitcnt vmcnt(" #n ")" ::: "memory")
; #define PG8_WAIT_L(n) asm volatile("s_waitcnt lgkmcnt(" #n ")" ::: "memory")
; #define PG8_BAR __builtin_amdgcn_s_barrier()
; #define PG8_SCHED __builtin_amdgcn_sched_barrier(0)
; template <class Epi, class Sched, bool ALIGN_EPI = false, bool SP2 = false>
; __device__ __forceinline__ void gemm_phase(PG8_LAS unsigned char* lds, const Gemm g, const Sched& S, const Epi& E) {
;     ...
;         const bool has_next = S.next(ui + 1, nxt);
;         const char* nA = has_next ? (const char*)g.A + (size_t)nxt.pm * tstep : cA; const char* nB = has_next ? (const char*)g.Bt + (size_t)nxt.pn * tstep : cB;
;         for (int t = 0; t < nt; t += 2) {
;             const bool last = (t == nt - 2);
;             const char* a1 = cA + (size_t)(t + 1) * kstep;
;             const char* a2 = last ? nA : cA + (size_t)(t + 2) * kstep; const char* b2 = last ? nB : cB + (size_t)(t + 2) * kstep;
;             const char* a3 = a2 + kstep; const char* b3 = b2 + kstep;
;             if (last && has_next) S.a_ready(nxt);
;             if constexpr (SP2) {
;             PG8_LDB(B0, 0, 0); PG8_LDB(B1, 0, 1); PG8_SCHED; PG8_LDA(At, 0, 0); PG8_STAGE(PG8_SA(1, 1), a1 + hstep, voffA);
;             PG8_WAIT_V(8); PG8_WAIT_L(0); PG8_BAR; PG8_MMA(0, 0, At, B0); PG8_MMA(0, 1, At, B1); PG8_BAR; PG8_SCHED;
;             PG8_LDA(At, 0, 1); PG8_STAGE(PG8_SB(0, 0), b2, voffB); PG8_STAGE(PG8_SB(0, 1), b2 + hstep, voffB); PG8_STAGE(PG8_SA(0, 0), a2, voffA);
;             PG8_WAIT_V(8); PG8_WAIT_L(0); PG8_BAR; PG8_MMA(1, 0, At, B0); PG8_MMA(1, 1, At, B1); PG8_BAR; PG8_SCHED;
.LBB0_734:
	s_ashr_i32 s39, s38, 31
	v_cmp_lt_i64_e32 vcc, s[40:41], v[140:141]
	s_lshl_b64 s[40:41], s[38:39], 19
	s_add_u32 s40, s9, s40
	s_addc_u32 s41, s22, s41
	s_and_b64 s[42:43], vcc, exec
	s_cselect_b32 s39, s41, s47
	s_cselect_b32 s65, s40, s46
	s_ashr_i32 s37, s36, 31
	s_lshl_b64 s[42:43], s[36:37], 19
	s_add_u32 s42, s23, s42
	s_addc_u32 s43, s52, s43
	s_and_b64 s[50:51], vcc, exec
	s_cselect_b32 s37, s43, s49
	s_cselect_b32 s66, s42, s48
	s_add_u32 s46, s46, 0x40080
	s_addc_u32 s47, s47, 0
	s_add_u32 s67, s48, 0x100
	s_addc_u32 s68, s49, 0
	s_mov_b32 s69, -2
	ds_read_b128 v[144:147], v155
	ds_read_b128 v[148:151], v155 offset:1024
	ds_read_b128 v[158:161], v155 offset:2048
	ds_read_b128 v[162:165], v155 offset:3072
	ds_read_b128 v[166:169], v156
	ds_read_b128 v[170:173], v156 offset:1024
	ds_read_b128 v[174:177], v156 offset:2048
	ds_read_b128 v[178:181], v156 offset:3072
	s_add_u32 s48, s46, 0xfffc0080
	s_addc_u32 s49, s47, -1
	s_cmp_eq_u32 s69, 12
	s_cselect_b32 s51, s39, s49
	s_cselect_b32 s50, s65, s48
	s_cselect_b32 s49, s37, s68
	s_cselect_b32 s48, s66, s67
	s_add_i32 m0, s45, 0xc000
	ds_read_b128 v[182:185], v157
	ds_read_b128 v[186:189], v157 offset:1024
	ds_read_b128 v[190:193], v157 offset:2048
	ds_read_b128 v[194:197], v157 offset:3072
	ds_read_b128 v[198:201], v157 offset:4096
	ds_read_b128 v[202:205], v157 offset:5120
	ds_read_b128 v[206:209], v157 offset:6144
	ds_read_b128 v[214:217], v157 offset:7168
	global_load_lds_dwordx4 v136, s[46:47]
	s_add_i32 m0, s45, 0xe000
	s_nop 0
	global_load_lds_dwordx4 v138, s[46:47]
	s_waitcnt vmcnt(8) lgkmcnt(0)
	s_barrier
	v_mfma_f32_16x16x32_bf16 v[124:127], v[144:147], v[182:185], 0
	v_mfma_f32_16x16x32_bf16 v[120:123], v[158:161], v[182:185], 0
	v_mfma_f32_16x16x32_bf16 v[116:119], v[144:147], v[190:193], 0
	v_mfma_f32_16x16x32_bf16 v[112:115], v[158:161], v[190:193], 0
	v_mfma_f32_16x16x32_bf16 v[96:99], v[144:147], v[198:201], 0
	v_mfma_f32_16x16x32_bf16 v[88:91], v[158:161], v[198:201], 0
	v_mfma_f32_16x16x32_bf16 v[80:83], v[144:147], v[206:209], 0
	v_mfma_f32_16x16x32_bf16 v[72:75], v[158:161], v[206:209], 0
	v_mfma_f32_16x16x32_bf16 v[124:127], v[148:151], v[186:189], v[124:127]
	v_mfma_f32_16x16x32_bf16 v[120:123], v[162:165], v[186:189], v[120:123]
	v_mfma_f32_16x16x32_bf16 v[116:119], v[148:151], v[194:197], v[116:119]
	v_mfma_f32_16x16x32_bf16 v[112:115], v[162:165], v[194:197], v[112:115]
	v_mfma_f32_16x16x32_bf16 v[96:99], v[148:151], v[202:205], v[96:99]
	v_mfma_f32_16x16x32_bf16 v[88:91], v[162:165], v[202:205], v[88:91]
	v_mfma_f32_16x16x32_bf16 v[80:83], v[148:151], v[214:217], v[80:83]
	v_mfma_f32_16x16x32_bf16 v[72:75], v[162:165], v[214:217], v[72:75]
	v_mfma_f32_16x16x32_bf16 v[108:111], v[166:169], v[182:185], 0
	v_mfma_f32_16x16x32_bf16 v[104:107], v[174:177], v[182:185], 0
	v_mfma_f32_16x16x32_bf16 v[100:103], v[166:169], v[190:193], 0
	v_mfma_f32_16x16x32_bf16 v[92:95], v[174:177], v[190:193], 0
	v_mfma_f32_16x16x32_bf16 v[84:87], v[166:169], v[198:201], 0
	v_mfma_f32_16x16x32_bf16 v[76:79], v[174:177], v[198:201], 0
	v_mfma_f32_16x16x32_bf16 v[68:71], v[166:169], v[206:209], 0
	v_mfma_f32_16x16x32_bf16 v[64:67], v[174:177], v[206:209], 0
	v_mfma_f32_16x16x32_bf16 v[108:111], v[170:173], v[186:189], v[108:111]
	v_mfma_f32_16x16x32_bf16 v[104:107], v[178:181], v[186:189], v[104:107]
	v_mfma_f32_16x16x32_bf16 v[100:103], v[170:173], v[194:197], v[100:103]
	v_mfma_f32_16x16x32_bf16 v[92:95], v[178:181], v[194:197], v[92:95]
	v_mfma_f32_16x16x32_bf16 v[84:87], v[170:173], v[202:205], v[84:87]
	v_mfma_f32_16x16x32_bf16 v[76:79], v[178:181], v[202:205], v[76:79]
	v_mfma_f32_16x16x32_bf16 v[68:71], v[170:173], v[214:217], v[68:71]
	v_mfma_f32_16x16x32_bf16 v[64:67], v[178:181], v[214:217], v[64:67]
	s_barrier
	s_add_i32 s70, s62, s53
	s_mov_b32 m0, s70
	ds_read_b128 v[182:185], v157 offset:16384
	ds_read_b128 v[186:189], v157 offset:17408
	ds_read_b128 v[190:193], v157 offset:18432
	ds_read_b128 v[194:197], v157 offset:19456
	ds_read_b128 v[198:201], v157 offset:20480
	ds_read_b128 v[202:205], v157 offset:21504
	ds_read_b128 v[206:209], v157 offset:22528
	ds_read_b128 v[214:217], v157 offset:23552
	global_load_lds_dwordx4 v130, s[48:49]
	s_add_i32 m0, s70, 0x2000
	s_add_u32 s70, s48, 0x40000
	s_addc_u32 s71, s49, 0
	s_add_i32 s72, s63, s53
	global_load_lds_dwordx4 v134, s[48:49]
	s_mov_b32 m0, s72
	s_nop 0
	global_load_lds_dwordx4 v130, s[70:71]
	s_add_i32 m0, s72, 0x2000
	s_nop 0
	global_load_lds_dwordx4 v134, s[70:71]
	s_mov_b32 m0, s45
	s_nop 0
	global_load_lds_dwordx4 v128, s[50:51]
	s_mov_b32 m0, s54
	s_nop 0
	global_load_lds_dwordx4 v132, s[50:51]
	s_waitcnt vmcnt(8) lgkmcnt(0)
	s_barrier
; #define PG8_STAGE(bufoff, gbase, voff) do { _Pragma("unroll") for (int _i = 0; _i < 2; ++_i) \
;         __builtin_amdgcn_global_load_lds((const unsigned*)((const char*)(gbase) + (voff)[_i]), (PG8_LAS unsigned*)(lds + (bufoff) + ldsw + _i * 8192), 16, 0, 0); } while (0)
; #define PG8_LDA(dst, b, h) do { _Pragma("unroll") for (int m = 0; m < 4; ++m) _Pragma("unroll") for (int k = 0; k < 2; ++k) dst[m][k] = *(const PG8_LAS bf16x8*)(lds + PG8_SA(b, h) + aoff + m * 2048 + k * 1024); } while (0)
; #define PG8_LDB(dst, b, h) do { _Pragma("unroll") for (int n = 0; n < 2; ++n) _Pragma("unroll") for (int k = 0; k < 2; ++k) dst[n][k] = *(const PG8_LAS bf16x8*)(lds + PG8_SB(b, h) + boff + n * 2048 + k * 1024); } while (0)
; #define PG8_MMA(ai, bj, At, Bt) do { __builtin_amdgcn_s_setprio(1); _Pragma("unroll") for (int m = 0; m < 4; ++m) _Pragma("unroll") for (int n = 0; n < 2; ++n) _Pragma("unroll") for (int k = 0; k < 2; ++k) \
;         acc[ai][bj][m][n] = __builtin_amdgcn_mfma_f32_16x16x32_bf16(Bt[n][k], At[m][k], acc[ai][bj][m][n], 0, 0, 0); __builtin_amdgcn_s_setprio(0); } while (0)
; #define PG8_WAIT_V(n) asm volatile("s_waitcnt vmcnt(" #n ")" ::: "memory")
; #define PG8_WAIT_L(n) asm volatile("s_waitcnt lgkmcnt(" #n ")" ::: "memory")
; #define PG8_BAR __builtin_amdgcn_s_barrier()
; #define PG8_SCHED __builtin_amdgcn_sched_barrier(0)
; template <class Epi, class Sched, bool ALIGN_EPI = false, bool SP2 = false>
; __device__ __forceinline__ void gemm_phase(PG8_LAS unsigned char* lds, const Gemm g, const Sched& S, const Epi& E) {
;     ...
;             PG8_WAIT_V(8); PG8_WAIT_L(0); PG8_BAR; PG8_MMA(0, 0, At, B0); PG8_MMA(0, 1, At, B1); PG8_BAR; PG8_SCHED;
;             PG8_LDA(At, 0, 1); PG8_STAGE(PG8_SB(0, 0), b2, voffB); PG8_STAGE(PG8_SB(0, 1), b2 + hstep, voffB); PG8_STAGE(PG8_SA(0, 0), a2, voffA);
;             PG8_WAIT_V(8); PG8_WAIT_L(0); PG8_BAR; PG8_MMA(1, 0, At, B0); PG8_MMA(1, 1, At, B1); PG8_BAR; PG8_SCHED;
;             PG8_LDB(B0, 1, 0); PG8_LDB(B1, 1, 1); PG8_SCHED; PG8_LDA(At, 1, 0); PG8_STAGE(PG8_SA(0, 1), a2 + hstep, voffA);
;             PG8_WAIT_V(8); PG8_WAIT_L(0); PG8_BAR; PG8_MMA(0, 0, At, B0); PG8_MMA(0, 1, At, B1); PG8_BAR; PG8_SCHED;
	v_mfma_f32_16x16x32_bf16 v[60:63], v[144:147], v[182:185], 0
	v_mfma_f32_16x16x32_bf16 v[56:59], v[158:161], v[182:185], 0
	v_mfma_f32_16x16x32_bf16 v[48:51], v[144:147], v[190:193], 0
	v_mfma_f32_16x16x32_bf16 v[40:43], v[158:161], v[190:193], 0
	v_mfma_f32_16x16x32_bf16 v[32:35], v[144:147], v[198:201], 0
	v_mfma_f32_16x16x32_bf16 v[24:27], v[158:161], v[198:201], 0
	v_mfma_f32_16x16x32_bf16 v[16:19], v[144:147], v[206:209], 0
	v_mfma_f32_16x16x32_bf16 v[8:11], v[158:161], v[206:209], 0
	v_mfma_f32_16x16x32_bf16 v[60:63], v[148:151], v[186:189], v[60:63]
	v_mfma_f32_16x16x32_bf16 v[56:59], v[162:165], v[186:189], v[56:59]
	v_mfma_f32_16x16x32_bf16 v[48:51], v[148:151], v[194:197], v[48:51]
	v_mfma_f32_16x16x32_bf16 v[40:43], v[162:165], v[194:197], v[40:43]
	v_mfma_f32_16x16x32_bf16 v[32:35], v[148:151], v[202:205], v[32:35]
	v_mfma_f32_16x16x32_bf16 v[24:27], v[162:165], v[202:205], v[24:27]
	v_mfma_f32_16x16x32_bf16 v[16:19], v[148:151], v[214:217], v[16:19]
	v_mfma_f32_16x16x32_bf16 v[8:11], v[162:165], v[214:217], v[8:11]
	v_mfma_f32_16x16x32_bf16 v[52:55], v[166:169], v[182:185], 0
	v_mfma_f32_16x16x32_bf16 v[44:47], v[174:177], v[182:185], 0
	v_mfma_f32_16x16x32_bf16 v[36:39], v[166:169], v[190:193], 0
	v_mfma_f32_16x16x32_bf16 v[28:31], v[174:177], v[190:193], 0
	v_mfma_f32_16x16x32_bf16 v[20:23], v[166:169], v[198:201], 0
	v_mfma_f32_16x16x32_bf16 v[12:15], v[174:177], v[198:201], 0
	v_mfma_f32_16x16x32_bf16 v[4:7], v[166:169], v[206:209], 0
	v_mfma_f32_16x16x32_bf16 v[0:3], v[174:177], v[206:209], 0
	v_mfma_f32_16x16x32_bf16 v[52:55], v[170:173], v[186:189], v[52:55]
	v_mfma_f32_16x16x32_bf16 v[44:47], v[178:181], v[186:189], v[44:47]
	v_mfma_f32_16x16x32_bf16 v[36:39], v[170:173], v[194:197], v[36:39]
	v_mfma_f32_16x16x32_bf16 v[28:31], v[178:181], v[194:197], v[28:31]
	v_mfma_f32_16x16x32_bf16 v[20:23], v[170:173], v[202:205], v[20:23]
	v_mfma_f32_16x16x32_bf16 v[12:15], v[178:181], v[202:205], v[12:15]
	v_mfma_f32_16x16x32_bf16 v[4:7], v[170:173], v[214:217], v[4:7]
	v_mfma_f32_16x16x32_bf16 v[0:3], v[178:181], v[214:217], v[0:3]
	s_barrier
	s_add_i32 s70, 0, 0x18000
	s_add_i32 s71, 0, 0x1c000
	v_add_u32_e32 v162, s70, v153
	v_add_u32_e32 v178, s71, v153
	ds_read_b128 v[144:147], v162
	ds_read_b128 v[148:151], v162 offset:1024
	ds_read_b128 v[158:161], v162 offset:2048
	ds_read_b128 v[162:165], v162 offset:3072
	ds_read_b128 v[166:169], v178
	ds_read_b128 v[170:173], v178 offset:1024
	ds_read_b128 v[174:177], v178 offset:2048
	ds_read_b128 v[178:181], v178 offset:3072
	s_add_u32 s80, s50, 0x80
	s_addc_u32 s81, s51, 0
	s_add_u32 s50, s50, 0x40000
	s_addc_u32 s51, s51, 0
	s_mov_b32 m0, s55
	ds_read_b128 v[182:185], v157 offset:32768
	ds_read_b128 v[186:189], v157 offset:33792
	ds_read_b128 v[190:193], v157 offset:34816
	ds_read_b128 v[194:197], v157 offset:35840
	ds_read_b128 v[198:201], v157 offset:36864
	ds_read_b128 v[202:205], v157 offset:37888
	ds_read_b128 v[206:209], v157 offset:38912
	ds_read_b128 v[214:217], v157 offset:39936
	global_load_lds_dwordx4 v128, s[50:51]
	s_mov_b32 m0, s56
	s_nop 0
	global_load_lds_dwordx4 v132, s[50:51]
	s_waitcnt vmcnt(8) lgkmcnt(0)
	s_barrier
	v_mfma_f32_16x16x32_bf16 v[124:127], v[144:147], v[182:185], v[124:127]
	v_mfma_f32_16x16x32_bf16 v[120:123], v[158:161], v[182:185], v[120:123]
	v_mfma_f32_16x16x32_bf16 v[116:119], v[144:147], v[190:193], v[116:119]
	v_mfma_f32_16x16x32_bf16 v[112:115], v[158:161], v[190:193], v[112:115]
	v_mfma_f32_16x16x32_bf16 v[96:99], v[144:147], v[198:201], v[96:99]
	v_mfma_f32_16x16x32_bf16 v[88:91], v[158:161], v[198:201], v[88:91]
	v_mfma_f32_16x16x32_bf16 v[80:83], v[144:147], v[206:209], v[80:83]
	v_mfma_f32_16x16x32_bf16 v[72:75], v[158:161], v[206:209], v[72:75]
	v_mfma_f32_16x16x32_bf16 v[124:127], v[148:151], v[186:189], v[124:127]
	v_mfma_f32_16x16x32_bf16 v[120:123], v[162:165], v[186:189], v[120:123]
	v_mfma_f32_16x16x32_bf16 v[116:119], v[148:151], v[194:197], v[116:119]
	v_mfma_f32_16x16x32_bf16 v[112:115], v[162:165], v[194:197], v[112:115]
	v_mfma_f32_16x16x32_bf16 v[96:99], v[148:151], v[202:205], v[96:99]
	v_mfma_f32_16x16x32_bf16 v[88:91], v[162:165], v[202:205], v[88:91]
	v_mfma_f32_16x16x32_bf16 v[80:83], v[148:151], v[214:217], v[80:83]
	v_mfma_f32_16x16x32_bf16 v[72:75], v[162:165], v[214:217], v[72:75]
	v_mfma_f32_16x16x32_bf16 v[108:111], v[166:169], v[182:185], v[108:111]
	v_mfma_f32_16x16x32_bf16 v[104:107], v[174:177], v[182:185], v[104:107]
	v_mfma_f32_16x16x32_bf16 v[100:103], v[166:169], v[190:193], v[100:103]
	v_mfma_f32_16x16x32_bf16 v[92:95], v[174:177], v[190:193], v[92:95]
	v_mfma_f32_16x16x32_bf16 v[84:87], v[166:169], v[198:201], v[84:87]
	v_mfma_f32_16x16x32_bf16 v[76:79], v[174:177], v[198:201], v[76:79]
	v_mfma_f32_16x16x32_bf16 v[68:71], v[166:169], v[206:209], v[68:71]
	v_mfma_f32_16x16x32_bf16 v[64:67], v[174:177], v[206:209], v[64:67]
	v_mfma_f32_16x16x32_bf16 v[108:111], v[170:173], v[186:189], v[108:111]
	v_mfma_f32_16x16x32_bf16 v[104:107], v[178:181], v[186:189], v[104:107]
	v_mfma_f32_16x16x32_bf16 v[100:103], v[170:173], v[194:197], v[100:103]
	v_mfma_f32_16x16x32_bf16 v[92:95], v[178:181], v[194:197], v[92:95]
	v_mfma_f32_16x16x32_bf16 v[84:87], v[170:173], v[202:205], v[84:87]
	v_mfma_f32_16x16x32_bf16 v[76:79], v[178:181], v[202:205], v[76:79]
	v_mfma_f32_16x16x32_bf16 v[68:71], v[170:173], v[214:217], v[68:71]
	v_mfma_f32_16x16x32_bf16 v[64:67], v[178:181], v[214:217], v[64:67]
	s_barrier
; #define PG8_STAGE(bufoff, gbase, voff) do { _Pragma("unroll") for (int _i = 0; _i < 2; ++_i) \
;         __builtin_amdgcn_global_load_lds((const unsigned*)((const char*)(gbase) + (voff)[_i]), (PG8_LAS unsigned*)(lds + (bufoff) + ldsw + _i * 8192), 16, 0, 0); } while (0)
; #define PG8_LDA(dst, b, h) do { _Pragma("unroll") for (int m = 0; m < 4; ++m) _Pragma("unroll") for (int k = 0; k < 2; ++k) dst[m][k] = *(const PG8_LAS bf16x8*)(lds + PG8_SA(b, h) + aoff + m * 2048 + k * 1024); } while (0)
; #define PG8_LDB(dst, b, h) do { _Pragma("unroll") for (int n = 0; n < 2; ++n) _Pragma("unroll") for (int k = 0; k < 2; ++k) dst[n][k] = *(const PG8_LAS bf16x8*)(lds + PG8_SB(b, h) + boff + n * 2048 + k * 1024); } while (0)
; #define PG8_MMA(ai, bj, At, Bt) do { __builtin_amdgcn_s_setprio(1); _Pragma("unroll") for (int m = 0; m < 4; ++m) _Pragma("unroll") for (int n = 0; n < 2; ++n) _Pragma("unroll") for (int k = 0; k < 2; ++k) \
;         acc[ai][bj][m][n] = __builtin_amdgcn_mfma_f32_16x16x32_bf16(Bt[n][k], At[m][k], acc[ai][bj][m][n], 0, 0, 0); __builtin_amdgcn_s_setprio(0); } while (0)
; #define PG8_WAIT_V(n) asm volatile("s_waitcnt vmcnt(" #n ")" ::: "memory")
; #define PG8_WAIT_L(n) asm volatile("s_waitcnt lgkmcnt(" #n ")" ::: "memory")
; #define PG8_BAR __builtin_amdgcn_s_barrier()
; #define PG8_SCHED __builtin_amdgcn_sched_barrier(0)
; template <class Epi, class Sched, bool ALIGN_EPI = false, bool SP2 = false>
; __device__ __forceinline__ void gemm_phase(PG8_LAS unsigned char* lds, const Gemm g, const Sched& S, const Epi& E) {
;     ...
;             PG8_WAIT_V(8); PG8_WAIT_L(0); PG8_BAR; PG8_MMA(1, 0, At, B0); PG8_MMA(1, 1, At, B1); PG8_BAR; PG8_SCHED;
;             PG8_LDB(B0, 1, 0); PG8_LDB(B1, 1, 1); PG8_SCHED; PG8_LDA(At, 1, 0); PG8_STAGE(PG8_SA(0, 1), a2 + hstep, voffA);
;             PG8_WAIT_V(8); PG8_WAIT_L(0); PG8_BAR; PG8_MMA(0, 0, At, B0); PG8_MMA(0, 1, At, B1); PG8_BAR; PG8_SCHED;
;             PG8_LDA(At, 1, 1); PG8_STAGE(PG8_SB(1, 0), b3, voffB); PG8_STAGE(PG8_SB(1, 1), b3 + hstep, voffB); PG8_STAGE(PG8_SA(1, 0), a3, voffA);
;             PG8_WAIT_V(8); PG8_WAIT_L(0); PG8_BAR; PG8_MMA(1, 0, At, B0); PG8_MMA(1, 1, At, B1); PG8_BAR; PG8_SCHED;
	s_add_i32 s50, s70, s53
	s_add_u32 s82, s48, 0x80
	s_addc_u32 s83, s49, 0
	s_mov_b32 m0, s50
	ds_read_b128 v[182:185], v157 offset:49152
	ds_read_b128 v[186:189], v157 offset:50176
	ds_read_b128 v[190:193], v157 offset:51200
	ds_read_b128 v[194:197], v157 offset:52224
	ds_read_b128 v[198:201], v157 offset:53248
	ds_read_b128 v[202:205], v157 offset:54272
	ds_read_b128 v[206:209], v157 offset:55296
	ds_read_b128 v[214:217], v157 offset:56320
	global_load_lds_dwordx4 v130, s[82:83]
	s_add_i32 m0, s50, 0x2000
	s_add_u32 s48, s48, 0x40080
	s_addc_u32 s49, s49, 0
	s_add_i32 s50, s71, s53
	global_load_lds_dwordx4 v134, s[82:83]
	s_mov_b32 m0, s50
	s_nop 0
	global_load_lds_dwordx4 v130, s[48:49]
	s_add_i32 m0, s50, 0x2000
	s_nop 0
	global_load_lds_dwordx4 v134, s[48:49]
	s_mov_b32 m0, s58
	s_nop 0
	global_load_lds_dwordx4 v128, s[80:81]
	s_mov_b32 m0, s59
	s_nop 0
	global_load_lds_dwordx4 v132, s[80:81]
	s_waitcnt vmcnt(8) lgkmcnt(0)
	s_barrier
	v_mfma_f32_16x16x32_bf16 v[60:63], v[144:147], v[182:185], v[60:63]
	v_mfma_f32_16x16x32_bf16 v[56:59], v[158:161], v[182:185], v[56:59]
	v_mfma_f32_16x16x32_bf16 v[48:51], v[144:147], v[190:193], v[48:51]
	v_mfma_f32_16x16x32_bf16 v[40:43], v[158:161], v[190:193], v[40:43]
	v_mfma_f32_16x16x32_bf16 v[32:35], v[144:147], v[198:201], v[32:35]
	v_mfma_f32_16x16x32_bf16 v[24:27], v[158:161], v[198:201], v[24:27]
	v_mfma_f32_16x16x32_bf16 v[16:19], v[144:147], v[206:209], v[16:19]
	v_mfma_f32_16x16x32_bf16 v[8:11], v[158:161], v[206:209], v[8:11]
	v_mfma_f32_16x16x32_bf16 v[60:63], v[148:151], v[186:189], v[60:63]
	v_mfma_f32_16x16x32_bf16 v[56:59], v[162:165], v[186:189], v[56:59]
	v_mfma_f32_16x16x32_bf16 v[48:51], v[148:151], v[194:197], v[48:51]
	v_mfma_f32_16x16x32_bf16 v[40:43], v[162:165], v[194:197], v[40:43]
	v_mfma_f32_16x16x32_bf16 v[32:35], v[148:151], v[202:205], v[32:35]
	v_mfma_f32_16x16x32_bf16 v[24:27], v[162:165], v[202:205], v[24:27]
	v_mfma_f32_16x16x32_bf16 v[16:19], v[148:151], v[214:217], v[16:19]
	v_mfma_f32_16x16x32_bf16 v[8:11], v[162:165], v[214:217], v[8:11]
	v_mfma_f32_16x16x32_bf16 v[52:55], v[166:169], v[182:185], v[52:55]
	v_mfma_f32_16x16x32_bf16 v[44:47], v[174:177], v[182:185], v[44:47]
	v_mfma_f32_16x16x32_bf16 v[36:39], v[166:169], v[190:193], v[36:39]
	v_mfma_f32_16x16x32_bf16 v[28:31], v[174:177], v[190:193], v[28:31]
	v_mfma_f32_16x16x32_bf16 v[20:23], v[166:169], v[198:201], v[20:23]
	v_mfma_f32_16x16x32_bf16 v[12:15], v[174:177], v[198:201], v[12:15]
	v_mfma_f32_16x16x32_bf16 v[4:7], v[166:169], v[206:209], v[4:7]
	v_mfma_f32_16x16x32_bf16 v[0:3], v[174:177], v[206:209], v[0:3]
	v_mfma_f32_16x16x32_bf16 v[52:55], v[170:173], v[186:189], v[52:55]
	v_mfma_f32_16x16x32_bf16 v[44:47], v[178:181], v[186:189], v[44:47]
	v_mfma_f32_16x16x32_bf16 v[36:39], v[170:173], v[194:197], v[36:39]
	v_mfma_f32_16x16x32_bf16 v[28:31], v[178:181], v[194:197], v[28:31]
	v_mfma_f32_16x16x32_bf16 v[20:23], v[170:173], v[202:205], v[20:23]
	v_mfma_f32_16x16x32_bf16 v[12:15], v[178:181], v[202:205], v[12:15]
	v_mfma_f32_16x16x32_bf16 v[4:7], v[170:173], v[214:217], v[4:7]
	v_mfma_f32_16x16x32_bf16 v[0:3], v[178:181], v[214:217], v[0:3]
	s_barrier
	s_add_i32 s69, s69, 2
	s_add_u32 s46, s46, 0x100
	s_addc_u32 s47, s47, 0
	s_add_u32 s67, s67, 0x100
	s_addc_u32 s68, s68, 0
	s_cmp_gt_u32 s69, 13
.LBB0_735:
	ds_read_b128 v[144:147], v155
	ds_read_b128 v[148:151], v155 offset:1024
	ds_read_b128 v[158:161], v155 offset:2048
	ds_read_b128 v[162:165], v155 offset:3072
	ds_read_b128 v[166:169], v156
	ds_read_b128 v[170:173], v156 offset:1024
	ds_read_b128 v[174:177], v156 offset:2048
	ds_read_b128 v[178:181], v156 offset:3072
	s_add_u32 s48, s46, 0xfffc0080
	s_addc_u32 s49, s47, -1
	s_cmp_eq_u32 s69, 12
	s_cselect_b32 s51, s39, s49
	s_cselect_b32 s50, s65, s48
	s_cselect_b32 s49, s37, s68
	s_cselect_b32 s48, s66, s67
	s_add_i32 m0, s45, 0xc000
	ds_read_b128 v[182:185], v157
	ds_read_b128 v[186:189], v157 offset:1024
	ds_read_b128 v[190:193], v157 offset:2048
	ds_read_b128 v[194:197], v157 offset:3072
	ds_read_b128 v[198:201], v157 offset:4096
	ds_read_b128 v[202:205], v157 offset:5120
	ds_read_b128 v[206:209], v157 offset:6144
	ds_read_b128 v[214:217], v157 offset:7168
	global_load_lds_dwordx4 v136, s[46:47]
	s_add_i32 m0, s45, 0xe000
	s_nop 0
	global_load_lds_dwordx4 v138, s[46:47]
	s_waitcnt vmcnt(8) lgkmcnt(0)
	s_barrier
	v_mfma_f32_16x16x32_bf16 v[124:127], v[144:147], v[182:185], v[124:127]
	v_mfma_f32_16x16x32_bf16 v[120:123], v[158:161], v[182:185], v[120:123]
	v_mfma_f32_16x16x32_bf16 v[116:119], v[144:147], v[190:193], v[116:119]
	v_mfma_f32_16x16x32_bf16 v[112:115], v[158:161], v[190:193], v[112:115]
	v_mfma_f32_16x16x32_bf16 v[96:99], v[144:147], v[198:201], v[96:99]
	v_mfma_f32_16x16x32_bf16 v[88:91], v[158:161], v[198:201], v[88:91]
	v_mfma_f32_16x16x32_bf16 v[80:83], v[144:147], v[206:209], v[80:83]
	v_mfma_f32_16x16x32_bf16 v[72:75], v[158:161], v[206:209], v[72:75]
	v_mfma_f32_16x16x32_bf16 v[124:127], v[148:151], v[186:189], v[124:127]
	v_mfma_f32_16x16x32_bf16 v[120:123], v[162:165], v[186:189], v[120:123]
	v_mfma_f32_16x16x32_bf16 v[116:119], v[148:151], v[194:197], v[116:119]
	v_mfma_f32_16x16x32_bf16 v[112:115], v[162:165], v[194:197], v[112:115]
	v_mfma_f32_16x16x32_bf16 v[96:99], v[148:151], v[202:205], v[96:99]
	v_mfma_f32_16x16x32_bf16 v[88:91], v[162:165], v[202:205], v[88:91]
	v_mfma_f32_16x16x32_bf16 v[80:83], v[148:151], v[214:217], v[80:83]
	v_mfma_f32_16x16x32_bf16 v[72:75], v[162:165], v[214:217], v[72:75]
	v_mfma_f32_16x16x32_bf16 v[108:111], v[166:169], v[182:185], v[108:111]
	v_mfma_f32_16x16x32_bf16 v[104:107], v[174:177], v[182:185], v[104:107]
	v_mfma_f32_16x16x32_bf16 v[100:103], v[166:169], v[190:193], v[100:103]
	v_mfma_f32_16x16x32_bf16 v[92:95], v[174:177], v[190:193], v[92:95]
	v_mfma_f32_16x16x32_bf16 v[84:87], v[166:169], v[198:201], v[84:87]
	v_mfma_f32_16x16x32_bf16 v[76:79], v[174:177], v[198:201], v[76:79]
	v_mfma_f32_16x16x32_bf16 v[68:71], v[166:169], v[206:209], v[68:71]
	v_mfma_f32_16x16x32_bf16 v[64:67], v[174:177], v[206:209], v[64:67]
	v_mfma_f32_16x16x32_bf16 v[108:111], v[170:173], v[186:189], v[108:111]
	v_mfma_f32_16x16x32_bf16 v[104:107], v[178:181], v[186:189], v[104:107]
	v_mfma_f32_16x16x32_bf16 v[100:103], v[170:173], v[194:197], v[100:103]
	v_mfma_f32_16x16x32_bf16 v[92:95], v[178:181], v[194:197], v[92:95]
	v_mfma_f32_16x16x32_bf16 v[84:87], v[170:173], v[202:205], v[84:87]
	v_mfma_f32_16x16x32_bf16 v[76:79], v[178:181], v[202:205], v[76:79]
	v_mfma_f32_16x16x32_bf16 v[68:71], v[170:173], v[214:217], v[68:71]
	v_mfma_f32_16x16x32_bf16 v[64:67], v[178:181], v[214:217], v[64:67]
	s_barrier
; #define PG8_STAGE(bufoff, gbase, voff) do { _Pragma("unroll") for (int _i = 0; _i < 2; ++_i) \
;         __builtin_amdgcn_global_load_lds((const unsigned*)((const char*)(gbase) + (voff)[_i]), (PG8_LAS unsigned*)(lds + (bufoff) + ldsw + _i * 8192), 16, 0, 0); } while (0)
; #define PG8_LDA(dst, b, h) do { _Pragma("unroll") for (int m = 0; m < 4; ++m) _Pragma("unroll") for (int k = 0; k < 2; ++k) dst[m][k] = *(const PG8_LAS bf16x8*)(lds + PG8_SA(b, h) + aoff + m * 2048 + k * 1024); } while (0)
; #define PG8_LDB(dst, b, h) do { _Pragma("unroll") for (int n = 0; n < 2; ++n) _Pragma("unroll") for (int k = 0; k < 2; ++k) dst[n][k] = *(const PG8_LAS bf16x8*)(lds + PG8_SB(b, h) + boff + n * 2048 + k * 1024); } while (0)
; #define PG8_MMA(ai, bj, At, Bt) do { __builtin_amdgcn_s_setprio(1); _Pragma("unroll") for (int m = 0; m < 4; ++m) _Pragma("unroll") for (int n = 0; n < 2; ++n) _Pragma("unroll") for (int k = 0; k < 2; ++k) \
;         acc[ai][bj][m][n] = __builtin_amdgcn_mfma_f32_16x16x32_bf16(Bt[n][k], At[m][k], acc[ai][bj][m][n], 0, 0, 0); __builtin_amdgcn_s_setprio(0); } while (0)
; #define PG8_WAIT_V(n) asm volatile("s_waitcnt vmcnt(" #n ")" ::: "memory")
; #define PG8_WAIT_L(n) asm volatile("s_waitcnt lgkmcnt(" #n ")" ::: "memory")
; #define PG8_BAR __builtin_amdgcn_s_barrier()
; #define PG8_SCHED __builtin_amdgcn_sched_barrier(0)
; template <class Epi, class Sched, bool ALIGN_EPI = false, bool SP2 = false>
; __device__ __forceinline__ void gemm_phase(PG8_LAS unsigned char* lds, const Gemm g, const Sched& S, const Epi& E) {
;     ...
;             PG8_LDA(At, 0, 1); PG8_STAGE(PG8_SB(0, 0), b2, voffB); PG8_STAGE(PG8_SB(0, 1), b2 + hstep, voffB); PG8_STAGE(PG8_SA(0, 0), a2, voffA);
;             PG8_WAIT_V(8); PG8_WAIT_L(0); PG8_BAR; PG8_MMA(1, 0, At, B0); PG8_MMA(1, 1, At, B1); PG8_BAR; PG8_SCHED;
;             PG8_LDB(B0, 1, 0); PG8_LDB(B1, 1, 1); PG8_SCHED; PG8_LDA(At, 1, 0); PG8_STAGE(PG8_SA(0, 1), a2 + hstep, voffA);
;             PG8_WAIT_V(8); PG8_WAIT_L(0); PG8_BAR; PG8_MMA(0, 0, At, B0); PG8_MMA(0, 1, At, B1); PG8_BAR; PG8_SCHED;
	s_add_i32 s70, s62, s53
	s_mov_b32 m0, s70
	ds_read_b128 v[182:185], v157 offset:16384
	ds_read_b128 v[186:189], v157 offset:17408
	ds_read_b128 v[190:193], v157 offset:18432
	ds_read_b128 v[194:197], v157 offset:19456
	ds_read_b128 v[198:201], v157 offset:20480
	ds_read_b128 v[202:205], v157 offset:21504
	ds_read_b128 v[206:209], v157 offset:22528
	ds_read_b128 v[214:217], v157 offset:23552
	global_load_lds_dwordx4 v130, s[48:49]
	s_add_i32 m0, s70, 0x2000
	s_add_u32 s70, s48, 0x40000
	s_addc_u32 s71, s49, 0
	s_add_i32 s72, s63, s53
	global_load_lds_dwordx4 v134, s[48:49]
	s_mov_b32 m0, s72
	s_nop 0
	global_load_lds_dwordx4 v130, s[70:71]
	s_add_i32 m0, s72, 0x2000
	s_nop 0
	global_load_lds_dwordx4 v134, s[70:71]
	s_mov_b32 m0, s45
	s_nop 0
	global_load_lds_dwordx4 v128, s[50:51]
	s_mov_b32 m0, s54
	s_nop 0
	global_load_lds_dwordx4 v132, s[50:51]
	s_waitcnt vmcnt(8) lgkmcnt(0)
	s_barrier
	v_mfma_f32_16x16x32_bf16 v[60:63], v[144:147], v[182:185], v[60:63]
	v_mfma_f32_16x16x32_bf16 v[56:59], v[158:161], v[182:185], v[56:59]
	v_mfma_f32_16x16x32_bf16 v[48:51], v[144:147], v[190:193], v[48:51]
	v_mfma_f32_16x16x32_bf16 v[40:43], v[158:161], v[190:193], v[40:43]
	v_mfma_f32_16x16x32_bf16 v[32:35], v[144:147], v[198:201], v[32:35]
	v_mfma_f32_16x16x32_bf16 v[24:27], v[158:161], v[198:201], v[24:27]
	v_mfma_f32_16x16x32_bf16 v[16:19], v[144:147], v[206:209], v[16:19]
	v_mfma_f32_16x16x32_bf16 v[8:11], v[158:161], v[206:209], v[8:11]
	v_mfma_f32_16x16x32_bf16 v[60:63], v[148:151], v[186:189], v[60:63]
	v_mfma_f32_16x16x32_bf16 v[56:59], v[162:165], v[186:189], v[56:59]
	v_mfma_f32_16x16x32_bf16 v[48:51], v[148:151], v[194:197], v[48:51]
	v_mfma_f32_16x16x32_bf16 v[40:43], v[162:165], v[194:197], v[40:43]
	v_mfma_f32_16x16x32_bf16 v[32:35], v[148:151], v[202:205], v[32:35]
	v_mfma_f32_16x16x32_bf16 v[24:27], v[162:165], v[202:205], v[24:27]
	v_mfma_f32_16x16x32_bf16 v[16:19], v[148:151], v[214:217], v[16:19]
	v_mfma_f32_16x16x32_bf16 v[8:11], v[162:165], v[214:217], v[8:11]
	v_mfma_f32_16x16x32_bf16 v[52:55], v[166:169], v[182:185], v[52:55]
	v_mfma_f32_16x16x32_bf16 v[44:47], v[174:177], v[182:185], v[44:47]
	v_mfma_f32_16x16x32_bf16 v[36:39], v[166:169], v[190:193], v[36:39]
	v_mfma_f32_16x16x32_bf16 v[28:31], v[174:177], v[190:193], v[28:31]
	v_mfma_f32_16x16x32_bf16 v[20:23], v[166:169], v[198:201], v[20:23]
	v_mfma_f32_16x16x32_bf16 v[12:15], v[174:177], v[198:201], v[12:15]
	v_mfma_f32_16x16x32_bf16 v[4:7], v[166:169], v[206:209], v[4:7]
	v_mfma_f32_16x16x32_bf16 v[0:3], v[174:177], v[206:209], v[0:3]
	v_mfma_f32_16x16x32_bf16 v[52:55], v[170:173], v[186:189], v[52:55]
	v_mfma_f32_16x16x32_bf16 v[44:47], v[178:181], v[186:189], v[44:47]
	v_mfma_f32_16x16x32_bf16 v[36:39], v[170:173], v[194:197], v[36:39]
	v_mfma_f32_16x16x32_bf16 v[28:31], v[178:181], v[194:197], v[28:31]
	v_mfma_f32_16x16x32_bf16 v[20:23], v[170:173], v[202:205], v[20:23]
	v_mfma_f32_16x16x32_bf16 v[12:15], v[178:181], v[202:205], v[12:15]
	v_mfma_f32_16x16x32_bf16 v[4:7], v[170:173], v[214:217], v[4:7]
	v_mfma_f32_16x16x32_bf16 v[0:3], v[178:181], v[214:217], v[0:3]
	s_barrier
	s_add_i32 s70, 0, 0x18000
	s_add_i32 s71, 0, 0x1c000
	v_add_u32_e32 v162, s70, v153
	v_add_u32_e32 v178, s71, v153
	ds_read_b128 v[144:147], v162
	ds_read_b128 v[148:151], v162 offset:1024
	ds_read_b128 v[158:161], v162 offset:2048
	ds_read_b128 v[162:165], v162 offset:3072
	ds_read_b128 v[166:169], v178
	ds_read_b128 v[170:173], v178 offset:1024
	ds_read_b128 v[174:177], v178 offset:2048
	ds_read_b128 v[178:181], v178 offset:3072
	s_add_u32 s80, s50, 0x80
	s_addc_u32 s81, s51, 0
	s_add_u32 s50, s50, 0x40000
	s_addc_u32 s51, s51, 0
	s_mov_b32 m0, s55
	ds_read_b128 v[182:185], v157 offset:32768
	ds_read_b128 v[186:189], v157 offset:33792
	ds_read_b128 v[190:193], v157 offset:34816
	ds_read_b128 v[194:197], v157 offset:35840
	ds_read_b128 v[198:201], v157 offset:36864
	ds_read_b128 v[202:205], v157 offset:37888
	ds_read_b128 v[206:209], v157 offset:38912
	ds_read_b128 v[214:217], v157 offset:39936
	global_load_lds_dwordx4 v128, s[50:51]
	s_mov_b32 m0, s56
	s_nop 0
	global_load_lds_dwordx4 v132, s[50:51]
	s_waitcnt vmcnt(8) lgkmcnt(0)
	s_barrier
	v_mfma_f32_16x16x32_bf16 v[124:127], v[144:147], v[182:185], v[124:127]
	v_mfma_f32_16x16x32_bf16 v[120:123], v[158:161], v[182:185], v[120:123]
	v_mfma_f32_16x16x32_bf16 v[116:119], v[144:147], v[190:193], v[116:119]
	v_mfma_f32_16x16x32_bf16 v[112:115], v[158:161], v[190:193], v[112:115]
	v_mfma_f32_16x16x32_bf16 v[96:99], v[144:147], v[198:201], v[96:99]
	v_mfma_f32_16x16x32_bf16 v[88:91], v[158:161], v[198:201], v[88:91]
	v_mfma_f32_16x16x32_bf16 v[80:83], v[144:147], v[206:209], v[80:83]
	v_mfma_f32_16x16x32_bf16 v[72:75], v[158:161], v[206:209], v[72:75]
	v_mfma_f32_16x16x32_bf16 v[124:127], v[148:151], v[186:189], v[124:127]
	v_mfma_f32_16x16x32_bf16 v[120:123], v[162:165], v[186:189], v[120:123]
	v_mfma_f32_16x16x32_bf16 v[116:119], v[148:151], v[194:197], v[116:119]
	v_mfma_f32_16x16x32_bf16 v[112:115], v[162:165], v[194:197], v[112:115]
	v_mfma_f32_16x16x32_bf16 v[96:99], v[148:151], v[202:205], v[96:99]
	v_mfma_f32_16x16x32_bf16 v[88:91], v[162:165], v[202:205], v[88:91]
	v_mfma_f32_16x16x32_bf16 v[80:83], v[148:151], v[214:217], v[80:83]
	v_mfma_f32_16x16x32_bf16 v[72:75], v[162:165], v[214:217], v[72:75]
	v_mfma_f32_16x16x32_bf16 v[108:111], v[166:169], v[182:185], v[108:111]
	v_mfma_f32_16x16x32_bf16 v[104:107], v[174:177], v[182:185], v[104:107]
	v_mfma_f32_16x16x32_bf16 v[100:103], v[166:169], v[190:193], v[100:103]
	v_mfma_f32_16x16x32_bf16 v[92:95], v[174:177], v[190:193], v[92:95]
	v_mfma_f32_16x16x32_bf16 v[84:87], v[166:169], v[198:201], v[84:87]
	v_mfma_f32_16x16x32_bf16 v[76:79], v[174:177], v[198:201], v[76:79]
	v_mfma_f32_16x16x32_bf16 v[68:71], v[166:169], v[206:209], v[68:71]
	v_mfma_f32_16x16x32_bf16 v[64:67], v[174:177], v[206:209], v[64:67]
	v_mfma_f32_16x16x32_bf16 v[108:111], v[170:173], v[186:189], v[108:111]
	v_mfma_f32_16x16x32_bf16 v[104:107], v[178:181], v[186:189], v[104:107]
	v_mfma_f32_16x16x32_bf16 v[100:103], v[170:173], v[194:197], v[100:103]
	v_mfma_f32_16x16x32_bf16 v[92:95], v[178:181], v[194:197], v[92:95]
	v_mfma_f32_16x16x32_bf16 v[84:87], v[170:173], v[202:205], v[84:87]
	v_mfma_f32_16x16x32_bf16 v[76:79], v[178:181], v[202:205], v[76:79]
	v_mfma_f32_16x16x32_bf16 v[68:71], v[170:173], v[214:217], v[68:71]
	v_mfma_f32_16x16x32_bf16 v[64:67], v[178:181], v[214:217], v[64:67]
	s_barrier
; __device__ __forceinline__ float bf_lo(unsigned w) { return __uint_as_float(w << 16); }
; __device__ __forceinline__ float bf_hi(unsigned w) { return __uint_as_float(w & 0xffff0000u); }
; __device__ __forceinline__ u32x4 pack8(const f32x4 a, const f32x4 b) { u32x4 w; w.x = cvt_pk_bf16(a[0], a[1]); w.y = cvt_pk_bf16(a[2], a[3]); w.z = cvt_pk_bf16(b[0], b[1]); w.w = cvt_pk_bf16(b[2], b[3]); return w; }
; #define PG8_WAIT_V(n) asm volatile("s_waitcnt vmcnt(" #n ")" ::: "memory")
; #define PG8_WAIT_L(n) asm volatile("s_waitcnt lgkmcnt(" #n ")" ::: "memory")
;     __device__ __forceinline__ void operator()(const f32x4 (&acc)[2][2][4][2], const Unit& u, int wr, int wc, int fr, int fq) const {
;         const int row0 = u.pm * BM + wr * 64 + fr, col0 = u.pn * BM + wc * 32 + 8 * fq;
; #pragma unroll
;         for (int ai = 0; ai < 2; ++ai) { u32x4 gw[4][2], pw[4][2];
; #pragma unroll
;             for (int m = 0; m < 4; ++m) { const size_t off = (size_t)(row0 + ai * HALF + m * 16) * 2048 + col0;
; #pragma unroll
;                 for (int bj = 0; bj < 2; ++bj) { gw[m][bj] = *(const u32x4*)(G + off + bj * HALF); if (PASS == 1) pw[m][bj] = *(const u32x4*)(MIX + off + bj * HALF); } }
; #pragma unroll
;             for (int m = 0; m < 4; ++m) { const size_t off = (size_t)(row0 + ai * HALF + m * 16) * 2048 + col0;
; #pragma unroll
;                 for (int bj = 0; bj < 2; ++bj) { const u32x4 g4 = gw[m][bj];
;                     f32x4 v0 = (f32x4){bf_lo(g4.x), bf_hi(g4.x), bf_lo(g4.y), bf_hi(g4.y)} * acc[ai][bj][m][0], v1 = (f32x4){bf_lo(g4.z), bf_hi(g4.z), bf_lo(g4.w), bf_hi(g4.w)} * acc[ai][bj][m][1];
;                     if (PASS == 1) { const u32x4 p4 = pw[m][bj]; v0 += (f32x4){bf_lo(p4.x), bf_hi(p4.x), bf_lo(p4.y), bf_hi(p4.y)}; v1 += (f32x4){bf_lo(p4.z), bf_hi(p4.z), bf_lo(p4.w), bf_hi(p4.w)}; }
;                     *(u32x4*)(MIX + off + bj * HALF) = pack8(v0, v1); } } }
; template <class Epi, class Sched, bool ALIGN_EPI = false, bool SP2 = false>
; __device__ __forceinline__ void gemm_phase(PG8_LAS unsigned char* lds, const Gemm g, const Sched& S, const Epi& E) {
;     ...
;             PG8_LDA(At, 1, 1); PG8_STAGE(PG8_SB(1, 0), b3, voffB); PG8_STAGE(PG8_SB(1, 1), b3 + hstep, voffB); PG8_STAGE(PG8_SA(1, 0), a3, voffA);
;             PG8_WAIT_V(8); PG8_WAIT_L(0); PG8_BAR; PG8_MMA(1, 0, At, B0); PG8_MMA(1, 1, At, B1); PG8_BAR; PG8_SCHED;
	s_add_i32 s50, s70, s53
	s_add_u32 s82, s48, 0x80
	s_addc_u32 s83, s49, 0
	s_mov_b32 m0, s50
	ds_read_b128 v[182:185], v157 offset:49152
	ds_read_b128 v[186:189], v157 offset:50176
	ds_read_b128 v[190:193], v157 offset:51200
	ds_read_b128 v[194:197], v157 offset:52224
	ds_read_b128 v[198:201], v157 offset:53248
	ds_read_b128 v[202:205], v157 offset:54272
	ds_read_b128 v[206:209], v157 offset:55296
	ds_read_b128 v[214:217], v157 offset:56320
	global_load_lds_dwordx4 v130, s[82:83]
	s_add_i32 m0, s50, 0x2000
	s_add_u32 s48, s48, 0x40080
	s_addc_u32 s49, s49, 0
	s_add_i32 s50, s71, s53
	global_load_lds_dwordx4 v134, s[82:83]
	s_mov_b32 m0, s50
	s_nop 0
	global_load_lds_dwordx4 v130, s[48:49]
	s_add_i32 m0, s50, 0x2000
	s_nop 0
	global_load_lds_dwordx4 v134, s[48:49]
	s_mov_b32 m0, s58
	s_nop 0
	global_load_lds_dwordx4 v128, s[80:81]
	s_mov_b32 m0, s59
	s_nop 0
	global_load_lds_dwordx4 v132, s[80:81]
	s_waitcnt vmcnt(8) lgkmcnt(0)
	s_barrier
	v_mfma_f32_16x16x32_bf16 v[60:63], v[144:147], v[182:185], v[60:63]
	v_mfma_f32_16x16x32_bf16 v[56:59], v[158:161], v[182:185], v[56:59]
	v_mfma_f32_16x16x32_bf16 v[48:51], v[144:147], v[190:193], v[48:51]
	v_mfma_f32_16x16x32_bf16 v[40:43], v[158:161], v[190:193], v[40:43]
	v_mfma_f32_16x16x32_bf16 v[32:35], v[144:147], v[198:201], v[32:35]
	v_mfma_f32_16x16x32_bf16 v[24:27], v[158:161], v[198:201], v[24:27]
	v_mfma_f32_16x16x32_bf16 v[16:19], v[144:147], v[206:209], v[16:19]
	v_mfma_f32_16x16x32_bf16 v[8:11], v[158:161], v[206:209], v[8:11]
	v_mfma_f32_16x16x32_bf16 v[60:63], v[148:151], v[186:189], v[60:63]
	v_mfma_f32_16x16x32_bf16 v[56:59], v[162:165], v[186:189], v[56:59]
	v_mfma_f32_16x16x32_bf16 v[48:51], v[148:151], v[194:197], v[48:51]
	v_mfma_f32_16x16x32_bf16 v[40:43], v[162:165], v[194:197], v[40:43]
	v_mfma_f32_16x16x32_bf16 v[32:35], v[148:151], v[202:205], v[32:35]
	v_mfma_f32_16x16x32_bf16 v[24:27], v[162:165], v[202:205], v[24:27]
	v_mfma_f32_16x16x32_bf16 v[16:19], v[148:151], v[214:217], v[16:19]
	v_mfma_f32_16x16x32_bf16 v[8:11], v[162:165], v[214:217], v[8:11]
	v_mfma_f32_16x16x32_bf16 v[52:55], v[166:169], v[182:185], v[52:55]
	v_mfma_f32_16x16x32_bf16 v[44:47], v[174:177], v[182:185], v[44:47]
	v_mfma_f32_16x16x32_bf16 v[36:39], v[166:169], v[190:193], v[36:39]
	v_mfma_f32_16x16x32_bf16 v[28:31], v[174:177], v[190:193], v[28:31]
	v_mfma_f32_16x16x32_bf16 v[20:23], v[166:169], v[198:201], v[20:23]
	v_mfma_f32_16x16x32_bf16 v[12:15], v[174:177], v[198:201], v[12:15]
	v_mfma_f32_16x16x32_bf16 v[4:7], v[166:169], v[206:209], v[4:7]
	v_mfma_f32_16x16x32_bf16 v[0:3], v[174:177], v[206:209], v[0:3]
	v_mfma_f32_16x16x32_bf16 v[52:55], v[170:173], v[186:189], v[52:55]
	v_mfma_f32_16x16x32_bf16 v[44:47], v[178:181], v[186:189], v[44:47]
	v_mfma_f32_16x16x32_bf16 v[36:39], v[170:173], v[194:197], v[36:39]
	v_mfma_f32_16x16x32_bf16 v[28:31], v[178:181], v[194:197], v[28:31]
	v_mfma_f32_16x16x32_bf16 v[20:23], v[170:173], v[202:205], v[20:23]
	v_mfma_f32_16x16x32_bf16 v[12:15], v[178:181], v[202:205], v[12:15]
	v_mfma_f32_16x16x32_bf16 v[4:7], v[170:173], v[214:217], v[4:7]
	v_mfma_f32_16x16x32_bf16 v[0:3], v[178:181], v[214:217], v[0:3]
	s_barrier
	s_add_i32 s69, s69, 2
	s_add_u32 s46, s46, 0x100
	s_addc_u32 s47, s47, 0
	s_add_u32 s67, s67, 0x100
	s_addc_u32 s68, s68, 0
	s_cmp_gt_u32 s69, 13
	s_cbranch_scc0 .LBB0_735
	v_lshl_add_u32 v150, s44, 8, v152
	v_lshl_or_b32 v144, s64, 8, v154
	v_ashrrev_i32_e32 v145, 31, v144
	v_or_b32_e32 v166, 16, v150
	v_lshlrev_b64 v[144:145], 1, v[144:145]
	v_ashrrev_i32_e32 v151, 31, v150
	v_ashrrev_i32_e32 v167, 31, v166
	v_lshl_add_u64 v[146:147], s[12:13], 0, v[144:145]
	v_lshlrev_b64 v[148:149], 12, v[150:151]
	v_lshlrev_b64 v[178:179], 12, v[166:167]
	v_lshl_add_u64 v[162:163], v[146:147], 0, v[148:149]
	v_lshl_add_u64 v[170:171], v[146:147], 0, v[178:179]
	global_load_dwordx4 v[158:161], v[162:163], off
	s_nop 0
	global_load_dwordx4 v[162:165], v[162:163], off offset:256
	s_nop 0
	global_load_dwordx4 v[166:169], v[170:171], off
	s_nop 0
	global_load_dwordx4 v[170:173], v[170:171], off offset:256
	v_or_b32_e32 v174, 32, v150
	v_ashrrev_i32_e32 v175, 31, v174
	v_lshlrev_b64 v[190:191], 12, v[174:175]
	v_lshl_add_u64 v[180:181], v[146:147], 0, v[190:191]
	global_load_dwordx4 v[174:177], v[180:181], off
	v_or_b32_e32 v150, 48, v150
	v_ashrrev_i32_e32 v151, 31, v150
	v_lshlrev_b64 v[150:151], 12, v[150:151]
	v_lshl_add_u64 v[182:183], s[14:15], 0, v[148:149]
	v_lshl_add_u64 v[186:187], v[146:147], 0, v[150:151]
	v_lshl_add_u64 v[192:193], v[182:183], 0, v[144:145]
	v_lshl_add_u64 v[194:195], s[14:15], 0, v[178:179]
	global_load_dwordx4 v[178:181], v[180:181], off offset:256
	s_nop 0
	global_load_dwordx4 v[182:185], v[186:187], off
	s_nop 0
	global_load_dwordx4 v[186:189], v[186:187], off offset:256
	v_lshl_add_u64 v[194:195], v[194:195], 0, v[144:145]
	s_and_b64 vcc, exec, s[10:11]
	s_mov_b32 s64, s36
	s_mov_b32 s44, s38
	s_mov_b64 s[48:49], s[42:43]
	s_mov_b64 s[46:47], s[40:41]
	s_waitcnt vmcnt(0)
; __device__ __forceinline__ float bf_lo(unsigned w) { return __uint_as_float(w << 16); }
; __device__ __forceinline__ float bf_hi(unsigned w) { return __uint_as_float(w & 0xffff0000u); }
; __device__ __forceinline__ u32x4 pack8(const f32x4 a, const f32x4 b) { u32x4 w; w.x = cvt_pk_bf16(a[0], a[1]); w.y = cvt_pk_bf16(a[2], a[3]); w.z = cvt_pk_bf16(b[0], b[1]); w.w = cvt_pk_bf16(b[2], b[3]); return w; }
;     __device__ __forceinline__ void operator()(const f32x4 (&acc)[2][2][4][2], const Unit& u, int wr, int wc, int fr, int fq) const {
;     ...
;         for (int ai = 0; ai < 2; ++ai) { u32x4 gw[4][2], pw[4][2];
; #pragma unroll
;             for (int m = 0; m < 4; ++m) { const size_t off = (size_t)(row0 + ai * HALF + m * 16) * 2048 + col0;
; #pragma unroll
;                 for (int bj = 0; bj < 2; ++bj) { gw[m][bj] = *(const u32x4*)(G + off + bj * HALF); if (PASS == 1) pw[m][bj] = *(const u32x4*)(MIX + off + bj * HALF); } }
; #pragma unroll
;             for (int m = 0; m < 4; ++m) { const size_t off = (size_t)(row0 + ai * HALF + m * 16) * 2048 + col0;
; #pragma unroll
;                 for (int bj = 0; bj < 2; ++bj) { const u32x4 g4 = gw[m][bj];
;                     f32x4 v0 = (f32x4){bf_lo(g4.x), bf_hi(g4.x), bf_lo(g4.y), bf_hi(g4.y)} * acc[ai][bj][m][0], v1 = (f32x4){bf_lo(g4.z), bf_hi(g4.z), bf_lo(g4.w), bf_hi(g4.w)} * acc[ai][bj][m][1];
;                     if (PASS == 1) { const u32x4 p4 = pw[m][bj]; v0 += (f32x4){bf_lo(p4.x), bf_hi(p4.x), bf_lo(p4.y), bf_hi(p4.y)}; v1 += (f32x4){bf_lo(p4.z), bf_hi(p4.z), bf_lo(p4.w), bf_hi(p4.w)}; }
;                     *(u32x4*)(MIX + off + bj * HALF) = pack8(v0, v1); } } }
	v_lshlrev_b32_e32 v196, 16, v158
	v_and_b32_e32 v197, 0xffff0000, v158
	v_lshlrev_b32_e32 v158, 16, v159
	v_and_b32_e32 v159, 0xffff0000, v159
	v_lshlrev_b32_e32 v198, 16, v160
	v_and_b32_e32 v199, 0xffff0000, v160
	v_lshlrev_b32_e32 v160, 16, v161
	v_and_b32_e32 v161, 0xffff0000, v161
	v_lshlrev_b32_e32 v200, 16, v162
	v_and_b32_e32 v201, 0xffff0000, v162
	v_lshlrev_b32_e32 v162, 16, v163
	v_and_b32_e32 v163, 0xffff0000, v163
	v_lshlrev_b32_e32 v202, 16, v164
	v_and_b32_e32 v203, 0xffff0000, v164
	v_lshlrev_b32_e32 v164, 16, v165
	v_and_b32_e32 v165, 0xffff0000, v165
	v_lshlrev_b32_e32 v204, 16, v166
	v_and_b32_e32 v205, 0xffff0000, v166
	v_lshlrev_b32_e32 v166, 16, v167
	v_and_b32_e32 v167, 0xffff0000, v167
	v_lshlrev_b32_e32 v206, 16, v168
	v_and_b32_e32 v207, 0xffff0000, v168
	v_lshlrev_b32_e32 v168, 16, v169
	v_and_b32_e32 v169, 0xffff0000, v169
	v_lshlrev_b32_e32 v208, 16, v170
	v_and_b32_e32 v209, 0xffff0000, v170
	v_lshlrev_b32_e32 v170, 16, v171
	v_and_b32_e32 v171, 0xffff0000, v171
	v_pk_mul_f32 v[126:127], v[126:127], v[158:159]
	v_pk_mul_f32 v[124:125], v[124:125], v[196:197]
	v_pk_mul_f32 v[122:123], v[122:123], v[160:161]
	v_pk_mul_f32 v[120:121], v[120:121], v[198:199]
	v_pk_mul_f32 v[110:111], v[110:111], v[162:163]
	v_pk_mul_f32 v[108:109], v[108:109], v[200:201]
	v_pk_mul_f32 v[158:159], v[106:107], v[164:165]
	v_pk_mul_f32 v[106:107], v[104:105], v[202:203]
	v_pk_mul_f32 v[118:119], v[118:119], v[166:167]
	v_pk_mul_f32 v[116:117], v[116:117], v[204:205]
	v_pk_mul_f32 v[114:115], v[114:115], v[168:169]
	v_pk_mul_f32 v[112:113], v[112:113], v[206:207]
	v_pk_mul_f32 v[160:161], v[102:103], v[170:171]
	v_pk_mul_f32 v[162:163], v[100:101], v[208:209]
	v_cvt_pk_bf16_f32 v100, v124, v125
	v_cvt_pk_bf16_f32 v101, v126, v127
	v_cvt_pk_bf16_f32 v102, v120, v121
	v_cvt_pk_bf16_f32 v103, v122, v123
	v_cvt_pk_bf16_f32 v104, v108, v109
	v_cvt_pk_bf16_f32 v105, v110, v111
	v_cvt_pk_bf16_f32 v106, v106, v107
	v_cvt_pk_bf16_f32 v107, v158, v159
	v_cvt_pk_bf16_f32 v108, v116, v117
	v_cvt_pk_bf16_f32 v109, v118, v119
	v_cvt_pk_bf16_f32 v110, v112, v113
	v_cvt_pk_bf16_f32 v111, v114, v115
	global_store_dwordx4 v[192:193], v[100:103], off
	global_store_dwordx4 v[192:193], v[104:107], off offset:256
	global_store_dwordx4 v[194:195], v[108:111], off
	v_lshlrev_b32_e32 v100, 16, v172
	v_and_b32_e32 v101, 0xffff0000, v172
	v_lshlrev_b32_e32 v102, 16, v173
	v_and_b32_e32 v103, 0xffff0000, v173
	v_pk_mul_f32 v[102:103], v[94:95], v[102:103]
	v_pk_mul_f32 v[94:95], v[92:93], v[100:101]
	v_cvt_pk_bf16_f32 v92, v162, v163
	v_cvt_pk_bf16_f32 v93, v160, v161
	v_cvt_pk_bf16_f32 v94, v94, v95
	v_cvt_pk_bf16_f32 v95, v102, v103
	global_store_dwordx4 v[194:195], v[92:95], off offset:256
	v_lshl_add_u64 v[100:101], v[148:149], 0, s[30:31]
	v_lshl_add_u64 v[102:103], v[148:149], 0, s[34:35]
	v_lshlrev_b32_e32 v92, 16, v174
	v_and_b32_e32 v93, 0xffff0000, v174
	v_lshlrev_b32_e32 v94, 16, v175
	v_and_b32_e32 v95, 0xffff0000, v175
	v_pk_mul_f32 v[94:95], v[98:99], v[94:95]
	v_pk_mul_f32 v[92:93], v[96:97], v[92:93]
	v_lshlrev_b32_e32 v96, 16, v176
	v_and_b32_e32 v97, 0xffff0000, v176
	v_lshlrev_b32_e32 v98, 16, v177
	v_and_b32_e32 v99, 0xffff0000, v177
	v_pk_mul_f32 v[98:99], v[90:91], v[98:99]
	v_pk_mul_f32 v[90:91], v[88:89], v[96:97]
	v_cvt_pk_bf16_f32 v88, v92, v93
	v_lshl_add_u64 v[92:93], s[14:15], 0, v[190:191]
	v_cvt_pk_bf16_f32 v89, v94, v95
	v_cvt_pk_bf16_f32 v90, v90, v91
	v_cvt_pk_bf16_f32 v91, v98, v99
	v_lshl_add_u64 v[92:93], v[92:93], 0, v[144:145]
	global_store_dwordx4 v[92:93], v[88:91], off
	v_lshl_add_u64 v[96:97], v[148:149], 0, s[26:27]
	v_lshl_add_u64 v[98:99], v[148:149], 0, s[28:29]
	v_lshlrev_b32_e32 v88, 16, v178
	v_and_b32_e32 v89, 0xffff0000, v178
	v_lshlrev_b32_e32 v90, 16, v179
	v_and_b32_e32 v91, 0xffff0000, v179
	v_pk_mul_f32 v[86:87], v[86:87], v[90:91]
	v_pk_mul_f32 v[84:85], v[84:85], v[88:89]
	v_lshlrev_b32_e32 v88, 16, v180
	v_and_b32_e32 v89, 0xffff0000, v180
	v_lshlrev_b32_e32 v90, 16, v181
	v_and_b32_e32 v91, 0xffff0000, v181
	v_pk_mul_f32 v[90:91], v[78:79], v[90:91]
	v_pk_mul_f32 v[78:79], v[76:77], v[88:89]
	v_cvt_pk_bf16_f32 v76, v84, v85
	v_cvt_pk_bf16_f32 v77, v86, v87
	v_cvt_pk_bf16_f32 v78, v78, v79
	v_cvt_pk_bf16_f32 v79, v90, v91
	global_store_dwordx4 v[92:93], v[76:79], off offset:256
	s_nop 1
	v_lshlrev_b32_e32 v76, 16, v182
	v_and_b32_e32 v77, 0xffff0000, v182
	v_lshlrev_b32_e32 v78, 16, v183
	v_and_b32_e32 v79, 0xffff0000, v183
	v_pk_mul_f32 v[78:79], v[82:83], v[78:79]
	v_pk_mul_f32 v[76:77], v[80:81], v[76:77]
	v_lshlrev_b32_e32 v80, 16, v184
	v_and_b32_e32 v81, 0xffff0000, v184
	v_lshlrev_b32_e32 v82, 16, v185
	v_and_b32_e32 v83, 0xffff0000, v185
	v_pk_mul_f32 v[82:83], v[74:75], v[82:83]
	v_pk_mul_f32 v[74:75], v[72:73], v[80:81]
	v_cvt_pk_bf16_f32 v72, v76, v77
	v_lshl_add_u64 v[76:77], s[14:15], 0, v[150:151]
	v_cvt_pk_bf16_f32 v73, v78, v79
	v_cvt_pk_bf16_f32 v74, v74, v75
	v_cvt_pk_bf16_f32 v75, v82, v83
	v_lshl_add_u64 v[76:77], v[76:77], 0, v[144:145]
	global_store_dwordx4 v[76:77], v[72:75], off
	s_nop 1
	v_lshlrev_b32_e32 v72, 16, v186
	v_and_b32_e32 v73, 0xffff0000, v186
	v_lshlrev_b32_e32 v74, 16, v187
	v_and_b32_e32 v75, 0xffff0000, v187
	v_pk_mul_f32 v[70:71], v[70:71], v[74:75]
	v_pk_mul_f32 v[68:69], v[68:69], v[72:73]
	v_lshlrev_b32_e32 v72, 16, v188
	v_and_b32_e32 v73, 0xffff0000, v188
	v_lshlrev_b32_e32 v74, 16, v189
	v_and_b32_e32 v75, 0xffff0000, v189
	v_pk_mul_f32 v[74:75], v[66:67], v[74:75]
	v_pk_mul_f32 v[66:67], v[64:65], v[72:73]
	v_cvt_pk_bf16_f32 v64, v68, v69
	v_cvt_pk_bf16_f32 v65, v70, v71
	v_cvt_pk_bf16_f32 v66, v66, v67
	v_cvt_pk_bf16_f32 v67, v74, v75
	global_store_dwordx4 v[76:77], v[64:67], off offset:256
	s_nop 1
	v_lshl_add_u64 v[64:65], v[146:147], 0, v[96:97]
	global_load_dwordx4 v[68:71], v[64:65], off
	global_load_dwordx4 v[72:75], v[64:65], off offset:256
	v_lshl_add_u64 v[64:65], v[146:147], 0, v[98:99]
	global_load_dwordx4 v[76:79], v[64:65], off
	global_load_dwordx4 v[80:83], v[64:65], off offset:256
	v_lshl_add_u64 v[64:65], v[146:147], 0, v[100:101]
	global_load_dwordx4 v[84:87], v[64:65], off
	global_load_dwordx4 v[88:91], v[64:65], off offset:256
	v_lshl_add_u64 v[64:65], v[146:147], 0, v[102:103]
	global_load_dwordx4 v[92:95], v[64:65], off
	s_nop 0
	global_load_dwordx4 v[64:67], v[64:65], off offset:256
	s_waitcnt vmcnt(7)
; __device__ __forceinline__ float bf_lo(unsigned w) { return __uint_as_float(w << 16); }
; __device__ __forceinline__ float bf_hi(unsigned w) { return __uint_as_float(w & 0xffff0000u); }
; __device__ __forceinline__ u32x4 pack8(const f32x4 a, const f32x4 b) { u32x4 w; w.x = cvt_pk_bf16(a[0], a[1]); w.y = cvt_pk_bf16(a[2], a[3]); w.z = cvt_pk_bf16(b[0], b[1]); w.w = cvt_pk_bf16(b[2], b[3]); return w; }
; #define PG8_WAIT_V(n) asm volatile("s_waitcnt vmcnt(" #n ")" ::: "memory")
; #define PG8_BAR __builtin_amdgcn_s_barrier()
;     __device__ __forceinline__ void operator()(const f32x4 (&acc)[2][2][4][2], const Unit& u, int wr, int wc, int fr, int fq) const {
;     ...
;         for (int ai = 0; ai < 2; ++ai) { u32x4 gw[4][2], pw[4][2];
; #pragma unroll
;             for (int m = 0; m < 4; ++m) { const size_t off = (size_t)(row0 + ai * HALF + m * 16) * 2048 + col0;
; #pragma unroll
;                 for (int bj = 0; bj < 2; ++bj) { gw[m][bj] = *(const u32x4*)(G + off + bj * HALF); if (PASS == 1) pw[m][bj] = *(const u32x4*)(MIX + off + bj * HALF); } }
; #pragma unroll
;             for (int m = 0; m < 4; ++m) { const size_t off = (size_t)(row0 + ai * HALF + m * 16) * 2048 + col0;
; #pragma unroll
;                 for (int bj = 0; bj < 2; ++bj) { const u32x4 g4 = gw[m][bj];
;                     f32x4 v0 = (f32x4){bf_lo(g4.x), bf_hi(g4.x), bf_lo(g4.y), bf_hi(g4.y)} * acc[ai][bj][m][0], v1 = (f32x4){bf_lo(g4.z), bf_hi(g4.z), bf_lo(g4.w), bf_hi(g4.w)} * acc[ai][bj][m][1];
;                     if (PASS == 1) { const u32x4 p4 = pw[m][bj]; v0 += (f32x4){bf_lo(p4.x), bf_hi(p4.x), bf_lo(p4.y), bf_hi(p4.y)}; v1 += (f32x4){bf_lo(p4.z), bf_hi(p4.z), bf_lo(p4.w), bf_hi(p4.w)}; }
;                     *(u32x4*)(MIX + off + bj * HALF) = pack8(v0, v1); } } }
; template <class Epi, class Sched, bool ALIGN_EPI = false, bool SP2 = false>
; __device__ __forceinline__ void gemm_phase(PG8_LAS unsigned char* lds, const Gemm g, const Sched& S, const Epi& E) {
;     ...
;     PG8_WAIT_V(0);
;     if constexpr (!ALIGN_EPI) { if (wr == 0) PG8_BAR; }
;     PG8_BAR;
	v_lshlrev_b32_e32 v104, 16, v68
	v_and_b32_e32 v105, 0xffff0000, v68
	v_lshlrev_b32_e32 v68, 16, v69
	v_and_b32_e32 v69, 0xffff0000, v69
	v_pk_mul_f32 v[62:63], v[62:63], v[68:69]
	v_pk_mul_f32 v[60:61], v[60:61], v[104:105]
	v_lshlrev_b32_e32 v68, 16, v70
	v_and_b32_e32 v69, 0xffff0000, v70
	v_lshlrev_b32_e32 v70, 16, v71
	v_and_b32_e32 v71, 0xffff0000, v71
	v_pk_mul_f32 v[70:71], v[58:59], v[70:71]
	v_pk_mul_f32 v[58:59], v[56:57], v[68:69]
	v_cvt_pk_bf16_f32 v56, v60, v61
	v_lshl_add_u64 v[60:61], s[14:15], 0, v[96:97]
	v_cvt_pk_bf16_f32 v57, v62, v63
	v_cvt_pk_bf16_f32 v58, v58, v59
	v_cvt_pk_bf16_f32 v59, v70, v71
	v_lshl_add_u64 v[60:61], v[60:61], 0, v[144:145]
	global_store_dwordx4 v[60:61], v[56:59], off
	s_waitcnt vmcnt(7)
	s_nop 0
	v_lshlrev_b32_e32 v56, 16, v72
	v_and_b32_e32 v57, 0xffff0000, v72
	v_lshlrev_b32_e32 v58, 16, v73
	v_and_b32_e32 v59, 0xffff0000, v73
	v_pk_mul_f32 v[54:55], v[54:55], v[58:59]
	v_pk_mul_f32 v[52:53], v[52:53], v[56:57]
	v_lshlrev_b32_e32 v56, 16, v74
	v_and_b32_e32 v57, 0xffff0000, v74
	v_lshlrev_b32_e32 v58, 16, v75
	v_and_b32_e32 v59, 0xffff0000, v75
	v_pk_mul_f32 v[58:59], v[46:47], v[58:59]
	v_pk_mul_f32 v[46:47], v[44:45], v[56:57]
	v_cvt_pk_bf16_f32 v44, v52, v53
	v_cvt_pk_bf16_f32 v45, v54, v55
	v_cvt_pk_bf16_f32 v46, v46, v47
	v_cvt_pk_bf16_f32 v47, v58, v59
	global_store_dwordx4 v[60:61], v[44:47], off offset:256
	s_waitcnt vmcnt(7)
	s_nop 0
	v_lshlrev_b32_e32 v44, 16, v76
	v_and_b32_e32 v45, 0xffff0000, v76
	v_lshlrev_b32_e32 v46, 16, v77
	v_and_b32_e32 v47, 0xffff0000, v77
	v_pk_mul_f32 v[46:47], v[50:51], v[46:47]
	v_pk_mul_f32 v[44:45], v[48:49], v[44:45]
	v_lshlrev_b32_e32 v48, 16, v78
	v_and_b32_e32 v49, 0xffff0000, v78
	v_lshlrev_b32_e32 v50, 16, v79
	v_and_b32_e32 v51, 0xffff0000, v79
	v_pk_mul_f32 v[50:51], v[42:43], v[50:51]
	v_pk_mul_f32 v[42:43], v[40:41], v[48:49]
	v_cvt_pk_bf16_f32 v40, v44, v45
	v_lshl_add_u64 v[44:45], s[14:15], 0, v[98:99]
	v_cvt_pk_bf16_f32 v41, v46, v47
	v_cvt_pk_bf16_f32 v42, v42, v43
	v_cvt_pk_bf16_f32 v43, v50, v51
	v_lshl_add_u64 v[44:45], v[44:45], 0, v[144:145]
	global_store_dwordx4 v[44:45], v[40:43], off
	s_waitcnt vmcnt(7)
	s_nop 0
	v_lshlrev_b32_e32 v40, 16, v80
	v_and_b32_e32 v41, 0xffff0000, v80
	v_lshlrev_b32_e32 v42, 16, v81
	v_and_b32_e32 v43, 0xffff0000, v81
	v_pk_mul_f32 v[38:39], v[38:39], v[42:43]
	v_pk_mul_f32 v[36:37], v[36:37], v[40:41]
	v_lshlrev_b32_e32 v40, 16, v82
	v_and_b32_e32 v41, 0xffff0000, v82
	v_lshlrev_b32_e32 v42, 16, v83
	v_and_b32_e32 v43, 0xffff0000, v83
	v_pk_mul_f32 v[42:43], v[30:31], v[42:43]
	v_pk_mul_f32 v[30:31], v[28:29], v[40:41]
	v_cvt_pk_bf16_f32 v28, v36, v37
	v_cvt_pk_bf16_f32 v29, v38, v39
	v_cvt_pk_bf16_f32 v30, v30, v31
	v_cvt_pk_bf16_f32 v31, v42, v43
	global_store_dwordx4 v[44:45], v[28:31], off offset:256
	s_waitcnt vmcnt(7)
	s_nop 0
	v_lshlrev_b32_e32 v28, 16, v84
	v_and_b32_e32 v29, 0xffff0000, v84
	v_lshlrev_b32_e32 v30, 16, v85
	v_and_b32_e32 v31, 0xffff0000, v85
	v_pk_mul_f32 v[30:31], v[34:35], v[30:31]
	v_pk_mul_f32 v[28:29], v[32:33], v[28:29]
	v_lshlrev_b32_e32 v32, 16, v86
	v_and_b32_e32 v33, 0xffff0000, v86
	v_lshlrev_b32_e32 v34, 16, v87
	v_and_b32_e32 v35, 0xffff0000, v87
	v_pk_mul_f32 v[34:35], v[26:27], v[34:35]
	v_pk_mul_f32 v[26:27], v[24:25], v[32:33]
	v_cvt_pk_bf16_f32 v24, v28, v29
	v_lshl_add_u64 v[28:29], s[14:15], 0, v[100:101]
	v_cvt_pk_bf16_f32 v25, v30, v31
	v_cvt_pk_bf16_f32 v26, v26, v27
	v_cvt_pk_bf16_f32 v27, v34, v35
	v_lshl_add_u64 v[28:29], v[28:29], 0, v[144:145]
	global_store_dwordx4 v[28:29], v[24:27], off
	s_waitcnt vmcnt(7)
	s_nop 0
	v_lshlrev_b32_e32 v24, 16, v88
	v_and_b32_e32 v25, 0xffff0000, v88
	v_lshlrev_b32_e32 v26, 16, v89
	v_and_b32_e32 v27, 0xffff0000, v89
	v_pk_mul_f32 v[22:23], v[22:23], v[26:27]
	v_pk_mul_f32 v[20:21], v[20:21], v[24:25]
	v_lshlrev_b32_e32 v24, 16, v90
	v_and_b32_e32 v25, 0xffff0000, v90
	v_lshlrev_b32_e32 v26, 16, v91
	v_and_b32_e32 v27, 0xffff0000, v91
	v_pk_mul_f32 v[26:27], v[14:15], v[26:27]
	v_pk_mul_f32 v[14:15], v[12:13], v[24:25]
	v_cvt_pk_bf16_f32 v12, v20, v21
	v_cvt_pk_bf16_f32 v13, v22, v23
	v_cvt_pk_bf16_f32 v14, v14, v15
	v_cvt_pk_bf16_f32 v15, v26, v27
	global_store_dwordx4 v[28:29], v[12:15], off offset:256
	s_waitcnt vmcnt(7)
	s_nop 0
	v_lshlrev_b32_e32 v12, 16, v92
	v_and_b32_e32 v13, 0xffff0000, v92
	v_lshlrev_b32_e32 v14, 16, v93
	v_and_b32_e32 v15, 0xffff0000, v93
	v_pk_mul_f32 v[14:15], v[18:19], v[14:15]
	v_pk_mul_f32 v[12:13], v[16:17], v[12:13]
	v_lshlrev_b32_e32 v16, 16, v94
	v_and_b32_e32 v17, 0xffff0000, v94
	v_lshlrev_b32_e32 v18, 16, v95
	v_and_b32_e32 v19, 0xffff0000, v95
	v_pk_mul_f32 v[18:19], v[10:11], v[18:19]
	v_pk_mul_f32 v[10:11], v[8:9], v[16:17]
	v_cvt_pk_bf16_f32 v8, v12, v13
	v_lshl_add_u64 v[12:13], s[14:15], 0, v[102:103]
	v_cvt_pk_bf16_f32 v9, v14, v15
	v_cvt_pk_bf16_f32 v10, v10, v11
	v_cvt_pk_bf16_f32 v11, v18, v19
	v_lshl_add_u64 v[12:13], v[12:13], 0, v[144:145]
	global_store_dwordx4 v[12:13], v[8:11], off
	s_waitcnt vmcnt(7)
	s_nop 0
	v_lshlrev_b32_e32 v8, 16, v64
	v_and_b32_e32 v9, 0xffff0000, v64
	v_lshlrev_b32_e32 v10, 16, v65
	v_and_b32_e32 v11, 0xffff0000, v65
	v_pk_mul_f32 v[6:7], v[6:7], v[10:11]
	v_pk_mul_f32 v[4:5], v[4:5], v[8:9]
	v_lshlrev_b32_e32 v8, 16, v66
	v_and_b32_e32 v9, 0xffff0000, v66
	v_lshlrev_b32_e32 v10, 16, v67
	v_and_b32_e32 v11, 0xffff0000, v67
	v_pk_mul_f32 v[10:11], v[2:3], v[10:11]
	v_pk_mul_f32 v[2:3], v[0:1], v[8:9]
	v_cvt_pk_bf16_f32 v0, v4, v5
	v_cvt_pk_bf16_f32 v1, v6, v7
	v_cvt_pk_bf16_f32 v2, v2, v3
	v_cvt_pk_bf16_f32 v3, v10, v11
	global_store_dwordx4 v[12:13], v[0:3], off offset:256
	s_cbranch_vccz .LBB0_728
	s_waitcnt vmcnt(0)
	s_cmpk_gt_u32 s3, 0xff
	s_cbranch_scc1 .LBB0_739
	s_barrier

; #define PG8_STAGE(bufoff, gbase, voff) do { _Pragma("unroll") for (int _i = 0; _i < 2; ++_i) \
;         __builtin_amdgcn_global_load_lds((const unsigned*)((const char*)(gbase) + (voff)[_i]), (PG8_LAS unsigned*)(lds + (bufoff) + ldsw + _i * 8192), 16, 0, 0); } while (0)
; #define PG8_LDA(dst, b, h) do { _Pragma("unroll") for (int m = 0; m < 4; ++m) _Pragma("unroll") for (int k = 0; k < 2; ++k) dst[m][k] = *(const PG8_LAS bf16x8*)(lds + PG8_SA(b, h) + aoff + m * 2048 + k * 1024); } while (0)
; #define PG8_LDB(dst, b, h) do { _Pragma("unroll") for (int n = 0; n < 2; ++n) _Pragma("unroll") for (int k = 0; k < 2; ++k) dst[n][k] = *(const PG8_LAS bf16x8*)(lds + PG8_SB(b, h) + boff + n * 2048 + k * 1024); } while (0)
; #define PG8_WAIT_V(n) asm volatile("s_waitcnt vmcnt(" #n ")" ::: "memory")
; #define PG8_WAIT_L(n) asm volatile("s_waitcnt lgkmcnt(" #n ")" ::: "memory")
; #define PG8_BAR __builtin_amdgcn_s_barrier()
; #define PG8_SCHED __builtin_amdgcn_sched_barrier(0)
; template <class Epi, class Sched, bool ALIGN_EPI = false, bool SP2 = false>
; __device__ __forceinline__ void gemm_phase(PG8_LAS unsigned char* lds, const Gemm g, const Sched& S, const Epi& E) {
;     ...
;         const bool has_next = S.next(ui + 1, nxt);
;         const char* nA = has_next ? (const char*)g.A + (size_t)nxt.pm * tstep : cA; const char* nB = has_next ? (const char*)g.Bt + (size_t)nxt.pn * tstep : cB;
;         for (int t = 0; t < nt; t += 2) {
;             const bool last = (t == nt - 2);
;             const char* a1 = cA + (size_t)(t + 1) * kstep;
;             const char* a2 = last ? nA : cA + (size_t)(t + 2) * kstep; const char* b2 = last ? nB : cB + (size_t)(t + 2) * kstep;
;             const char* a3 = a2 + kstep; const char* b3 = b2 + kstep;
;             if (last && has_next) S.a_ready(nxt);
;             if constexpr (SP2) {
;             PG8_LDB(B0, 0, 0); PG8_LDB(B1, 0, 1); PG8_SCHED; PG8_LDA(At, 0, 0); PG8_STAGE(PG8_SA(1, 1), a1 + hstep, voffA);
;             PG8_WAIT_V(8); PG8_WAIT_L(0); PG8_BAR; PG8_MMA(0, 0, At, B0); PG8_MMA(0, 1, At, B1); PG8_BAR; PG8_SCHED;
;             PG8_LDA(At, 0, 1); PG8_STAGE(PG8_SB(0, 0), b2, voffB); PG8_STAGE(PG8_SB(0, 1), b2 + hstep, voffB); PG8_STAGE(PG8_SA(0, 0), a2, voffA);
;             PG8_WAIT_V(8); PG8_WAIT_L(0); PG8_BAR; PG8_MMA(1, 0, At, B0); PG8_MMA(1, 1, At, B1); PG8_BAR; PG8_SCHED;
.LBB0_754:
	s_ashr_i32 s29, s28, 31
	v_cmp_lt_i64_e32 vcc, s[30:31], v[160:161]
	s_lshl_b64 s[30:31], s[28:29], 19
	s_add_u32 s30, s9, s30
	s_addc_u32 s31, s22, s31
	s_and_b64 s[34:35], vcc, exec
	s_cselect_b32 s29, s31, s39
	s_cselect_b32 s57, s30, s38
	s_ashr_i32 s27, s26, 31
	s_lshl_b64 s[34:35], s[26:27], 19
	s_add_u32 s34, s23, s34
	s_addc_u32 s35, s44, s35
	s_and_b64 s[42:43], vcc, exec
	s_cselect_b32 s27, s35, s41
	s_cselect_b32 s58, s34, s40
	s_add_u32 s38, s38, 0x40080
	s_addc_u32 s39, s39, 0
	s_add_u32 s59, s40, 0x100
	s_addc_u32 s60, s41, 0
	s_mov_b32 s61, -2
	ds_read_b128 v[128:131], v177
	ds_read_b128 v[132:135], v177 offset:1024
	ds_read_b128 v[136:139], v177 offset:2048
	ds_read_b128 v[140:143], v177 offset:3072
	ds_read_b128 v[144:147], v178
	ds_read_b128 v[164:167], v178 offset:1024
	ds_read_b128 v[168:171], v178 offset:2048
	ds_read_b128 v[180:183], v178 offset:3072
	s_add_u32 s40, s38, 0xfffc0080
	s_addc_u32 s41, s39, -1
	s_cmp_eq_u32 s61, 12
	s_cselect_b32 s43, s29, s41
	s_cselect_b32 s42, s57, s40
	s_cselect_b32 s41, s27, s60
	s_cselect_b32 s40, s58, s59
	s_add_i32 m0, s37, 0xc000
	ds_read_b128 v[184:187], v179
	ds_read_b128 v[188:191], v179 offset:1024
	ds_read_b128 v[192:195], v179 offset:2048
	ds_read_b128 v[196:199], v179 offset:3072
	ds_read_b128 v[200:203], v179 offset:4096
	ds_read_b128 v[204:207], v179 offset:5120
	ds_read_b128 v[208:211], v179 offset:6144
	ds_read_b128 v[214:217], v179 offset:7168
	global_load_lds_dwordx4 v156, s[38:39]
	s_add_i32 m0, s37, 0xe000
	s_nop 0
	global_load_lds_dwordx4 v158, s[38:39]
	s_waitcnt vmcnt(8) lgkmcnt(0)
	s_barrier
	v_mfma_f32_16x16x32_bf16 v[124:127], v[128:131], v[184:187], 0
	v_mfma_f32_16x16x32_bf16 v[120:123], v[136:139], v[184:187], 0
	v_mfma_f32_16x16x32_bf16 v[108:111], v[128:131], v[192:195], 0
	v_mfma_f32_16x16x32_bf16 v[104:107], v[136:139], v[192:195], 0
	v_mfma_f32_16x16x32_bf16 v[92:95], v[128:131], v[200:203], 0
	v_mfma_f32_16x16x32_bf16 v[88:91], v[136:139], v[200:203], 0
	v_mfma_f32_16x16x32_bf16 v[76:79], v[128:131], v[208:211], 0
	v_mfma_f32_16x16x32_bf16 v[72:75], v[136:139], v[208:211], 0
	v_mfma_f32_16x16x32_bf16 v[124:127], v[132:135], v[188:191], v[124:127]
	v_mfma_f32_16x16x32_bf16 v[120:123], v[140:143], v[188:191], v[120:123]
	v_mfma_f32_16x16x32_bf16 v[108:111], v[132:135], v[196:199], v[108:111]
	v_mfma_f32_16x16x32_bf16 v[104:107], v[140:143], v[196:199], v[104:107]
	v_mfma_f32_16x16x32_bf16 v[92:95], v[132:135], v[204:207], v[92:95]
	v_mfma_f32_16x16x32_bf16 v[88:91], v[140:143], v[204:207], v[88:91]
	v_mfma_f32_16x16x32_bf16 v[76:79], v[132:135], v[214:217], v[76:79]
	v_mfma_f32_16x16x32_bf16 v[72:75], v[140:143], v[214:217], v[72:75]
	v_mfma_f32_16x16x32_bf16 v[116:119], v[144:147], v[184:187], 0
	v_mfma_f32_16x16x32_bf16 v[112:115], v[168:171], v[184:187], 0
	v_mfma_f32_16x16x32_bf16 v[100:103], v[144:147], v[192:195], 0
	v_mfma_f32_16x16x32_bf16 v[96:99], v[168:171], v[192:195], 0
	v_mfma_f32_16x16x32_bf16 v[84:87], v[144:147], v[200:203], 0
	v_mfma_f32_16x16x32_bf16 v[80:83], v[168:171], v[200:203], 0
	v_mfma_f32_16x16x32_bf16 v[68:71], v[144:147], v[208:211], 0
	v_mfma_f32_16x16x32_bf16 v[64:67], v[168:171], v[208:211], 0
	v_mfma_f32_16x16x32_bf16 v[116:119], v[164:167], v[188:191], v[116:119]
	v_mfma_f32_16x16x32_bf16 v[112:115], v[180:183], v[188:191], v[112:115]
	v_mfma_f32_16x16x32_bf16 v[100:103], v[164:167], v[196:199], v[100:103]
	v_mfma_f32_16x16x32_bf16 v[96:99], v[180:183], v[196:199], v[96:99]
	v_mfma_f32_16x16x32_bf16 v[84:87], v[164:167], v[204:207], v[84:87]
	v_mfma_f32_16x16x32_bf16 v[80:83], v[180:183], v[204:207], v[80:83]
	v_mfma_f32_16x16x32_bf16 v[68:71], v[164:167], v[214:217], v[68:71]
	v_mfma_f32_16x16x32_bf16 v[64:67], v[180:183], v[214:217], v[64:67]
	s_barrier
	s_add_i32 s62, s54, s45
	s_mov_b32 m0, s62
	ds_read_b128 v[184:187], v179 offset:16384
	ds_read_b128 v[188:191], v179 offset:17408
	ds_read_b128 v[192:195], v179 offset:18432
	ds_read_b128 v[196:199], v179 offset:19456
	ds_read_b128 v[200:203], v179 offset:20480
	ds_read_b128 v[204:207], v179 offset:21504
	ds_read_b128 v[208:211], v179 offset:22528
	ds_read_b128 v[214:217], v179 offset:23552
	global_load_lds_dwordx4 v150, s[40:41]
	s_add_i32 m0, s62, 0x2000
	s_add_u32 s62, s40, 0x40000
	s_addc_u32 s63, s41, 0
	s_add_i32 s64, s55, s45
	global_load_lds_dwordx4 v154, s[40:41]
	s_mov_b32 m0, s64
	s_nop 0
	global_load_lds_dwordx4 v150, s[62:63]
	s_add_i32 m0, s64, 0x2000
	s_nop 0
	global_load_lds_dwordx4 v154, s[62:63]
	s_mov_b32 m0, s37
	s_nop 0
	global_load_lds_dwordx4 v148, s[42:43]
	s_mov_b32 m0, s46
	s_nop 0
	global_load_lds_dwordx4 v152, s[42:43]
	s_waitcnt vmcnt(8) lgkmcnt(0)
	s_barrier
; #define PG8_STAGE(bufoff, gbase, voff) do { _Pragma("unroll") for (int _i = 0; _i < 2; ++_i) \
;         __builtin_amdgcn_global_load_lds((const unsigned*)((const char*)(gbase) + (voff)[_i]), (PG8_LAS unsigned*)(lds + (bufoff) + ldsw + _i * 8192), 16, 0, 0); } while (0)
; #define PG8_LDA(dst, b, h) do { _Pragma("unroll") for (int m = 0; m < 4; ++m) _Pragma("unroll") for (int k = 0; k < 2; ++k) dst[m][k] = *(const PG8_LAS bf16x8*)(lds + PG8_SA(b, h) + aoff + m * 2048 + k * 1024); } while (0)
; #define PG8_LDB(dst, b, h) do { _Pragma("unroll") for (int n = 0; n < 2; ++n) _Pragma("unroll") for (int k = 0; k < 2; ++k) dst[n][k] = *(const PG8_LAS bf16x8*)(lds + PG8_SB(b, h) + boff + n * 2048 + k * 1024); } while (0)
; #define PG8_MMA(ai, bj, At, Bt) do { __builtin_amdgcn_s_setprio(1); _Pragma("unroll") for (int m = 0; m < 4; ++m) _Pragma("unroll") for (int n = 0; n < 2; ++n) _Pragma("unroll") for (int k = 0; k < 2; ++k) \
;         acc[ai][bj][m][n] = __builtin_amdgcn_mfma_f32_16x16x32_bf16(Bt[n][k], At[m][k], acc[ai][bj][m][n], 0, 0, 0); __builtin_amdgcn_s_setprio(0); } while (0)
; #define PG8_WAIT_V(n) asm volatile("s_waitcnt vmcnt(" #n ")" ::: "memory")
; #define PG8_WAIT_L(n) asm volatile("s_waitcnt lgkmcnt(" #n ")" ::: "memory")
; #define PG8_BAR __builtin_amdgcn_s_barrier()
; #define PG8_SCHED __builtin_amdgcn_sched_barrier(0)
; template <class Epi, class Sched, bool ALIGN_EPI = false, bool SP2 = false>
; __device__ __forceinline__ void gemm_phase(PG8_LAS unsigned char* lds, const Gemm g, const Sched& S, const Epi& E) {
;     ...
;             PG8_WAIT_V(8); PG8_WAIT_L(0); PG8_BAR; PG8_MMA(0, 0, At, B0); PG8_MMA(0, 1, At, B1); PG8_BAR; PG8_SCHED;
;             PG8_LDA(At, 0, 1); PG8_STAGE(PG8_SB(0, 0), b2, voffB); PG8_STAGE(PG8_SB(0, 1), b2 + hstep, voffB); PG8_STAGE(PG8_SA(0, 0), a2, voffA);
;             PG8_WAIT_V(8); PG8_WAIT_L(0); PG8_BAR; PG8_MMA(1, 0, At, B0); PG8_MMA(1, 1, At, B1); PG8_BAR; PG8_SCHED;
;             PG8_LDB(B0, 1, 0); PG8_LDB(B1, 1, 1); PG8_SCHED; PG8_LDA(At, 1, 0); PG8_STAGE(PG8_SA(0, 1), a2 + hstep, voffA);
;             PG8_WAIT_V(8); PG8_WAIT_L(0); PG8_BAR; PG8_MMA(0, 0, At, B0); PG8_MMA(0, 1, At, B1); PG8_BAR; PG8_SCHED;
	v_mfma_f32_16x16x32_bf16 v[60:63], v[128:131], v[184:187], 0
	v_mfma_f32_16x16x32_bf16 v[56:59], v[136:139], v[184:187], 0
	v_mfma_f32_16x16x32_bf16 v[44:47], v[128:131], v[192:195], 0
	v_mfma_f32_16x16x32_bf16 v[40:43], v[136:139], v[192:195], 0
	v_mfma_f32_16x16x32_bf16 v[28:31], v[128:131], v[200:203], 0
	v_mfma_f32_16x16x32_bf16 v[24:27], v[136:139], v[200:203], 0
	v_mfma_f32_16x16x32_bf16 v[12:15], v[128:131], v[208:211], 0
	v_mfma_f32_16x16x32_bf16 v[8:11], v[136:139], v[208:211], 0
	v_mfma_f32_16x16x32_bf16 v[60:63], v[132:135], v[188:191], v[60:63]
	v_mfma_f32_16x16x32_bf16 v[56:59], v[140:143], v[188:191], v[56:59]
	v_mfma_f32_16x16x32_bf16 v[44:47], v[132:135], v[196:199], v[44:47]
	v_mfma_f32_16x16x32_bf16 v[40:43], v[140:143], v[196:199], v[40:43]
	v_mfma_f32_16x16x32_bf16 v[28:31], v[132:135], v[204:207], v[28:31]
	v_mfma_f32_16x16x32_bf16 v[24:27], v[140:143], v[204:207], v[24:27]
	v_mfma_f32_16x16x32_bf16 v[12:15], v[132:135], v[214:217], v[12:15]
	v_mfma_f32_16x16x32_bf16 v[8:11], v[140:143], v[214:217], v[8:11]
	v_mfma_f32_16x16x32_bf16 v[52:55], v[144:147], v[184:187], 0
	v_mfma_f32_16x16x32_bf16 v[48:51], v[168:171], v[184:187], 0
	v_mfma_f32_16x16x32_bf16 v[36:39], v[144:147], v[192:195], 0
	v_mfma_f32_16x16x32_bf16 v[32:35], v[168:171], v[192:195], 0
	v_mfma_f32_16x16x32_bf16 v[20:23], v[144:147], v[200:203], 0
	v_mfma_f32_16x16x32_bf16 v[16:19], v[168:171], v[200:203], 0
	v_mfma_f32_16x16x32_bf16 v[4:7], v[144:147], v[208:211], 0
	v_mfma_f32_16x16x32_bf16 v[0:3], v[168:171], v[208:211], 0
	v_mfma_f32_16x16x32_bf16 v[52:55], v[164:167], v[188:191], v[52:55]
	v_mfma_f32_16x16x32_bf16 v[48:51], v[180:183], v[188:191], v[48:51]
	v_mfma_f32_16x16x32_bf16 v[36:39], v[164:167], v[196:199], v[36:39]
	v_mfma_f32_16x16x32_bf16 v[32:35], v[180:183], v[196:199], v[32:35]
	v_mfma_f32_16x16x32_bf16 v[20:23], v[164:167], v[204:207], v[20:23]
	v_mfma_f32_16x16x32_bf16 v[16:19], v[180:183], v[204:207], v[16:19]
	v_mfma_f32_16x16x32_bf16 v[4:7], v[164:167], v[214:217], v[4:7]
	v_mfma_f32_16x16x32_bf16 v[0:3], v[180:183], v[214:217], v[0:3]
	s_barrier
	s_add_i32 s62, 0, 0x18000
	s_add_i32 s63, 0, 0x1c000
	v_add_u32_e32 v140, s62, v175
	v_add_u32_e32 v180, s63, v175
	ds_read_b128 v[128:131], v140
	ds_read_b128 v[132:135], v140 offset:1024
	ds_read_b128 v[136:139], v140 offset:2048
	ds_read_b128 v[140:143], v140 offset:3072
	ds_read_b128 v[144:147], v180
	ds_read_b128 v[164:167], v180 offset:1024
	ds_read_b128 v[168:171], v180 offset:2048
	ds_read_b128 v[180:183], v180 offset:3072
	s_add_u32 s84, s42, 0x80
	s_addc_u32 s85, s43, 0
	s_add_u32 s42, s42, 0x40000
	s_addc_u32 s43, s43, 0
	s_mov_b32 m0, s47
	ds_read_b128 v[184:187], v179 offset:32768
	ds_read_b128 v[188:191], v179 offset:33792
	ds_read_b128 v[192:195], v179 offset:34816
	ds_read_b128 v[196:199], v179 offset:35840
	ds_read_b128 v[200:203], v179 offset:36864
	ds_read_b128 v[204:207], v179 offset:37888
	ds_read_b128 v[208:211], v179 offset:38912
	ds_read_b128 v[214:217], v179 offset:39936
	global_load_lds_dwordx4 v148, s[42:43]
	s_mov_b32 m0, s48
	s_nop 0
	global_load_lds_dwordx4 v152, s[42:43]
	s_waitcnt vmcnt(8) lgkmcnt(0)
	s_barrier
	v_mfma_f32_16x16x32_bf16 v[124:127], v[128:131], v[184:187], v[124:127]
	v_mfma_f32_16x16x32_bf16 v[120:123], v[136:139], v[184:187], v[120:123]
	v_mfma_f32_16x16x32_bf16 v[108:111], v[128:131], v[192:195], v[108:111]
	v_mfma_f32_16x16x32_bf16 v[104:107], v[136:139], v[192:195], v[104:107]
	v_mfma_f32_16x16x32_bf16 v[92:95], v[128:131], v[200:203], v[92:95]
	v_mfma_f32_16x16x32_bf16 v[88:91], v[136:139], v[200:203], v[88:91]
	v_mfma_f32_16x16x32_bf16 v[76:79], v[128:131], v[208:211], v[76:79]
	v_mfma_f32_16x16x32_bf16 v[72:75], v[136:139], v[208:211], v[72:75]
	v_mfma_f32_16x16x32_bf16 v[124:127], v[132:135], v[188:191], v[124:127]
	v_mfma_f32_16x16x32_bf16 v[120:123], v[140:143], v[188:191], v[120:123]
	v_mfma_f32_16x16x32_bf16 v[108:111], v[132:135], v[196:199], v[108:111]
	v_mfma_f32_16x16x32_bf16 v[104:107], v[140:143], v[196:199], v[104:107]
	v_mfma_f32_16x16x32_bf16 v[92:95], v[132:135], v[204:207], v[92:95]
	v_mfma_f32_16x16x32_bf16 v[88:91], v[140:143], v[204:207], v[88:91]
	v_mfma_f32_16x16x32_bf16 v[76:79], v[132:135], v[214:217], v[76:79]
	v_mfma_f32_16x16x32_bf16 v[72:75], v[140:143], v[214:217], v[72:75]
	v_mfma_f32_16x16x32_bf16 v[116:119], v[144:147], v[184:187], v[116:119]
	v_mfma_f32_16x16x32_bf16 v[112:115], v[168:171], v[184:187], v[112:115]
	v_mfma_f32_16x16x32_bf16 v[100:103], v[144:147], v[192:195], v[100:103]
	v_mfma_f32_16x16x32_bf16 v[96:99], v[168:171], v[192:195], v[96:99]
	v_mfma_f32_16x16x32_bf16 v[84:87], v[144:147], v[200:203], v[84:87]
	v_mfma_f32_16x16x32_bf16 v[80:83], v[168:171], v[200:203], v[80:83]
	v_mfma_f32_16x16x32_bf16 v[68:71], v[144:147], v[208:211], v[68:71]
	v_mfma_f32_16x16x32_bf16 v[64:67], v[168:171], v[208:211], v[64:67]
	v_mfma_f32_16x16x32_bf16 v[116:119], v[164:167], v[188:191], v[116:119]
	v_mfma_f32_16x16x32_bf16 v[112:115], v[180:183], v[188:191], v[112:115]
	v_mfma_f32_16x16x32_bf16 v[100:103], v[164:167], v[196:199], v[100:103]
	v_mfma_f32_16x16x32_bf16 v[96:99], v[180:183], v[196:199], v[96:99]
	v_mfma_f32_16x16x32_bf16 v[84:87], v[164:167], v[204:207], v[84:87]
	v_mfma_f32_16x16x32_bf16 v[80:83], v[180:183], v[204:207], v[80:83]
	v_mfma_f32_16x16x32_bf16 v[68:71], v[164:167], v[214:217], v[68:71]
	v_mfma_f32_16x16x32_bf16 v[64:67], v[180:183], v[214:217], v[64:67]
	s_barrier
; #define PG8_STAGE(bufoff, gbase, voff) do { _Pragma("unroll") for (int _i = 0; _i < 2; ++_i) \
;         __builtin_amdgcn_global_load_lds((const unsigned*)((const char*)(gbase) + (voff)[_i]), (PG8_LAS unsigned*)(lds + (bufoff) + ldsw + _i * 8192), 16, 0, 0); } while (0)
; #define PG8_LDA(dst, b, h) do { _Pragma("unroll") for (int m = 0; m < 4; ++m) _Pragma("unroll") for (int k = 0; k < 2; ++k) dst[m][k] = *(const PG8_LAS bf16x8*)(lds + PG8_SA(b, h) + aoff + m * 2048 + k * 1024); } while (0)
; #define PG8_LDB(dst, b, h) do { _Pragma("unroll") for (int n = 0; n < 2; ++n) _Pragma("unroll") for (int k = 0; k < 2; ++k) dst[n][k] = *(const PG8_LAS bf16x8*)(lds + PG8_SB(b, h) + boff + n * 2048 + k * 1024); } while (0)
; #define PG8_MMA(ai, bj, At, Bt) do { __builtin_amdgcn_s_setprio(1); _Pragma("unroll") for (int m = 0; m < 4; ++m) _Pragma("unroll") for (int n = 0; n < 2; ++n) _Pragma("unroll") for (int k = 0; k < 2; ++k) \
;         acc[ai][bj][m][n] = __builtin_amdgcn_mfma_f32_16x16x32_bf16(Bt[n][k], At[m][k], acc[ai][bj][m][n], 0, 0, 0); __builtin_amdgcn_s_setprio(0); } while (0)
; #define PG8_WAIT_V(n) asm volatile("s_waitcnt vmcnt(" #n ")" ::: "memory")
; #define PG8_WAIT_L(n) asm volatile("s_waitcnt lgkmcnt(" #n ")" ::: "memory")
; #define PG8_BAR __builtin_amdgcn_s_barrier()
; #define PG8_SCHED __builtin_amdgcn_sched_barrier(0)
; template <class Epi, class Sched, bool ALIGN_EPI = false, bool SP2 = false>
; __device__ __forceinline__ void gemm_phase(PG8_LAS unsigned char* lds, const Gemm g, const Sched& S, const Epi& E) {
;     ...
;             PG8_WAIT_V(8); PG8_WAIT_L(0); PG8_BAR; PG8_MMA(1, 0, At, B0); PG8_MMA(1, 1, At, B1); PG8_BAR; PG8_SCHED;
;             PG8_LDB(B0, 1, 0); PG8_LDB(B1, 1, 1); PG8_SCHED; PG8_LDA(At, 1, 0); PG8_STAGE(PG8_SA(0, 1), a2 + hstep, voffA);
;             PG8_WAIT_V(8); PG8_WAIT_L(0); PG8_BAR; PG8_MMA(0, 0, At, B0); PG8_MMA(0, 1, At, B1); PG8_BAR; PG8_SCHED;
;             PG8_LDA(At, 1, 1); PG8_STAGE(PG8_SB(1, 0), b3, voffB); PG8_STAGE(PG8_SB(1, 1), b3 + hstep, voffB); PG8_STAGE(PG8_SA(1, 0), a3, voffA);
;             PG8_WAIT_V(8); PG8_WAIT_L(0); PG8_BAR; PG8_MMA(1, 0, At, B0); PG8_MMA(1, 1, At, B1); PG8_BAR; PG8_SCHED;
	s_add_i32 s42, s62, s45
	s_add_u32 s86, s40, 0x80
	s_addc_u32 s87, s41, 0
	s_mov_b32 m0, s42
	ds_read_b128 v[184:187], v179 offset:49152
	ds_read_b128 v[188:191], v179 offset:50176
	ds_read_b128 v[192:195], v179 offset:51200
	ds_read_b128 v[196:199], v179 offset:52224
	ds_read_b128 v[200:203], v179 offset:53248
	ds_read_b128 v[204:207], v179 offset:54272
	ds_read_b128 v[208:211], v179 offset:55296
	ds_read_b128 v[214:217], v179 offset:56320
	global_load_lds_dwordx4 v150, s[86:87]
	s_add_i32 m0, s42, 0x2000
	s_add_u32 s40, s40, 0x40080
	s_addc_u32 s41, s41, 0
	s_add_i32 s42, s63, s45
	global_load_lds_dwordx4 v154, s[86:87]
	s_mov_b32 m0, s42
	s_nop 0
	global_load_lds_dwordx4 v150, s[40:41]
	s_add_i32 m0, s42, 0x2000
	s_nop 0
	global_load_lds_dwordx4 v154, s[40:41]
	s_mov_b32 m0, s50
	s_nop 0
	global_load_lds_dwordx4 v148, s[84:85]
	s_mov_b32 m0, s51
	s_nop 0
	global_load_lds_dwordx4 v152, s[84:85]
	s_waitcnt vmcnt(8) lgkmcnt(0)
	s_barrier
	v_mfma_f32_16x16x32_bf16 v[60:63], v[128:131], v[184:187], v[60:63]
	v_mfma_f32_16x16x32_bf16 v[56:59], v[136:139], v[184:187], v[56:59]
	v_mfma_f32_16x16x32_bf16 v[44:47], v[128:131], v[192:195], v[44:47]
	v_mfma_f32_16x16x32_bf16 v[40:43], v[136:139], v[192:195], v[40:43]
	v_mfma_f32_16x16x32_bf16 v[28:31], v[128:131], v[200:203], v[28:31]
	v_mfma_f32_16x16x32_bf16 v[24:27], v[136:139], v[200:203], v[24:27]
	v_mfma_f32_16x16x32_bf16 v[12:15], v[128:131], v[208:211], v[12:15]
	v_mfma_f32_16x16x32_bf16 v[8:11], v[136:139], v[208:211], v[8:11]
	v_mfma_f32_16x16x32_bf16 v[60:63], v[132:135], v[188:191], v[60:63]
	v_mfma_f32_16x16x32_bf16 v[56:59], v[140:143], v[188:191], v[56:59]
	v_mfma_f32_16x16x32_bf16 v[44:47], v[132:135], v[196:199], v[44:47]
	v_mfma_f32_16x16x32_bf16 v[40:43], v[140:143], v[196:199], v[40:43]
	v_mfma_f32_16x16x32_bf16 v[28:31], v[132:135], v[204:207], v[28:31]
	v_mfma_f32_16x16x32_bf16 v[24:27], v[140:143], v[204:207], v[24:27]
	v_mfma_f32_16x16x32_bf16 v[12:15], v[132:135], v[214:217], v[12:15]
	v_mfma_f32_16x16x32_bf16 v[8:11], v[140:143], v[214:217], v[8:11]
	v_mfma_f32_16x16x32_bf16 v[52:55], v[144:147], v[184:187], v[52:55]
	v_mfma_f32_16x16x32_bf16 v[48:51], v[168:171], v[184:187], v[48:51]
	v_mfma_f32_16x16x32_bf16 v[36:39], v[144:147], v[192:195], v[36:39]
	v_mfma_f32_16x16x32_bf16 v[32:35], v[168:171], v[192:195], v[32:35]
	v_mfma_f32_16x16x32_bf16 v[20:23], v[144:147], v[200:203], v[20:23]
	v_mfma_f32_16x16x32_bf16 v[16:19], v[168:171], v[200:203], v[16:19]
	v_mfma_f32_16x16x32_bf16 v[4:7], v[144:147], v[208:211], v[4:7]
	v_mfma_f32_16x16x32_bf16 v[0:3], v[168:171], v[208:211], v[0:3]
	v_mfma_f32_16x16x32_bf16 v[52:55], v[164:167], v[188:191], v[52:55]
	v_mfma_f32_16x16x32_bf16 v[48:51], v[180:183], v[188:191], v[48:51]
	v_mfma_f32_16x16x32_bf16 v[36:39], v[164:167], v[196:199], v[36:39]
	v_mfma_f32_16x16x32_bf16 v[32:35], v[180:183], v[196:199], v[32:35]
	v_mfma_f32_16x16x32_bf16 v[20:23], v[164:167], v[204:207], v[20:23]
	v_mfma_f32_16x16x32_bf16 v[16:19], v[180:183], v[204:207], v[16:19]
	v_mfma_f32_16x16x32_bf16 v[4:7], v[164:167], v[214:217], v[4:7]
	v_mfma_f32_16x16x32_bf16 v[0:3], v[180:183], v[214:217], v[0:3]
	s_barrier
	s_add_i32 s61, s61, 2
	s_add_u32 s38, s38, 0x100
	s_addc_u32 s39, s39, 0
	s_add_u32 s59, s59, 0x100
	s_addc_u32 s60, s60, 0
	s_cmp_gt_u32 s61, 13
.LBB0_755:
	ds_read_b128 v[128:131], v177
	ds_read_b128 v[132:135], v177 offset:1024
	ds_read_b128 v[136:139], v177 offset:2048
	ds_read_b128 v[140:143], v177 offset:3072
	ds_read_b128 v[144:147], v178
	ds_read_b128 v[164:167], v178 offset:1024
	ds_read_b128 v[168:171], v178 offset:2048
	ds_read_b128 v[180:183], v178 offset:3072
	s_add_u32 s40, s38, 0xfffc0080
	s_addc_u32 s41, s39, -1
	s_cmp_eq_u32 s61, 12
	s_cselect_b32 s43, s29, s41
	s_cselect_b32 s42, s57, s40
	s_cselect_b32 s41, s27, s60
	s_cselect_b32 s40, s58, s59
	s_add_i32 m0, s37, 0xc000
	ds_read_b128 v[184:187], v179
	ds_read_b128 v[188:191], v179 offset:1024
	ds_read_b128 v[192:195], v179 offset:2048
	ds_read_b128 v[196:199], v179 offset:3072
	ds_read_b128 v[200:203], v179 offset:4096
	ds_read_b128 v[204:207], v179 offset:5120
	ds_read_b128 v[208:211], v179 offset:6144
	ds_read_b128 v[214:217], v179 offset:7168
	global_load_lds_dwordx4 v156, s[38:39]
	s_add_i32 m0, s37, 0xe000
	s_nop 0
	global_load_lds_dwordx4 v158, s[38:39]
	s_waitcnt vmcnt(8) lgkmcnt(0)
	s_barrier
	v_mfma_f32_16x16x32_bf16 v[124:127], v[128:131], v[184:187], v[124:127]
	v_mfma_f32_16x16x32_bf16 v[120:123], v[136:139], v[184:187], v[120:123]
	v_mfma_f32_16x16x32_bf16 v[108:111], v[128:131], v[192:195], v[108:111]
	v_mfma_f32_16x16x32_bf16 v[104:107], v[136:139], v[192:195], v[104:107]
	v_mfma_f32_16x16x32_bf16 v[92:95], v[128:131], v[200:203], v[92:95]
	v_mfma_f32_16x16x32_bf16 v[88:91], v[136:139], v[200:203], v[88:91]
	v_mfma_f32_16x16x32_bf16 v[76:79], v[128:131], v[208:211], v[76:79]
	v_mfma_f32_16x16x32_bf16 v[72:75], v[136:139], v[208:211], v[72:75]
	v_mfma_f32_16x16x32_bf16 v[124:127], v[132:135], v[188:191], v[124:127]
	v_mfma_f32_16x16x32_bf16 v[120:123], v[140:143], v[188:191], v[120:123]
	v_mfma_f32_16x16x32_bf16 v[108:111], v[132:135], v[196:199], v[108:111]
	v_mfma_f32_16x16x32_bf16 v[104:107], v[140:143], v[196:199], v[104:107]
	v_mfma_f32_16x16x32_bf16 v[92:95], v[132:135], v[204:207], v[92:95]
	v_mfma_f32_16x16x32_bf16 v[88:91], v[140:143], v[204:207], v[88:91]
	v_mfma_f32_16x16x32_bf16 v[76:79], v[132:135], v[214:217], v[76:79]
	v_mfma_f32_16x16x32_bf16 v[72:75], v[140:143], v[214:217], v[72:75]
	v_mfma_f32_16x16x32_bf16 v[116:119], v[144:147], v[184:187], v[116:119]
	v_mfma_f32_16x16x32_bf16 v[112:115], v[168:171], v[184:187], v[112:115]
	v_mfma_f32_16x16x32_bf16 v[100:103], v[144:147], v[192:195], v[100:103]
	v_mfma_f32_16x16x32_bf16 v[96:99], v[168:171], v[192:195], v[96:99]
	v_mfma_f32_16x16x32_bf16 v[84:87], v[144:147], v[200:203], v[84:87]
	v_mfma_f32_16x16x32_bf16 v[80:83], v[168:171], v[200:203], v[80:83]
	v_mfma_f32_16x16x32_bf16 v[68:71], v[144:147], v[208:211], v[68:71]
	v_mfma_f32_16x16x32_bf16 v[64:67], v[168:171], v[208:211], v[64:67]
	v_mfma_f32_16x16x32_bf16 v[116:119], v[164:167], v[188:191], v[116:119]
	v_mfma_f32_16x16x32_bf16 v[112:115], v[180:183], v[188:191], v[112:115]
	v_mfma_f32_16x16x32_bf16 v[100:103], v[164:167], v[196:199], v[100:103]
	v_mfma_f32_16x16x32_bf16 v[96:99], v[180:183], v[196:199], v[96:99]
	v_mfma_f32_16x16x32_bf16 v[84:87], v[164:167], v[204:207], v[84:87]
	v_mfma_f32_16x16x32_bf16 v[80:83], v[180:183], v[204:207], v[80:83]
	v_mfma_f32_16x16x32_bf16 v[68:71], v[164:167], v[214:217], v[68:71]
	v_mfma_f32_16x16x32_bf16 v[64:67], v[180:183], v[214:217], v[64:67]
	s_barrier
; #define PG8_STAGE(bufoff, gbase, voff) do { _Pragma("unroll") for (int _i = 0; _i < 2; ++_i) \
;         __builtin_amdgcn_global_load_lds((const unsigned*)((const char*)(gbase) + (voff)[_i]), (PG8_LAS unsigned*)(lds + (bufoff) + ldsw + _i * 8192), 16, 0, 0); } while (0)
; #define PG8_LDA(dst, b, h) do { _Pragma("unroll") for (int m = 0; m < 4; ++m) _Pragma("unroll") for (int k = 0; k < 2; ++k) dst[m][k] = *(const PG8_LAS bf16x8*)(lds + PG8_SA(b, h) + aoff + m * 2048 + k * 1024); } while (0)
; #define PG8_LDB(dst, b, h) do { _Pragma("unroll") for (int n = 0; n < 2; ++n) _Pragma("unroll") for (int k = 0; k < 2; ++k) dst[n][k] = *(const PG8_LAS bf16x8*)(lds + PG8_SB(b, h) + boff + n * 2048 + k * 1024); } while (0)
; #define PG8_MMA(ai, bj, At, Bt) do { __builtin_amdgcn_s_setprio(1); _Pragma("unroll") for (int m = 0; m < 4; ++m) _Pragma("unroll") for (int n = 0; n < 2; ++n) _Pragma("unroll") for (int k = 0; k < 2; ++k) \
;         acc[ai][bj][m][n] = __builtin_amdgcn_mfma_f32_16x16x32_bf16(Bt[n][k], At[m][k], acc[ai][bj][m][n], 0, 0, 0); __builtin_amdgcn_s_setprio(0); } while (0)
; #define PG8_WAIT_V(n) asm volatile("s_waitcnt vmcnt(" #n ")" ::: "memory")
; #define PG8_WAIT_L(n) asm volatile("s_waitcnt lgkmcnt(" #n ")" ::: "memory")
; #define PG8_BAR __builtin_amdgcn_s_barrier()
; #define PG8_SCHED __builtin_amdgcn_sched_barrier(0)
; template <class Epi, class Sched, bool ALIGN_EPI = false, bool SP2 = false>
; __device__ __forceinline__ void gemm_phase(PG8_LAS unsigned char* lds, const Gemm g, const Sched& S, const Epi& E) {
;     ...
;             PG8_LDA(At, 0, 1); PG8_STAGE(PG8_SB(0, 0), b2, voffB); PG8_STAGE(PG8_SB(0, 1), b2 + hstep, voffB); PG8_STAGE(PG8_SA(0, 0), a2, voffA);
;             PG8_WAIT_V(8); PG8_WAIT_L(0); PG8_BAR; PG8_MMA(1, 0, At, B0); PG8_MMA(1, 1, At, B1); PG8_BAR; PG8_SCHED;
;             PG8_LDB(B0, 1, 0); PG8_LDB(B1, 1, 1); PG8_SCHED; PG8_LDA(At, 1, 0); PG8_STAGE(PG8_SA(0, 1), a2 + hstep, voffA);
;             PG8_WAIT_V(8); PG8_WAIT_L(0); PG8_BAR; PG8_MMA(0, 0, At, B0); PG8_MMA(0, 1, At, B1); PG8_BAR; PG8_SCHED;
	s_add_i32 s62, s54, s45
	s_mov_b32 m0, s62
	ds_read_b128 v[184:187], v179 offset:16384
	ds_read_b128 v[188:191], v179 offset:17408
	ds_read_b128 v[192:195], v179 offset:18432
	ds_read_b128 v[196:199], v179 offset:19456
	ds_read_b128 v[200:203], v179 offset:20480
	ds_read_b128 v[204:207], v179 offset:21504
	ds_read_b128 v[208:211], v179 offset:22528
	ds_read_b128 v[214:217], v179 offset:23552
	global_load_lds_dwordx4 v150, s[40:41]
	s_add_i32 m0, s62, 0x2000
	s_add_u32 s62, s40, 0x40000
	s_addc_u32 s63, s41, 0
	s_add_i32 s64, s55, s45
	global_load_lds_dwordx4 v154, s[40:41]
	s_mov_b32 m0, s64
	s_nop 0
	global_load_lds_dwordx4 v150, s[62:63]
	s_add_i32 m0, s64, 0x2000
	s_nop 0
	global_load_lds_dwordx4 v154, s[62:63]
	s_mov_b32 m0, s37
	s_nop 0
	global_load_lds_dwordx4 v148, s[42:43]
	s_mov_b32 m0, s46
	s_nop 0
	global_load_lds_dwordx4 v152, s[42:43]
	s_waitcnt vmcnt(8) lgkmcnt(0)
	s_barrier
	v_mfma_f32_16x16x32_bf16 v[60:63], v[128:131], v[184:187], v[60:63]
	v_mfma_f32_16x16x32_bf16 v[56:59], v[136:139], v[184:187], v[56:59]
	v_mfma_f32_16x16x32_bf16 v[44:47], v[128:131], v[192:195], v[44:47]
	v_mfma_f32_16x16x32_bf16 v[40:43], v[136:139], v[192:195], v[40:43]
	v_mfma_f32_16x16x32_bf16 v[28:31], v[128:131], v[200:203], v[28:31]
	v_mfma_f32_16x16x32_bf16 v[24:27], v[136:139], v[200:203], v[24:27]
	v_mfma_f32_16x16x32_bf16 v[12:15], v[128:131], v[208:211], v[12:15]
	v_mfma_f32_16x16x32_bf16 v[8:11], v[136:139], v[208:211], v[8:11]
	v_mfma_f32_16x16x32_bf16 v[60:63], v[132:135], v[188:191], v[60:63]
	v_mfma_f32_16x16x32_bf16 v[56:59], v[140:143], v[188:191], v[56:59]
	v_mfma_f32_16x16x32_bf16 v[44:47], v[132:135], v[196:199], v[44:47]
	v_mfma_f32_16x16x32_bf16 v[40:43], v[140:143], v[196:199], v[40:43]
	v_mfma_f32_16x16x32_bf16 v[28:31], v[132:135], v[204:207], v[28:31]
	v_mfma_f32_16x16x32_bf16 v[24:27], v[140:143], v[204:207], v[24:27]
	v_mfma_f32_16x16x32_bf16 v[12:15], v[132:135], v[214:217], v[12:15]
	v_mfma_f32_16x16x32_bf16 v[8:11], v[140:143], v[214:217], v[8:11]
	v_mfma_f32_16x16x32_bf16 v[52:55], v[144:147], v[184:187], v[52:55]
	v_mfma_f32_16x16x32_bf16 v[48:51], v[168:171], v[184:187], v[48:51]
	v_mfma_f32_16x16x32_bf16 v[36:39], v[144:147], v[192:195], v[36:39]
	v_mfma_f32_16x16x32_bf16 v[32:35], v[168:171], v[192:195], v[32:35]
	v_mfma_f32_16x16x32_bf16 v[20:23], v[144:147], v[200:203], v[20:23]
	v_mfma_f32_16x16x32_bf16 v[16:19], v[168:171], v[200:203], v[16:19]
	v_mfma_f32_16x16x32_bf16 v[4:7], v[144:147], v[208:211], v[4:7]
	v_mfma_f32_16x16x32_bf16 v[0:3], v[168:171], v[208:211], v[0:3]
	v_mfma_f32_16x16x32_bf16 v[52:55], v[164:167], v[188:191], v[52:55]
	v_mfma_f32_16x16x32_bf16 v[48:51], v[180:183], v[188:191], v[48:51]
	v_mfma_f32_16x16x32_bf16 v[36:39], v[164:167], v[196:199], v[36:39]
	v_mfma_f32_16x16x32_bf16 v[32:35], v[180:183], v[196:199], v[32:35]
	v_mfma_f32_16x16x32_bf16 v[20:23], v[164:167], v[204:207], v[20:23]
	v_mfma_f32_16x16x32_bf16 v[16:19], v[180:183], v[204:207], v[16:19]
	v_mfma_f32_16x16x32_bf16 v[4:7], v[164:167], v[214:217], v[4:7]
	v_mfma_f32_16x16x32_bf16 v[0:3], v[180:183], v[214:217], v[0:3]
	s_barrier
	s_add_i32 s62, 0, 0x18000
	s_add_i32 s63, 0, 0x1c000
	v_add_u32_e32 v140, s62, v175
	v_add_u32_e32 v180, s63, v175
	ds_read_b128 v[128:131], v140
	ds_read_b128 v[132:135], v140 offset:1024
	ds_read_b128 v[136:139], v140 offset:2048
	ds_read_b128 v[140:143], v140 offset:3072
	ds_read_b128 v[144:147], v180
	ds_read_b128 v[164:167], v180 offset:1024
	ds_read_b128 v[168:171], v180 offset:2048
	ds_read_b128 v[180:183], v180 offset:3072
	s_add_u32 s84, s42, 0x80
	s_addc_u32 s85, s43, 0
	s_add_u32 s42, s42, 0x40000
	s_addc_u32 s43, s43, 0
	s_mov_b32 m0, s47
	ds_read_b128 v[184:187], v179 offset:32768
	ds_read_b128 v[188:191], v179 offset:33792
	ds_read_b128 v[192:195], v179 offset:34816
	ds_read_b128 v[196:199], v179 offset:35840
	ds_read_b128 v[200:203], v179 offset:36864
	ds_read_b128 v[204:207], v179 offset:37888
	ds_read_b128 v[208:211], v179 offset:38912
	ds_read_b128 v[214:217], v179 offset:39936
	global_load_lds_dwordx4 v148, s[42:43]
	s_mov_b32 m0, s48
	s_nop 0
	global_load_lds_dwordx4 v152, s[42:43]
	s_waitcnt vmcnt(8) lgkmcnt(0)
	s_barrier
	v_mfma_f32_16x16x32_bf16 v[124:127], v[128:131], v[184:187], v[124:127]
	v_mfma_f32_16x16x32_bf16 v[120:123], v[136:139], v[184:187], v[120:123]
	v_mfma_f32_16x16x32_bf16 v[108:111], v[128:131], v[192:195], v[108:111]
	v_mfma_f32_16x16x32_bf16 v[104:107], v[136:139], v[192:195], v[104:107]
	v_mfma_f32_16x16x32_bf16 v[92:95], v[128:131], v[200:203], v[92:95]
	v_mfma_f32_16x16x32_bf16 v[88:91], v[136:139], v[200:203], v[88:91]
	v_mfma_f32_16x16x32_bf16 v[76:79], v[128:131], v[208:211], v[76:79]
	v_mfma_f32_16x16x32_bf16 v[72:75], v[136:139], v[208:211], v[72:75]
	v_mfma_f32_16x16x32_bf16 v[124:127], v[132:135], v[188:191], v[124:127]
	v_mfma_f32_16x16x32_bf16 v[120:123], v[140:143], v[188:191], v[120:123]
	v_mfma_f32_16x16x32_bf16 v[108:111], v[132:135], v[196:199], v[108:111]
	v_mfma_f32_16x16x32_bf16 v[104:107], v[140:143], v[196:199], v[104:107]
	v_mfma_f32_16x16x32_bf16 v[92:95], v[132:135], v[204:207], v[92:95]
	v_mfma_f32_16x16x32_bf16 v[88:91], v[140:143], v[204:207], v[88:91]
	v_mfma_f32_16x16x32_bf16 v[76:79], v[132:135], v[214:217], v[76:79]
	v_mfma_f32_16x16x32_bf16 v[72:75], v[140:143], v[214:217], v[72:75]
	v_mfma_f32_16x16x32_bf16 v[116:119], v[144:147], v[184:187], v[116:119]
	v_mfma_f32_16x16x32_bf16 v[112:115], v[168:171], v[184:187], v[112:115]
	v_mfma_f32_16x16x32_bf16 v[100:103], v[144:147], v[192:195], v[100:103]
	v_mfma_f32_16x16x32_bf16 v[96:99], v[168:171], v[192:195], v[96:99]
	v_mfma_f32_16x16x32_bf16 v[84:87], v[144:147], v[200:203], v[84:87]
	v_mfma_f32_16x16x32_bf16 v[80:83], v[168:171], v[200:203], v[80:83]
	v_mfma_f32_16x16x32_bf16 v[68:71], v[144:147], v[208:211], v[68:71]
	v_mfma_f32_16x16x32_bf16 v[64:67], v[168:171], v[208:211], v[64:67]
	v_mfma_f32_16x16x32_bf16 v[116:119], v[164:167], v[188:191], v[116:119]
	v_mfma_f32_16x16x32_bf16 v[112:115], v[180:183], v[188:191], v[112:115]
	v_mfma_f32_16x16x32_bf16 v[100:103], v[164:167], v[196:199], v[100:103]
	v_mfma_f32_16x16x32_bf16 v[96:99], v[180:183], v[196:199], v[96:99]
	v_mfma_f32_16x16x32_bf16 v[84:87], v[164:167], v[204:207], v[84:87]
	v_mfma_f32_16x16x32_bf16 v[80:83], v[180:183], v[204:207], v[80:83]
	v_mfma_f32_16x16x32_bf16 v[68:71], v[164:167], v[214:217], v[68:71]
	v_mfma_f32_16x16x32_bf16 v[64:67], v[180:183], v[214:217], v[64:67]
	s_barrier
; __device__ __forceinline__ float bf_lo(unsigned w) { return __uint_as_float(w << 16); }
; __device__ __forceinline__ float bf_hi(unsigned w) { return __uint_as_float(w & 0xffff0000u); }
; __device__ __forceinline__ u32x4 pack8(const f32x4 a, const f32x4 b) { u32x4 w; w.x = cvt_pk_bf16(a[0], a[1]); w.y = cvt_pk_bf16(a[2], a[3]); w.z = cvt_pk_bf16(b[0], b[1]); w.w = cvt_pk_bf16(b[2], b[3]); return w; }
; #define PG8_WAIT_V(n) asm volatile("s_waitcnt vmcnt(" #n ")" ::: "memory")
; #define PG8_WAIT_L(n) asm volatile("s_waitcnt lgkmcnt(" #n ")" ::: "memory")
;     __device__ __forceinline__ void operator()(const f32x4 (&acc)[2][2][4][2], const Unit& u, int wr, int wc, int fr, int fq) const {
;         const int row0 = u.pm * BM + wr * 64 + fr, col0 = u.pn * BM + wc * 32 + 8 * fq;
; #pragma unroll
;         for (int ai = 0; ai < 2; ++ai) { u32x4 gw[4][2], pw[4][2];
; #pragma unroll
;             for (int m = 0; m < 4; ++m) { const size_t off = (size_t)(row0 + ai * HALF + m * 16) * 2048 + col0;
; #pragma unroll
;                 for (int bj = 0; bj < 2; ++bj) { gw[m][bj] = *(const u32x4*)(G + off + bj * HALF); if (PASS == 1) pw[m][bj] = *(const u32x4*)(MIX + off + bj * HALF); } }
; #pragma unroll
;             for (int m = 0; m < 4; ++m) { const size_t off = (size_t)(row0 + ai * HALF + m * 16) * 2048 + col0;
; #pragma unroll
;                 for (int bj = 0; bj < 2; ++bj) { const u32x4 g4 = gw[m][bj];
;                     f32x4 v0 = (f32x4){bf_lo(g4.x), bf_hi(g4.x), bf_lo(g4.y), bf_hi(g4.y)} * acc[ai][bj][m][0], v1 = (f32x4){bf_lo(g4.z), bf_hi(g4.z), bf_lo(g4.w), bf_hi(g4.w)} * acc[ai][bj][m][1];
;                     if (PASS == 1) { const u32x4 p4 = pw[m][bj]; v0 += (f32x4){bf_lo(p4.x), bf_hi(p4.x), bf_lo(p4.y), bf_hi(p4.y)}; v1 += (f32x4){bf_lo(p4.z), bf_hi(p4.z), bf_lo(p4.w), bf_hi(p4.w)}; }
;                     *(u32x4*)(MIX + off + bj * HALF) = pack8(v0, v1); } } }
; template <class Epi, class Sched, bool ALIGN_EPI = false, bool SP2 = false>
; __device__ __forceinline__ void gemm_phase(PG8_LAS unsigned char* lds, const Gemm g, const Sched& S, const Epi& E) {
;     ...
;             PG8_LDA(At, 1, 1); PG8_STAGE(PG8_SB(1, 0), b3, voffB); PG8_STAGE(PG8_SB(1, 1), b3 + hstep, voffB); PG8_STAGE(PG8_SA(1, 0), a3, voffA);
;             PG8_WAIT_V(8); PG8_WAIT_L(0); PG8_BAR; PG8_MMA(1, 0, At, B0); PG8_MMA(1, 1, At, B1); PG8_BAR; PG8_SCHED;
	s_add_i32 s42, s62, s45
	s_add_u32 s86, s40, 0x80
	s_addc_u32 s87, s41, 0
	s_mov_b32 m0, s42
	ds_read_b128 v[184:187], v179 offset:49152
	ds_read_b128 v[188:191], v179 offset:50176
	ds_read_b128 v[192:195], v179 offset:51200
	ds_read_b128 v[196:199], v179 offset:52224
	ds_read_b128 v[200:203], v179 offset:53248
	ds_read_b128 v[204:207], v179 offset:54272
	ds_read_b128 v[208:211], v179 offset:55296
	ds_read_b128 v[214:217], v179 offset:56320
	global_load_lds_dwordx4 v150, s[86:87]
	s_add_i32 m0, s42, 0x2000
	s_add_u32 s40, s40, 0x40080
	s_addc_u32 s41, s41, 0
	s_add_i32 s42, s63, s45
	global_load_lds_dwordx4 v154, s[86:87]
	s_mov_b32 m0, s42
	s_nop 0
	global_load_lds_dwordx4 v150, s[40:41]
	s_add_i32 m0, s42, 0x2000
	s_nop 0
	global_load_lds_dwordx4 v154, s[40:41]
	s_mov_b32 m0, s50
	s_nop 0
	global_load_lds_dwordx4 v148, s[84:85]
	s_mov_b32 m0, s51
	s_nop 0
	global_load_lds_dwordx4 v152, s[84:85]
	s_waitcnt vmcnt(8) lgkmcnt(0)
	s_barrier
	v_mfma_f32_16x16x32_bf16 v[60:63], v[128:131], v[184:187], v[60:63]
	v_mfma_f32_16x16x32_bf16 v[56:59], v[136:139], v[184:187], v[56:59]
	v_mfma_f32_16x16x32_bf16 v[44:47], v[128:131], v[192:195], v[44:47]
	v_mfma_f32_16x16x32_bf16 v[40:43], v[136:139], v[192:195], v[40:43]
	v_mfma_f32_16x16x32_bf16 v[28:31], v[128:131], v[200:203], v[28:31]
	v_mfma_f32_16x16x32_bf16 v[24:27], v[136:139], v[200:203], v[24:27]
	v_mfma_f32_16x16x32_bf16 v[12:15], v[128:131], v[208:211], v[12:15]
	v_mfma_f32_16x16x32_bf16 v[8:11], v[136:139], v[208:211], v[8:11]
	v_mfma_f32_16x16x32_bf16 v[60:63], v[132:135], v[188:191], v[60:63]
	v_mfma_f32_16x16x32_bf16 v[56:59], v[140:143], v[188:191], v[56:59]
	v_mfma_f32_16x16x32_bf16 v[44:47], v[132:135], v[196:199], v[44:47]
	v_mfma_f32_16x16x32_bf16 v[40:43], v[140:143], v[196:199], v[40:43]
	v_mfma_f32_16x16x32_bf16 v[28:31], v[132:135], v[204:207], v[28:31]
	v_mfma_f32_16x16x32_bf16 v[24:27], v[140:143], v[204:207], v[24:27]
	v_mfma_f32_16x16x32_bf16 v[12:15], v[132:135], v[214:217], v[12:15]
	v_mfma_f32_16x16x32_bf16 v[8:11], v[140:143], v[214:217], v[8:11]
	v_mfma_f32_16x16x32_bf16 v[52:55], v[144:147], v[184:187], v[52:55]
	v_mfma_f32_16x16x32_bf16 v[48:51], v[168:171], v[184:187], v[48:51]
	v_mfma_f32_16x16x32_bf16 v[36:39], v[144:147], v[192:195], v[36:39]
	v_mfma_f32_16x16x32_bf16 v[32:35], v[168:171], v[192:195], v[32:35]
	v_mfma_f32_16x16x32_bf16 v[20:23], v[144:147], v[200:203], v[20:23]
	v_mfma_f32_16x16x32_bf16 v[16:19], v[168:171], v[200:203], v[16:19]
	v_mfma_f32_16x16x32_bf16 v[4:7], v[144:147], v[208:211], v[4:7]
	v_mfma_f32_16x16x32_bf16 v[0:3], v[168:171], v[208:211], v[0:3]
	v_mfma_f32_16x16x32_bf16 v[52:55], v[164:167], v[188:191], v[52:55]
	v_mfma_f32_16x16x32_bf16 v[48:51], v[180:183], v[188:191], v[48:51]
	v_mfma_f32_16x16x32_bf16 v[36:39], v[164:167], v[196:199], v[36:39]
	v_mfma_f32_16x16x32_bf16 v[32:35], v[180:183], v[196:199], v[32:35]
	v_mfma_f32_16x16x32_bf16 v[20:23], v[164:167], v[204:207], v[20:23]
	v_mfma_f32_16x16x32_bf16 v[16:19], v[180:183], v[204:207], v[16:19]
	v_mfma_f32_16x16x32_bf16 v[4:7], v[164:167], v[214:217], v[4:7]
	v_mfma_f32_16x16x32_bf16 v[0:3], v[180:183], v[214:217], v[0:3]
	s_barrier
	s_add_i32 s61, s61, 2
	s_add_u32 s38, s38, 0x100
	s_addc_u32 s39, s39, 0
	s_add_u32 s59, s59, 0x100
	s_addc_u32 s60, s60, 0
	s_cmp_gt_u32 s61, 13
	s_cbranch_scc0 .LBB0_755
	v_lshl_add_u32 v168, s36, 8, v174
	v_lshl_or_b32 v166, s56, 8, v176
	v_ashrrev_i32_e32 v169, 31, v168
	v_ashrrev_i32_e32 v167, 31, v166
	v_lshlrev_b64 v[128:129], 11, v[168:169]
	v_lshl_add_u64 v[128:129], v[128:129], 0, v[166:167]
	v_lshlrev_b64 v[128:129], 1, v[128:129]
	v_lshl_add_u64 v[130:131], s[12:13], 0, v[128:129]
	global_load_dwordx4 v[180:183], v[130:131], off
	v_lshl_add_u64 v[128:129], s[14:15], 0, v[128:129]
	v_or_b32_e32 v212, 16, v168
	global_load_dwordx4 v[184:187], v[128:129], off
	global_load_dwordx4 v[188:191], v[130:131], off offset:256
	global_load_dwordx4 v[192:195], v[128:129], off offset:256
	v_ashrrev_i32_e32 v213, 31, v212
	v_lshlrev_b64 v[128:129], 11, v[212:213]
	v_lshl_add_u64 v[128:129], v[128:129], 0, v[166:167]
	v_lshlrev_b64 v[128:129], 1, v[128:129]
	v_lshl_add_u64 v[130:131], s[12:13], 0, v[128:129]
	v_lshl_add_u64 v[128:129], s[14:15], 0, v[128:129]
	global_load_dwordx4 v[196:199], v[130:131], off
	global_load_dwordx4 v[200:203], v[128:129], off
	v_or_b32_e32 v172, 32, v168
	v_or_b32_e32 v170, 48, v168
	v_ashrrev_i32_e32 v173, 31, v172
	v_ashrrev_i32_e32 v171, 31, v170
	v_lshlrev_b64 v[132:133], 12, v[168:169]
	v_lshlrev_b64 v[134:135], 11, v[172:173]
	v_lshlrev_b64 v[136:137], 11, v[170:171]
	v_lshlrev_b64 v[164:165], 1, v[166:167]
	v_lshl_add_u64 v[132:133], s[14:15], 0, v[132:133]
	v_lshl_add_u64 v[134:135], v[134:135], 0, v[166:167]
	v_lshl_add_u64 v[136:137], v[136:137], 0, v[166:167]
	v_lshl_add_u64 v[218:219], v[132:133], 0, v[164:165]
	v_lshlrev_b64 v[132:133], 1, v[134:135]
	v_lshlrev_b64 v[134:135], 1, v[136:137]
	v_lshl_add_u64 v[136:137], s[12:13], 0, v[132:133]
	v_lshl_add_u64 v[132:133], s[14:15], 0, v[132:133]
	v_lshl_add_u64 v[138:139], s[12:13], 0, v[134:135]
	v_lshl_add_u64 v[230:231], s[14:15], 0, v[134:135]
	global_load_dwordx4 v[204:207], v[130:131], off offset:256
	global_load_dwordx4 v[208:211], v[128:129], off offset:256
	global_load_dwordx4 v[214:217], v[136:137], off
	global_load_dwordx4 v[222:225], v[136:137], off offset:256
	global_load_dwordx4 v[232:235], v[132:133], off
	global_load_dwordx4 v[144:147], v[132:133], off offset:256
	global_load_dwordx4 v[140:143], v[138:139], off
	s_nop 0
	global_load_dwordx4 v[132:135], v[138:139], off offset:256
	s_nop 0
	global_load_dwordx4 v[136:139], v[230:231], off
	global_load_dwordx4 v[128:131], v[230:231], off offset:256
	s_and_b64 vcc, exec, s[10:11]
	s_mov_b32 s56, s26
	s_mov_b32 s36, s28
	s_mov_b64 s[40:41], s[34:35]
	s_mov_b64 s[38:39], s[30:31]
	s_waitcnt vmcnt(0)
; __device__ __forceinline__ float bf_lo(unsigned w) { return __uint_as_float(w << 16); }
; __device__ __forceinline__ float bf_hi(unsigned w) { return __uint_as_float(w & 0xffff0000u); }
; __device__ __forceinline__ u32x4 pack8(const f32x4 a, const f32x4 b) { u32x4 w; w.x = cvt_pk_bf16(a[0], a[1]); w.y = cvt_pk_bf16(a[2], a[3]); w.z = cvt_pk_bf16(b[0], b[1]); w.w = cvt_pk_bf16(b[2], b[3]); return w; }
;     __device__ __forceinline__ void operator()(const f32x4 (&acc)[2][2][4][2], const Unit& u, int wr, int wc, int fr, int fq) const {
;     ...
;         for (int ai = 0; ai < 2; ++ai) { u32x4 gw[4][2], pw[4][2];
; #pragma unroll
;             for (int m = 0; m < 4; ++m) { const size_t off = (size_t)(row0 + ai * HALF + m * 16) * 2048 + col0;
; #pragma unroll
;                 for (int bj = 0; bj < 2; ++bj) { gw[m][bj] = *(const u32x4*)(G + off + bj * HALF); if (PASS == 1) pw[m][bj] = *(const u32x4*)(MIX + off + bj * HALF); } }
; #pragma unroll
;             for (int m = 0; m < 4; ++m) { const size_t off = (size_t)(row0 + ai * HALF + m * 16) * 2048 + col0;
; #pragma unroll
;                 for (int bj = 0; bj < 2; ++bj) { const u32x4 g4 = gw[m][bj];
;                     f32x4 v0 = (f32x4){bf_lo(g4.x), bf_hi(g4.x), bf_lo(g4.y), bf_hi(g4.y)} * acc[ai][bj][m][0], v1 = (f32x4){bf_lo(g4.z), bf_hi(g4.z), bf_lo(g4.w), bf_hi(g4.w)} * acc[ai][bj][m][1];
;                     if (PASS == 1) { const u32x4 p4 = pw[m][bj]; v0 += (f32x4){bf_lo(p4.x), bf_hi(p4.x), bf_lo(p4.y), bf_hi(p4.y)}; v1 += (f32x4){bf_lo(p4.z), bf_hi(p4.z), bf_lo(p4.w), bf_hi(p4.w)}; }
;                     *(u32x4*)(MIX + off + bj * HALF) = pack8(v0, v1); } } }
	v_lshlrev_b32_e32 v230, 16, v180
	v_and_b32_e32 v231, 0xffff0000, v180
	v_lshlrev_b32_e32 v180, 16, v181
	v_and_b32_e32 v181, 0xffff0000, v181
	v_lshlrev_b32_e32 v236, 16, v182
	v_and_b32_e32 v237, 0xffff0000, v182
	v_lshlrev_b32_e32 v182, 16, v183
	v_and_b32_e32 v183, 0xffff0000, v183
	v_lshlrev_b32_e32 v238, 16, v184
	v_and_b32_e32 v239, 0xffff0000, v184
	v_lshlrev_b32_e32 v184, 16, v185
	v_and_b32_e32 v185, 0xffff0000, v185
	v_lshlrev_b32_e32 v240, 16, v186
	v_and_b32_e32 v241, 0xffff0000, v186
	v_lshlrev_b32_e32 v186, 16, v187
	v_and_b32_e32 v187, 0xffff0000, v187
	v_lshlrev_b32_e32 v242, 16, v188
	v_and_b32_e32 v243, 0xffff0000, v188
	v_lshlrev_b32_e32 v188, 16, v189
	v_and_b32_e32 v189, 0xffff0000, v189
	v_lshlrev_b32_e32 v246, 16, v192
	v_and_b32_e32 v247, 0xffff0000, v192
	v_lshlrev_b32_e32 v192, 16, v193
	v_and_b32_e32 v193, 0xffff0000, v193
	v_pk_fma_f32 v[126:127], v[126:127], v[180:181], v[184:185]
	v_pk_fma_f32 v[124:125], v[124:125], v[230:231], v[238:239]
	v_pk_fma_f32 v[122:123], v[122:123], v[182:183], v[186:187]
	v_pk_fma_f32 v[120:121], v[120:121], v[236:237], v[240:241]
	v_pk_fma_f32 v[180:181], v[118:119], v[188:189], v[192:193]
	v_pk_fma_f32 v[182:183], v[116:117], v[242:243], v[246:247]
	v_cvt_pk_bf16_f32 v116, v124, v125
	v_cvt_pk_bf16_f32 v117, v126, v127
	v_cvt_pk_bf16_f32 v118, v120, v121
	v_cvt_pk_bf16_f32 v119, v122, v123
	v_lshlrev_b32_e32 v244, 16, v190
	v_and_b32_e32 v245, 0xffff0000, v190
	v_lshlrev_b32_e32 v190, 16, v191
	v_and_b32_e32 v191, 0xffff0000, v191
	v_lshlrev_b32_e32 v248, 16, v194
	global_store_dwordx4 v[218:219], v[116:119], off
	v_and_b32_e32 v249, 0xffff0000, v194
	v_lshlrev_b32_e32 v122, 16, v200
	v_lshlrev_b32_e32 v116, 16, v195
	v_and_b32_e32 v117, 0xffff0000, v195
	v_pk_fma_f32 v[116:117], v[114:115], v[190:191], v[116:117]
	v_pk_fma_f32 v[114:115], v[112:113], v[244:245], v[248:249]
	v_cvt_pk_bf16_f32 v112, v182, v183
	v_cvt_pk_bf16_f32 v113, v180, v181
	v_cvt_pk_bf16_f32 v114, v114, v115
	v_cvt_pk_bf16_f32 v115, v116, v117
	global_store_dwordx4 v[218:219], v[112:115], off offset:256
	v_lshlrev_b32_e32 v116, 16, v197
	v_and_b32_e32 v117, 0xffff0000, v197
	v_lshlrev_b32_e32 v114, 16, v196
	v_and_b32_e32 v115, 0xffff0000, v196
	v_and_b32_e32 v123, 0xffff0000, v200
	v_lshlrev_b32_e32 v124, 16, v201
	v_and_b32_e32 v125, 0xffff0000, v201
	v_lshlrev_b64 v[112:113], 12, v[212:213]
	v_lshlrev_b32_e32 v118, 16, v198
	v_and_b32_e32 v119, 0xffff0000, v198
	v_lshlrev_b32_e32 v120, 16, v199
	v_and_b32_e32 v121, 0xffff0000, v199
	v_pk_fma_f32 v[110:111], v[110:111], v[116:117], v[124:125]
	v_pk_fma_f32 v[108:109], v[108:109], v[114:115], v[122:123]
	v_lshlrev_b32_e32 v114, 16, v202
	v_and_b32_e32 v115, 0xffff0000, v202
	v_lshlrev_b32_e32 v116, 16, v203
	v_and_b32_e32 v117, 0xffff0000, v203
	v_pk_fma_f32 v[116:117], v[106:107], v[120:121], v[116:117]
	v_pk_fma_f32 v[106:107], v[104:105], v[118:119], v[114:115]
	v_cvt_pk_bf16_f32 v104, v108, v109
	v_lshl_add_u64 v[108:109], s[14:15], 0, v[112:113]
	v_cvt_pk_bf16_f32 v105, v110, v111
	v_cvt_pk_bf16_f32 v106, v106, v107
	v_cvt_pk_bf16_f32 v107, v116, v117
	v_lshl_add_u64 v[108:109], v[108:109], 0, v[164:165]
	global_store_dwordx4 v[108:109], v[104:107], off
	v_lshlrev_b32_e32 v114, 16, v208
	v_and_b32_e32 v115, 0xffff0000, v208
	v_lshlrev_b32_e32 v104, 16, v204
	v_and_b32_e32 v105, 0xffff0000, v204
	v_lshlrev_b32_e32 v106, 16, v205
	v_and_b32_e32 v107, 0xffff0000, v205
	v_lshlrev_b32_e32 v116, 16, v209
	v_and_b32_e32 v117, 0xffff0000, v209
	v_lshlrev_b32_e32 v110, 16, v206
	v_and_b32_e32 v111, 0xffff0000, v206
	v_lshlrev_b32_e32 v112, 16, v207
	v_and_b32_e32 v113, 0xffff0000, v207
	v_pk_fma_f32 v[102:103], v[102:103], v[106:107], v[116:117]
	v_pk_fma_f32 v[100:101], v[100:101], v[104:105], v[114:115]
	v_lshlrev_b32_e32 v104, 16, v210
	v_and_b32_e32 v105, 0xffff0000, v210
	v_lshlrev_b32_e32 v106, 16, v211
	v_and_b32_e32 v107, 0xffff0000, v211
	v_pk_fma_f32 v[106:107], v[98:99], v[112:113], v[106:107]
	v_pk_fma_f32 v[98:99], v[96:97], v[110:111], v[104:105]
	v_cvt_pk_bf16_f32 v96, v100, v101
	v_cvt_pk_bf16_f32 v97, v102, v103
	v_cvt_pk_bf16_f32 v98, v98, v99
	v_cvt_pk_bf16_f32 v99, v106, v107
	global_store_dwordx4 v[108:109], v[96:99], off offset:256
	v_lshlrev_b32_e32 v100, 16, v215
	v_and_b32_e32 v101, 0xffff0000, v215
	v_lshlrev_b32_e32 v98, 16, v214
	v_and_b32_e32 v99, 0xffff0000, v214
	v_lshlrev_b32_e32 v106, 16, v232
	v_and_b32_e32 v107, 0xffff0000, v232
	v_lshlrev_b32_e32 v108, 16, v233
	v_and_b32_e32 v109, 0xffff0000, v233
	v_lshlrev_b64 v[96:97], 12, v[172:173]
	v_lshlrev_b32_e32 v102, 16, v216
	v_and_b32_e32 v103, 0xffff0000, v216
	v_lshlrev_b32_e32 v104, 16, v217
	v_and_b32_e32 v105, 0xffff0000, v217
	v_pk_fma_f32 v[94:95], v[94:95], v[100:101], v[108:109]
	v_pk_fma_f32 v[92:93], v[92:93], v[98:99], v[106:107]
	v_lshlrev_b32_e32 v98, 16, v234
	v_and_b32_e32 v99, 0xffff0000, v234
	v_lshlrev_b32_e32 v100, 16, v235
	v_and_b32_e32 v101, 0xffff0000, v235
	v_pk_fma_f32 v[100:101], v[90:91], v[104:105], v[100:101]
	v_pk_fma_f32 v[90:91], v[88:89], v[102:103], v[98:99]
	v_cvt_pk_bf16_f32 v88, v92, v93
	v_lshl_add_u64 v[92:93], s[14:15], 0, v[96:97]
	v_cvt_pk_bf16_f32 v89, v94, v95
	v_cvt_pk_bf16_f32 v90, v90, v91
	v_cvt_pk_bf16_f32 v91, v100, v101
	v_lshl_add_u64 v[92:93], v[92:93], 0, v[164:165]
	global_store_dwordx4 v[92:93], v[88:91], off
	v_lshlrev_b32_e32 v98, 16, v144
	v_and_b32_e32 v99, 0xffff0000, v144
	v_lshlrev_b32_e32 v88, 16, v222
	v_and_b32_e32 v89, 0xffff0000, v222
	v_lshlrev_b32_e32 v90, 16, v223
	v_and_b32_e32 v91, 0xffff0000, v223
	v_lshlrev_b32_e32 v100, 16, v145
	v_and_b32_e32 v101, 0xffff0000, v145
	v_lshlrev_b32_e32 v94, 16, v224
; __device__ __forceinline__ float bf_lo(unsigned w) { return __uint_as_float(w << 16); }
; __device__ __forceinline__ float bf_hi(unsigned w) { return __uint_as_float(w & 0xffff0000u); }
; __device__ __forceinline__ u32x4 pack8(const f32x4 a, const f32x4 b) { u32x4 w; w.x = cvt_pk_bf16(a[0], a[1]); w.y = cvt_pk_bf16(a[2], a[3]); w.z = cvt_pk_bf16(b[0], b[1]); w.w = cvt_pk_bf16(b[2], b[3]); return w; }
;     __device__ __forceinline__ void operator()(const f32x4 (&acc)[2][2][4][2], const Unit& u, int wr, int wc, int fr, int fq) const {
;     ...
;         for (int ai = 0; ai < 2; ++ai) { u32x4 gw[4][2], pw[4][2];
; #pragma unroll
;             for (int m = 0; m < 4; ++m) { const size_t off = (size_t)(row0 + ai * HALF + m * 16) * 2048 + col0;
; #pragma unroll
;                 for (int bj = 0; bj < 2; ++bj) { gw[m][bj] = *(const u32x4*)(G + off + bj * HALF); if (PASS == 1) pw[m][bj] = *(const u32x4*)(MIX + off + bj * HALF); } }
; #pragma unroll
;             for (int m = 0; m < 4; ++m) { const size_t off = (size_t)(row0 + ai * HALF + m * 16) * 2048 + col0;
; #pragma unroll
;                 for (int bj = 0; bj < 2; ++bj) { const u32x4 g4 = gw[m][bj];
;                     f32x4 v0 = (f32x4){bf_lo(g4.x), bf_hi(g4.x), bf_lo(g4.y), bf_hi(g4.y)} * acc[ai][bj][m][0], v1 = (f32x4){bf_lo(g4.z), bf_hi(g4.z), bf_lo(g4.w), bf_hi(g4.w)} * acc[ai][bj][m][1];
;                     if (PASS == 1) { const u32x4 p4 = pw[m][bj]; v0 += (f32x4){bf_lo(p4.x), bf_hi(p4.x), bf_lo(p4.y), bf_hi(p4.y)}; v1 += (f32x4){bf_lo(p4.z), bf_hi(p4.z), bf_lo(p4.w), bf_hi(p4.w)}; }
;                     *(u32x4*)(MIX + off + bj * HALF) = pack8(v0, v1); } } }
	v_and_b32_e32 v95, 0xffff0000, v224
	v_lshlrev_b32_e32 v96, 16, v225
	v_and_b32_e32 v97, 0xffff0000, v225
	v_pk_fma_f32 v[86:87], v[86:87], v[90:91], v[100:101]
	v_pk_fma_f32 v[84:85], v[84:85], v[88:89], v[98:99]
	v_lshlrev_b32_e32 v88, 16, v146
	v_and_b32_e32 v89, 0xffff0000, v146
	v_lshlrev_b32_e32 v90, 16, v147
	v_and_b32_e32 v91, 0xffff0000, v147
	v_pk_fma_f32 v[90:91], v[82:83], v[96:97], v[90:91]
	v_pk_fma_f32 v[82:83], v[80:81], v[94:95], v[88:89]
	v_cvt_pk_bf16_f32 v80, v84, v85
	v_cvt_pk_bf16_f32 v81, v86, v87
	v_cvt_pk_bf16_f32 v82, v82, v83
	v_cvt_pk_bf16_f32 v83, v90, v91
	global_store_dwordx4 v[92:93], v[80:83], off offset:256
	v_lshlrev_b32_e32 v84, 16, v141
	v_and_b32_e32 v85, 0xffff0000, v141
	v_lshlrev_b32_e32 v82, 16, v140
	v_and_b32_e32 v83, 0xffff0000, v140
	v_lshlrev_b32_e32 v90, 16, v136
	v_and_b32_e32 v91, 0xffff0000, v136
	v_lshlrev_b32_e32 v92, 16, v137
	v_and_b32_e32 v93, 0xffff0000, v137
	v_lshlrev_b64 v[80:81], 12, v[170:171]
	v_lshlrev_b32_e32 v86, 16, v142
	v_and_b32_e32 v87, 0xffff0000, v142
	v_lshlrev_b32_e32 v88, 16, v143
	v_and_b32_e32 v89, 0xffff0000, v143
	v_pk_fma_f32 v[78:79], v[78:79], v[84:85], v[92:93]
	v_pk_fma_f32 v[76:77], v[76:77], v[82:83], v[90:91]
	v_lshlrev_b32_e32 v82, 16, v138
	v_and_b32_e32 v83, 0xffff0000, v138
	v_lshlrev_b32_e32 v84, 16, v139
	v_and_b32_e32 v85, 0xffff0000, v139
	v_pk_fma_f32 v[84:85], v[74:75], v[88:89], v[84:85]
	v_pk_fma_f32 v[74:75], v[72:73], v[86:87], v[82:83]
	v_cvt_pk_bf16_f32 v72, v76, v77
	v_lshl_add_u64 v[76:77], s[14:15], 0, v[80:81]
	v_cvt_pk_bf16_f32 v73, v78, v79
	v_cvt_pk_bf16_f32 v74, v74, v75
	v_cvt_pk_bf16_f32 v75, v84, v85
	v_lshl_add_u64 v[76:77], v[76:77], 0, v[164:165]
	global_store_dwordx4 v[76:77], v[72:75], off
	v_lshlrev_b32_e32 v82, 16, v128
	v_and_b32_e32 v83, 0xffff0000, v128
	v_lshlrev_b32_e32 v72, 16, v132
	v_and_b32_e32 v73, 0xffff0000, v132
	v_lshlrev_b32_e32 v74, 16, v133
	v_and_b32_e32 v75, 0xffff0000, v133
	v_lshlrev_b32_e32 v84, 16, v129
	v_and_b32_e32 v85, 0xffff0000, v129
	v_lshlrev_b32_e32 v78, 16, v134
	v_and_b32_e32 v79, 0xffff0000, v134
	v_lshlrev_b32_e32 v80, 16, v135
	v_and_b32_e32 v81, 0xffff0000, v135
	v_pk_fma_f32 v[70:71], v[70:71], v[74:75], v[84:85]
	v_pk_fma_f32 v[68:69], v[68:69], v[72:73], v[82:83]
	v_lshlrev_b32_e32 v72, 16, v130
	v_and_b32_e32 v73, 0xffff0000, v130
	v_lshlrev_b32_e32 v74, 16, v131
	v_and_b32_e32 v75, 0xffff0000, v131
	v_pk_fma_f32 v[74:75], v[66:67], v[80:81], v[74:75]
	v_pk_fma_f32 v[66:67], v[64:65], v[78:79], v[72:73]
	v_add_u32_e32 v130, 0x80, v168
	v_cvt_pk_bf16_f32 v64, v68, v69
	v_cvt_pk_bf16_f32 v65, v70, v71
	v_cvt_pk_bf16_f32 v66, v66, v67
	v_cvt_pk_bf16_f32 v67, v74, v75
	v_ashrrev_i32_e32 v131, 31, v130
	global_store_dwordx4 v[76:77], v[64:67], off offset:256
	v_add_u32_e32 v132, 0x90, v168
	v_ashrrev_i32_e32 v133, 31, v132
	v_lshlrev_b64 v[64:65], 11, v[130:131]
	v_lshl_add_u64 v[64:65], v[64:65], 0, v[166:167]
	v_lshlrev_b64 v[64:65], 1, v[64:65]
	v_lshl_add_u64 v[66:67], s[12:13], 0, v[64:65]
	global_load_dwordx4 v[90:93], v[66:67], off
	v_lshl_add_u64 v[64:65], s[14:15], 0, v[64:65]
	global_load_dwordx4 v[94:97], v[64:65], off
	global_load_dwordx4 v[98:101], v[66:67], off offset:256
	global_load_dwordx4 v[102:105], v[64:65], off offset:256
	v_lshlrev_b64 v[64:65], 11, v[132:133]
	v_lshl_add_u64 v[64:65], v[64:65], 0, v[166:167]
	v_lshlrev_b64 v[64:65], 1, v[64:65]
	v_lshl_add_u64 v[66:67], s[12:13], 0, v[64:65]
	v_lshl_add_u64 v[64:65], s[14:15], 0, v[64:65]
	global_load_dwordx4 v[106:109], v[66:67], off
	global_load_dwordx4 v[110:113], v[66:67], off offset:256
	global_load_dwordx4 v[114:117], v[64:65], off
	global_load_dwordx4 v[118:121], v[64:65], off offset:256
	v_add_u32_e32 v134, 0xa0, v168
	v_ashrrev_i32_e32 v135, 31, v134
	v_lshlrev_b64 v[64:65], 11, v[134:135]
	v_lshl_add_u64 v[64:65], v[64:65], 0, v[166:167]
	v_lshlrev_b64 v[64:65], 1, v[64:65]
	v_lshl_add_u64 v[66:67], s[12:13], 0, v[64:65]
	v_lshl_add_u64 v[64:65], s[14:15], 0, v[64:65]
	global_load_dwordx4 v[122:125], v[66:67], off
	global_load_dwordx4 v[84:87], v[66:67], off offset:256
	global_load_dwordx4 v[126:129], v[64:65], off
	global_load_dwordx4 v[80:83], v[64:65], off offset:256
	v_add_u32_e32 v88, 0xb0, v168
	v_ashrrev_i32_e32 v89, 31, v88
	v_lshlrev_b64 v[64:65], 11, v[88:89]
	v_lshl_add_u64 v[64:65], v[64:65], 0, v[166:167]
	v_lshlrev_b64 v[64:65], 1, v[64:65]
	v_lshl_add_u64 v[66:67], s[12:13], 0, v[64:65]
	v_lshl_add_u64 v[64:65], s[14:15], 0, v[64:65]
	global_load_dwordx4 v[76:79], v[66:67], off
	global_load_dwordx4 v[68:71], v[66:67], off offset:256
	global_load_dwordx4 v[72:75], v[64:65], off
	s_nop 0
	global_load_dwordx4 v[64:67], v[64:65], off offset:256
	v_lshlrev_b64 v[130:131], 12, v[130:131]
	s_waitcnt vmcnt(15)
	v_lshlrev_b32_e32 v136, 16, v90
	v_and_b32_e32 v137, 0xffff0000, v90
	v_lshlrev_b32_e32 v90, 16, v91
	v_and_b32_e32 v91, 0xffff0000, v91
	s_waitcnt vmcnt(14)
	v_lshlrev_b32_e32 v140, 16, v94
	v_and_b32_e32 v141, 0xffff0000, v94
	v_lshlrev_b32_e32 v94, 16, v95
	v_and_b32_e32 v95, 0xffff0000, v95
	v_lshlrev_b32_e32 v138, 16, v92
	v_and_b32_e32 v139, 0xffff0000, v92
	v_lshlrev_b32_e32 v92, 16, v93
	v_and_b32_e32 v93, 0xffff0000, v93
	v_pk_fma_f32 v[62:63], v[62:63], v[90:91], v[94:95]
	v_pk_fma_f32 v[60:61], v[60:61], v[136:137], v[140:141]
	v_lshlrev_b32_e32 v90, 16, v96
	v_and_b32_e32 v91, 0xffff0000, v96
	v_lshlrev_b32_e32 v94, 16, v97
	v_and_b32_e32 v95, 0xffff0000, v97
	v_pk_fma_f32 v[92:93], v[58:59], v[92:93], v[94:95]
	v_pk_fma_f32 v[58:59], v[56:57], v[138:139], v[90:91]
	v_cvt_pk_bf16_f32 v56, v60, v61
	v_lshl_add_u64 v[60:61], s[14:15], 0, v[130:131]
	v_cvt_pk_bf16_f32 v57, v62, v63
	v_cvt_pk_bf16_f32 v58, v58, v59
	v_cvt_pk_bf16_f32 v59, v92, v93
	v_lshl_add_u64 v[60:61], v[60:61], 0, v[164:165]
	global_store_dwordx4 v[60:61], v[56:59], off
	s_waitcnt vmcnt(13)
; __device__ __forceinline__ float bf_lo(unsigned w) { return __uint_as_float(w << 16); }
; __device__ __forceinline__ float bf_hi(unsigned w) { return __uint_as_float(w & 0xffff0000u); }
; __device__ __forceinline__ u32x4 pack8(const f32x4 a, const f32x4 b) { u32x4 w; w.x = cvt_pk_bf16(a[0], a[1]); w.y = cvt_pk_bf16(a[2], a[3]); w.z = cvt_pk_bf16(b[0], b[1]); w.w = cvt_pk_bf16(b[2], b[3]); return w; }
;     __device__ __forceinline__ void operator()(const f32x4 (&acc)[2][2][4][2], const Unit& u, int wr, int wc, int fr, int fq) const {
;     ...
;         for (int ai = 0; ai < 2; ++ai) { u32x4 gw[4][2], pw[4][2];
; #pragma unroll
;             for (int m = 0; m < 4; ++m) { const size_t off = (size_t)(row0 + ai * HALF + m * 16) * 2048 + col0;
; #pragma unroll
;                 for (int bj = 0; bj < 2; ++bj) { gw[m][bj] = *(const u32x4*)(G + off + bj * HALF); if (PASS == 1) pw[m][bj] = *(const u32x4*)(MIX + off + bj * HALF); } }
; #pragma unroll
;             for (int m = 0; m < 4; ++m) { const size_t off = (size_t)(row0 + ai * HALF + m * 16) * 2048 + col0;
; #pragma unroll
;                 for (int bj = 0; bj < 2; ++bj) { const u32x4 g4 = gw[m][bj];
;                     f32x4 v0 = (f32x4){bf_lo(g4.x), bf_hi(g4.x), bf_lo(g4.y), bf_hi(g4.y)} * acc[ai][bj][m][0], v1 = (f32x4){bf_lo(g4.z), bf_hi(g4.z), bf_lo(g4.w), bf_hi(g4.w)} * acc[ai][bj][m][1];
;                     if (PASS == 1) { const u32x4 p4 = pw[m][bj]; v0 += (f32x4){bf_lo(p4.x), bf_hi(p4.x), bf_lo(p4.y), bf_hi(p4.y)}; v1 += (f32x4){bf_lo(p4.z), bf_hi(p4.z), bf_lo(p4.w), bf_hi(p4.w)}; }
;                     *(u32x4*)(MIX + off + bj * HALF) = pack8(v0, v1); } } }
	v_lshlrev_b32_e32 v92, 16, v102
	v_and_b32_e32 v93, 0xffff0000, v102
	v_lshlrev_b32_e32 v56, 16, v98
	v_and_b32_e32 v57, 0xffff0000, v98
	v_lshlrev_b32_e32 v58, 16, v99
	v_and_b32_e32 v59, 0xffff0000, v99
	v_lshlrev_b32_e32 v94, 16, v103
	v_and_b32_e32 v95, 0xffff0000, v103
	v_lshlrev_b32_e32 v62, 16, v100
	v_and_b32_e32 v63, 0xffff0000, v100
	v_lshlrev_b32_e32 v90, 16, v101
	v_and_b32_e32 v91, 0xffff0000, v101
	v_pk_fma_f32 v[54:55], v[54:55], v[58:59], v[94:95]
	v_pk_fma_f32 v[52:53], v[52:53], v[56:57], v[92:93]
	v_lshlrev_b32_e32 v56, 16, v104
	v_and_b32_e32 v57, 0xffff0000, v104
	v_lshlrev_b32_e32 v58, 16, v105
	v_and_b32_e32 v59, 0xffff0000, v105
	v_pk_fma_f32 v[58:59], v[50:51], v[90:91], v[58:59]
	v_pk_fma_f32 v[50:51], v[48:49], v[62:63], v[56:57]
	v_cvt_pk_bf16_f32 v48, v52, v53
	v_cvt_pk_bf16_f32 v49, v54, v55
	v_cvt_pk_bf16_f32 v50, v50, v51
	v_cvt_pk_bf16_f32 v51, v58, v59
	global_store_dwordx4 v[60:61], v[48:51], off offset:256
	s_waitcnt vmcnt(13)
	v_lshlrev_b32_e32 v52, 16, v107
	v_and_b32_e32 v53, 0xffff0000, v107
	v_lshlrev_b32_e32 v50, 16, v106
	v_and_b32_e32 v51, 0xffff0000, v106
	s_waitcnt vmcnt(11)
	v_lshlrev_b32_e32 v58, 16, v114
	v_and_b32_e32 v59, 0xffff0000, v114
	v_lshlrev_b32_e32 v60, 16, v115
	v_and_b32_e32 v61, 0xffff0000, v115
	v_lshlrev_b64 v[48:49], 12, v[132:133]
	v_lshlrev_b32_e32 v54, 16, v108
	v_and_b32_e32 v55, 0xffff0000, v108
	v_lshlrev_b32_e32 v56, 16, v109
	v_and_b32_e32 v57, 0xffff0000, v109
	v_pk_fma_f32 v[46:47], v[46:47], v[52:53], v[60:61]
	v_pk_fma_f32 v[44:45], v[44:45], v[50:51], v[58:59]
	v_lshlrev_b32_e32 v50, 16, v116
	v_and_b32_e32 v51, 0xffff0000, v116
	v_lshlrev_b32_e32 v52, 16, v117
	v_and_b32_e32 v53, 0xffff0000, v117
	v_pk_fma_f32 v[52:53], v[42:43], v[56:57], v[52:53]
	v_pk_fma_f32 v[42:43], v[40:41], v[54:55], v[50:51]
	v_cvt_pk_bf16_f32 v40, v44, v45
	v_lshl_add_u64 v[44:45], s[14:15], 0, v[48:49]
	v_cvt_pk_bf16_f32 v41, v46, v47
	v_cvt_pk_bf16_f32 v42, v42, v43
	v_cvt_pk_bf16_f32 v43, v52, v53
	v_lshl_add_u64 v[44:45], v[44:45], 0, v[164:165]
	global_store_dwordx4 v[44:45], v[40:43], off
	s_waitcnt vmcnt(11)
	v_lshlrev_b32_e32 v50, 16, v118
	v_and_b32_e32 v51, 0xffff0000, v118
	v_lshlrev_b32_e32 v40, 16, v110
	v_and_b32_e32 v41, 0xffff0000, v110
	v_lshlrev_b32_e32 v42, 16, v111
	v_and_b32_e32 v43, 0xffff0000, v111
	v_lshlrev_b32_e32 v52, 16, v119
	v_and_b32_e32 v53, 0xffff0000, v119
	v_lshlrev_b32_e32 v46, 16, v112
	v_and_b32_e32 v47, 0xffff0000, v112
	v_lshlrev_b32_e32 v48, 16, v113
	v_and_b32_e32 v49, 0xffff0000, v113
	v_pk_fma_f32 v[38:39], v[38:39], v[42:43], v[52:53]
	v_pk_fma_f32 v[36:37], v[36:37], v[40:41], v[50:51]
	v_lshlrev_b32_e32 v40, 16, v120
	v_and_b32_e32 v41, 0xffff0000, v120
	v_lshlrev_b32_e32 v42, 16, v121
	v_and_b32_e32 v43, 0xffff0000, v121
	v_pk_fma_f32 v[42:43], v[34:35], v[48:49], v[42:43]
	v_pk_fma_f32 v[34:35], v[32:33], v[46:47], v[40:41]
	v_cvt_pk_bf16_f32 v32, v36, v37
	v_cvt_pk_bf16_f32 v33, v38, v39
	v_cvt_pk_bf16_f32 v34, v34, v35
	v_cvt_pk_bf16_f32 v35, v42, v43
	global_store_dwordx4 v[44:45], v[32:35], off offset:256
	s_waitcnt vmcnt(11)
	v_lshlrev_b32_e32 v36, 16, v123
	v_and_b32_e32 v37, 0xffff0000, v123
	v_lshlrev_b32_e32 v34, 16, v122
	v_and_b32_e32 v35, 0xffff0000, v122
	s_waitcnt vmcnt(9)
; __device__ __forceinline__ float bf_lo(unsigned w) { return __uint_as_float(w << 16); }
; __device__ __forceinline__ float bf_hi(unsigned w) { return __uint_as_float(w & 0xffff0000u); }
; __device__ __forceinline__ u32x4 pack8(const f32x4 a, const f32x4 b) { u32x4 w; w.x = cvt_pk_bf16(a[0], a[1]); w.y = cvt_pk_bf16(a[2], a[3]); w.z = cvt_pk_bf16(b[0], b[1]); w.w = cvt_pk_bf16(b[2], b[3]); return w; }
; #define PG8_WAIT_V(n) asm volatile("s_waitcnt vmcnt(" #n ")" ::: "memory")
; #define PG8_BAR __builtin_amdgcn_s_barrier()
;     __device__ __forceinline__ void operator()(const f32x4 (&acc)[2][2][4][2], const Unit& u, int wr, int wc, int fr, int fq) const {
;     ...
;         for (int ai = 0; ai < 2; ++ai) { u32x4 gw[4][2], pw[4][2];
; #pragma unroll
;             for (int m = 0; m < 4; ++m) { const size_t off = (size_t)(row0 + ai * HALF + m * 16) * 2048 + col0;
; #pragma unroll
;                 for (int bj = 0; bj < 2; ++bj) { gw[m][bj] = *(const u32x4*)(G + off + bj * HALF); if (PASS == 1) pw[m][bj] = *(const u32x4*)(MIX + off + bj * HALF); } }
; #pragma unroll
;             for (int m = 0; m < 4; ++m) { const size_t off = (size_t)(row0 + ai * HALF + m * 16) * 2048 + col0;
; #pragma unroll
;                 for (int bj = 0; bj < 2; ++bj) { const u32x4 g4 = gw[m][bj];
;                     f32x4 v0 = (f32x4){bf_lo(g4.x), bf_hi(g4.x), bf_lo(g4.y), bf_hi(g4.y)} * acc[ai][bj][m][0], v1 = (f32x4){bf_lo(g4.z), bf_hi(g4.z), bf_lo(g4.w), bf_hi(g4.w)} * acc[ai][bj][m][1];
;                     if (PASS == 1) { const u32x4 p4 = pw[m][bj]; v0 += (f32x4){bf_lo(p4.x), bf_hi(p4.x), bf_lo(p4.y), bf_hi(p4.y)}; v1 += (f32x4){bf_lo(p4.z), bf_hi(p4.z), bf_lo(p4.w), bf_hi(p4.w)}; }
;                     *(u32x4*)(MIX + off + bj * HALF) = pack8(v0, v1); } } }
; template <class Epi, class Sched, bool ALIGN_EPI = false, bool SP2 = false>
; __device__ __forceinline__ void gemm_phase(PG8_LAS unsigned char* lds, const Gemm g, const Sched& S, const Epi& E) {
;     ...
;     PG8_WAIT_V(0);
;     if constexpr (!ALIGN_EPI) { if (wr == 0) PG8_BAR; }
;     PG8_BAR;
	v_lshlrev_b32_e32 v42, 16, v126
	v_and_b32_e32 v43, 0xffff0000, v126
	v_lshlrev_b32_e32 v44, 16, v127
	v_and_b32_e32 v45, 0xffff0000, v127
	v_lshlrev_b64 v[32:33], 12, v[134:135]
	v_lshlrev_b32_e32 v38, 16, v124
	v_and_b32_e32 v39, 0xffff0000, v124
	v_lshlrev_b32_e32 v40, 16, v125
	v_and_b32_e32 v41, 0xffff0000, v125
	v_pk_fma_f32 v[30:31], v[30:31], v[36:37], v[44:45]
	v_pk_fma_f32 v[28:29], v[28:29], v[34:35], v[42:43]
	v_lshlrev_b32_e32 v34, 16, v128
	v_and_b32_e32 v35, 0xffff0000, v128
	v_lshlrev_b32_e32 v36, 16, v129
	v_and_b32_e32 v37, 0xffff0000, v129
	v_pk_fma_f32 v[36:37], v[26:27], v[40:41], v[36:37]
	v_pk_fma_f32 v[26:27], v[24:25], v[38:39], v[34:35]
	v_cvt_pk_bf16_f32 v24, v28, v29
	v_lshl_add_u64 v[28:29], s[14:15], 0, v[32:33]
	v_cvt_pk_bf16_f32 v25, v30, v31
	v_cvt_pk_bf16_f32 v26, v26, v27
	v_cvt_pk_bf16_f32 v27, v36, v37
	v_lshl_add_u64 v[28:29], v[28:29], 0, v[164:165]
	global_store_dwordx4 v[28:29], v[24:27], off
	s_waitcnt vmcnt(9)
	v_lshlrev_b32_e32 v34, 16, v80
	v_and_b32_e32 v35, 0xffff0000, v80
	v_lshlrev_b32_e32 v24, 16, v84
	v_and_b32_e32 v25, 0xffff0000, v84
	v_lshlrev_b32_e32 v26, 16, v85
	v_and_b32_e32 v27, 0xffff0000, v85
	v_lshlrev_b32_e32 v36, 16, v81
	v_and_b32_e32 v37, 0xffff0000, v81
	v_lshlrev_b32_e32 v30, 16, v86
	v_and_b32_e32 v31, 0xffff0000, v86
	v_lshlrev_b32_e32 v32, 16, v87
	v_and_b32_e32 v33, 0xffff0000, v87
	v_pk_fma_f32 v[22:23], v[22:23], v[26:27], v[36:37]
	v_pk_fma_f32 v[20:21], v[20:21], v[24:25], v[34:35]
	v_lshlrev_b32_e32 v24, 16, v82
	v_and_b32_e32 v25, 0xffff0000, v82
	v_lshlrev_b32_e32 v26, 16, v83
	v_and_b32_e32 v27, 0xffff0000, v83
	v_pk_fma_f32 v[26:27], v[18:19], v[32:33], v[26:27]
	v_pk_fma_f32 v[18:19], v[16:17], v[30:31], v[24:25]
	v_cvt_pk_bf16_f32 v16, v20, v21
	v_cvt_pk_bf16_f32 v17, v22, v23
	v_cvt_pk_bf16_f32 v18, v18, v19
	v_cvt_pk_bf16_f32 v19, v26, v27
	global_store_dwordx4 v[28:29], v[16:19], off offset:256
	s_waitcnt vmcnt(9)
	v_lshlrev_b32_e32 v20, 16, v77
	v_and_b32_e32 v21, 0xffff0000, v77
	v_lshlrev_b32_e32 v18, 16, v76
	v_and_b32_e32 v19, 0xffff0000, v76
	s_waitcnt vmcnt(7)
	v_lshlrev_b32_e32 v26, 16, v72
	v_and_b32_e32 v27, 0xffff0000, v72
	v_lshlrev_b32_e32 v28, 16, v73
	v_and_b32_e32 v29, 0xffff0000, v73
	v_lshlrev_b64 v[16:17], 12, v[88:89]
	v_lshlrev_b32_e32 v22, 16, v78
	v_and_b32_e32 v23, 0xffff0000, v78
	v_lshlrev_b32_e32 v24, 16, v79
	v_and_b32_e32 v25, 0xffff0000, v79
	v_pk_fma_f32 v[14:15], v[14:15], v[20:21], v[28:29]
	v_pk_fma_f32 v[12:13], v[12:13], v[18:19], v[26:27]
	v_lshlrev_b32_e32 v18, 16, v74
	v_and_b32_e32 v19, 0xffff0000, v74
	v_lshlrev_b32_e32 v20, 16, v75
	v_and_b32_e32 v21, 0xffff0000, v75
	v_pk_fma_f32 v[20:21], v[10:11], v[24:25], v[20:21]
	v_pk_fma_f32 v[10:11], v[8:9], v[22:23], v[18:19]
	v_cvt_pk_bf16_f32 v8, v12, v13
	v_lshl_add_u64 v[12:13], s[14:15], 0, v[16:17]
	v_cvt_pk_bf16_f32 v9, v14, v15
	v_cvt_pk_bf16_f32 v10, v10, v11
	v_cvt_pk_bf16_f32 v11, v20, v21
	v_lshl_add_u64 v[12:13], v[12:13], 0, v[164:165]
	global_store_dwordx4 v[12:13], v[8:11], off
	s_waitcnt vmcnt(7)
	v_lshlrev_b32_e32 v18, 16, v64
	v_and_b32_e32 v19, 0xffff0000, v64
	v_lshlrev_b32_e32 v8, 16, v68
	v_and_b32_e32 v9, 0xffff0000, v68
	v_lshlrev_b32_e32 v10, 16, v69
	v_and_b32_e32 v11, 0xffff0000, v69
	v_lshlrev_b32_e32 v20, 16, v65
	v_and_b32_e32 v21, 0xffff0000, v65
	v_lshlrev_b32_e32 v14, 16, v70
	v_and_b32_e32 v15, 0xffff0000, v70
	v_lshlrev_b32_e32 v16, 16, v71
	v_and_b32_e32 v17, 0xffff0000, v71
	v_pk_fma_f32 v[6:7], v[6:7], v[10:11], v[20:21]
	v_pk_fma_f32 v[4:5], v[4:5], v[8:9], v[18:19]
	v_lshlrev_b32_e32 v8, 16, v66
	v_and_b32_e32 v9, 0xffff0000, v66
	v_lshlrev_b32_e32 v10, 16, v67
	v_and_b32_e32 v11, 0xffff0000, v67
	v_pk_fma_f32 v[10:11], v[2:3], v[16:17], v[10:11]
	v_pk_fma_f32 v[2:3], v[0:1], v[14:15], v[8:9]
	v_cvt_pk_bf16_f32 v0, v4, v5
	v_cvt_pk_bf16_f32 v1, v6, v7
	v_cvt_pk_bf16_f32 v2, v2, v3
	v_cvt_pk_bf16_f32 v3, v10, v11
	global_store_dwordx4 v[12:13], v[0:3], off offset:256
	s_cbranch_vccz .LBB0_748
	s_waitcnt vmcnt(0)
	s_cmpk_gt_u32 s3, 0xff
	s_cbranch_scc1 .LBB0_759
	s_barrier

; #define PG8_STAGE(bufoff, gbase, voff) do { _Pragma("unroll") for (int _i = 0; _i < 2; ++_i) \
;         __builtin_amdgcn_global_load_lds((const unsigned*)((const char*)(gbase) + (voff)[_i]), (PG8_LAS unsigned*)(lds + (bufoff) + ldsw + _i * 8192), 16, 0, 0); } while (0)
; #define PG8_LDA(dst, b, h) do { _Pragma("unroll") for (int m = 0; m < 4; ++m) _Pragma("unroll") for (int k = 0; k < 2; ++k) dst[m][k] = *(const PG8_LAS bf16x8*)(lds + PG8_SA(b, h) + aoff + m * 2048 + k * 1024); } while (0)
; #define PG8_LDB(dst, b, h) do { _Pragma("unroll") for (int n = 0; n < 2; ++n) _Pragma("unroll") for (int k = 0; k < 2; ++k) dst[n][k] = *(const PG8_LAS bf16x8*)(lds + PG8_SB(b, h) + boff + n * 2048 + k * 1024); } while (0)
; #define PG8_WAIT_V(n) asm volatile("s_waitcnt vmcnt(" #n ")" ::: "memory")
; #define PG8_WAIT_L(n) asm volatile("s_waitcnt lgkmcnt(" #n ")" ::: "memory")
; #define PG8_BAR __builtin_amdgcn_s_barrier()
; #define PG8_SCHED __builtin_amdgcn_sched_barrier(0)
; template <class Epi, class Sched, bool ALIGN_EPI = false, bool SP2 = false>
; __device__ __forceinline__ void gemm_phase(PG8_LAS unsigned char* lds, const Gemm g, const Sched& S, const Epi& E) {
;     ...
;         const bool has_next = S.next(ui + 1, nxt);
;         const char* nA = has_next ? (const char*)g.A + (size_t)nxt.pm * tstep : cA; const char* nB = has_next ? (const char*)g.Bt + (size_t)nxt.pn * tstep : cB;
;         for (int t = 0; t < nt; t += 2) {
;             const bool last = (t == nt - 2);
;             const char* a1 = cA + (size_t)(t + 1) * kstep;
;             const char* a2 = last ? nA : cA + (size_t)(t + 2) * kstep; const char* b2 = last ? nB : cB + (size_t)(t + 2) * kstep;
;             const char* a3 = a2 + kstep; const char* b3 = b2 + kstep;
;             if (last && has_next) S.a_ready(nxt);
;             if constexpr (SP2) {
;             PG8_LDB(B0, 0, 0); PG8_LDB(B1, 0, 1); PG8_SCHED; PG8_LDA(At, 0, 0); PG8_STAGE(PG8_SA(1, 1), a1 + hstep, voffA);
;             PG8_WAIT_V(8); PG8_WAIT_L(0); PG8_BAR; PG8_MMA(0, 0, At, B0); PG8_MMA(0, 1, At, B1); PG8_BAR; PG8_SCHED;
;             PG8_LDA(At, 0, 1); PG8_STAGE(PG8_SB(0, 0), b2, voffB); PG8_STAGE(PG8_SB(0, 1), b2 + hstep, voffB); PG8_STAGE(PG8_SA(0, 0), a2, voffA);
;             PG8_WAIT_V(8); PG8_WAIT_L(0); PG8_BAR; PG8_MMA(1, 0, At, B0); PG8_MMA(1, 1, At, B1); PG8_BAR; PG8_SCHED;
.LBB0_826:
	s_ashr_i32 s39, s38, 31
	v_cmp_lt_i64_e32 vcc, s[40:41], v[156:157]
	s_lshl_b64 s[40:41], s[38:39], 20
	s_add_u32 s40, s9, s40
	s_addc_u32 s41, s22, s41
	s_and_b64 s[42:43], vcc, exec
	s_cselect_b32 s39, s41, s47
	s_cselect_b32 s67, s40, s46
	s_ashr_i32 s37, s36, 31
	s_lshl_b64 s[42:43], s[36:37], 20
	s_add_u32 s42, s23, s42
	s_addc_u32 s43, s52, s43
	s_and_b64 s[50:51], vcc, exec
	s_cselect_b32 s37, s43, s49
	s_cselect_b32 s68, s42, s48
	s_add_u32 s46, s46, 0x80080
	s_addc_u32 s47, s47, 0
	s_add_u32 s69, s48, 0x100
	s_addc_u32 s70, s49, 0
	s_mov_b32 s71, -2
	ds_read_b128 v[128:131], v169
	ds_read_b128 v[132:135], v169 offset:1024
	ds_read_b128 v[136:139], v169 offset:2048
	ds_read_b128 v[140:143], v169 offset:3072
	ds_read_b128 v[160:163], v170
	ds_read_b128 v[172:175], v170 offset:1024
	ds_read_b128 v[176:179], v170 offset:2048
	ds_read_b128 v[180:183], v170 offset:3072
	s_add_u32 s48, s46, 0xfff80080
	s_addc_u32 s49, s47, -1
	s_cmp_eq_u32 s71, 28
	s_cselect_b32 s51, s39, s49
	s_cselect_b32 s50, s67, s48
	s_cselect_b32 s49, s37, s70
	s_cselect_b32 s48, s68, s69
	s_add_i32 m0, s45, 0xc000
	ds_read_b128 v[184:187], v171
	ds_read_b128 v[188:191], v171 offset:1024
	ds_read_b128 v[192:195], v171 offset:2048
	ds_read_b128 v[196:199], v171 offset:3072
	ds_read_b128 v[200:203], v171 offset:4096
	ds_read_b128 v[204:207], v171 offset:5120
	ds_read_b128 v[208:211], v171 offset:6144
	ds_read_b128 v[214:217], v171 offset:7168
	global_load_lds_dwordx4 v152, s[46:47]
	s_add_i32 m0, s45, 0xe000
	s_nop 0
	global_load_lds_dwordx4 v154, s[46:47]
	s_waitcnt vmcnt(8) lgkmcnt(0)
	s_barrier
	v_mfma_f32_16x16x32_bf16 v[124:127], v[128:131], v[184:187], 0
	v_mfma_f32_16x16x32_bf16 v[120:123], v[136:139], v[184:187], 0
	v_mfma_f32_16x16x32_bf16 v[116:119], v[128:131], v[192:195], 0
	v_mfma_f32_16x16x32_bf16 v[112:115], v[136:139], v[192:195], 0
	v_mfma_f32_16x16x32_bf16 v[108:111], v[128:131], v[200:203], 0
	v_mfma_f32_16x16x32_bf16 v[96:99], v[136:139], v[200:203], 0
	v_mfma_f32_16x16x32_bf16 v[80:83], v[128:131], v[208:211], 0
	v_mfma_f32_16x16x32_bf16 v[72:75], v[136:139], v[208:211], 0
	v_mfma_f32_16x16x32_bf16 v[124:127], v[132:135], v[188:191], v[124:127]
	v_mfma_f32_16x16x32_bf16 v[120:123], v[140:143], v[188:191], v[120:123]
	v_mfma_f32_16x16x32_bf16 v[116:119], v[132:135], v[196:199], v[116:119]
	v_mfma_f32_16x16x32_bf16 v[112:115], v[140:143], v[196:199], v[112:115]
	v_mfma_f32_16x16x32_bf16 v[108:111], v[132:135], v[204:207], v[108:111]
	v_mfma_f32_16x16x32_bf16 v[96:99], v[140:143], v[204:207], v[96:99]
	v_mfma_f32_16x16x32_bf16 v[80:83], v[132:135], v[214:217], v[80:83]
	v_mfma_f32_16x16x32_bf16 v[72:75], v[140:143], v[214:217], v[72:75]
	v_mfma_f32_16x16x32_bf16 v[104:107], v[160:163], v[184:187], 0
	v_mfma_f32_16x16x32_bf16 v[100:103], v[176:179], v[184:187], 0
	v_mfma_f32_16x16x32_bf16 v[92:95], v[160:163], v[192:195], 0
	v_mfma_f32_16x16x32_bf16 v[88:91], v[176:179], v[192:195], 0
	v_mfma_f32_16x16x32_bf16 v[84:87], v[160:163], v[200:203], 0
	v_mfma_f32_16x16x32_bf16 v[76:79], v[176:179], v[200:203], 0
	v_mfma_f32_16x16x32_bf16 v[68:71], v[160:163], v[208:211], 0
	v_mfma_f32_16x16x32_bf16 v[64:67], v[176:179], v[208:211], 0
	v_mfma_f32_16x16x32_bf16 v[104:107], v[172:175], v[188:191], v[104:107]
	v_mfma_f32_16x16x32_bf16 v[100:103], v[180:183], v[188:191], v[100:103]
	v_mfma_f32_16x16x32_bf16 v[92:95], v[172:175], v[196:199], v[92:95]
	v_mfma_f32_16x16x32_bf16 v[88:91], v[180:183], v[196:199], v[88:91]
	v_mfma_f32_16x16x32_bf16 v[84:87], v[172:175], v[204:207], v[84:87]
	v_mfma_f32_16x16x32_bf16 v[76:79], v[180:183], v[204:207], v[76:79]
	v_mfma_f32_16x16x32_bf16 v[68:71], v[172:175], v[214:217], v[68:71]
	v_mfma_f32_16x16x32_bf16 v[64:67], v[180:183], v[214:217], v[64:67]
	s_barrier
	s_add_i32 s72, s64, s53
	s_mov_b32 m0, s72
	ds_read_b128 v[184:187], v171 offset:16384
	ds_read_b128 v[188:191], v171 offset:17408
	ds_read_b128 v[192:195], v171 offset:18432
	ds_read_b128 v[196:199], v171 offset:19456
	ds_read_b128 v[200:203], v171 offset:20480
	ds_read_b128 v[204:207], v171 offset:21504
	ds_read_b128 v[208:211], v171 offset:22528
	ds_read_b128 v[214:217], v171 offset:23552
	global_load_lds_dwordx4 v146, s[48:49]
	s_add_i32 m0, s72, 0x2000
	s_add_u32 s72, s48, 0x80000
	s_addc_u32 s73, s49, 0
	s_add_i32 s74, s65, s53
	global_load_lds_dwordx4 v150, s[48:49]
	s_mov_b32 m0, s74
	s_nop 0
	global_load_lds_dwordx4 v146, s[72:73]
	s_add_i32 m0, s74, 0x2000
	s_nop 0
	global_load_lds_dwordx4 v150, s[72:73]
	s_mov_b32 m0, s45
	s_nop 0
	global_load_lds_dwordx4 v144, s[50:51]
	s_mov_b32 m0, s54
	s_nop 0
	global_load_lds_dwordx4 v148, s[50:51]
	s_waitcnt vmcnt(8) lgkmcnt(0)
	s_barrier
; #define PG8_STAGE(bufoff, gbase, voff) do { _Pragma("unroll") for (int _i = 0; _i < 2; ++_i) \
;         __builtin_amdgcn_global_load_lds((const unsigned*)((const char*)(gbase) + (voff)[_i]), (PG8_LAS unsigned*)(lds + (bufoff) + ldsw + _i * 8192), 16, 0, 0); } while (0)
; #define PG8_LDA(dst, b, h) do { _Pragma("unroll") for (int m = 0; m < 4; ++m) _Pragma("unroll") for (int k = 0; k < 2; ++k) dst[m][k] = *(const PG8_LAS bf16x8*)(lds + PG8_SA(b, h) + aoff + m * 2048 + k * 1024); } while (0)
; #define PG8_LDB(dst, b, h) do { _Pragma("unroll") for (int n = 0; n < 2; ++n) _Pragma("unroll") for (int k = 0; k < 2; ++k) dst[n][k] = *(const PG8_LAS bf16x8*)(lds + PG8_SB(b, h) + boff + n * 2048 + k * 1024); } while (0)
; #define PG8_MMA(ai, bj, At, Bt) do { __builtin_amdgcn_s_setprio(1); _Pragma("unroll") for (int m = 0; m < 4; ++m) _Pragma("unroll") for (int n = 0; n < 2; ++n) _Pragma("unroll") for (int k = 0; k < 2; ++k) \
;         acc[ai][bj][m][n] = __builtin_amdgcn_mfma_f32_16x16x32_bf16(Bt[n][k], At[m][k], acc[ai][bj][m][n], 0, 0, 0); __builtin_amdgcn_s_setprio(0); } while (0)
; #define PG8_WAIT_V(n) asm volatile("s_waitcnt vmcnt(" #n ")" ::: "memory")
; #define PG8_WAIT_L(n) asm volatile("s_waitcnt lgkmcnt(" #n ")" ::: "memory")
; #define PG8_BAR __builtin_amdgcn_s_barrier()
; #define PG8_SCHED __builtin_amdgcn_sched_barrier(0)
; template <class Epi, class Sched, bool ALIGN_EPI = false, bool SP2 = false>
; __device__ __forceinline__ void gemm_phase(PG8_LAS unsigned char* lds, const Gemm g, const Sched& S, const Epi& E) {
;     ...
;             PG8_LDB(B0, 0, 0); PG8_LDB(B1, 0, 1); PG8_SCHED; PG8_LDA(At, 0, 0); PG8_STAGE(PG8_SA(1, 1), a1 + hstep, voffA);
;             PG8_WAIT_V(8); PG8_WAIT_L(0); PG8_BAR; PG8_MMA(0, 0, At, B0); PG8_MMA(0, 1, At, B1); PG8_BAR; PG8_SCHED;
;             PG8_LDA(At, 0, 1); PG8_STAGE(PG8_SB(0, 0), b2, voffB); PG8_STAGE(PG8_SB(0, 1), b2 + hstep, voffB); PG8_STAGE(PG8_SA(0, 0), a2, voffA);
;             PG8_WAIT_V(8); PG8_WAIT_L(0); PG8_BAR; PG8_MMA(1, 0, At, B0); PG8_MMA(1, 1, At, B1); PG8_BAR; PG8_SCHED;
;             PG8_LDB(B0, 1, 0); PG8_LDB(B1, 1, 1); PG8_SCHED; PG8_LDA(At, 1, 0); PG8_STAGE(PG8_SA(0, 1), a2 + hstep, voffA);
;             PG8_WAIT_V(8); PG8_WAIT_L(0); PG8_BAR; PG8_MMA(0, 0, At, B0); PG8_MMA(0, 1, At, B1); PG8_BAR; PG8_SCHED;
	v_mfma_f32_16x16x32_bf16 v[60:63], v[128:131], v[184:187], 0
	v_mfma_f32_16x16x32_bf16 v[56:59], v[136:139], v[184:187], 0
	v_mfma_f32_16x16x32_bf16 v[52:55], v[128:131], v[192:195], 0
	v_mfma_f32_16x16x32_bf16 v[48:51], v[136:139], v[192:195], 0
	v_mfma_f32_16x16x32_bf16 v[44:47], v[128:131], v[200:203], 0
	v_mfma_f32_16x16x32_bf16 v[32:35], v[136:139], v[200:203], 0
	v_mfma_f32_16x16x32_bf16 v[20:23], v[128:131], v[208:211], 0
	v_mfma_f32_16x16x32_bf16 v[8:11], v[136:139], v[208:211], 0
	v_mfma_f32_16x16x32_bf16 v[60:63], v[132:135], v[188:191], v[60:63]
	v_mfma_f32_16x16x32_bf16 v[56:59], v[140:143], v[188:191], v[56:59]
	v_mfma_f32_16x16x32_bf16 v[52:55], v[132:135], v[196:199], v[52:55]
	v_mfma_f32_16x16x32_bf16 v[48:51], v[140:143], v[196:199], v[48:51]
	v_mfma_f32_16x16x32_bf16 v[44:47], v[132:135], v[204:207], v[44:47]
	v_mfma_f32_16x16x32_bf16 v[32:35], v[140:143], v[204:207], v[32:35]
	v_mfma_f32_16x16x32_bf16 v[20:23], v[132:135], v[214:217], v[20:23]
	v_mfma_f32_16x16x32_bf16 v[8:11], v[140:143], v[214:217], v[8:11]
	v_mfma_f32_16x16x32_bf16 v[40:43], v[160:163], v[184:187], 0
	v_mfma_f32_16x16x32_bf16 v[36:39], v[176:179], v[184:187], 0
	v_mfma_f32_16x16x32_bf16 v[28:31], v[160:163], v[192:195], 0
	v_mfma_f32_16x16x32_bf16 v[24:27], v[176:179], v[192:195], 0
	v_mfma_f32_16x16x32_bf16 v[16:19], v[160:163], v[200:203], 0
	v_mfma_f32_16x16x32_bf16 v[12:15], v[176:179], v[200:203], 0
	v_mfma_f32_16x16x32_bf16 v[4:7], v[160:163], v[208:211], 0
	v_mfma_f32_16x16x32_bf16 v[0:3], v[176:179], v[208:211], 0
	v_mfma_f32_16x16x32_bf16 v[40:43], v[172:175], v[188:191], v[40:43]
	v_mfma_f32_16x16x32_bf16 v[36:39], v[180:183], v[188:191], v[36:39]
	v_mfma_f32_16x16x32_bf16 v[28:31], v[172:175], v[196:199], v[28:31]
	v_mfma_f32_16x16x32_bf16 v[24:27], v[180:183], v[196:199], v[24:27]
	v_mfma_f32_16x16x32_bf16 v[16:19], v[172:175], v[204:207], v[16:19]
	v_mfma_f32_16x16x32_bf16 v[12:15], v[180:183], v[204:207], v[12:15]
	v_mfma_f32_16x16x32_bf16 v[4:7], v[172:175], v[214:217], v[4:7]
	v_mfma_f32_16x16x32_bf16 v[0:3], v[180:183], v[214:217], v[0:3]
	s_barrier
	s_add_i32 s72, 0, 0x18000
	s_add_i32 s73, 0, 0x1c000
	v_add_u32_e32 v140, s72, v167
	v_add_u32_e32 v180, s73, v167
	ds_read_b128 v[128:131], v140
	ds_read_b128 v[132:135], v140 offset:1024
	ds_read_b128 v[136:139], v140 offset:2048
	ds_read_b128 v[140:143], v140 offset:3072
	ds_read_b128 v[160:163], v180
	ds_read_b128 v[172:175], v180 offset:1024
	ds_read_b128 v[176:179], v180 offset:2048
	ds_read_b128 v[180:183], v180 offset:3072
	s_add_u32 s84, s50, 0x80
	s_addc_u32 s85, s51, 0
	s_add_u32 s50, s50, 0x80000
	s_addc_u32 s51, s51, 0
	s_mov_b32 m0, s55
	ds_read_b128 v[184:187], v171 offset:32768
	ds_read_b128 v[188:191], v171 offset:33792
	ds_read_b128 v[192:195], v171 offset:34816
	ds_read_b128 v[196:199], v171 offset:35840
	ds_read_b128 v[200:203], v171 offset:36864
	ds_read_b128 v[204:207], v171 offset:37888
	ds_read_b128 v[208:211], v171 offset:38912
	ds_read_b128 v[214:217], v171 offset:39936
	global_load_lds_dwordx4 v144, s[50:51]
	s_mov_b32 m0, s56
	s_nop 0
	global_load_lds_dwordx4 v148, s[50:51]
	s_waitcnt vmcnt(8) lgkmcnt(0)
	s_barrier
	v_mfma_f32_16x16x32_bf16 v[124:127], v[128:131], v[184:187], v[124:127]
	v_mfma_f32_16x16x32_bf16 v[120:123], v[136:139], v[184:187], v[120:123]
	v_mfma_f32_16x16x32_bf16 v[116:119], v[128:131], v[192:195], v[116:119]
	v_mfma_f32_16x16x32_bf16 v[112:115], v[136:139], v[192:195], v[112:115]
	v_mfma_f32_16x16x32_bf16 v[108:111], v[128:131], v[200:203], v[108:111]
	v_mfma_f32_16x16x32_bf16 v[96:99], v[136:139], v[200:203], v[96:99]
	v_mfma_f32_16x16x32_bf16 v[80:83], v[128:131], v[208:211], v[80:83]
	v_mfma_f32_16x16x32_bf16 v[72:75], v[136:139], v[208:211], v[72:75]
	v_mfma_f32_16x16x32_bf16 v[124:127], v[132:135], v[188:191], v[124:127]
	v_mfma_f32_16x16x32_bf16 v[120:123], v[140:143], v[188:191], v[120:123]
	v_mfma_f32_16x16x32_bf16 v[116:119], v[132:135], v[196:199], v[116:119]
	v_mfma_f32_16x16x32_bf16 v[112:115], v[140:143], v[196:199], v[112:115]
	v_mfma_f32_16x16x32_bf16 v[108:111], v[132:135], v[204:207], v[108:111]
	v_mfma_f32_16x16x32_bf16 v[96:99], v[140:143], v[204:207], v[96:99]
	v_mfma_f32_16x16x32_bf16 v[80:83], v[132:135], v[214:217], v[80:83]
	v_mfma_f32_16x16x32_bf16 v[72:75], v[140:143], v[214:217], v[72:75]
	v_mfma_f32_16x16x32_bf16 v[104:107], v[160:163], v[184:187], v[104:107]
	v_mfma_f32_16x16x32_bf16 v[100:103], v[176:179], v[184:187], v[100:103]
	v_mfma_f32_16x16x32_bf16 v[92:95], v[160:163], v[192:195], v[92:95]
	v_mfma_f32_16x16x32_bf16 v[88:91], v[176:179], v[192:195], v[88:91]
	v_mfma_f32_16x16x32_bf16 v[84:87], v[160:163], v[200:203], v[84:87]
	v_mfma_f32_16x16x32_bf16 v[76:79], v[176:179], v[200:203], v[76:79]
	v_mfma_f32_16x16x32_bf16 v[68:71], v[160:163], v[208:211], v[68:71]
	v_mfma_f32_16x16x32_bf16 v[64:67], v[176:179], v[208:211], v[64:67]
	v_mfma_f32_16x16x32_bf16 v[104:107], v[172:175], v[188:191], v[104:107]
	v_mfma_f32_16x16x32_bf16 v[100:103], v[180:183], v[188:191], v[100:103]
	v_mfma_f32_16x16x32_bf16 v[92:95], v[172:175], v[196:199], v[92:95]
	v_mfma_f32_16x16x32_bf16 v[88:91], v[180:183], v[196:199], v[88:91]
	v_mfma_f32_16x16x32_bf16 v[84:87], v[172:175], v[204:207], v[84:87]
	v_mfma_f32_16x16x32_bf16 v[76:79], v[180:183], v[204:207], v[76:79]
	v_mfma_f32_16x16x32_bf16 v[68:71], v[172:175], v[214:217], v[68:71]
	v_mfma_f32_16x16x32_bf16 v[64:67], v[180:183], v[214:217], v[64:67]
	s_barrier
; #define PG8_STAGE(bufoff, gbase, voff) do { _Pragma("unroll") for (int _i = 0; _i < 2; ++_i) \
;         __builtin_amdgcn_global_load_lds((const unsigned*)((const char*)(gbase) + (voff)[_i]), (PG8_LAS unsigned*)(lds + (bufoff) + ldsw + _i * 8192), 16, 0, 0); } while (0)
; #define PG8_LDA(dst, b, h) do { _Pragma("unroll") for (int m = 0; m < 4; ++m) _Pragma("unroll") for (int k = 0; k < 2; ++k) dst[m][k] = *(const PG8_LAS bf16x8*)(lds + PG8_SA(b, h) + aoff + m * 2048 + k * 1024); } while (0)
; #define PG8_LDB(dst, b, h) do { _Pragma("unroll") for (int n = 0; n < 2; ++n) _Pragma("unroll") for (int k = 0; k < 2; ++k) dst[n][k] = *(const PG8_LAS bf16x8*)(lds + PG8_SB(b, h) + boff + n * 2048 + k * 1024); } while (0)
; #define PG8_MMA(ai, bj, At, Bt) do { __builtin_amdgcn_s_setprio(1); _Pragma("unroll") for (int m = 0; m < 4; ++m) _Pragma("unroll") for (int n = 0; n < 2; ++n) _Pragma("unroll") for (int k = 0; k < 2; ++k) \
;         acc[ai][bj][m][n] = __builtin_amdgcn_mfma_f32_16x16x32_bf16(Bt[n][k], At[m][k], acc[ai][bj][m][n], 0, 0, 0); __builtin_amdgcn_s_setprio(0); } while (0)
; #define PG8_WAIT_V(n) asm volatile("s_waitcnt vmcnt(" #n ")" ::: "memory")
; template <class Epi, class Sched, bool ALIGN_EPI = false, bool SP2 = false>
; __device__ __forceinline__ void gemm_phase(PG8_LAS unsigned char* lds, const Gemm g, const Sched& S, const Epi& E) {
;     ...
;             PG8_LDB(B0, 0, 0); PG8_LDB(B1, 0, 1); PG8_SCHED; PG8_LDA(At, 0, 0); PG8_STAGE(PG8_SA(1, 1), a1 + hstep, voffA);
;             PG8_WAIT_V(8); PG8_WAIT_L(0); PG8_BAR; PG8_MMA(0, 0, At, B0); PG8_MMA(0, 1, At, B1); PG8_BAR; PG8_SCHED;
;             PG8_LDA(At, 0, 1); PG8_STAGE(PG8_SB(0, 0), b2, voffB); PG8_STAGE(PG8_SB(0, 1), b2 + hstep, voffB); PG8_STAGE(PG8_SA(0, 0), a2, voffA);
;             PG8_WAIT_V(8); PG8_WAIT_L(0); PG8_BAR; PG8_MMA(1, 0, At, B0); PG8_MMA(1, 1, At, B1); PG8_BAR; PG8_SCHED;
;             PG8_LDB(B0, 1, 0); PG8_LDB(B1, 1, 1); PG8_SCHED; PG8_LDA(At, 1, 0); PG8_STAGE(PG8_SA(0, 1), a2 + hstep, voffA);
;             PG8_WAIT_V(8); PG8_WAIT_L(0); PG8_BAR; PG8_MMA(0, 0, At, B0); PG8_MMA(0, 1, At, B1); PG8_BAR; PG8_SCHED;
;             PG8_LDA(At, 1, 1); PG8_STAGE(PG8_SB(1, 0), b3, voffB); PG8_STAGE(PG8_SB(1, 1), b3 + hstep, voffB); PG8_STAGE(PG8_SA(1, 0), a3, voffA);
;             PG8_WAIT_V(8); PG8_WAIT_L(0); PG8_BAR; PG8_MMA(1, 0, At, B0); PG8_MMA(1, 1, At, B1); PG8_BAR; PG8_SCHED;
	s_add_i32 s50, s72, s53
	s_add_u32 s86, s48, 0x80
	s_addc_u32 s87, s49, 0
	s_mov_b32 m0, s50
	ds_read_b128 v[184:187], v171 offset:49152
	ds_read_b128 v[188:191], v171 offset:50176
	ds_read_b128 v[192:195], v171 offset:51200
	ds_read_b128 v[196:199], v171 offset:52224
	ds_read_b128 v[200:203], v171 offset:53248
	ds_read_b128 v[204:207], v171 offset:54272
	ds_read_b128 v[208:211], v171 offset:55296
	ds_read_b128 v[214:217], v171 offset:56320
	global_load_lds_dwordx4 v146, s[86:87]
	s_add_i32 m0, s50, 0x2000
	s_add_u32 s48, s48, 0x80080
	s_addc_u32 s49, s49, 0
	s_add_i32 s50, s73, s53
	global_load_lds_dwordx4 v150, s[86:87]
	s_mov_b32 m0, s50
	s_nop 0
	global_load_lds_dwordx4 v146, s[48:49]
	s_add_i32 m0, s50, 0x2000
	s_nop 0
	global_load_lds_dwordx4 v150, s[48:49]
	s_mov_b32 m0, s60
	s_nop 0
	global_load_lds_dwordx4 v144, s[84:85]
	s_mov_b32 m0, s61
	s_nop 0
	global_load_lds_dwordx4 v148, s[84:85]
	s_waitcnt vmcnt(8) lgkmcnt(0)
	s_barrier
	v_mfma_f32_16x16x32_bf16 v[60:63], v[128:131], v[184:187], v[60:63]
	v_mfma_f32_16x16x32_bf16 v[56:59], v[136:139], v[184:187], v[56:59]
	v_mfma_f32_16x16x32_bf16 v[52:55], v[128:131], v[192:195], v[52:55]
	v_mfma_f32_16x16x32_bf16 v[48:51], v[136:139], v[192:195], v[48:51]
	v_mfma_f32_16x16x32_bf16 v[44:47], v[128:131], v[200:203], v[44:47]
	v_mfma_f32_16x16x32_bf16 v[32:35], v[136:139], v[200:203], v[32:35]
	v_mfma_f32_16x16x32_bf16 v[20:23], v[128:131], v[208:211], v[20:23]
	v_mfma_f32_16x16x32_bf16 v[8:11], v[136:139], v[208:211], v[8:11]
	v_mfma_f32_16x16x32_bf16 v[60:63], v[132:135], v[188:191], v[60:63]
	v_mfma_f32_16x16x32_bf16 v[56:59], v[140:143], v[188:191], v[56:59]
	v_mfma_f32_16x16x32_bf16 v[52:55], v[132:135], v[196:199], v[52:55]
	v_mfma_f32_16x16x32_bf16 v[48:51], v[140:143], v[196:199], v[48:51]
	v_mfma_f32_16x16x32_bf16 v[44:47], v[132:135], v[204:207], v[44:47]
	v_mfma_f32_16x16x32_bf16 v[32:35], v[140:143], v[204:207], v[32:35]
	v_mfma_f32_16x16x32_bf16 v[20:23], v[132:135], v[214:217], v[20:23]
	v_mfma_f32_16x16x32_bf16 v[8:11], v[140:143], v[214:217], v[8:11]
	v_mfma_f32_16x16x32_bf16 v[40:43], v[160:163], v[184:187], v[40:43]
	v_mfma_f32_16x16x32_bf16 v[36:39], v[176:179], v[184:187], v[36:39]
	v_mfma_f32_16x16x32_bf16 v[28:31], v[160:163], v[192:195], v[28:31]
	v_mfma_f32_16x16x32_bf16 v[24:27], v[176:179], v[192:195], v[24:27]
	v_mfma_f32_16x16x32_bf16 v[16:19], v[160:163], v[200:203], v[16:19]
	v_mfma_f32_16x16x32_bf16 v[12:15], v[176:179], v[200:203], v[12:15]
	v_mfma_f32_16x16x32_bf16 v[4:7], v[160:163], v[208:211], v[4:7]
	v_mfma_f32_16x16x32_bf16 v[0:3], v[176:179], v[208:211], v[0:3]
	v_mfma_f32_16x16x32_bf16 v[40:43], v[172:175], v[188:191], v[40:43]
	v_mfma_f32_16x16x32_bf16 v[36:39], v[180:183], v[188:191], v[36:39]
	v_mfma_f32_16x16x32_bf16 v[28:31], v[172:175], v[196:199], v[28:31]
	v_mfma_f32_16x16x32_bf16 v[24:27], v[180:183], v[196:199], v[24:27]
	v_mfma_f32_16x16x32_bf16 v[16:19], v[172:175], v[204:207], v[16:19]
	v_mfma_f32_16x16x32_bf16 v[12:15], v[180:183], v[204:207], v[12:15]
	v_mfma_f32_16x16x32_bf16 v[4:7], v[172:175], v[214:217], v[4:7]
	v_mfma_f32_16x16x32_bf16 v[0:3], v[180:183], v[214:217], v[0:3]
	s_barrier
	s_add_i32 s71, s71, 2
	s_add_u32 s46, s46, 0x100
	s_addc_u32 s47, s47, 0
	s_add_u32 s69, s69, 0x100
	s_addc_u32 s70, s70, 0
	s_cmp_gt_u32 s71, 29
.LBB0_827:
	ds_read_b128 v[128:131], v169
	ds_read_b128 v[132:135], v169 offset:1024
	ds_read_b128 v[136:139], v169 offset:2048
	ds_read_b128 v[140:143], v169 offset:3072
	ds_read_b128 v[160:163], v170
	ds_read_b128 v[172:175], v170 offset:1024
	ds_read_b128 v[176:179], v170 offset:2048
	ds_read_b128 v[180:183], v170 offset:3072
	s_add_u32 s48, s46, 0xfff80080
	s_addc_u32 s49, s47, -1
	s_cmp_eq_u32 s71, 28
	s_cselect_b32 s51, s39, s49
	s_cselect_b32 s50, s67, s48
	s_cselect_b32 s49, s37, s70
	s_cselect_b32 s48, s68, s69
	s_add_i32 m0, s45, 0xc000
	ds_read_b128 v[184:187], v171
	ds_read_b128 v[188:191], v171 offset:1024
	ds_read_b128 v[192:195], v171 offset:2048
	ds_read_b128 v[196:199], v171 offset:3072
	ds_read_b128 v[200:203], v171 offset:4096
	ds_read_b128 v[204:207], v171 offset:5120
	ds_read_b128 v[208:211], v171 offset:6144
	ds_read_b128 v[214:217], v171 offset:7168
	global_load_lds_dwordx4 v152, s[46:47]
	s_add_i32 m0, s45, 0xe000
	s_nop 0
	global_load_lds_dwordx4 v154, s[46:47]
	s_waitcnt vmcnt(8) lgkmcnt(0)
	s_barrier
	v_mfma_f32_16x16x32_bf16 v[124:127], v[128:131], v[184:187], v[124:127]
	v_mfma_f32_16x16x32_bf16 v[120:123], v[136:139], v[184:187], v[120:123]
	v_mfma_f32_16x16x32_bf16 v[116:119], v[128:131], v[192:195], v[116:119]
	v_mfma_f32_16x16x32_bf16 v[112:115], v[136:139], v[192:195], v[112:115]
	v_mfma_f32_16x16x32_bf16 v[108:111], v[128:131], v[200:203], v[108:111]
	v_mfma_f32_16x16x32_bf16 v[96:99], v[136:139], v[200:203], v[96:99]
	v_mfma_f32_16x16x32_bf16 v[80:83], v[128:131], v[208:211], v[80:83]
	v_mfma_f32_16x16x32_bf16 v[72:75], v[136:139], v[208:211], v[72:75]
	v_mfma_f32_16x16x32_bf16 v[124:127], v[132:135], v[188:191], v[124:127]
	v_mfma_f32_16x16x32_bf16 v[120:123], v[140:143], v[188:191], v[120:123]
	v_mfma_f32_16x16x32_bf16 v[116:119], v[132:135], v[196:199], v[116:119]
	v_mfma_f32_16x16x32_bf16 v[112:115], v[140:143], v[196:199], v[112:115]
	v_mfma_f32_16x16x32_bf16 v[108:111], v[132:135], v[204:207], v[108:111]
	v_mfma_f32_16x16x32_bf16 v[96:99], v[140:143], v[204:207], v[96:99]
	v_mfma_f32_16x16x32_bf16 v[80:83], v[132:135], v[214:217], v[80:83]
	v_mfma_f32_16x16x32_bf16 v[72:75], v[140:143], v[214:217], v[72:75]
	v_mfma_f32_16x16x32_bf16 v[104:107], v[160:163], v[184:187], v[104:107]
	v_mfma_f32_16x16x32_bf16 v[100:103], v[176:179], v[184:187], v[100:103]
	v_mfma_f32_16x16x32_bf16 v[92:95], v[160:163], v[192:195], v[92:95]
	v_mfma_f32_16x16x32_bf16 v[88:91], v[176:179], v[192:195], v[88:91]
	v_mfma_f32_16x16x32_bf16 v[84:87], v[160:163], v[200:203], v[84:87]
	v_mfma_f32_16x16x32_bf16 v[76:79], v[176:179], v[200:203], v[76:79]
	v_mfma_f32_16x16x32_bf16 v[68:71], v[160:163], v[208:211], v[68:71]
	v_mfma_f32_16x16x32_bf16 v[64:67], v[176:179], v[208:211], v[64:67]
	v_mfma_f32_16x16x32_bf16 v[104:107], v[172:175], v[188:191], v[104:107]
	v_mfma_f32_16x16x32_bf16 v[100:103], v[180:183], v[188:191], v[100:103]
	v_mfma_f32_16x16x32_bf16 v[92:95], v[172:175], v[196:199], v[92:95]
	v_mfma_f32_16x16x32_bf16 v[88:91], v[180:183], v[196:199], v[88:91]
	v_mfma_f32_16x16x32_bf16 v[84:87], v[172:175], v[204:207], v[84:87]
	v_mfma_f32_16x16x32_bf16 v[76:79], v[180:183], v[204:207], v[76:79]
	v_mfma_f32_16x16x32_bf16 v[68:71], v[172:175], v[214:217], v[68:71]
	v_mfma_f32_16x16x32_bf16 v[64:67], v[180:183], v[214:217], v[64:67]
	s_barrier
; #define PG8_STAGE(bufoff, gbase, voff) do { _Pragma("unroll") for (int _i = 0; _i < 2; ++_i) \
;         __builtin_amdgcn_global_load_lds((const unsigned*)((const char*)(gbase) + (voff)[_i]), (PG8_LAS unsigned*)(lds + (bufoff) + ldsw + _i * 8192), 16, 0, 0); } while (0)
; #define PG8_LDA(dst, b, h) do { _Pragma("unroll") for (int m = 0; m < 4; ++m) _Pragma("unroll") for (int k = 0; k < 2; ++k) dst[m][k] = *(const PG8_LAS bf16x8*)(lds + PG8_SA(b, h) + aoff + m * 2048 + k * 1024); } while (0)
; #define PG8_LDB(dst, b, h) do { _Pragma("unroll") for (int n = 0; n < 2; ++n) _Pragma("unroll") for (int k = 0; k < 2; ++k) dst[n][k] = *(const PG8_LAS bf16x8*)(lds + PG8_SB(b, h) + boff + n * 2048 + k * 1024); } while (0)
; #define PG8_MMA(ai, bj, At, Bt) do { __builtin_amdgcn_s_setprio(1); _Pragma("unroll") for (int m = 0; m < 4; ++m) _Pragma("unroll") for (int n = 0; n < 2; ++n) _Pragma("unroll") for (int k = 0; k < 2; ++k) \
;         acc[ai][bj][m][n] = __builtin_amdgcn_mfma_f32_16x16x32_bf16(Bt[n][k], At[m][k], acc[ai][bj][m][n], 0, 0, 0); __builtin_amdgcn_s_setprio(0); } while (0)
; #define PG8_WAIT_V(n) asm volatile("s_waitcnt vmcnt(" #n ")" ::: "memory")
; #define PG8_WAIT_L(n) asm volatile("s_waitcnt lgkmcnt(" #n ")" ::: "memory")
; #define PG8_BAR __builtin_amdgcn_s_barrier()
; #define PG8_SCHED __builtin_amdgcn_sched_barrier(0)
; template <class Epi, class Sched, bool ALIGN_EPI = false, bool SP2 = false>
; __device__ __forceinline__ void gemm_phase(PG8_LAS unsigned char* lds, const Gemm g, const Sched& S, const Epi& E) {
;     ...
;             PG8_LDA(At, 0, 1); PG8_STAGE(PG8_SB(0, 0), b2, voffB); PG8_STAGE(PG8_SB(0, 1), b2 + hstep, voffB); PG8_STAGE(PG8_SA(0, 0), a2, voffA);
;             PG8_WAIT_V(8); PG8_WAIT_L(0); PG8_BAR; PG8_MMA(1, 0, At, B0); PG8_MMA(1, 1, At, B1); PG8_BAR; PG8_SCHED;
;             PG8_LDB(B0, 1, 0); PG8_LDB(B1, 1, 1); PG8_SCHED; PG8_LDA(At, 1, 0); PG8_STAGE(PG8_SA(0, 1), a2 + hstep, voffA);
;             PG8_WAIT_V(8); PG8_WAIT_L(0); PG8_BAR; PG8_MMA(0, 0, At, B0); PG8_MMA(0, 1, At, B1); PG8_BAR; PG8_SCHED;
	s_add_i32 s72, s64, s53
	s_mov_b32 m0, s72
	ds_read_b128 v[184:187], v171 offset:16384
	ds_read_b128 v[188:191], v171 offset:17408
	ds_read_b128 v[192:195], v171 offset:18432
	ds_read_b128 v[196:199], v171 offset:19456
	ds_read_b128 v[200:203], v171 offset:20480
	ds_read_b128 v[204:207], v171 offset:21504
	ds_read_b128 v[208:211], v171 offset:22528
	ds_read_b128 v[214:217], v171 offset:23552
	global_load_lds_dwordx4 v146, s[48:49]
	s_add_i32 m0, s72, 0x2000
	s_add_u32 s72, s48, 0x80000
	s_addc_u32 s73, s49, 0
	s_add_i32 s74, s65, s53
	global_load_lds_dwordx4 v150, s[48:49]
	s_mov_b32 m0, s74
	s_nop 0
	global_load_lds_dwordx4 v146, s[72:73]
	s_add_i32 m0, s74, 0x2000
	s_nop 0
	global_load_lds_dwordx4 v150, s[72:73]
	s_mov_b32 m0, s45
	s_nop 0
	global_load_lds_dwordx4 v144, s[50:51]
	s_mov_b32 m0, s54
	s_nop 0
	global_load_lds_dwordx4 v148, s[50:51]
	s_waitcnt vmcnt(8) lgkmcnt(0)
	s_barrier
	v_mfma_f32_16x16x32_bf16 v[60:63], v[128:131], v[184:187], v[60:63]
	v_mfma_f32_16x16x32_bf16 v[56:59], v[136:139], v[184:187], v[56:59]
	v_mfma_f32_16x16x32_bf16 v[52:55], v[128:131], v[192:195], v[52:55]
	v_mfma_f32_16x16x32_bf16 v[48:51], v[136:139], v[192:195], v[48:51]
	v_mfma_f32_16x16x32_bf16 v[44:47], v[128:131], v[200:203], v[44:47]
	v_mfma_f32_16x16x32_bf16 v[32:35], v[136:139], v[200:203], v[32:35]
	v_mfma_f32_16x16x32_bf16 v[20:23], v[128:131], v[208:211], v[20:23]
	v_mfma_f32_16x16x32_bf16 v[8:11], v[136:139], v[208:211], v[8:11]
	v_mfma_f32_16x16x32_bf16 v[60:63], v[132:135], v[188:191], v[60:63]
	v_mfma_f32_16x16x32_bf16 v[56:59], v[140:143], v[188:191], v[56:59]
	v_mfma_f32_16x16x32_bf16 v[52:55], v[132:135], v[196:199], v[52:55]
	v_mfma_f32_16x16x32_bf16 v[48:51], v[140:143], v[196:199], v[48:51]
	v_mfma_f32_16x16x32_bf16 v[44:47], v[132:135], v[204:207], v[44:47]
	v_mfma_f32_16x16x32_bf16 v[32:35], v[140:143], v[204:207], v[32:35]
	v_mfma_f32_16x16x32_bf16 v[20:23], v[132:135], v[214:217], v[20:23]
	v_mfma_f32_16x16x32_bf16 v[8:11], v[140:143], v[214:217], v[8:11]
	v_mfma_f32_16x16x32_bf16 v[40:43], v[160:163], v[184:187], v[40:43]
	v_mfma_f32_16x16x32_bf16 v[36:39], v[176:179], v[184:187], v[36:39]
	v_mfma_f32_16x16x32_bf16 v[28:31], v[160:163], v[192:195], v[28:31]
	v_mfma_f32_16x16x32_bf16 v[24:27], v[176:179], v[192:195], v[24:27]
	v_mfma_f32_16x16x32_bf16 v[16:19], v[160:163], v[200:203], v[16:19]
	v_mfma_f32_16x16x32_bf16 v[12:15], v[176:179], v[200:203], v[12:15]
	v_mfma_f32_16x16x32_bf16 v[4:7], v[160:163], v[208:211], v[4:7]
	v_mfma_f32_16x16x32_bf16 v[0:3], v[176:179], v[208:211], v[0:3]
	v_mfma_f32_16x16x32_bf16 v[40:43], v[172:175], v[188:191], v[40:43]
	v_mfma_f32_16x16x32_bf16 v[36:39], v[180:183], v[188:191], v[36:39]
	v_mfma_f32_16x16x32_bf16 v[28:31], v[172:175], v[196:199], v[28:31]
	v_mfma_f32_16x16x32_bf16 v[24:27], v[180:183], v[196:199], v[24:27]
	v_mfma_f32_16x16x32_bf16 v[16:19], v[172:175], v[204:207], v[16:19]
	v_mfma_f32_16x16x32_bf16 v[12:15], v[180:183], v[204:207], v[12:15]
	v_mfma_f32_16x16x32_bf16 v[4:7], v[172:175], v[214:217], v[4:7]
	v_mfma_f32_16x16x32_bf16 v[0:3], v[180:183], v[214:217], v[0:3]
	s_barrier
	s_add_i32 s72, 0, 0x18000
	s_add_i32 s73, 0, 0x1c000
	v_add_u32_e32 v140, s72, v167
	v_add_u32_e32 v180, s73, v167
	ds_read_b128 v[128:131], v140
	ds_read_b128 v[132:135], v140 offset:1024
	ds_read_b128 v[136:139], v140 offset:2048
	ds_read_b128 v[140:143], v140 offset:3072
	ds_read_b128 v[160:163], v180
	ds_read_b128 v[172:175], v180 offset:1024
	ds_read_b128 v[176:179], v180 offset:2048
	ds_read_b128 v[180:183], v180 offset:3072
	s_add_u32 s84, s50, 0x80
	s_addc_u32 s85, s51, 0
	s_add_u32 s50, s50, 0x80000
	s_addc_u32 s51, s51, 0
	s_mov_b32 m0, s55
	ds_read_b128 v[184:187], v171 offset:32768
	ds_read_b128 v[188:191], v171 offset:33792
	ds_read_b128 v[192:195], v171 offset:34816
	ds_read_b128 v[196:199], v171 offset:35840
	ds_read_b128 v[200:203], v171 offset:36864
	ds_read_b128 v[204:207], v171 offset:37888
	ds_read_b128 v[208:211], v171 offset:38912
	ds_read_b128 v[214:217], v171 offset:39936
	global_load_lds_dwordx4 v144, s[50:51]
	s_mov_b32 m0, s56
	s_nop 0
	global_load_lds_dwordx4 v148, s[50:51]
	s_waitcnt vmcnt(8) lgkmcnt(0)
	s_barrier
	v_mfma_f32_16x16x32_bf16 v[124:127], v[128:131], v[184:187], v[124:127]
	v_mfma_f32_16x16x32_bf16 v[120:123], v[136:139], v[184:187], v[120:123]
	v_mfma_f32_16x16x32_bf16 v[116:119], v[128:131], v[192:195], v[116:119]
	v_mfma_f32_16x16x32_bf16 v[112:115], v[136:139], v[192:195], v[112:115]
	v_mfma_f32_16x16x32_bf16 v[108:111], v[128:131], v[200:203], v[108:111]
	v_mfma_f32_16x16x32_bf16 v[96:99], v[136:139], v[200:203], v[96:99]
	v_mfma_f32_16x16x32_bf16 v[80:83], v[128:131], v[208:211], v[80:83]
	v_mfma_f32_16x16x32_bf16 v[72:75], v[136:139], v[208:211], v[72:75]
	v_mfma_f32_16x16x32_bf16 v[124:127], v[132:135], v[188:191], v[124:127]
	v_mfma_f32_16x16x32_bf16 v[120:123], v[140:143], v[188:191], v[120:123]
	v_mfma_f32_16x16x32_bf16 v[116:119], v[132:135], v[196:199], v[116:119]
	v_mfma_f32_16x16x32_bf16 v[112:115], v[140:143], v[196:199], v[112:115]
	v_mfma_f32_16x16x32_bf16 v[108:111], v[132:135], v[204:207], v[108:111]
	v_mfma_f32_16x16x32_bf16 v[96:99], v[140:143], v[204:207], v[96:99]
	v_mfma_f32_16x16x32_bf16 v[80:83], v[132:135], v[214:217], v[80:83]
	v_mfma_f32_16x16x32_bf16 v[72:75], v[140:143], v[214:217], v[72:75]
	v_mfma_f32_16x16x32_bf16 v[104:107], v[160:163], v[184:187], v[104:107]
	v_mfma_f32_16x16x32_bf16 v[100:103], v[176:179], v[184:187], v[100:103]
	v_mfma_f32_16x16x32_bf16 v[92:95], v[160:163], v[192:195], v[92:95]
	v_mfma_f32_16x16x32_bf16 v[88:91], v[176:179], v[192:195], v[88:91]
	v_mfma_f32_16x16x32_bf16 v[84:87], v[160:163], v[200:203], v[84:87]
	v_mfma_f32_16x16x32_bf16 v[76:79], v[176:179], v[200:203], v[76:79]
	v_mfma_f32_16x16x32_bf16 v[68:71], v[160:163], v[208:211], v[68:71]
	v_mfma_f32_16x16x32_bf16 v[64:67], v[176:179], v[208:211], v[64:67]
	v_mfma_f32_16x16x32_bf16 v[104:107], v[172:175], v[188:191], v[104:107]
	v_mfma_f32_16x16x32_bf16 v[100:103], v[180:183], v[188:191], v[100:103]
	v_mfma_f32_16x16x32_bf16 v[92:95], v[172:175], v[196:199], v[92:95]
	v_mfma_f32_16x16x32_bf16 v[88:91], v[180:183], v[196:199], v[88:91]
	v_mfma_f32_16x16x32_bf16 v[84:87], v[172:175], v[204:207], v[84:87]
	v_mfma_f32_16x16x32_bf16 v[76:79], v[180:183], v[204:207], v[76:79]
	v_mfma_f32_16x16x32_bf16 v[68:71], v[172:175], v[214:217], v[68:71]
	v_mfma_f32_16x16x32_bf16 v[64:67], v[180:183], v[214:217], v[64:67]
	s_barrier
; #define PG8_STAGE(bufoff, gbase, voff) do { _Pragma("unroll") for (int _i = 0; _i < 2; ++_i) \
;         __builtin_amdgcn_global_load_lds((const unsigned*)((const char*)(gbase) + (voff)[_i]), (PG8_LAS unsigned*)(lds + (bufoff) + ldsw + _i * 8192), 16, 0, 0); } while (0)
; #define PG8_LDA(dst, b, h) do { _Pragma("unroll") for (int m = 0; m < 4; ++m) _Pragma("unroll") for (int k = 0; k < 2; ++k) dst[m][k] = *(const PG8_LAS bf16x8*)(lds + PG8_SA(b, h) + aoff + m * 2048 + k * 1024); } while (0)
; #define PG8_MMA(ai, bj, At, Bt) do { __builtin_amdgcn_s_setprio(1); _Pragma("unroll") for (int m = 0; m < 4; ++m) _Pragma("unroll") for (int n = 0; n < 2; ++n) _Pragma("unroll") for (int k = 0; k < 2; ++k) \
;         acc[ai][bj][m][n] = __builtin_amdgcn_mfma_f32_16x16x32_bf16(Bt[n][k], At[m][k], acc[ai][bj][m][n], 0, 0, 0); __builtin_amdgcn_s_setprio(0); } while (0)
; #define PG8_WAIT_V(n) asm volatile("s_waitcnt vmcnt(" #n ")" ::: "memory")
; #define PG8_WAIT_L(n) asm volatile("s_waitcnt lgkmcnt(" #n ")" ::: "memory")
;     __device__ __forceinline__ void operator()(const f32x4 (&acc)[2][2][4][2], const Unit& u, int wr, int wc, int fr, int fq) const {
;         const int row0 = u.pm * BM + wr * 64 + fr, col0 = u.pn * BM + wc * 32 + 8 * fq;
;         const float* gp = gate + (u.pm >> 5) * 18432 + col0;
;         f32x4 gv[2][2];
; #pragma unroll
;         for (int bj = 0; bj < 2; ++bj)
; #pragma unroll
;             for (int n = 0; n < 2; ++n) gv[bj][n] = *(const f32x4*)(gp + bj * HALF + 4 * n) * scale;
; #pragma unroll
;         for (int ai = 0; ai < 2; ++ai) { f32x4 r[4][2][2];
; #pragma unroll
;             for (int m = 0; m < 4; ++m) { const size_t off = (size_t)(row0 + ai * HALF + m * 16) * 2048 + col0;
; #pragma unroll
;                 for (int bj = 0; bj < 2; ++bj)
; #pragma unroll
;                     for (int n = 0; n < 2; ++n) r[m][bj][n] = *(const f32x4*)(res + off + bj * HALF + 4 * n); }
; template <class Epi, class Sched, bool ALIGN_EPI = false, bool SP2 = false>
; __device__ __forceinline__ void gemm_phase(PG8_LAS unsigned char* lds, const Gemm g, const Sched& S, const Epi& E) {
;     ...
;             PG8_LDA(At, 1, 1); PG8_STAGE(PG8_SB(1, 0), b3, voffB); PG8_STAGE(PG8_SB(1, 1), b3 + hstep, voffB); PG8_STAGE(PG8_SA(1, 0), a3, voffA);
;             PG8_WAIT_V(8); PG8_WAIT_L(0); PG8_BAR; PG8_MMA(1, 0, At, B0); PG8_MMA(1, 1, At, B1); PG8_BAR; PG8_SCHED;
	s_add_i32 s50, s72, s53
	s_add_u32 s86, s48, 0x80
	s_addc_u32 s87, s49, 0
	s_mov_b32 m0, s50
	ds_read_b128 v[184:187], v171 offset:49152
	ds_read_b128 v[188:191], v171 offset:50176
	ds_read_b128 v[192:195], v171 offset:51200
	ds_read_b128 v[196:199], v171 offset:52224
	ds_read_b128 v[200:203], v171 offset:53248
	ds_read_b128 v[204:207], v171 offset:54272
	ds_read_b128 v[208:211], v171 offset:55296
	ds_read_b128 v[214:217], v171 offset:56320
	global_load_lds_dwordx4 v146, s[86:87]
	s_add_i32 m0, s50, 0x2000
	s_add_u32 s48, s48, 0x80080
	s_addc_u32 s49, s49, 0
	s_add_i32 s50, s73, s53
	global_load_lds_dwordx4 v150, s[86:87]
	s_mov_b32 m0, s50
	s_nop 0
	global_load_lds_dwordx4 v146, s[48:49]
	s_add_i32 m0, s50, 0x2000
	s_nop 0
	global_load_lds_dwordx4 v150, s[48:49]
	s_mov_b32 m0, s60
	s_nop 0
	global_load_lds_dwordx4 v144, s[84:85]
	s_mov_b32 m0, s61
	s_nop 0
	global_load_lds_dwordx4 v148, s[84:85]
	s_waitcnt vmcnt(8) lgkmcnt(0)
	s_barrier
	v_mfma_f32_16x16x32_bf16 v[60:63], v[128:131], v[184:187], v[60:63]
	v_mfma_f32_16x16x32_bf16 v[56:59], v[136:139], v[184:187], v[56:59]
	v_mfma_f32_16x16x32_bf16 v[52:55], v[128:131], v[192:195], v[52:55]
	v_mfma_f32_16x16x32_bf16 v[48:51], v[136:139], v[192:195], v[48:51]
	v_mfma_f32_16x16x32_bf16 v[44:47], v[128:131], v[200:203], v[44:47]
	v_mfma_f32_16x16x32_bf16 v[32:35], v[136:139], v[200:203], v[32:35]
	v_mfma_f32_16x16x32_bf16 v[20:23], v[128:131], v[208:211], v[20:23]
	v_mfma_f32_16x16x32_bf16 v[8:11], v[136:139], v[208:211], v[8:11]
	v_mfma_f32_16x16x32_bf16 v[60:63], v[132:135], v[188:191], v[60:63]
	v_mfma_f32_16x16x32_bf16 v[56:59], v[140:143], v[188:191], v[56:59]
	v_mfma_f32_16x16x32_bf16 v[52:55], v[132:135], v[196:199], v[52:55]
	v_mfma_f32_16x16x32_bf16 v[48:51], v[140:143], v[196:199], v[48:51]
	v_mfma_f32_16x16x32_bf16 v[44:47], v[132:135], v[204:207], v[44:47]
	v_mfma_f32_16x16x32_bf16 v[32:35], v[140:143], v[204:207], v[32:35]
	v_mfma_f32_16x16x32_bf16 v[20:23], v[132:135], v[214:217], v[20:23]
	v_mfma_f32_16x16x32_bf16 v[8:11], v[140:143], v[214:217], v[8:11]
	v_mfma_f32_16x16x32_bf16 v[40:43], v[160:163], v[184:187], v[40:43]
	v_mfma_f32_16x16x32_bf16 v[36:39], v[176:179], v[184:187], v[36:39]
	v_mfma_f32_16x16x32_bf16 v[28:31], v[160:163], v[192:195], v[28:31]
	v_mfma_f32_16x16x32_bf16 v[24:27], v[176:179], v[192:195], v[24:27]
	v_mfma_f32_16x16x32_bf16 v[16:19], v[160:163], v[200:203], v[16:19]
	v_mfma_f32_16x16x32_bf16 v[12:15], v[176:179], v[200:203], v[12:15]
	v_mfma_f32_16x16x32_bf16 v[4:7], v[160:163], v[208:211], v[4:7]
	v_mfma_f32_16x16x32_bf16 v[0:3], v[176:179], v[208:211], v[0:3]
	v_mfma_f32_16x16x32_bf16 v[40:43], v[172:175], v[188:191], v[40:43]
	v_mfma_f32_16x16x32_bf16 v[36:39], v[180:183], v[188:191], v[36:39]
	v_mfma_f32_16x16x32_bf16 v[28:31], v[172:175], v[196:199], v[28:31]
	v_mfma_f32_16x16x32_bf16 v[24:27], v[180:183], v[196:199], v[24:27]
	v_mfma_f32_16x16x32_bf16 v[16:19], v[172:175], v[204:207], v[16:19]
	v_mfma_f32_16x16x32_bf16 v[12:15], v[180:183], v[204:207], v[12:15]
	v_mfma_f32_16x16x32_bf16 v[4:7], v[172:175], v[214:217], v[4:7]
	v_mfma_f32_16x16x32_bf16 v[0:3], v[180:183], v[214:217], v[0:3]
	s_barrier
	s_add_i32 s71, s71, 2
	s_add_u32 s46, s46, 0x100
	s_addc_u32 s47, s47, 0
	s_add_u32 s69, s69, 0x100
	s_addc_u32 s70, s70, 0
	s_cmp_gt_u32 s71, 29
	s_cbranch_scc0 .LBB0_827
	s_lshr_b32 s37, s44, 5
	s_mul_i32 s46, s37, 0x4800
	v_lshl_or_b32 v128, s66, 8, v168
	s_ashr_i32 s47, s46, 31
	v_lshl_add_u32 v212, s44, 8, v166
	s_lshl_b64 s[46:47], s[46:47], 2
	v_ashrrev_i32_e32 v129, 31, v128
	v_or_b32_e32 v188, 16, v212
	v_or_b32_e32 v204, 32, v212
	s_add_u32 s46, s58, s46
	v_lshlrev_b64 v[160:161], 2, v[128:129]
	v_ashrrev_i32_e32 v213, 31, v212
	v_ashrrev_i32_e32 v189, 31, v188
	v_ashrrev_i32_e32 v205, 31, v204
	s_addc_u32 s47, s59, s47
	v_lshl_add_u64 v[162:163], s[12:13], 0, v[160:161]
	v_lshlrev_b64 v[164:165], 13, v[212:213]
	v_lshlrev_b64 v[218:219], 13, v[188:189]
	v_lshlrev_b64 v[230:231], 13, v[204:205]
	v_or_b32_e32 v212, 48, v212
	v_lshl_add_u64 v[136:137], s[46:47], 0, v[160:161]
	v_lshl_add_u64 v[184:185], v[162:163], 0, v[164:165]
	v_lshl_add_u64 v[200:201], v[162:163], 0, v[218:219]
	v_lshl_add_u64 v[222:223], v[162:163], 0, v[230:231]
	v_ashrrev_i32_e32 v213, 31, v212
	global_load_dwordx4 v[132:135], v[136:137], off offset:16
	global_load_dwordx4 v[140:143], v[136:137], off
	global_load_dwordx4 v[172:175], v[184:185], off offset:16
	global_load_dwordx4 v[176:179], v[184:185], off
	global_load_dwordx4 v[128:131], v[136:137], off offset:528
	s_nop 0
	global_load_dwordx4 v[136:139], v[136:137], off offset:512
	s_nop 0
	global_load_dwordx4 v[180:183], v[184:185], off offset:528
	s_nop 0
	global_load_dwordx4 v[184:187], v[184:185], off offset:512
	s_nop 0
	global_load_dwordx4 v[188:191], v[200:201], off
	global_load_dwordx4 v[192:195], v[200:201], off offset:16
	global_load_dwordx4 v[196:199], v[200:201], off offset:528
	s_nop 0
	global_load_dwordx4 v[200:203], v[200:201], off offset:512
	s_nop 0
	global_load_dwordx4 v[204:207], v[222:223], off
	global_load_dwordx4 v[208:211], v[222:223], off offset:16
	global_load_dwordx4 v[214:217], v[222:223], off offset:512
	s_nop 0
	global_load_dwordx4 v[222:225], v[222:223], off offset:528
	v_lshlrev_b64 v[212:213], 13, v[212:213]
	v_lshl_add_u64 v[244:245], v[162:163], 0, v[212:213]
	global_load_dwordx4 v[232:235], v[244:245], off
	global_load_dwordx4 v[236:239], v[244:245], off offset:16
	global_load_dwordx4 v[240:243], v[244:245], off offset:512
	s_nop 0
	global_load_dwordx4 v[244:247], v[244:245], off offset:528
	v_lshl_add_u64 v[248:249], s[14:15], 0, v[164:165]
	v_lshl_add_u64 v[248:249], v[248:249], 0, v[160:161]
	v_lshl_add_u64 v[218:219], s[14:15], 0, v[218:219]
	v_lshl_add_u64 v[230:231], s[14:15], 0, v[230:231]
	v_lshl_add_u64 v[218:219], v[218:219], 0, v[160:161]
	v_lshl_add_u64 v[230:231], v[230:231], 0, v[160:161]
	s_and_b64 vcc, exec, s[10:11]
	s_mov_b32 s66, s36
	s_mov_b32 s44, s38
	s_mov_b64 s[48:49], s[42:43]
	s_mov_b64 s[46:47], s[40:41]
	s_waitcnt vmcnt(0)
;     __device__ __forceinline__ void operator()(const f32x4 (&acc)[2][2][4][2], const Unit& u, int wr, int wc, int fr, int fq) const {
;     ...
;         for (int ai = 0; ai < 2; ++ai) { f32x4 r[4][2][2];
; #pragma unroll
;             for (int m = 0; m < 4; ++m) { const size_t off = (size_t)(row0 + ai * HALF + m * 16) * 2048 + col0;
; #pragma unroll
;                 for (int bj = 0; bj < 2; ++bj)
; #pragma unroll
;                     for (int n = 0; n < 2; ++n) r[m][bj][n] = *(const f32x4*)(res + off + bj * HALF + 4 * n); }
; #pragma unroll
;             for (int m = 0; m < 4; ++m) { const size_t off = (size_t)(row0 + ai * HALF + m * 16) * 2048 + col0;
; #pragma unroll
;                 for (int bj = 0; bj < 2; ++bj)
; #pragma unroll
;                     for (int n = 0; n < 2; ++n) *(f32x4*)(out + off + bj * HALF + 4 * n) = r[m][bj][n] + gv[bj][n] * acc[ai][bj][m][n]; } }
	v_pk_fma_f32 v[122:123], v[122:123], v[134:135], v[174:175]
	v_pk_fma_f32 v[126:127], v[126:127], v[142:143], v[178:179]
	v_pk_fma_f32 v[124:125], v[124:125], v[140:141], v[176:177]
	v_pk_fma_f32 v[120:121], v[120:121], v[132:133], v[172:173]
	v_pk_fma_f32 v[76:77], v[76:77], v[128:129], v[222:223]
	v_pk_fma_f32 v[106:107], v[106:107], v[138:139], v[186:187]
	v_pk_fma_f32 v[104:105], v[104:105], v[136:137], v[184:185]
	v_pk_fma_f32 v[102:103], v[102:103], v[130:131], v[182:183]
	v_pk_fma_f32 v[100:101], v[100:101], v[128:129], v[180:181]
	v_pk_fma_f32 v[118:119], v[118:119], v[142:143], v[190:191]
	v_pk_fma_f32 v[116:117], v[116:117], v[140:141], v[188:189]
	v_pk_fma_f32 v[114:115], v[114:115], v[134:135], v[194:195]
	v_pk_fma_f32 v[112:113], v[112:113], v[132:133], v[192:193]
	v_pk_fma_f32 v[94:95], v[94:95], v[138:139], v[202:203]
	v_pk_fma_f32 v[92:93], v[92:93], v[136:137], v[200:201]
	v_pk_fma_f32 v[90:91], v[90:91], v[130:131], v[198:199]
	v_pk_fma_f32 v[88:89], v[88:89], v[128:129], v[196:197]
	v_pk_fma_f32 v[110:111], v[110:111], v[142:143], v[206:207]
	v_pk_fma_f32 v[108:109], v[108:109], v[140:141], v[204:205]
	v_pk_fma_f32 v[98:99], v[98:99], v[134:135], v[210:211]
	v_pk_fma_f32 v[96:97], v[96:97], v[132:133], v[208:209]
	v_pk_fma_f32 v[86:87], v[86:87], v[138:139], v[216:217]
	v_pk_fma_f32 v[84:85], v[84:85], v[136:137], v[214:215]
	v_pk_fma_f32 v[78:79], v[78:79], v[130:131], v[224:225]
	global_store_dwordx4 v[248:249], v[124:127], off
	global_store_dwordx4 v[248:249], v[120:123], off offset:16
	global_store_dwordx4 v[248:249], v[104:107], off offset:512
	global_store_dwordx4 v[248:249], v[100:103], off offset:528
	global_store_dwordx4 v[218:219], v[116:119], off
	global_store_dwordx4 v[218:219], v[112:115], off offset:16
	global_store_dwordx4 v[218:219], v[92:95], off offset:512
	global_store_dwordx4 v[218:219], v[88:91], off offset:528
	global_store_dwordx4 v[230:231], v[108:111], off
	global_store_dwordx4 v[230:231], v[96:99], off offset:16
	global_store_dwordx4 v[230:231], v[84:87], off offset:512
	global_store_dwordx4 v[230:231], v[76:79], off offset:528
	v_pk_fma_f32 v[74:75], v[74:75], v[134:135], v[238:239]
	v_pk_fma_f32 v[72:73], v[72:73], v[132:133], v[236:237]
	v_pk_fma_f32 v[76:77], v[80:81], v[140:141], v[232:233]
	v_lshl_add_u64 v[80:81], s[14:15], 0, v[212:213]
	v_pk_fma_f32 v[78:79], v[82:83], v[142:143], v[234:235]
	v_lshl_add_u64 v[80:81], v[80:81], 0, v[160:161]
	v_pk_fma_f32 v[70:71], v[70:71], v[138:139], v[242:243]
	v_pk_fma_f32 v[68:69], v[68:69], v[136:137], v[240:241]
	v_pk_fma_f32 v[66:67], v[66:67], v[130:131], v[246:247]
	v_pk_fma_f32 v[64:65], v[64:65], v[128:129], v[244:245]
	v_lshl_add_u64 v[172:173], v[164:165], 0, s[26:27]
	v_lshl_add_u64 v[174:175], v[164:165], 0, s[28:29]
	v_lshl_add_u64 v[176:177], v[164:165], 0, s[30:31]
	global_store_dwordx4 v[80:81], v[76:79], off
	global_store_dwordx4 v[80:81], v[72:75], off offset:16
	global_store_dwordx4 v[80:81], v[68:71], off offset:512
	global_store_dwordx4 v[80:81], v[64:67], off offset:528
	v_lshl_add_u64 v[76:77], v[162:163], 0, v[172:173]
	v_lshl_add_u64 v[92:93], v[162:163], 0, v[174:175]
	v_lshl_add_u64 v[108:109], v[162:163], 0, v[176:177]
	global_load_dwordx4 v[64:67], v[76:77], off
	global_load_dwordx4 v[68:71], v[76:77], off offset:16
	global_load_dwordx4 v[72:75], v[76:77], off offset:512
	s_nop 0
	global_load_dwordx4 v[76:79], v[76:77], off offset:528
	s_nop 0
	global_load_dwordx4 v[80:83], v[92:93], off
	global_load_dwordx4 v[84:87], v[92:93], off offset:16
	global_load_dwordx4 v[88:91], v[92:93], off offset:512
	s_nop 0
	global_load_dwordx4 v[92:95], v[92:93], off offset:528
	s_nop 0
	global_load_dwordx4 v[96:99], v[108:109], off
	global_load_dwordx4 v[100:103], v[108:109], off offset:16
	global_load_dwordx4 v[104:107], v[108:109], off offset:512
	s_nop 0
	global_load_dwordx4 v[108:111], v[108:109], off offset:528
	v_lshl_add_u64 v[164:165], v[164:165], 0, s[34:35]
	v_lshl_add_u64 v[124:125], v[162:163], 0, v[164:165]
	global_load_dwordx4 v[112:115], v[124:125], off
	global_load_dwordx4 v[116:119], v[124:125], off offset:16
	global_load_dwordx4 v[120:123], v[124:125], off offset:512
	s_nop 0
	global_load_dwordx4 v[124:127], v[124:125], off offset:528
	v_lshl_add_u64 v[162:163], s[14:15], 0, v[172:173]
	v_lshl_add_u64 v[172:173], s[14:15], 0, v[174:175]
	v_lshl_add_u64 v[174:175], s[14:15], 0, v[176:177]
	v_lshl_add_u64 v[162:163], v[162:163], 0, v[160:161]
	v_lshl_add_u64 v[172:173], v[172:173], 0, v[160:161]
	v_lshl_add_u64 v[174:175], v[174:175], 0, v[160:161]
	s_waitcnt vmcnt(15)
; #define PG8_WAIT_V(n) asm volatile("s_waitcnt vmcnt(" #n ")" ::: "memory")
; #define PG8_BAR __builtin_amdgcn_s_barrier()
;     __device__ __forceinline__ void operator()(const f32x4 (&acc)[2][2][4][2], const Unit& u, int wr, int wc, int fr, int fq) const {
;     ...
;             for (int m = 0; m < 4; ++m) { const size_t off = (size_t)(row0 + ai * HALF + m * 16) * 2048 + col0;
; #pragma unroll
;                 for (int bj = 0; bj < 2; ++bj)
; #pragma unroll
;                     for (int n = 0; n < 2; ++n) *(f32x4*)(out + off + bj * HALF + 4 * n) = r[m][bj][n] + gv[bj][n] * acc[ai][bj][m][n]; } }
; template <class Epi, class Sched, bool ALIGN_EPI = false, bool SP2 = false>
; __device__ __forceinline__ void gemm_phase(PG8_LAS unsigned char* lds, const Gemm g, const Sched& S, const Epi& E) {
;     ...
;         if constexpr (!Epi::AFTER_DRAIN) { E(acc, cur, wr, wc, fr, fq); S.done(cur); }
;         if (!has_next) break;
; #pragma unroll
;         for (int a = 0; a < 2; ++a)
; #pragma unroll
;             for (int b = 0; b < 2; ++b)
; #pragma unroll
;                 for (int m = 0; m < 4; ++m)
; #pragma unroll
;                     for (int n = 0; n < 2; ++n) acc[a][b][m][n] = (f32x4){0.f, 0.f, 0.f, 0.f};
;         cur = nxt; cA = nA; cB = nB; ++ui;
;         if constexpr (ALIGN_EPI) { if (wr == 1) PG8_BAR; }
;     }
;     PG8_WAIT_V(0);
;     if constexpr (!ALIGN_EPI) { if (wr == 0) PG8_BAR; }
	v_pk_fma_f32 v[62:63], v[62:63], v[142:143], v[66:67]
	v_pk_fma_f32 v[60:61], v[60:61], v[140:141], v[64:65]
	s_waitcnt vmcnt(14)
	v_pk_fma_f32 v[58:59], v[58:59], v[134:135], v[70:71]
	v_pk_fma_f32 v[56:57], v[56:57], v[132:133], v[68:69]
	s_waitcnt vmcnt(13)
	v_pk_fma_f32 v[42:43], v[42:43], v[138:139], v[74:75]
	s_waitcnt vmcnt(4)
	v_pk_fma_f32 v[12:13], v[12:13], v[128:129], v[108:109]
	v_pk_fma_f32 v[40:41], v[40:41], v[136:137], v[72:73]
	v_pk_fma_f32 v[38:39], v[38:39], v[130:131], v[78:79]
	v_pk_fma_f32 v[36:37], v[36:37], v[128:129], v[76:77]
	v_pk_fma_f32 v[54:55], v[54:55], v[142:143], v[82:83]
	v_pk_fma_f32 v[52:53], v[52:53], v[140:141], v[80:81]
	v_pk_fma_f32 v[50:51], v[50:51], v[134:135], v[86:87]
	v_pk_fma_f32 v[48:49], v[48:49], v[132:133], v[84:85]
	v_pk_fma_f32 v[30:31], v[30:31], v[138:139], v[90:91]
	v_pk_fma_f32 v[28:29], v[28:29], v[136:137], v[88:89]
	v_pk_fma_f32 v[26:27], v[26:27], v[130:131], v[94:95]
	v_pk_fma_f32 v[24:25], v[24:25], v[128:129], v[92:93]
	v_pk_fma_f32 v[46:47], v[46:47], v[142:143], v[98:99]
	v_pk_fma_f32 v[44:45], v[44:45], v[140:141], v[96:97]
	v_pk_fma_f32 v[34:35], v[34:35], v[134:135], v[102:103]
	v_pk_fma_f32 v[32:33], v[32:33], v[132:133], v[100:101]
	v_pk_fma_f32 v[18:19], v[18:19], v[138:139], v[106:107]
	v_pk_fma_f32 v[16:17], v[16:17], v[136:137], v[104:105]
	v_pk_fma_f32 v[14:15], v[14:15], v[130:131], v[110:111]
	global_store_dwordx4 v[162:163], v[60:63], off
	global_store_dwordx4 v[162:163], v[56:59], off offset:16
	global_store_dwordx4 v[162:163], v[40:43], off offset:512
	global_store_dwordx4 v[162:163], v[36:39], off offset:528
	global_store_dwordx4 v[172:173], v[52:55], off
	global_store_dwordx4 v[172:173], v[48:51], off offset:16
	global_store_dwordx4 v[172:173], v[28:31], off offset:512
	global_store_dwordx4 v[172:173], v[24:27], off offset:528
	global_store_dwordx4 v[174:175], v[44:47], off
	global_store_dwordx4 v[174:175], v[32:35], off offset:16
	global_store_dwordx4 v[174:175], v[16:19], off offset:512
	global_store_dwordx4 v[174:175], v[12:15], off offset:528
	s_waitcnt vmcnt(15)
	v_pk_fma_f32 v[22:23], v[22:23], v[142:143], v[114:115]
	v_pk_fma_f32 v[20:21], v[20:21], v[140:141], v[112:113]
	v_lshl_add_u64 v[12:13], s[14:15], 0, v[164:165]
	v_lshl_add_u64 v[12:13], v[12:13], 0, v[160:161]
	s_waitcnt vmcnt(14)
	v_pk_fma_f32 v[10:11], v[10:11], v[134:135], v[118:119]
	v_pk_fma_f32 v[8:9], v[8:9], v[132:133], v[116:117]
	s_waitcnt vmcnt(13)
	v_pk_fma_f32 v[6:7], v[6:7], v[138:139], v[122:123]
	v_pk_fma_f32 v[4:5], v[4:5], v[136:137], v[120:121]
	s_waitcnt vmcnt(12)
	v_pk_fma_f32 v[2:3], v[2:3], v[130:131], v[126:127]
	v_pk_fma_f32 v[0:1], v[0:1], v[128:129], v[124:125]
	global_store_dwordx4 v[12:13], v[20:23], off
	global_store_dwordx4 v[12:13], v[8:11], off offset:16
	global_store_dwordx4 v[12:13], v[4:7], off offset:512
	global_store_dwordx4 v[12:13], v[0:3], off offset:528
	s_cbranch_vccz .LBB0_820
	s_waitcnt vmcnt(0)
	s_cmpk_gt_u32 s3, 0xff
	s_cbranch_scc1 .LBB0_831
	s_barrier

; #define PG8_STAGE(bufoff, gbase, voff) do { _Pragma("unroll") for (int _i = 0; _i < 2; ++_i) \
;         __builtin_amdgcn_global_load_lds((const unsigned*)((const char*)(gbase) + (voff)[_i]), (PG8_LAS unsigned*)(lds + (bufoff) + ldsw + _i * 8192), 16, 0, 0); } while (0)
; #define PG8_LDA(dst, b, h) do { _Pragma("unroll") for (int m = 0; m < 4; ++m) _Pragma("unroll") for (int k = 0; k < 2; ++k) dst[m][k] = *(const PG8_LAS bf16x8*)(lds + PG8_SA(b, h) + aoff + m * 2048 + k * 1024); } while (0)
; #define PG8_LDB(dst, b, h) do { _Pragma("unroll") for (int n = 0; n < 2; ++n) _Pragma("unroll") for (int k = 0; k < 2; ++k) dst[n][k] = *(const PG8_LAS bf16x8*)(lds + PG8_SB(b, h) + boff + n * 2048 + k * 1024); } while (0)
; #define PG8_MMA(ai, bj, At, Bt) do { __builtin_amdgcn_s_setprio(1); _Pragma("unroll") for (int m = 0; m < 4; ++m) _Pragma("unroll") for (int n = 0; n < 2; ++n) _Pragma("unroll") for (int k = 0; k < 2; ++k) \
;         acc[ai][bj][m][n] = __builtin_amdgcn_mfma_f32_16x16x32_bf16(Bt[n][k], At[m][k], acc[ai][bj][m][n], 0, 0, 0); __builtin_amdgcn_s_setprio(0); } while (0)
; #define PG8_BAR __builtin_amdgcn_s_barrier()
; template <class Epi, class Sched, bool ALIGN_EPI = false, bool SP2 = false>
; __device__ __forceinline__ void gemm_phase(PG8_LAS unsigned char* lds, const Gemm g, const Sched& S, const Epi& E) {
;     ...
;         const bool has_next = S.next(ui + 1, nxt);
;         const char* nA = has_next ? (const char*)g.A + (size_t)nxt.pm * tstep : cA; const char* nB = has_next ? (const char*)g.Bt + (size_t)nxt.pn * tstep : cB;
;         for (int t = 0; t < nt; t += 2) {
;             const bool last = (t == nt - 2);
;             const char* a1 = cA + (size_t)(t + 1) * kstep;
;             const char* a2 = last ? nA : cA + (size_t)(t + 2) * kstep; const char* b2 = last ? nB : cB + (size_t)(t + 2) * kstep;
;             const char* a3 = a2 + kstep; const char* b3 = b2 + kstep;
;             if (last && has_next) S.a_ready(nxt);
;             if constexpr (SP2) {
;             PG8_LDB(B0, 0, 0); PG8_LDB(B1, 0, 1); PG8_SCHED; PG8_LDA(At, 0, 0); PG8_STAGE(PG8_SA(1, 1), a1 + hstep, voffA);
;             PG8_WAIT_V(8); PG8_WAIT_L(0); PG8_BAR; PG8_MMA(0, 0, At, B0); PG8_MMA(0, 1, At, B1); PG8_BAR; PG8_SCHED;
;             PG8_LDA(At, 0, 1); PG8_STAGE(PG8_SB(0, 0), b2, voffB); PG8_STAGE(PG8_SB(0, 1), b2 + hstep, voffB); PG8_STAGE(PG8_SA(0, 0), a2, voffA);
.LBB0_944:
	s_ashr_i32 s23, s22, 31
	v_cmp_lt_i64_e32 vcc, s[24:25], v[140:141]
	s_lshl_b64 s[24:25], s[22:23], 20
	s_add_u32 s24, s38, s24
	s_addc_u32 s25, s39, s25
	s_and_b64 s[26:27], vcc, exec
	s_cselect_b32 s23, s25, s31
	s_cselect_b32 s57, s24, s30
	s_ashr_i32 s15, s14, 31
	s_lshl_b64 s[26:27], s[14:15], 20
	s_add_u32 s26, s40, s26
	s_addc_u32 s27, s41, s27
	s_and_b64 s[36:37], vcc, exec
	s_cselect_b32 s15, s27, s35
	s_cselect_b32 s58, s26, s34
	s_add_u32 s30, s30, 0x80080
	s_addc_u32 s31, s31, 0
	s_add_u32 s59, s34, 0x100
	s_addc_u32 s60, s35, 0
	s_mov_b32 s61, -2
	ds_read_b128 v[152:155], v149
	ds_read_b128 v[156:159], v149 offset:1024
	ds_read_b128 v[160:163], v149 offset:2048
	ds_read_b128 v[164:167], v149 offset:3072
	ds_read_b128 v[168:171], v150
	ds_read_b128 v[172:175], v150 offset:1024
	ds_read_b128 v[176:179], v150 offset:2048
	ds_read_b128 v[180:183], v150 offset:3072
	s_add_u32 s34, s30, 0xfff80080
	s_addc_u32 s35, s31, -1
	s_cmp_eq_u32 s61, 28
	s_cselect_b32 s37, s23, s35
	s_cselect_b32 s36, s57, s34
	s_cselect_b32 s35, s15, s60
	s_cselect_b32 s34, s58, s59
	s_add_i32 m0, s29, 0xc000
	ds_read_b128 v[184:187], v151
	ds_read_b128 v[188:191], v151 offset:1024
	ds_read_b128 v[192:195], v151 offset:2048
	ds_read_b128 v[196:199], v151 offset:3072
	ds_read_b128 v[200:203], v151 offset:4096
	ds_read_b128 v[204:207], v151 offset:5120
	ds_read_b128 v[208:211], v151 offset:6144
	ds_read_b128 v[212:215], v151 offset:7168
	global_load_lds_dwordx4 v136, s[30:31]
	s_add_i32 m0, s29, 0xe000
	s_nop 0
	global_load_lds_dwordx4 v138, s[30:31]
	s_waitcnt vmcnt(8) lgkmcnt(0)
	s_barrier
	v_mfma_f32_16x16x32_bf16 v[124:127], v[152:155], v[184:187], 0
	v_mfma_f32_16x16x32_bf16 v[120:123], v[160:163], v[184:187], 0
	v_mfma_f32_16x16x32_bf16 v[108:111], v[152:155], v[192:195], 0
	v_mfma_f32_16x16x32_bf16 v[104:107], v[160:163], v[192:195], 0
	v_mfma_f32_16x16x32_bf16 v[92:95], v[152:155], v[200:203], 0
	v_mfma_f32_16x16x32_bf16 v[88:91], v[160:163], v[200:203], 0
	v_mfma_f32_16x16x32_bf16 v[76:79], v[152:155], v[208:211], 0
	v_mfma_f32_16x16x32_bf16 v[72:75], v[160:163], v[208:211], 0
	v_mfma_f32_16x16x32_bf16 v[124:127], v[156:159], v[188:191], v[124:127]
	v_mfma_f32_16x16x32_bf16 v[120:123], v[164:167], v[188:191], v[120:123]
	v_mfma_f32_16x16x32_bf16 v[108:111], v[156:159], v[196:199], v[108:111]
	v_mfma_f32_16x16x32_bf16 v[104:107], v[164:167], v[196:199], v[104:107]
	v_mfma_f32_16x16x32_bf16 v[92:95], v[156:159], v[204:207], v[92:95]
	v_mfma_f32_16x16x32_bf16 v[88:91], v[164:167], v[204:207], v[88:91]
	v_mfma_f32_16x16x32_bf16 v[76:79], v[156:159], v[212:215], v[76:79]
	v_mfma_f32_16x16x32_bf16 v[72:75], v[164:167], v[212:215], v[72:75]
	v_mfma_f32_16x16x32_bf16 v[116:119], v[168:171], v[184:187], 0
	v_mfma_f32_16x16x32_bf16 v[112:115], v[176:179], v[184:187], 0
	v_mfma_f32_16x16x32_bf16 v[100:103], v[168:171], v[192:195], 0
	v_mfma_f32_16x16x32_bf16 v[96:99], v[176:179], v[192:195], 0
	v_mfma_f32_16x16x32_bf16 v[84:87], v[168:171], v[200:203], 0
	v_mfma_f32_16x16x32_bf16 v[80:83], v[176:179], v[200:203], 0
	v_mfma_f32_16x16x32_bf16 v[68:71], v[168:171], v[208:211], 0
	v_mfma_f32_16x16x32_bf16 v[64:67], v[176:179], v[208:211], 0
	v_mfma_f32_16x16x32_bf16 v[116:119], v[172:175], v[188:191], v[116:119]
	v_mfma_f32_16x16x32_bf16 v[112:115], v[180:183], v[188:191], v[112:115]
	v_mfma_f32_16x16x32_bf16 v[100:103], v[172:175], v[196:199], v[100:103]
	v_mfma_f32_16x16x32_bf16 v[96:99], v[180:183], v[196:199], v[96:99]
	v_mfma_f32_16x16x32_bf16 v[84:87], v[172:175], v[204:207], v[84:87]
	v_mfma_f32_16x16x32_bf16 v[80:83], v[180:183], v[204:207], v[80:83]
	v_mfma_f32_16x16x32_bf16 v[68:71], v[172:175], v[212:215], v[68:71]
	v_mfma_f32_16x16x32_bf16 v[64:67], v[180:183], v[212:215], v[64:67]
	s_barrier
	s_add_i32 s62, s53, s42
	s_mov_b32 m0, s62
	ds_read_b128 v[184:187], v151 offset:16384
	ds_read_b128 v[188:191], v151 offset:17408
	ds_read_b128 v[192:195], v151 offset:18432
	ds_read_b128 v[196:199], v151 offset:19456
	ds_read_b128 v[200:203], v151 offset:20480
	ds_read_b128 v[204:207], v151 offset:21504
	ds_read_b128 v[208:211], v151 offset:22528
	ds_read_b128 v[212:215], v151 offset:23552
	global_load_lds_dwordx4 v132, s[34:35]
	s_add_i32 m0, s62, 0x2000
	s_add_u32 s62, s34, 0x80000
	s_addc_u32 s63, s35, 0
	s_add_i32 s64, s54, s42
	global_load_lds_dwordx4 v128, s[34:35]
	s_mov_b32 m0, s64
	s_nop 0
	global_load_lds_dwordx4 v132, s[62:63]
	s_add_i32 m0, s64, 0x2000
	s_nop 0
	global_load_lds_dwordx4 v128, s[62:63]
	s_mov_b32 m0, s29
	s_nop 0
	global_load_lds_dwordx4 v134, s[36:37]
	s_mov_b32 m0, s45
	s_nop 0
	global_load_lds_dwordx4 v130, s[36:37]
	s_waitcnt vmcnt(8) lgkmcnt(0)
	s_barrier
; #define PG8_STAGE(bufoff, gbase, voff) do { _Pragma("unroll") for (int _i = 0; _i < 2; ++_i) \
;         __builtin_amdgcn_global_load_lds((const unsigned*)((const char*)(gbase) + (voff)[_i]), (PG8_LAS unsigned*)(lds + (bufoff) + ldsw + _i * 8192), 16, 0, 0); } while (0)
; #define PG8_LDA(dst, b, h) do { _Pragma("unroll") for (int m = 0; m < 4; ++m) _Pragma("unroll") for (int k = 0; k < 2; ++k) dst[m][k] = *(const PG8_LAS bf16x8*)(lds + PG8_SA(b, h) + aoff + m * 2048 + k * 1024); } while (0)
; #define PG8_LDB(dst, b, h) do { _Pragma("unroll") for (int n = 0; n < 2; ++n) _Pragma("unroll") for (int k = 0; k < 2; ++k) dst[n][k] = *(const PG8_LAS bf16x8*)(lds + PG8_SB(b, h) + boff + n * 2048 + k * 1024); } while (0)
; #define PG8_MMA(ai, bj, At, Bt) do { __builtin_amdgcn_s_setprio(1); _Pragma("unroll") for (int m = 0; m < 4; ++m) _Pragma("unroll") for (int n = 0; n < 2; ++n) _Pragma("unroll") for (int k = 0; k < 2; ++k) \
;         acc[ai][bj][m][n] = __builtin_amdgcn_mfma_f32_16x16x32_bf16(Bt[n][k], At[m][k], acc[ai][bj][m][n], 0, 0, 0); __builtin_amdgcn_s_setprio(0); } while (0)
; #define PG8_WAIT_V(n) asm volatile("s_waitcnt vmcnt(" #n ")" ::: "memory")
; #define PG8_WAIT_L(n) asm volatile("s_waitcnt lgkmcnt(" #n ")" ::: "memory")
; #define PG8_BAR __builtin_amdgcn_s_barrier()
; #define PG8_SCHED __builtin_amdgcn_sched_barrier(0)
; template <class Epi, class Sched, bool ALIGN_EPI = false, bool SP2 = false>
; __device__ __forceinline__ void gemm_phase(PG8_LAS unsigned char* lds, const Gemm g, const Sched& S, const Epi& E) {
;     ...
;             PG8_WAIT_V(8); PG8_WAIT_L(0); PG8_BAR; PG8_MMA(0, 0, At, B0); PG8_MMA(0, 1, At, B1); PG8_BAR; PG8_SCHED;
;             PG8_LDA(At, 0, 1); PG8_STAGE(PG8_SB(0, 0), b2, voffB); PG8_STAGE(PG8_SB(0, 1), b2 + hstep, voffB); PG8_STAGE(PG8_SA(0, 0), a2, voffA);
;             PG8_WAIT_V(8); PG8_WAIT_L(0); PG8_BAR; PG8_MMA(1, 0, At, B0); PG8_MMA(1, 1, At, B1); PG8_BAR; PG8_SCHED;
;             PG8_LDB(B0, 1, 0); PG8_LDB(B1, 1, 1); PG8_SCHED; PG8_LDA(At, 1, 0); PG8_STAGE(PG8_SA(0, 1), a2 + hstep, voffA);
;             PG8_WAIT_V(8); PG8_WAIT_L(0); PG8_BAR; PG8_MMA(0, 0, At, B0); PG8_MMA(0, 1, At, B1); PG8_BAR; PG8_SCHED;
	v_mfma_f32_16x16x32_bf16 v[60:63], v[152:155], v[184:187], 0
	v_mfma_f32_16x16x32_bf16 v[56:59], v[160:163], v[184:187], 0
	v_mfma_f32_16x16x32_bf16 v[44:47], v[152:155], v[192:195], 0
	v_mfma_f32_16x16x32_bf16 v[40:43], v[160:163], v[192:195], 0
	v_mfma_f32_16x16x32_bf16 v[28:31], v[152:155], v[200:203], 0
	v_mfma_f32_16x16x32_bf16 v[24:27], v[160:163], v[200:203], 0
	v_mfma_f32_16x16x32_bf16 v[12:15], v[152:155], v[208:211], 0
	v_mfma_f32_16x16x32_bf16 v[8:11], v[160:163], v[208:211], 0
	v_mfma_f32_16x16x32_bf16 v[60:63], v[156:159], v[188:191], v[60:63]
	v_mfma_f32_16x16x32_bf16 v[56:59], v[164:167], v[188:191], v[56:59]
	v_mfma_f32_16x16x32_bf16 v[44:47], v[156:159], v[196:199], v[44:47]
	v_mfma_f32_16x16x32_bf16 v[40:43], v[164:167], v[196:199], v[40:43]
	v_mfma_f32_16x16x32_bf16 v[28:31], v[156:159], v[204:207], v[28:31]
	v_mfma_f32_16x16x32_bf16 v[24:27], v[164:167], v[204:207], v[24:27]
	v_mfma_f32_16x16x32_bf16 v[12:15], v[156:159], v[212:215], v[12:15]
	v_mfma_f32_16x16x32_bf16 v[8:11], v[164:167], v[212:215], v[8:11]
	v_mfma_f32_16x16x32_bf16 v[52:55], v[168:171], v[184:187], 0
	v_mfma_f32_16x16x32_bf16 v[48:51], v[176:179], v[184:187], 0
	v_mfma_f32_16x16x32_bf16 v[36:39], v[168:171], v[192:195], 0
	v_mfma_f32_16x16x32_bf16 v[32:35], v[176:179], v[192:195], 0
	v_mfma_f32_16x16x32_bf16 v[20:23], v[168:171], v[200:203], 0
	v_mfma_f32_16x16x32_bf16 v[16:19], v[176:179], v[200:203], 0
	v_mfma_f32_16x16x32_bf16 v[4:7], v[168:171], v[208:211], 0
	v_mfma_f32_16x16x32_bf16 v[0:3], v[176:179], v[208:211], 0
	v_mfma_f32_16x16x32_bf16 v[52:55], v[172:175], v[188:191], v[52:55]
	v_mfma_f32_16x16x32_bf16 v[48:51], v[180:183], v[188:191], v[48:51]
	v_mfma_f32_16x16x32_bf16 v[36:39], v[172:175], v[196:199], v[36:39]
	v_mfma_f32_16x16x32_bf16 v[32:35], v[180:183], v[196:199], v[32:35]
	v_mfma_f32_16x16x32_bf16 v[20:23], v[172:175], v[204:207], v[20:23]
	v_mfma_f32_16x16x32_bf16 v[16:19], v[180:183], v[204:207], v[16:19]
	v_mfma_f32_16x16x32_bf16 v[4:7], v[172:175], v[212:215], v[4:7]
	v_mfma_f32_16x16x32_bf16 v[0:3], v[180:183], v[212:215], v[0:3]
	s_barrier
	s_add_i32 s62, 0, 0x18000
	s_add_i32 s63, 0, 0x1c000
	v_add_u32_e32 v164, s62, v147
	v_add_u32_e32 v180, s63, v147
	ds_read_b128 v[152:155], v164
	ds_read_b128 v[156:159], v164 offset:1024
	ds_read_b128 v[160:163], v164 offset:2048
	ds_read_b128 v[164:167], v164 offset:3072
	ds_read_b128 v[168:171], v180
	ds_read_b128 v[172:175], v180 offset:1024
	ds_read_b128 v[176:179], v180 offset:2048
	ds_read_b128 v[180:183], v180 offset:3072
	s_add_u32 s84, s36, 0x80
	s_addc_u32 s85, s37, 0
	s_add_u32 s36, s36, 0x80000
	s_addc_u32 s37, s37, 0
	s_mov_b32 m0, s46
	ds_read_b128 v[184:187], v151 offset:32768
	ds_read_b128 v[188:191], v151 offset:33792
	ds_read_b128 v[192:195], v151 offset:34816
	ds_read_b128 v[196:199], v151 offset:35840
	ds_read_b128 v[200:203], v151 offset:36864
	ds_read_b128 v[204:207], v151 offset:37888
	ds_read_b128 v[208:211], v151 offset:38912
	ds_read_b128 v[212:215], v151 offset:39936
	global_load_lds_dwordx4 v134, s[36:37]
	s_mov_b32 m0, s47
	s_nop 0
	global_load_lds_dwordx4 v130, s[36:37]
	s_waitcnt vmcnt(8) lgkmcnt(0)
	s_barrier
	v_mfma_f32_16x16x32_bf16 v[124:127], v[152:155], v[184:187], v[124:127]
	v_mfma_f32_16x16x32_bf16 v[120:123], v[160:163], v[184:187], v[120:123]
	v_mfma_f32_16x16x32_bf16 v[108:111], v[152:155], v[192:195], v[108:111]
	v_mfma_f32_16x16x32_bf16 v[104:107], v[160:163], v[192:195], v[104:107]
	v_mfma_f32_16x16x32_bf16 v[92:95], v[152:155], v[200:203], v[92:95]
	v_mfma_f32_16x16x32_bf16 v[88:91], v[160:163], v[200:203], v[88:91]
	v_mfma_f32_16x16x32_bf16 v[76:79], v[152:155], v[208:211], v[76:79]
	v_mfma_f32_16x16x32_bf16 v[72:75], v[160:163], v[208:211], v[72:75]
	v_mfma_f32_16x16x32_bf16 v[124:127], v[156:159], v[188:191], v[124:127]
	v_mfma_f32_16x16x32_bf16 v[120:123], v[164:167], v[188:191], v[120:123]
	v_mfma_f32_16x16x32_bf16 v[108:111], v[156:159], v[196:199], v[108:111]
	v_mfma_f32_16x16x32_bf16 v[104:107], v[164:167], v[196:199], v[104:107]
	v_mfma_f32_16x16x32_bf16 v[92:95], v[156:159], v[204:207], v[92:95]
	v_mfma_f32_16x16x32_bf16 v[88:91], v[164:167], v[204:207], v[88:91]
	v_mfma_f32_16x16x32_bf16 v[76:79], v[156:159], v[212:215], v[76:79]
	v_mfma_f32_16x16x32_bf16 v[72:75], v[164:167], v[212:215], v[72:75]
	v_mfma_f32_16x16x32_bf16 v[116:119], v[168:171], v[184:187], v[116:119]
	v_mfma_f32_16x16x32_bf16 v[112:115], v[176:179], v[184:187], v[112:115]
	v_mfma_f32_16x16x32_bf16 v[100:103], v[168:171], v[192:195], v[100:103]
	v_mfma_f32_16x16x32_bf16 v[96:99], v[176:179], v[192:195], v[96:99]
	v_mfma_f32_16x16x32_bf16 v[84:87], v[168:171], v[200:203], v[84:87]
	v_mfma_f32_16x16x32_bf16 v[80:83], v[176:179], v[200:203], v[80:83]
	v_mfma_f32_16x16x32_bf16 v[68:71], v[168:171], v[208:211], v[68:71]
	v_mfma_f32_16x16x32_bf16 v[64:67], v[176:179], v[208:211], v[64:67]
	v_mfma_f32_16x16x32_bf16 v[116:119], v[172:175], v[188:191], v[116:119]
	v_mfma_f32_16x16x32_bf16 v[112:115], v[180:183], v[188:191], v[112:115]
	v_mfma_f32_16x16x32_bf16 v[100:103], v[172:175], v[196:199], v[100:103]
	v_mfma_f32_16x16x32_bf16 v[96:99], v[180:183], v[196:199], v[96:99]
	v_mfma_f32_16x16x32_bf16 v[84:87], v[172:175], v[204:207], v[84:87]
	v_mfma_f32_16x16x32_bf16 v[80:83], v[180:183], v[204:207], v[80:83]
	v_mfma_f32_16x16x32_bf16 v[68:71], v[172:175], v[212:215], v[68:71]
	v_mfma_f32_16x16x32_bf16 v[64:67], v[180:183], v[212:215], v[64:67]
	s_barrier
; #define PG8_STAGE(bufoff, gbase, voff) do { _Pragma("unroll") for (int _i = 0; _i < 2; ++_i) \
;         __builtin_amdgcn_global_load_lds((const unsigned*)((const char*)(gbase) + (voff)[_i]), (PG8_LAS unsigned*)(lds + (bufoff) + ldsw + _i * 8192), 16, 0, 0); } while (0)
; #define PG8_LDA(dst, b, h) do { _Pragma("unroll") for (int m = 0; m < 4; ++m) _Pragma("unroll") for (int k = 0; k < 2; ++k) dst[m][k] = *(const PG8_LAS bf16x8*)(lds + PG8_SA(b, h) + aoff + m * 2048 + k * 1024); } while (0)
; #define PG8_LDB(dst, b, h) do { _Pragma("unroll") for (int n = 0; n < 2; ++n) _Pragma("unroll") for (int k = 0; k < 2; ++k) dst[n][k] = *(const PG8_LAS bf16x8*)(lds + PG8_SB(b, h) + boff + n * 2048 + k * 1024); } while (0)
; #define PG8_MMA(ai, bj, At, Bt) do { __builtin_amdgcn_s_setprio(1); _Pragma("unroll") for (int m = 0; m < 4; ++m) _Pragma("unroll") for (int n = 0; n < 2; ++n) _Pragma("unroll") for (int k = 0; k < 2; ++k) \
;         acc[ai][bj][m][n] = __builtin_amdgcn_mfma_f32_16x16x32_bf16(Bt[n][k], At[m][k], acc[ai][bj][m][n], 0, 0, 0); __builtin_amdgcn_s_setprio(0); } while (0)
; #define PG8_WAIT_V(n) asm volatile("s_waitcnt vmcnt(" #n ")" ::: "memory")
; template <class Epi, class Sched, bool ALIGN_EPI = false, bool SP2 = false>
; __device__ __forceinline__ void gemm_phase(PG8_LAS unsigned char* lds, const Gemm g, const Sched& S, const Epi& E) {
;     ...
;             PG8_LDB(B0, 0, 0); PG8_LDB(B1, 0, 1); PG8_SCHED; PG8_LDA(At, 0, 0); PG8_STAGE(PG8_SA(1, 1), a1 + hstep, voffA);
;             PG8_WAIT_V(8); PG8_WAIT_L(0); PG8_BAR; PG8_MMA(0, 0, At, B0); PG8_MMA(0, 1, At, B1); PG8_BAR; PG8_SCHED;
;             PG8_LDA(At, 0, 1); PG8_STAGE(PG8_SB(0, 0), b2, voffB); PG8_STAGE(PG8_SB(0, 1), b2 + hstep, voffB); PG8_STAGE(PG8_SA(0, 0), a2, voffA);
;             PG8_WAIT_V(8); PG8_WAIT_L(0); PG8_BAR; PG8_MMA(1, 0, At, B0); PG8_MMA(1, 1, At, B1); PG8_BAR; PG8_SCHED;
;             PG8_LDB(B0, 1, 0); PG8_LDB(B1, 1, 1); PG8_SCHED; PG8_LDA(At, 1, 0); PG8_STAGE(PG8_SA(0, 1), a2 + hstep, voffA);
;             PG8_WAIT_V(8); PG8_WAIT_L(0); PG8_BAR; PG8_MMA(0, 0, At, B0); PG8_MMA(0, 1, At, B1); PG8_BAR; PG8_SCHED;
;             PG8_LDA(At, 1, 1); PG8_STAGE(PG8_SB(1, 0), b3, voffB); PG8_STAGE(PG8_SB(1, 1), b3 + hstep, voffB); PG8_STAGE(PG8_SA(1, 0), a3, voffA);
;             PG8_WAIT_V(8); PG8_WAIT_L(0); PG8_BAR; PG8_MMA(1, 0, At, B0); PG8_MMA(1, 1, At, B1); PG8_BAR; PG8_SCHED;
	s_add_i32 s36, s62, s42
	s_add_u32 s86, s34, 0x80
	s_addc_u32 s87, s35, 0
	s_mov_b32 m0, s36
	ds_read_b128 v[184:187], v151 offset:49152
	ds_read_b128 v[188:191], v151 offset:50176
	ds_read_b128 v[192:195], v151 offset:51200
	ds_read_b128 v[196:199], v151 offset:52224
	ds_read_b128 v[200:203], v151 offset:53248
	ds_read_b128 v[204:207], v151 offset:54272
	ds_read_b128 v[208:211], v151 offset:55296
	ds_read_b128 v[212:215], v151 offset:56320
	global_load_lds_dwordx4 v132, s[86:87]
	s_add_i32 m0, s36, 0x2000
	s_add_u32 s34, s34, 0x80080
	s_addc_u32 s35, s35, 0
	s_add_i32 s36, s63, s42
	global_load_lds_dwordx4 v128, s[86:87]
	s_mov_b32 m0, s36
	s_nop 0
	global_load_lds_dwordx4 v132, s[34:35]
	s_add_i32 m0, s36, 0x2000
	s_nop 0
	global_load_lds_dwordx4 v128, s[34:35]
	s_mov_b32 m0, s49
	s_nop 0
	global_load_lds_dwordx4 v134, s[84:85]
	s_mov_b32 m0, s50
	s_nop 0
	global_load_lds_dwordx4 v130, s[84:85]
	s_waitcnt vmcnt(8) lgkmcnt(0)
	s_barrier
	v_mfma_f32_16x16x32_bf16 v[60:63], v[152:155], v[184:187], v[60:63]
	v_mfma_f32_16x16x32_bf16 v[56:59], v[160:163], v[184:187], v[56:59]
	v_mfma_f32_16x16x32_bf16 v[44:47], v[152:155], v[192:195], v[44:47]
	v_mfma_f32_16x16x32_bf16 v[40:43], v[160:163], v[192:195], v[40:43]
	v_mfma_f32_16x16x32_bf16 v[28:31], v[152:155], v[200:203], v[28:31]
	v_mfma_f32_16x16x32_bf16 v[24:27], v[160:163], v[200:203], v[24:27]
	v_mfma_f32_16x16x32_bf16 v[12:15], v[152:155], v[208:211], v[12:15]
	v_mfma_f32_16x16x32_bf16 v[8:11], v[160:163], v[208:211], v[8:11]
	v_mfma_f32_16x16x32_bf16 v[60:63], v[156:159], v[188:191], v[60:63]
	v_mfma_f32_16x16x32_bf16 v[56:59], v[164:167], v[188:191], v[56:59]
	v_mfma_f32_16x16x32_bf16 v[44:47], v[156:159], v[196:199], v[44:47]
	v_mfma_f32_16x16x32_bf16 v[40:43], v[164:167], v[196:199], v[40:43]
	v_mfma_f32_16x16x32_bf16 v[28:31], v[156:159], v[204:207], v[28:31]
	v_mfma_f32_16x16x32_bf16 v[24:27], v[164:167], v[204:207], v[24:27]
	v_mfma_f32_16x16x32_bf16 v[12:15], v[156:159], v[212:215], v[12:15]
	v_mfma_f32_16x16x32_bf16 v[8:11], v[164:167], v[212:215], v[8:11]
	v_mfma_f32_16x16x32_bf16 v[52:55], v[168:171], v[184:187], v[52:55]
	v_mfma_f32_16x16x32_bf16 v[48:51], v[176:179], v[184:187], v[48:51]
	v_mfma_f32_16x16x32_bf16 v[36:39], v[168:171], v[192:195], v[36:39]
	v_mfma_f32_16x16x32_bf16 v[32:35], v[176:179], v[192:195], v[32:35]
	v_mfma_f32_16x16x32_bf16 v[20:23], v[168:171], v[200:203], v[20:23]
	v_mfma_f32_16x16x32_bf16 v[16:19], v[176:179], v[200:203], v[16:19]
	v_mfma_f32_16x16x32_bf16 v[4:7], v[168:171], v[208:211], v[4:7]
	v_mfma_f32_16x16x32_bf16 v[0:3], v[176:179], v[208:211], v[0:3]
	v_mfma_f32_16x16x32_bf16 v[52:55], v[172:175], v[188:191], v[52:55]
	v_mfma_f32_16x16x32_bf16 v[48:51], v[180:183], v[188:191], v[48:51]
	v_mfma_f32_16x16x32_bf16 v[36:39], v[172:175], v[196:199], v[36:39]
	v_mfma_f32_16x16x32_bf16 v[32:35], v[180:183], v[196:199], v[32:35]
	v_mfma_f32_16x16x32_bf16 v[20:23], v[172:175], v[204:207], v[20:23]
	v_mfma_f32_16x16x32_bf16 v[16:19], v[180:183], v[204:207], v[16:19]
	v_mfma_f32_16x16x32_bf16 v[4:7], v[172:175], v[212:215], v[4:7]
	v_mfma_f32_16x16x32_bf16 v[0:3], v[180:183], v[212:215], v[0:3]
	s_barrier
	s_add_i32 s61, s61, 2
	s_add_u32 s30, s30, 0x100
	s_addc_u32 s31, s31, 0
	s_add_u32 s59, s59, 0x100
	s_addc_u32 s60, s60, 0
	s_cmp_gt_u32 s61, 29
.LBB0_945:
	ds_read_b128 v[152:155], v149
	ds_read_b128 v[156:159], v149 offset:1024
	ds_read_b128 v[160:163], v149 offset:2048
	ds_read_b128 v[164:167], v149 offset:3072
	ds_read_b128 v[168:171], v150
	ds_read_b128 v[172:175], v150 offset:1024
	ds_read_b128 v[176:179], v150 offset:2048
	ds_read_b128 v[180:183], v150 offset:3072
	s_add_u32 s34, s30, 0xfff80080
	s_addc_u32 s35, s31, -1
	s_cmp_eq_u32 s61, 28
	s_cselect_b32 s37, s23, s35
	s_cselect_b32 s36, s57, s34
	s_cselect_b32 s35, s15, s60
	s_cselect_b32 s34, s58, s59
	s_add_i32 m0, s29, 0xc000
	ds_read_b128 v[184:187], v151
	ds_read_b128 v[188:191], v151 offset:1024
	ds_read_b128 v[192:195], v151 offset:2048
	ds_read_b128 v[196:199], v151 offset:3072
	ds_read_b128 v[200:203], v151 offset:4096
	ds_read_b128 v[204:207], v151 offset:5120
	ds_read_b128 v[208:211], v151 offset:6144
	ds_read_b128 v[212:215], v151 offset:7168
	global_load_lds_dwordx4 v136, s[30:31]
	s_add_i32 m0, s29, 0xe000
	s_nop 0
	global_load_lds_dwordx4 v138, s[30:31]
	s_waitcnt vmcnt(8) lgkmcnt(0)
	s_barrier
	v_mfma_f32_16x16x32_bf16 v[124:127], v[152:155], v[184:187], v[124:127]
	v_mfma_f32_16x16x32_bf16 v[120:123], v[160:163], v[184:187], v[120:123]
	v_mfma_f32_16x16x32_bf16 v[108:111], v[152:155], v[192:195], v[108:111]
	v_mfma_f32_16x16x32_bf16 v[104:107], v[160:163], v[192:195], v[104:107]
	v_mfma_f32_16x16x32_bf16 v[92:95], v[152:155], v[200:203], v[92:95]
	v_mfma_f32_16x16x32_bf16 v[88:91], v[160:163], v[200:203], v[88:91]
	v_mfma_f32_16x16x32_bf16 v[76:79], v[152:155], v[208:211], v[76:79]
	v_mfma_f32_16x16x32_bf16 v[72:75], v[160:163], v[208:211], v[72:75]
	v_mfma_f32_16x16x32_bf16 v[124:127], v[156:159], v[188:191], v[124:127]
	v_mfma_f32_16x16x32_bf16 v[120:123], v[164:167], v[188:191], v[120:123]
	v_mfma_f32_16x16x32_bf16 v[108:111], v[156:159], v[196:199], v[108:111]
	v_mfma_f32_16x16x32_bf16 v[104:107], v[164:167], v[196:199], v[104:107]
	v_mfma_f32_16x16x32_bf16 v[92:95], v[156:159], v[204:207], v[92:95]
	v_mfma_f32_16x16x32_bf16 v[88:91], v[164:167], v[204:207], v[88:91]
	v_mfma_f32_16x16x32_bf16 v[76:79], v[156:159], v[212:215], v[76:79]
	v_mfma_f32_16x16x32_bf16 v[72:75], v[164:167], v[212:215], v[72:75]
	v_mfma_f32_16x16x32_bf16 v[116:119], v[168:171], v[184:187], v[116:119]
	v_mfma_f32_16x16x32_bf16 v[112:115], v[176:179], v[184:187], v[112:115]
	v_mfma_f32_16x16x32_bf16 v[100:103], v[168:171], v[192:195], v[100:103]
	v_mfma_f32_16x16x32_bf16 v[96:99], v[176:179], v[192:195], v[96:99]
	v_mfma_f32_16x16x32_bf16 v[84:87], v[168:171], v[200:203], v[84:87]
	v_mfma_f32_16x16x32_bf16 v[80:83], v[176:179], v[200:203], v[80:83]
	v_mfma_f32_16x16x32_bf16 v[68:71], v[168:171], v[208:211], v[68:71]
	v_mfma_f32_16x16x32_bf16 v[64:67], v[176:179], v[208:211], v[64:67]
	v_mfma_f32_16x16x32_bf16 v[116:119], v[172:175], v[188:191], v[116:119]
	v_mfma_f32_16x16x32_bf16 v[112:115], v[180:183], v[188:191], v[112:115]
	v_mfma_f32_16x16x32_bf16 v[100:103], v[172:175], v[196:199], v[100:103]
	v_mfma_f32_16x16x32_bf16 v[96:99], v[180:183], v[196:199], v[96:99]
	v_mfma_f32_16x16x32_bf16 v[84:87], v[172:175], v[204:207], v[84:87]
	v_mfma_f32_16x16x32_bf16 v[80:83], v[180:183], v[204:207], v[80:83]
	v_mfma_f32_16x16x32_bf16 v[68:71], v[172:175], v[212:215], v[68:71]
	v_mfma_f32_16x16x32_bf16 v[64:67], v[180:183], v[212:215], v[64:67]
	s_barrier
; #define PG8_STAGE(bufoff, gbase, voff) do { _Pragma("unroll") for (int _i = 0; _i < 2; ++_i) \
;         __builtin_amdgcn_global_load_lds((const unsigned*)((const char*)(gbase) + (voff)[_i]), (PG8_LAS unsigned*)(lds + (bufoff) + ldsw + _i * 8192), 16, 0, 0); } while (0)
; #define PG8_LDA(dst, b, h) do { _Pragma("unroll") for (int m = 0; m < 4; ++m) _Pragma("unroll") for (int k = 0; k < 2; ++k) dst[m][k] = *(const PG8_LAS bf16x8*)(lds + PG8_SA(b, h) + aoff + m * 2048 + k * 1024); } while (0)
; #define PG8_LDB(dst, b, h) do { _Pragma("unroll") for (int n = 0; n < 2; ++n) _Pragma("unroll") for (int k = 0; k < 2; ++k) dst[n][k] = *(const PG8_LAS bf16x8*)(lds + PG8_SB(b, h) + boff + n * 2048 + k * 1024); } while (0)
; #define PG8_MMA(ai, bj, At, Bt) do { __builtin_amdgcn_s_setprio(1); _Pragma("unroll") for (int m = 0; m < 4; ++m) _Pragma("unroll") for (int n = 0; n < 2; ++n) _Pragma("unroll") for (int k = 0; k < 2; ++k) \
;         acc[ai][bj][m][n] = __builtin_amdgcn_mfma_f32_16x16x32_bf16(Bt[n][k], At[m][k], acc[ai][bj][m][n], 0, 0, 0); __builtin_amdgcn_s_setprio(0); } while (0)
; #define PG8_WAIT_V(n) asm volatile("s_waitcnt vmcnt(" #n ")" ::: "memory")
; #define PG8_WAIT_L(n) asm volatile("s_waitcnt lgkmcnt(" #n ")" ::: "memory")
; #define PG8_BAR __builtin_amdgcn_s_barrier()
; #define PG8_SCHED __builtin_amdgcn_sched_barrier(0)
; template <class Epi, class Sched, bool ALIGN_EPI = false, bool SP2 = false>
; __device__ __forceinline__ void gemm_phase(PG8_LAS unsigned char* lds, const Gemm g, const Sched& S, const Epi& E) {
;     ...
;             PG8_LDA(At, 0, 1); PG8_STAGE(PG8_SB(0, 0), b2, voffB); PG8_STAGE(PG8_SB(0, 1), b2 + hstep, voffB); PG8_STAGE(PG8_SA(0, 0), a2, voffA);
;             PG8_WAIT_V(8); PG8_WAIT_L(0); PG8_BAR; PG8_MMA(1, 0, At, B0); PG8_MMA(1, 1, At, B1); PG8_BAR; PG8_SCHED;
;             PG8_LDB(B0, 1, 0); PG8_LDB(B1, 1, 1); PG8_SCHED; PG8_LDA(At, 1, 0); PG8_STAGE(PG8_SA(0, 1), a2 + hstep, voffA);
;             PG8_WAIT_V(8); PG8_WAIT_L(0); PG8_BAR; PG8_MMA(0, 0, At, B0); PG8_MMA(0, 1, At, B1); PG8_BAR; PG8_SCHED;
	s_add_i32 s62, s53, s42
	s_mov_b32 m0, s62
	ds_read_b128 v[184:187], v151 offset:16384
	ds_read_b128 v[188:191], v151 offset:17408
	ds_read_b128 v[192:195], v151 offset:18432
	ds_read_b128 v[196:199], v151 offset:19456
	ds_read_b128 v[200:203], v151 offset:20480
	ds_read_b128 v[204:207], v151 offset:21504
	ds_read_b128 v[208:211], v151 offset:22528
	ds_read_b128 v[212:215], v151 offset:23552
	global_load_lds_dwordx4 v132, s[34:35]
	s_add_i32 m0, s62, 0x2000
	s_add_u32 s62, s34, 0x80000
	s_addc_u32 s63, s35, 0
	s_add_i32 s64, s54, s42
	global_load_lds_dwordx4 v128, s[34:35]
	s_mov_b32 m0, s64
	s_nop 0
	global_load_lds_dwordx4 v132, s[62:63]
	s_add_i32 m0, s64, 0x2000
	s_nop 0
	global_load_lds_dwordx4 v128, s[62:63]
	s_mov_b32 m0, s29
	s_nop 0
	global_load_lds_dwordx4 v134, s[36:37]
	s_mov_b32 m0, s45
	s_nop 0
	global_load_lds_dwordx4 v130, s[36:37]
	s_waitcnt vmcnt(8) lgkmcnt(0)
	s_barrier
	v_mfma_f32_16x16x32_bf16 v[60:63], v[152:155], v[184:187], v[60:63]
	v_mfma_f32_16x16x32_bf16 v[56:59], v[160:163], v[184:187], v[56:59]
	v_mfma_f32_16x16x32_bf16 v[44:47], v[152:155], v[192:195], v[44:47]
	v_mfma_f32_16x16x32_bf16 v[40:43], v[160:163], v[192:195], v[40:43]
	v_mfma_f32_16x16x32_bf16 v[28:31], v[152:155], v[200:203], v[28:31]
	v_mfma_f32_16x16x32_bf16 v[24:27], v[160:163], v[200:203], v[24:27]
	v_mfma_f32_16x16x32_bf16 v[12:15], v[152:155], v[208:211], v[12:15]
	v_mfma_f32_16x16x32_bf16 v[8:11], v[160:163], v[208:211], v[8:11]
	v_mfma_f32_16x16x32_bf16 v[60:63], v[156:159], v[188:191], v[60:63]
	v_mfma_f32_16x16x32_bf16 v[56:59], v[164:167], v[188:191], v[56:59]
	v_mfma_f32_16x16x32_bf16 v[44:47], v[156:159], v[196:199], v[44:47]
	v_mfma_f32_16x16x32_bf16 v[40:43], v[164:167], v[196:199], v[40:43]
	v_mfma_f32_16x16x32_bf16 v[28:31], v[156:159], v[204:207], v[28:31]
	v_mfma_f32_16x16x32_bf16 v[24:27], v[164:167], v[204:207], v[24:27]
	v_mfma_f32_16x16x32_bf16 v[12:15], v[156:159], v[212:215], v[12:15]
	v_mfma_f32_16x16x32_bf16 v[8:11], v[164:167], v[212:215], v[8:11]
	v_mfma_f32_16x16x32_bf16 v[52:55], v[168:171], v[184:187], v[52:55]
	v_mfma_f32_16x16x32_bf16 v[48:51], v[176:179], v[184:187], v[48:51]
	v_mfma_f32_16x16x32_bf16 v[36:39], v[168:171], v[192:195], v[36:39]
	v_mfma_f32_16x16x32_bf16 v[32:35], v[176:179], v[192:195], v[32:35]
	v_mfma_f32_16x16x32_bf16 v[20:23], v[168:171], v[200:203], v[20:23]
	v_mfma_f32_16x16x32_bf16 v[16:19], v[176:179], v[200:203], v[16:19]
	v_mfma_f32_16x16x32_bf16 v[4:7], v[168:171], v[208:211], v[4:7]
	v_mfma_f32_16x16x32_bf16 v[0:3], v[176:179], v[208:211], v[0:3]
	v_mfma_f32_16x16x32_bf16 v[52:55], v[172:175], v[188:191], v[52:55]
	v_mfma_f32_16x16x32_bf16 v[48:51], v[180:183], v[188:191], v[48:51]
	v_mfma_f32_16x16x32_bf16 v[36:39], v[172:175], v[196:199], v[36:39]
	v_mfma_f32_16x16x32_bf16 v[32:35], v[180:183], v[196:199], v[32:35]
	v_mfma_f32_16x16x32_bf16 v[20:23], v[172:175], v[204:207], v[20:23]
	v_mfma_f32_16x16x32_bf16 v[16:19], v[180:183], v[204:207], v[16:19]
	v_mfma_f32_16x16x32_bf16 v[4:7], v[172:175], v[212:215], v[4:7]
	v_mfma_f32_16x16x32_bf16 v[0:3], v[180:183], v[212:215], v[0:3]
	s_barrier
	s_add_i32 s62, 0, 0x18000
	s_add_i32 s63, 0, 0x1c000
	v_add_u32_e32 v164, s62, v147
	v_add_u32_e32 v180, s63, v147
	ds_read_b128 v[152:155], v164
	ds_read_b128 v[156:159], v164 offset:1024
	ds_read_b128 v[160:163], v164 offset:2048
	ds_read_b128 v[164:167], v164 offset:3072
	ds_read_b128 v[168:171], v180
	ds_read_b128 v[172:175], v180 offset:1024
	ds_read_b128 v[176:179], v180 offset:2048
	ds_read_b128 v[180:183], v180 offset:3072
	s_add_u32 s84, s36, 0x80
	s_addc_u32 s85, s37, 0
	s_add_u32 s36, s36, 0x80000
	s_addc_u32 s37, s37, 0
	s_mov_b32 m0, s46
	ds_read_b128 v[184:187], v151 offset:32768
	ds_read_b128 v[188:191], v151 offset:33792
	ds_read_b128 v[192:195], v151 offset:34816
	ds_read_b128 v[196:199], v151 offset:35840
	ds_read_b128 v[200:203], v151 offset:36864
	ds_read_b128 v[204:207], v151 offset:37888
	ds_read_b128 v[208:211], v151 offset:38912
	ds_read_b128 v[212:215], v151 offset:39936
	global_load_lds_dwordx4 v134, s[36:37]
	s_mov_b32 m0, s47
	s_nop 0
	global_load_lds_dwordx4 v130, s[36:37]
	s_waitcnt vmcnt(8) lgkmcnt(0)
	s_barrier
	v_mfma_f32_16x16x32_bf16 v[124:127], v[152:155], v[184:187], v[124:127]
	v_mfma_f32_16x16x32_bf16 v[120:123], v[160:163], v[184:187], v[120:123]
	v_mfma_f32_16x16x32_bf16 v[108:111], v[152:155], v[192:195], v[108:111]
	v_mfma_f32_16x16x32_bf16 v[104:107], v[160:163], v[192:195], v[104:107]
	v_mfma_f32_16x16x32_bf16 v[92:95], v[152:155], v[200:203], v[92:95]
	v_mfma_f32_16x16x32_bf16 v[88:91], v[160:163], v[200:203], v[88:91]
	v_mfma_f32_16x16x32_bf16 v[76:79], v[152:155], v[208:211], v[76:79]
	v_mfma_f32_16x16x32_bf16 v[72:75], v[160:163], v[208:211], v[72:75]
	v_mfma_f32_16x16x32_bf16 v[124:127], v[156:159], v[188:191], v[124:127]
	v_mfma_f32_16x16x32_bf16 v[120:123], v[164:167], v[188:191], v[120:123]
	v_mfma_f32_16x16x32_bf16 v[108:111], v[156:159], v[196:199], v[108:111]
	v_mfma_f32_16x16x32_bf16 v[104:107], v[164:167], v[196:199], v[104:107]
	v_mfma_f32_16x16x32_bf16 v[92:95], v[156:159], v[204:207], v[92:95]
	v_mfma_f32_16x16x32_bf16 v[88:91], v[164:167], v[204:207], v[88:91]
	v_mfma_f32_16x16x32_bf16 v[76:79], v[156:159], v[212:215], v[76:79]
	v_mfma_f32_16x16x32_bf16 v[72:75], v[164:167], v[212:215], v[72:75]
	v_mfma_f32_16x16x32_bf16 v[116:119], v[168:171], v[184:187], v[116:119]
	v_mfma_f32_16x16x32_bf16 v[112:115], v[176:179], v[184:187], v[112:115]
	v_mfma_f32_16x16x32_bf16 v[100:103], v[168:171], v[192:195], v[100:103]
	v_mfma_f32_16x16x32_bf16 v[96:99], v[176:179], v[192:195], v[96:99]
	v_mfma_f32_16x16x32_bf16 v[84:87], v[168:171], v[200:203], v[84:87]
	v_mfma_f32_16x16x32_bf16 v[80:83], v[176:179], v[200:203], v[80:83]
	v_mfma_f32_16x16x32_bf16 v[68:71], v[168:171], v[208:211], v[68:71]
	v_mfma_f32_16x16x32_bf16 v[64:67], v[176:179], v[208:211], v[64:67]
	v_mfma_f32_16x16x32_bf16 v[116:119], v[172:175], v[188:191], v[116:119]
	v_mfma_f32_16x16x32_bf16 v[112:115], v[180:183], v[188:191], v[112:115]
	v_mfma_f32_16x16x32_bf16 v[100:103], v[172:175], v[196:199], v[100:103]
	v_mfma_f32_16x16x32_bf16 v[96:99], v[180:183], v[196:199], v[96:99]
	v_mfma_f32_16x16x32_bf16 v[84:87], v[172:175], v[204:207], v[84:87]
	v_mfma_f32_16x16x32_bf16 v[80:83], v[180:183], v[204:207], v[80:83]
	v_mfma_f32_16x16x32_bf16 v[68:71], v[172:175], v[212:215], v[68:71]
	v_mfma_f32_16x16x32_bf16 v[64:67], v[180:183], v[212:215], v[64:67]
	s_barrier
; __device__ __forceinline__ float fsilu(float v) { return v * fsigmoid(v); }
; __device__ __forceinline__ u32x4 pack8(const f32x4 a, const f32x4 b) { u32x4 w; w.x = cvt_pk_bf16(a[0], a[1]); w.y = cvt_pk_bf16(a[2], a[3]); w.z = cvt_pk_bf16(b[0], b[1]); w.w = cvt_pk_bf16(b[2], b[3]); return w; }
; #define PG8_STAGE(bufoff, gbase, voff) do { _Pragma("unroll") for (int _i = 0; _i < 2; ++_i) \
;         __builtin_amdgcn_global_load_lds((const unsigned*)((const char*)(gbase) + (voff)[_i]), (PG8_LAS unsigned*)(lds + (bufoff) + ldsw + _i * 8192), 16, 0, 0); } while (0)
; #define PG8_LDA(dst, b, h) do { _Pragma("unroll") for (int m = 0; m < 4; ++m) _Pragma("unroll") for (int k = 0; k < 2; ++k) dst[m][k] = *(const PG8_LAS bf16x8*)(lds + PG8_SA(b, h) + aoff + m * 2048 + k * 1024); } while (0)
; #define PG8_MMA(ai, bj, At, Bt) do { __builtin_amdgcn_s_setprio(1); _Pragma("unroll") for (int m = 0; m < 4; ++m) _Pragma("unroll") for (int n = 0; n < 2; ++n) _Pragma("unroll") for (int k = 0; k < 2; ++k) \
;         acc[ai][bj][m][n] = __builtin_amdgcn_mfma_f32_16x16x32_bf16(Bt[n][k], At[m][k], acc[ai][bj][m][n], 0, 0, 0); __builtin_amdgcn_s_setprio(0); } while (0)
; #define PG8_BAR __builtin_amdgcn_s_barrier()
;     __device__ __forceinline__ void operator()(const f32x4 (&acc)[2][2][4][2], const Unit& u, int wr, int wc, int fr, int fq) const {
;         const int row0 = u.pm * BM + wr * 64 + fr, col0 = u.pn * 128 + wc * 32 + 8 * fq;
; #pragma unroll
;         for (int ai = 0; ai < 2; ++ai)
; #pragma unroll
;             for (int m = 0; m < 4; ++m) {
;                 bf16_t* rowp = O + (size_t)(row0 + ai * HALF + m * 16) * ldc + col0;
;                 f32x4 h0, h1;
; #pragma unroll
;                 for (int j = 0; j < 4; ++j) { h0[j] = fsilu(acc[ai][0][m][0][j]) * acc[ai][1][m][0][j]; h1[j] = fsilu(acc[ai][0][m][1][j]) * acc[ai][1][m][1][j]; }
;                 *(u32x4*)rowp = pack8(h0, h1);
; template <class Epi, class Sched, bool ALIGN_EPI = false, bool SP2 = false>
; __device__ __forceinline__ void gemm_phase(PG8_LAS unsigned char* lds, const Gemm g, const Sched& S, const Epi& E) {
;     ...
;             PG8_LDA(At, 1, 1); PG8_STAGE(PG8_SB(1, 0), b3, voffB); PG8_STAGE(PG8_SB(1, 1), b3 + hstep, voffB); PG8_STAGE(PG8_SA(1, 0), a3, voffA);
;             PG8_WAIT_V(8); PG8_WAIT_L(0); PG8_BAR; PG8_MMA(1, 0, At, B0); PG8_MMA(1, 1, At, B1); PG8_BAR; PG8_SCHED;
	s_add_i32 s36, s62, s42
	s_add_u32 s86, s34, 0x80
	s_addc_u32 s87, s35, 0
	s_mov_b32 m0, s36
	ds_read_b128 v[184:187], v151 offset:49152
	ds_read_b128 v[188:191], v151 offset:50176
	ds_read_b128 v[192:195], v151 offset:51200
	ds_read_b128 v[196:199], v151 offset:52224
	ds_read_b128 v[200:203], v151 offset:53248
	ds_read_b128 v[204:207], v151 offset:54272
	ds_read_b128 v[208:211], v151 offset:55296
	ds_read_b128 v[212:215], v151 offset:56320
	global_load_lds_dwordx4 v132, s[86:87]
	s_add_i32 m0, s36, 0x2000
	s_add_u32 s34, s34, 0x80080
	s_addc_u32 s35, s35, 0
	s_add_i32 s36, s63, s42
	global_load_lds_dwordx4 v128, s[86:87]
	s_mov_b32 m0, s36
	s_nop 0
	global_load_lds_dwordx4 v132, s[34:35]
	s_add_i32 m0, s36, 0x2000
	s_nop 0
	global_load_lds_dwordx4 v128, s[34:35]
	s_mov_b32 m0, s49
	s_nop 0
	global_load_lds_dwordx4 v134, s[84:85]
	s_mov_b32 m0, s50
	s_nop 0
	global_load_lds_dwordx4 v130, s[84:85]
	s_waitcnt vmcnt(8) lgkmcnt(0)
	s_barrier
	v_mfma_f32_16x16x32_bf16 v[60:63], v[152:155], v[184:187], v[60:63]
	v_mfma_f32_16x16x32_bf16 v[56:59], v[160:163], v[184:187], v[56:59]
	v_mfma_f32_16x16x32_bf16 v[44:47], v[152:155], v[192:195], v[44:47]
	v_mfma_f32_16x16x32_bf16 v[40:43], v[160:163], v[192:195], v[40:43]
	v_mfma_f32_16x16x32_bf16 v[28:31], v[152:155], v[200:203], v[28:31]
	v_mfma_f32_16x16x32_bf16 v[24:27], v[160:163], v[200:203], v[24:27]
	v_mfma_f32_16x16x32_bf16 v[12:15], v[152:155], v[208:211], v[12:15]
	v_mfma_f32_16x16x32_bf16 v[8:11], v[160:163], v[208:211], v[8:11]
	v_mfma_f32_16x16x32_bf16 v[60:63], v[156:159], v[188:191], v[60:63]
	v_mfma_f32_16x16x32_bf16 v[56:59], v[164:167], v[188:191], v[56:59]
	v_mfma_f32_16x16x32_bf16 v[44:47], v[156:159], v[196:199], v[44:47]
	v_mfma_f32_16x16x32_bf16 v[40:43], v[164:167], v[196:199], v[40:43]
	v_mfma_f32_16x16x32_bf16 v[28:31], v[156:159], v[204:207], v[28:31]
	v_mfma_f32_16x16x32_bf16 v[24:27], v[164:167], v[204:207], v[24:27]
	v_mfma_f32_16x16x32_bf16 v[12:15], v[156:159], v[212:215], v[12:15]
	v_mfma_f32_16x16x32_bf16 v[8:11], v[164:167], v[212:215], v[8:11]
	v_mfma_f32_16x16x32_bf16 v[52:55], v[168:171], v[184:187], v[52:55]
	v_mfma_f32_16x16x32_bf16 v[48:51], v[176:179], v[184:187], v[48:51]
	v_mfma_f32_16x16x32_bf16 v[36:39], v[168:171], v[192:195], v[36:39]
	v_mfma_f32_16x16x32_bf16 v[32:35], v[176:179], v[192:195], v[32:35]
	v_mfma_f32_16x16x32_bf16 v[20:23], v[168:171], v[200:203], v[20:23]
	v_mfma_f32_16x16x32_bf16 v[16:19], v[176:179], v[200:203], v[16:19]
	v_mfma_f32_16x16x32_bf16 v[4:7], v[168:171], v[208:211], v[4:7]
	v_mfma_f32_16x16x32_bf16 v[0:3], v[176:179], v[208:211], v[0:3]
	v_mfma_f32_16x16x32_bf16 v[52:55], v[172:175], v[188:191], v[52:55]
	v_mfma_f32_16x16x32_bf16 v[48:51], v[180:183], v[188:191], v[48:51]
	v_mfma_f32_16x16x32_bf16 v[36:39], v[172:175], v[196:199], v[36:39]
	v_mfma_f32_16x16x32_bf16 v[32:35], v[180:183], v[196:199], v[32:35]
	v_mfma_f32_16x16x32_bf16 v[20:23], v[172:175], v[204:207], v[20:23]
	v_mfma_f32_16x16x32_bf16 v[16:19], v[180:183], v[204:207], v[16:19]
	v_mfma_f32_16x16x32_bf16 v[4:7], v[172:175], v[212:215], v[4:7]
	v_mfma_f32_16x16x32_bf16 v[0:3], v[180:183], v[212:215], v[0:3]
	s_barrier
	s_add_i32 s61, s61, 2
	s_add_u32 s30, s30, 0x100
	s_addc_u32 s31, s31, 0
	s_add_u32 s59, s59, 0x100
	s_addc_u32 s60, s60, 0
	s_cmp_gt_u32 s61, 29
	s_cbranch_scc0 .LBB0_945
	v_mul_f32_e32 v153, 0xbfb8aa3b, v124
	v_mul_f32_e32 v158, 0xbfb8aa3b, v120
	v_exp_f32_e32 v153, v153
	v_exp_f32_e32 v159, v158
	v_mul_f32_e32 v158, 0xbfb8aa3b, v125
	v_exp_f32_e32 v160, v158
	v_add_f32_e32 v153, 1.0, v153
	v_rcp_f32_e32 v158, v153
	v_add_f32_e32 v153, 1.0, v159
	v_add_f32_e32 v159, 1.0, v160
	v_rcp_f32_e32 v159, v159
	v_mul_f32_e32 v160, 0xbfb8aa3b, v121
	v_exp_f32_e32 v161, v160
	v_rcp_f32_e32 v160, v153
	v_pk_mul_f32 v[124:125], v[124:125], v[158:159]
	v_mul_f32_e32 v153, 0xbfb8aa3b, v127
	v_pk_mul_f32 v[116:117], v[124:125], v[116:117]
	v_add_f32_e32 v124, 1.0, v161
	v_mul_f32_e32 v125, 0xbfb8aa3b, v122
	v_rcp_f32_e32 v161, v124
	v_mul_f32_e32 v124, 0xbfb8aa3b, v126
	v_exp_f32_e32 v125, v125
	v_exp_f32_e32 v124, v124
	v_exp_f32_e32 v153, v153
	v_mul_f32_e32 v158, 0xbfb8aa3b, v123
	v_exp_f32_e32 v159, v158
	v_add_f32_e32 v125, 1.0, v125
	v_add_f32_e32 v124, 1.0, v124
	v_rcp_f32_e32 v158, v125
	v_add_f32_e32 v125, 1.0, v153
	v_rcp_f32_e32 v124, v124
	v_rcp_f32_e32 v125, v125
	v_add_f32_e32 v153, 1.0, v159
	v_rcp_f32_e32 v159, v153
	v_pk_mul_f32 v[120:121], v[120:121], v[160:161]
	v_lshl_or_b32 v154, s56, 7, v148
	v_pk_mul_f32 v[120:121], v[120:121], v[112:113]
	v_pk_mul_f32 v[112:113], v[126:127], v[124:125]
	v_lshl_add_u32 v152, s28, 8, v146
	v_ashrrev_i32_e32 v155, 31, v154
	v_mov_b64_e32 v[144:145], s[10:11]
	v_pk_mul_f32 v[118:119], v[112:113], v[118:119]
	v_pk_mul_f32 v[112:113], v[122:123], v[158:159]
	v_mad_i64_i32 v[156:157], s[30:31], v152, s55, v[144:145]
	v_pk_mul_f32 v[122:123], v[112:113], v[114:115]
	v_lshlrev_b64 v[112:113], 1, v[154:155]
	v_lshl_add_u64 v[124:125], v[156:157], 0, v[112:113]
	v_cvt_pk_bf16_f32 v114, v116, v117
	v_cvt_pk_bf16_f32 v115, v118, v119
	v_cvt_pk_bf16_f32 v116, v120, v121
	v_cvt_pk_bf16_f32 v117, v122, v123
	global_store_dwordx4 v[124:125], v[114:117], off
	v_mul_f32_e32 v118, 0xbfb8aa3b, v109
	v_exp_f32_e32 v118, v118
	v_mul_f32_e32 v116, 0xbfb8aa3b, v108
	v_mul_f32_e32 v117, 0xbfb8aa3b, v104
	v_exp_f32_e32 v116, v116
	v_exp_f32_e32 v117, v117
	v_or_b32_e32 v114, 16, v152
	v_mad_i64_i32 v[114:115], s[30:31], v114, s55, v[144:145]
	v_add_f32_e32 v116, 1.0, v116
	v_add_f32_e32 v119, 1.0, v117
	v_add_f32_e32 v117, 1.0, v118
	v_rcp_f32_e32 v116, v116
	v_rcp_f32_e32 v117, v117
	v_mul_f32_e32 v118, 0xbfb8aa3b, v105
; __device__ __forceinline__ float fsilu(float v) { return v * fsigmoid(v); }
; __device__ __forceinline__ u32x4 pack8(const f32x4 a, const f32x4 b) { u32x4 w; w.x = cvt_pk_bf16(a[0], a[1]); w.y = cvt_pk_bf16(a[2], a[3]); w.z = cvt_pk_bf16(b[0], b[1]); w.w = cvt_pk_bf16(b[2], b[3]); return w; }
;     __device__ __forceinline__ void operator()(const f32x4 (&acc)[2][2][4][2], const Unit& u, int wr, int wc, int fr, int fq) const {
;         const int row0 = u.pm * BM + wr * 64 + fr, col0 = u.pn * 128 + wc * 32 + 8 * fq;
; #pragma unroll
;         for (int ai = 0; ai < 2; ++ai)
; #pragma unroll
;             for (int m = 0; m < 4; ++m) {
;                 bf16_t* rowp = O + (size_t)(row0 + ai * HALF + m * 16) * ldc + col0;
;                 f32x4 h0, h1;
; #pragma unroll
;                 for (int j = 0; j < 4; ++j) { h0[j] = fsilu(acc[ai][0][m][0][j]) * acc[ai][1][m][0][j]; h1[j] = fsilu(acc[ai][0][m][1][j]) * acc[ai][1][m][1][j]; }
;                 *(u32x4*)rowp = pack8(h0, h1);
	v_exp_f32_e32 v120, v118
	v_rcp_f32_e32 v118, v119
	v_pk_mul_f32 v[108:109], v[108:109], v[116:117]
	v_mul_f32_e32 v116, 0xbfb8aa3b, v111
	v_pk_mul_f32 v[100:101], v[108:109], v[100:101]
	v_add_f32_e32 v108, 1.0, v120
	v_rcp_f32_e32 v119, v108
	v_mul_f32_e32 v109, 0xbfb8aa3b, v106
	v_mul_f32_e32 v108, 0xbfb8aa3b, v110
	v_exp_f32_e32 v109, v109
	v_exp_f32_e32 v108, v108
	v_exp_f32_e32 v117, v116
	v_mul_f32_e32 v116, 0xbfb8aa3b, v107
	v_pk_mul_f32 v[104:105], v[104:105], v[118:119]
	v_exp_f32_e32 v118, v116
	v_add_f32_e32 v109, 1.0, v109
	v_add_f32_e32 v108, 1.0, v108
	v_rcp_f32_e32 v116, v109
	v_add_f32_e32 v109, 1.0, v117
	v_rcp_f32_e32 v108, v108
	v_rcp_f32_e32 v109, v109
	v_add_f32_e32 v117, 1.0, v118
	v_rcp_f32_e32 v117, v117
	v_pk_mul_f32 v[104:105], v[104:105], v[96:97]
	v_pk_mul_f32 v[96:97], v[110:111], v[108:109]
	v_lshl_add_u64 v[108:109], v[114:115], 0, v[112:113]
	v_pk_mul_f32 v[102:103], v[96:97], v[102:103]
	v_pk_mul_f32 v[96:97], v[106:107], v[116:117]
	s_and_b64 vcc, exec, s[8:9]
	v_pk_mul_f32 v[106:107], v[96:97], v[98:99]
	v_cvt_pk_bf16_f32 v96, v100, v101
	v_cvt_pk_bf16_f32 v97, v102, v103
	v_cvt_pk_bf16_f32 v98, v104, v105
	v_cvt_pk_bf16_f32 v99, v106, v107
	global_store_dwordx4 v[108:109], v[96:99], off
	v_mul_f32_e32 v100, 0xbfb8aa3b, v93
	v_exp_f32_e32 v100, v100
	v_mul_f32_e32 v98, 0xbfb8aa3b, v92
	v_mul_f32_e32 v99, 0xbfb8aa3b, v88
	v_exp_f32_e32 v98, v98
	v_exp_f32_e32 v99, v99
	v_or_b32_e32 v96, 32, v152
	v_mad_i64_i32 v[96:97], s[30:31], v96, s55, v[144:145]
	v_add_f32_e32 v98, 1.0, v98
	v_add_f32_e32 v101, 1.0, v99
	v_add_f32_e32 v99, 1.0, v100
	v_rcp_f32_e32 v98, v98
	v_rcp_f32_e32 v99, v99
	v_mul_f32_e32 v100, 0xbfb8aa3b, v89
	v_exp_f32_e32 v102, v100
	v_rcp_f32_e32 v100, v101
	v_pk_mul_f32 v[92:93], v[92:93], v[98:99]
	v_mul_f32_e32 v98, 0xbfb8aa3b, v95
	v_pk_mul_f32 v[84:85], v[92:93], v[84:85]
	v_add_f32_e32 v92, 1.0, v102
	v_rcp_f32_e32 v101, v92
	v_mul_f32_e32 v93, 0xbfb8aa3b, v90
	v_mul_f32_e32 v92, 0xbfb8aa3b, v94
	v_exp_f32_e32 v93, v93
	v_exp_f32_e32 v92, v92
	v_exp_f32_e32 v99, v98
	v_mul_f32_e32 v98, 0xbfb8aa3b, v91
	v_pk_mul_f32 v[88:89], v[88:89], v[100:101]
	v_exp_f32_e32 v100, v98
	v_add_f32_e32 v93, 1.0, v93
	v_add_f32_e32 v92, 1.0, v92
	v_rcp_f32_e32 v98, v93
	v_add_f32_e32 v93, 1.0, v99
	v_rcp_f32_e32 v92, v92
	v_rcp_f32_e32 v93, v93
	v_add_f32_e32 v99, 1.0, v100
	v_rcp_f32_e32 v99, v99
	v_pk_mul_f32 v[88:89], v[88:89], v[80:81]
	v_pk_mul_f32 v[80:81], v[94:95], v[92:93]
	v_lshl_add_u64 v[92:93], v[96:97], 0, v[112:113]
	v_pk_mul_f32 v[86:87], v[80:81], v[86:87]
	v_pk_mul_f32 v[80:81], v[90:91], v[98:99]
	s_mov_b32 s56, s14
	v_pk_mul_f32 v[90:91], v[80:81], v[82:83]
	v_cvt_pk_bf16_f32 v80, v84, v85
	v_cvt_pk_bf16_f32 v81, v86, v87
	v_cvt_pk_bf16_f32 v82, v88, v89
	v_cvt_pk_bf16_f32 v83, v90, v91
	global_store_dwordx4 v[92:93], v[80:83], off
	v_mul_f32_e32 v84, 0xbfb8aa3b, v77
	v_exp_f32_e32 v84, v84
	v_mul_f32_e32 v82, 0xbfb8aa3b, v76
	v_mul_f32_e32 v83, 0xbfb8aa3b, v72
	v_exp_f32_e32 v82, v82
	v_exp_f32_e32 v83, v83
	v_or_b32_e32 v80, 48, v152
	v_mad_i64_i32 v[80:81], s[30:31], v80, s55, v[144:145]
	v_add_f32_e32 v82, 1.0, v82
	v_add_f32_e32 v85, 1.0, v83
	v_add_f32_e32 v83, 1.0, v84
	v_rcp_f32_e32 v82, v82
	v_rcp_f32_e32 v83, v83
	v_mul_f32_e32 v84, 0xbfb8aa3b, v73
	v_exp_f32_e32 v86, v84
	v_rcp_f32_e32 v84, v85
	v_pk_mul_f32 v[76:77], v[76:77], v[82:83]
	v_mul_f32_e32 v82, 0xbfb8aa3b, v79
	v_pk_mul_f32 v[68:69], v[76:77], v[68:69]
	v_add_f32_e32 v76, 1.0, v86
	v_rcp_f32_e32 v85, v76
	v_mul_f32_e32 v77, 0xbfb8aa3b, v74
	v_mul_f32_e32 v76, 0xbfb8aa3b, v78
	v_exp_f32_e32 v77, v77
	v_exp_f32_e32 v76, v76
	v_exp_f32_e32 v83, v82
	v_mul_f32_e32 v82, 0xbfb8aa3b, v75
	v_pk_mul_f32 v[72:73], v[72:73], v[84:85]
	v_exp_f32_e32 v84, v82
	v_add_f32_e32 v77, 1.0, v77
	v_add_f32_e32 v76, 1.0, v76
	v_rcp_f32_e32 v82, v77
	v_add_f32_e32 v77, 1.0, v83
	v_rcp_f32_e32 v76, v76
	v_rcp_f32_e32 v77, v77
	v_add_f32_e32 v83, 1.0, v84
	v_rcp_f32_e32 v83, v83
	v_pk_mul_f32 v[72:73], v[72:73], v[64:65]
	v_pk_mul_f32 v[64:65], v[78:79], v[76:77]
	v_lshl_add_u64 v[76:77], v[80:81], 0, v[112:113]
	v_pk_mul_f32 v[70:71], v[64:65], v[70:71]
	v_pk_mul_f32 v[64:65], v[74:75], v[82:83]
	s_mov_b32 s28, s22
	v_pk_mul_f32 v[74:75], v[64:65], v[66:67]
	v_cvt_pk_bf16_f32 v64, v68, v69
	v_cvt_pk_bf16_f32 v65, v70, v71
	v_cvt_pk_bf16_f32 v66, v72, v73
	v_cvt_pk_bf16_f32 v67, v74, v75
	global_store_dwordx4 v[76:77], v[64:67], off
	v_mul_f32_e32 v68, 0xbfb8aa3b, v61
	v_exp_f32_e32 v68, v68
	v_mul_f32_e32 v66, 0xbfb8aa3b, v60
	v_mul_f32_e32 v67, 0xbfb8aa3b, v56
	v_exp_f32_e32 v66, v66
	v_exp_f32_e32 v67, v67
	v_add_u32_e32 v64, 0x80, v152
	v_mad_i64_i32 v[64:65], s[30:31], v64, s55, v[144:145]
	v_add_f32_e32 v66, 1.0, v66
	v_add_f32_e32 v69, 1.0, v67
	v_add_f32_e32 v67, 1.0, v68
	v_rcp_f32_e32 v66, v66
	v_rcp_f32_e32 v67, v67
	v_mul_f32_e32 v68, 0xbfb8aa3b, v57
	v_exp_f32_e32 v70, v68
	v_rcp_f32_e32 v68, v69
	v_pk_mul_f32 v[60:61], v[60:61], v[66:67]
	v_mul_f32_e32 v66, 0xbfb8aa3b, v63
	v_pk_mul_f32 v[52:53], v[60:61], v[52:53]
	v_add_f32_e32 v60, 1.0, v70
	v_rcp_f32_e32 v69, v60
	v_mul_f32_e32 v61, 0xbfb8aa3b, v58
	v_mul_f32_e32 v60, 0xbfb8aa3b, v62
	v_exp_f32_e32 v61, v61
	v_exp_f32_e32 v60, v60
	v_exp_f32_e32 v67, v66
	v_mul_f32_e32 v66, 0xbfb8aa3b, v59
	v_pk_mul_f32 v[56:57], v[56:57], v[68:69]
	v_exp_f32_e32 v68, v66
	v_add_f32_e32 v61, 1.0, v61
	v_add_f32_e32 v60, 1.0, v60
	v_rcp_f32_e32 v66, v61
; __device__ __forceinline__ float fsilu(float v) { return v * fsigmoid(v); }
; __device__ __forceinline__ u32x4 pack8(const f32x4 a, const f32x4 b) { u32x4 w; w.x = cvt_pk_bf16(a[0], a[1]); w.y = cvt_pk_bf16(a[2], a[3]); w.z = cvt_pk_bf16(b[0], b[1]); w.w = cvt_pk_bf16(b[2], b[3]); return w; }
; #define PG8_WAIT_V(n) asm volatile("s_waitcnt vmcnt(" #n ")" ::: "memory")
; #define PG8_BAR __builtin_amdgcn_s_barrier()
;     __device__ __forceinline__ void operator()(const f32x4 (&acc)[2][2][4][2], const Unit& u, int wr, int wc, int fr, int fq) const {
;         const int row0 = u.pm * BM + wr * 64 + fr, col0 = u.pn * 128 + wc * 32 + 8 * fq;
; #pragma unroll
;         for (int ai = 0; ai < 2; ++ai)
; #pragma unroll
;             for (int m = 0; m < 4; ++m) {
;                 bf16_t* rowp = O + (size_t)(row0 + ai * HALF + m * 16) * ldc + col0;
;                 f32x4 h0, h1;
; #pragma unroll
;                 for (int j = 0; j < 4; ++j) { h0[j] = fsilu(acc[ai][0][m][0][j]) * acc[ai][1][m][0][j]; h1[j] = fsilu(acc[ai][0][m][1][j]) * acc[ai][1][m][1][j]; }
;                 *(u32x4*)rowp = pack8(h0, h1);
; template <class Epi, class Sched, bool ALIGN_EPI = false, bool SP2 = false>
; __device__ __forceinline__ void gemm_phase(PG8_LAS unsigned char* lds, const Gemm g, const Sched& S, const Epi& E) {
;     ...
;         if (!has_next) break;
; #pragma unroll
;         for (int a = 0; a < 2; ++a)
; #pragma unroll
;             for (int b = 0; b < 2; ++b)
; #pragma unroll
;                 for (int m = 0; m < 4; ++m)
; #pragma unroll
;                     for (int n = 0; n < 2; ++n) acc[a][b][m][n] = (f32x4){0.f, 0.f, 0.f, 0.f};
;         cur = nxt; cA = nA; cB = nB; ++ui;
;         if constexpr (ALIGN_EPI) { if (wr == 1) PG8_BAR; }
;     }
;     PG8_WAIT_V(0);
;     if constexpr (!ALIGN_EPI) { if (wr == 0) PG8_BAR; }
	v_add_f32_e32 v61, 1.0, v67
	v_rcp_f32_e32 v60, v60
	v_rcp_f32_e32 v61, v61
	v_add_f32_e32 v67, 1.0, v68
	v_rcp_f32_e32 v67, v67
	v_pk_mul_f32 v[56:57], v[56:57], v[48:49]
	v_pk_mul_f32 v[48:49], v[62:63], v[60:61]
	v_lshl_add_u64 v[60:61], v[64:65], 0, v[112:113]
	v_pk_mul_f32 v[54:55], v[48:49], v[54:55]
	v_pk_mul_f32 v[48:49], v[58:59], v[66:67]
	s_mov_b64 s[34:35], s[26:27]
	v_pk_mul_f32 v[58:59], v[48:49], v[50:51]
	v_cvt_pk_bf16_f32 v48, v52, v53
	v_cvt_pk_bf16_f32 v49, v54, v55
	v_cvt_pk_bf16_f32 v50, v56, v57
	v_cvt_pk_bf16_f32 v51, v58, v59
	global_store_dwordx4 v[60:61], v[48:51], off
	v_mul_f32_e32 v52, 0xbfb8aa3b, v45
	v_exp_f32_e32 v52, v52
	v_mul_f32_e32 v50, 0xbfb8aa3b, v44
	v_mul_f32_e32 v51, 0xbfb8aa3b, v40
	v_exp_f32_e32 v50, v50
	v_exp_f32_e32 v51, v51
	v_add_u32_e32 v48, 0x90, v152
	v_mad_i64_i32 v[48:49], s[30:31], v48, s55, v[144:145]
	v_add_f32_e32 v50, 1.0, v50
	v_add_f32_e32 v53, 1.0, v51
	v_add_f32_e32 v51, 1.0, v52
	v_rcp_f32_e32 v50, v50
	v_rcp_f32_e32 v51, v51
	v_mul_f32_e32 v52, 0xbfb8aa3b, v41
	v_exp_f32_e32 v54, v52
	v_rcp_f32_e32 v52, v53
	v_pk_mul_f32 v[44:45], v[44:45], v[50:51]
	v_mul_f32_e32 v50, 0xbfb8aa3b, v47
	v_pk_mul_f32 v[36:37], v[44:45], v[36:37]
	v_add_f32_e32 v44, 1.0, v54
	v_rcp_f32_e32 v53, v44
	v_mul_f32_e32 v45, 0xbfb8aa3b, v42
	v_mul_f32_e32 v44, 0xbfb8aa3b, v46
	v_exp_f32_e32 v45, v45
	v_exp_f32_e32 v44, v44
	v_exp_f32_e32 v51, v50
	v_mul_f32_e32 v50, 0xbfb8aa3b, v43
	v_pk_mul_f32 v[40:41], v[40:41], v[52:53]
	v_exp_f32_e32 v52, v50
	v_add_f32_e32 v45, 1.0, v45
	v_add_f32_e32 v44, 1.0, v44
	v_rcp_f32_e32 v50, v45
	v_add_f32_e32 v45, 1.0, v51
	v_rcp_f32_e32 v44, v44
	v_rcp_f32_e32 v45, v45
	v_add_f32_e32 v51, 1.0, v52
	v_rcp_f32_e32 v51, v51
	v_pk_mul_f32 v[40:41], v[40:41], v[32:33]
	v_pk_mul_f32 v[32:33], v[46:47], v[44:45]
	v_lshl_add_u64 v[44:45], v[48:49], 0, v[112:113]
	v_pk_mul_f32 v[38:39], v[32:33], v[38:39]
	v_pk_mul_f32 v[32:33], v[42:43], v[50:51]
	s_nop 0
	v_pk_mul_f32 v[42:43], v[32:33], v[34:35]
	v_cvt_pk_bf16_f32 v32, v36, v37
	v_cvt_pk_bf16_f32 v33, v38, v39
	v_cvt_pk_bf16_f32 v34, v40, v41
	v_cvt_pk_bf16_f32 v35, v42, v43
	global_store_dwordx4 v[44:45], v[32:35], off
	v_mul_f32_e32 v36, 0xbfb8aa3b, v29
	v_exp_f32_e32 v36, v36
	v_mul_f32_e32 v34, 0xbfb8aa3b, v28
	v_mul_f32_e32 v35, 0xbfb8aa3b, v24
	v_exp_f32_e32 v34, v34
	v_exp_f32_e32 v35, v35
	v_add_u32_e32 v32, 0xa0, v152
	v_mad_i64_i32 v[32:33], s[30:31], v32, s55, v[144:145]
	v_add_f32_e32 v34, 1.0, v34
	v_add_f32_e32 v37, 1.0, v35
	v_add_f32_e32 v35, 1.0, v36
	v_rcp_f32_e32 v34, v34
	v_rcp_f32_e32 v35, v35
	v_mul_f32_e32 v36, 0xbfb8aa3b, v25
	v_exp_f32_e32 v38, v36
	v_rcp_f32_e32 v36, v37
	v_pk_mul_f32 v[28:29], v[28:29], v[34:35]
	v_mul_f32_e32 v34, 0xbfb8aa3b, v31
	v_pk_mul_f32 v[20:21], v[28:29], v[20:21]
	v_add_f32_e32 v28, 1.0, v38
	v_rcp_f32_e32 v37, v28
	v_mul_f32_e32 v29, 0xbfb8aa3b, v26
	v_mul_f32_e32 v28, 0xbfb8aa3b, v30
	v_exp_f32_e32 v29, v29
	v_exp_f32_e32 v28, v28
	v_exp_f32_e32 v35, v34
	v_mul_f32_e32 v34, 0xbfb8aa3b, v27
	v_pk_mul_f32 v[24:25], v[24:25], v[36:37]
	v_exp_f32_e32 v36, v34
	v_add_f32_e32 v29, 1.0, v29
	v_add_f32_e32 v28, 1.0, v28
	v_rcp_f32_e32 v34, v29
	v_add_f32_e32 v29, 1.0, v35
	v_rcp_f32_e32 v28, v28
	v_rcp_f32_e32 v29, v29
	v_add_f32_e32 v35, 1.0, v36
	v_rcp_f32_e32 v35, v35
	v_pk_mul_f32 v[24:25], v[24:25], v[16:17]
	v_pk_mul_f32 v[16:17], v[30:31], v[28:29]
	v_lshl_add_u64 v[28:29], v[32:33], 0, v[112:113]
	v_pk_mul_f32 v[22:23], v[16:17], v[22:23]
	v_pk_mul_f32 v[16:17], v[26:27], v[34:35]
	s_nop 0
	v_pk_mul_f32 v[26:27], v[16:17], v[18:19]
	v_cvt_pk_bf16_f32 v16, v20, v21
	v_cvt_pk_bf16_f32 v17, v22, v23
	v_cvt_pk_bf16_f32 v18, v24, v25
	v_cvt_pk_bf16_f32 v19, v26, v27
	global_store_dwordx4 v[28:29], v[16:19], off
	v_mul_f32_e32 v20, 0xbfb8aa3b, v13
	v_exp_f32_e32 v20, v20
	v_mul_f32_e32 v18, 0xbfb8aa3b, v12
	v_mul_f32_e32 v19, 0xbfb8aa3b, v8
	v_exp_f32_e32 v18, v18
	v_exp_f32_e32 v19, v19
	v_add_u32_e32 v16, 0xb0, v152
	v_mad_i64_i32 v[16:17], s[30:31], v16, s55, v[144:145]
	v_add_f32_e32 v18, 1.0, v18
	v_add_f32_e32 v21, 1.0, v19
	v_add_f32_e32 v19, 1.0, v20
	v_rcp_f32_e32 v18, v18
	v_rcp_f32_e32 v19, v19
	v_mul_f32_e32 v20, 0xbfb8aa3b, v9
	v_exp_f32_e32 v22, v20
	v_rcp_f32_e32 v20, v21
	v_pk_mul_f32 v[12:13], v[12:13], v[18:19]
	v_mul_f32_e32 v18, 0xbfb8aa3b, v15
	v_pk_mul_f32 v[4:5], v[12:13], v[4:5]
	v_add_f32_e32 v12, 1.0, v22
	v_rcp_f32_e32 v21, v12
	v_mul_f32_e32 v13, 0xbfb8aa3b, v10
	v_mul_f32_e32 v12, 0xbfb8aa3b, v14
	v_exp_f32_e32 v13, v13
	v_exp_f32_e32 v12, v12
	v_exp_f32_e32 v19, v18
	v_mul_f32_e32 v18, 0xbfb8aa3b, v11
	v_pk_mul_f32 v[8:9], v[8:9], v[20:21]
	v_exp_f32_e32 v20, v18
	v_add_f32_e32 v13, 1.0, v13
	v_add_f32_e32 v12, 1.0, v12
	v_rcp_f32_e32 v18, v13
	v_add_f32_e32 v13, 1.0, v19
	v_rcp_f32_e32 v12, v12
	v_rcp_f32_e32 v13, v13
	v_add_f32_e32 v19, 1.0, v20
	v_rcp_f32_e32 v19, v19
	v_pk_mul_f32 v[8:9], v[8:9], v[0:1]
	v_pk_mul_f32 v[0:1], v[14:15], v[12:13]
	v_lshl_add_u64 v[12:13], v[16:17], 0, v[112:113]
	v_pk_mul_f32 v[6:7], v[0:1], v[6:7]
	v_pk_mul_f32 v[0:1], v[10:11], v[18:19]
	s_mov_b64 s[30:31], s[24:25]
	v_pk_mul_f32 v[10:11], v[0:1], v[2:3]
	v_cvt_pk_bf16_f32 v0, v4, v5
	v_cvt_pk_bf16_f32 v1, v6, v7
	v_cvt_pk_bf16_f32 v2, v8, v9
	v_cvt_pk_bf16_f32 v3, v10, v11
	global_store_dwordx4 v[12:13], v[0:3], off
	s_cbranch_vccz .LBB0_942
	s_waitcnt vmcnt(0)
	s_cmpk_gt_u32 s3, 0xff
	s_cbranch_scc1 .LBB0_949
	s_barrier

; #define PG8_STAGE(bufoff, gbase, voff) do { _Pragma("unroll") for (int _i = 0; _i < 2; ++_i) \
;         __builtin_amdgcn_global_load_lds((const unsigned*)((const char*)(gbase) + (voff)[_i]), (PG8_LAS unsigned*)(lds + (bufoff) + ldsw + _i * 8192), 16, 0, 0); } while (0)
; #define PG8_LDA(dst, b, h) do { _Pragma("unroll") for (int m = 0; m < 4; ++m) _Pragma("unroll") for (int k = 0; k < 2; ++k) dst[m][k] = *(const PG8_LAS bf16x8*)(lds + PG8_SA(b, h) + aoff + m * 2048 + k * 1024); } while (0)
; #define PG8_LDB(dst, b, h) do { _Pragma("unroll") for (int n = 0; n < 2; ++n) _Pragma("unroll") for (int k = 0; k < 2; ++k) dst[n][k] = *(const PG8_LAS bf16x8*)(lds + PG8_SB(b, h) + boff + n * 2048 + k * 1024); } while (0)
; #define PG8_WAIT_V(n) asm volatile("s_waitcnt vmcnt(" #n ")" ::: "memory")
; #define PG8_WAIT_L(n) asm volatile("s_waitcnt lgkmcnt(" #n ")" ::: "memory")
; #define PG8_BAR __builtin_amdgcn_s_barrier()
; #define PG8_SCHED __builtin_amdgcn_sched_barrier(0)
; template <class Epi, class Sched, bool ALIGN_EPI = false, bool SP2 = false>
; __device__ __forceinline__ void gemm_phase(PG8_LAS unsigned char* lds, const Gemm g, const Sched& S, const Epi& E) {
;     ...
;         const bool has_next = S.next(ui + 1, nxt);
;         const char* nA = has_next ? (const char*)g.A + (size_t)nxt.pm * tstep : cA; const char* nB = has_next ? (const char*)g.Bt + (size_t)nxt.pn * tstep : cB;
;         for (int t = 0; t < nt; t += 2) {
;             const bool last = (t == nt - 2);
;             const char* a1 = cA + (size_t)(t + 1) * kstep;
;             const char* a2 = last ? nA : cA + (size_t)(t + 2) * kstep; const char* b2 = last ? nB : cB + (size_t)(t + 2) * kstep;
;             const char* a3 = a2 + kstep; const char* b3 = b2 + kstep;
;             if (last && has_next) S.a_ready(nxt);
;             if constexpr (SP2) {
;             PG8_LDB(B0, 0, 0); PG8_LDB(B1, 0, 1); PG8_SCHED; PG8_LDA(At, 0, 0); PG8_STAGE(PG8_SA(1, 1), a1 + hstep, voffA);
;             PG8_WAIT_V(8); PG8_WAIT_L(0); PG8_BAR; PG8_MMA(0, 0, At, B0); PG8_MMA(0, 1, At, B1); PG8_BAR; PG8_SCHED;
;             PG8_LDA(At, 0, 1); PG8_STAGE(PG8_SB(0, 0), b2, voffB); PG8_STAGE(PG8_SB(0, 1), b2 + hstep, voffB); PG8_STAGE(PG8_SA(0, 0), a2, voffA);
;             PG8_WAIT_V(8); PG8_WAIT_L(0); PG8_BAR; PG8_MMA(1, 0, At, B0); PG8_MMA(1, 1, At, B1); PG8_BAR; PG8_SCHED;
.LBB0_1020:
	s_add_u32 s54, s26, 0x100
	s_addc_u32 s55, s27, 0
	s_mov_b32 s56, -2
	ds_read_b128 v[144:147], v169
	ds_read_b128 v[148:151], v169 offset:1024
	ds_read_b128 v[152:155], v169 offset:2048
	ds_read_b128 v[156:159], v169 offset:3072
	ds_read_b128 v[160:163], v170
	ds_read_b128 v[172:175], v170 offset:1024
	ds_read_b128 v[176:179], v170 offset:2048
	ds_read_b128 v[180:183], v170 offset:3072
	s_add_u32 s26, s24, 0x100
	s_addc_u32 s27, s25, 0
	s_cmpk_eq_i32 s56, 0x54
	s_cselect_b32 s31, s5, s27
	s_cselect_b32 s30, s4, s26
	s_cselect_b32 s29, s7, s55
	s_cselect_b32 s28, s6, s54
	s_add_i32 m0, s38, 0xc000
	ds_read_b128 v[184:187], v171
	ds_read_b128 v[188:191], v171 offset:1024
	ds_read_b128 v[192:195], v171 offset:2048
	ds_read_b128 v[196:199], v171 offset:3072
	ds_read_b128 v[200:203], v171 offset:4096
	ds_read_b128 v[204:207], v171 offset:5120
	ds_read_b128 v[208:211], v171 offset:6144
	ds_read_b128 v[212:215], v171 offset:7168
	global_load_lds_dwordx4 v136, s[24:25]
	s_add_i32 m0, s38, 0xe000
	s_nop 0
	global_load_lds_dwordx4 v138, s[24:25]
	s_waitcnt vmcnt(8) lgkmcnt(0)
	s_barrier
	v_mfma_f32_16x16x32_bf16 v[124:127], v[144:147], v[184:187], 0
	v_mfma_f32_16x16x32_bf16 v[120:123], v[152:155], v[184:187], 0
	v_mfma_f32_16x16x32_bf16 v[116:119], v[144:147], v[192:195], 0
	v_mfma_f32_16x16x32_bf16 v[112:115], v[152:155], v[192:195], 0
	v_mfma_f32_16x16x32_bf16 v[108:111], v[144:147], v[200:203], 0
	v_mfma_f32_16x16x32_bf16 v[96:99], v[152:155], v[200:203], 0
	v_mfma_f32_16x16x32_bf16 v[84:87], v[144:147], v[208:211], 0
	v_mfma_f32_16x16x32_bf16 v[76:79], v[152:155], v[208:211], 0
	v_mfma_f32_16x16x32_bf16 v[124:127], v[148:151], v[188:191], v[124:127]
	v_mfma_f32_16x16x32_bf16 v[120:123], v[156:159], v[188:191], v[120:123]
	v_mfma_f32_16x16x32_bf16 v[116:119], v[148:151], v[196:199], v[116:119]
	v_mfma_f32_16x16x32_bf16 v[112:115], v[156:159], v[196:199], v[112:115]
	v_mfma_f32_16x16x32_bf16 v[108:111], v[148:151], v[204:207], v[108:111]
	v_mfma_f32_16x16x32_bf16 v[96:99], v[156:159], v[204:207], v[96:99]
	v_mfma_f32_16x16x32_bf16 v[84:87], v[148:151], v[212:215], v[84:87]
	v_mfma_f32_16x16x32_bf16 v[76:79], v[156:159], v[212:215], v[76:79]
	v_mfma_f32_16x16x32_bf16 v[104:107], v[160:163], v[184:187], 0
	v_mfma_f32_16x16x32_bf16 v[100:103], v[176:179], v[184:187], 0
	v_mfma_f32_16x16x32_bf16 v[92:95], v[160:163], v[192:195], 0
	v_mfma_f32_16x16x32_bf16 v[88:91], v[176:179], v[192:195], 0
	v_mfma_f32_16x16x32_bf16 v[80:83], v[160:163], v[200:203], 0
	v_mfma_f32_16x16x32_bf16 v[72:75], v[176:179], v[200:203], 0
	v_mfma_f32_16x16x32_bf16 v[68:71], v[160:163], v[208:211], 0
	v_mfma_f32_16x16x32_bf16 v[64:67], v[176:179], v[208:211], 0
	v_mfma_f32_16x16x32_bf16 v[104:107], v[172:175], v[188:191], v[104:107]
	v_mfma_f32_16x16x32_bf16 v[100:103], v[180:183], v[188:191], v[100:103]
	v_mfma_f32_16x16x32_bf16 v[92:95], v[172:175], v[196:199], v[92:95]
	v_mfma_f32_16x16x32_bf16 v[88:91], v[180:183], v[196:199], v[88:91]
	v_mfma_f32_16x16x32_bf16 v[80:83], v[172:175], v[204:207], v[80:83]
	v_mfma_f32_16x16x32_bf16 v[72:75], v[180:183], v[204:207], v[72:75]
	v_mfma_f32_16x16x32_bf16 v[68:71], v[172:175], v[212:215], v[68:71]
	v_mfma_f32_16x16x32_bf16 v[64:67], v[180:183], v[212:215], v[64:67]
	s_barrier
	s_add_i32 s24, s48, s37
	s_mov_b32 m0, s24
	ds_read_b128 v[184:187], v171 offset:16384
	ds_read_b128 v[188:191], v171 offset:17408
	ds_read_b128 v[192:195], v171 offset:18432
	ds_read_b128 v[196:199], v171 offset:19456
	ds_read_b128 v[200:203], v171 offset:20480
	ds_read_b128 v[204:207], v171 offset:21504
	ds_read_b128 v[208:211], v171 offset:22528
	ds_read_b128 v[212:215], v171 offset:23552
	global_load_lds_dwordx4 v130, s[28:29]
	s_add_i32 m0, s24, 0x2000
	s_add_u32 s24, s28, 0x160000
	s_addc_u32 s25, s29, 0
	s_add_i32 s57, s49, s37
	global_load_lds_dwordx4 v134, s[28:29]
	s_mov_b32 m0, s57
	s_nop 0
	global_load_lds_dwordx4 v130, s[24:25]
	s_add_i32 m0, s57, 0x2000
	s_nop 0
	global_load_lds_dwordx4 v134, s[24:25]
	s_mov_b32 m0, s38
	s_nop 0
	global_load_lds_dwordx4 v128, s[30:31]
	s_mov_b32 m0, s39
	s_nop 0
	global_load_lds_dwordx4 v132, s[30:31]
	s_waitcnt vmcnt(8) lgkmcnt(0)
	s_barrier
	v_mfma_f32_16x16x32_bf16 v[60:63], v[144:147], v[184:187], 0
	v_mfma_f32_16x16x32_bf16 v[56:59], v[152:155], v[184:187], 0
	v_mfma_f32_16x16x32_bf16 v[52:55], v[144:147], v[192:195], 0
	v_mfma_f32_16x16x32_bf16 v[48:51], v[152:155], v[192:195], 0
	v_mfma_f32_16x16x32_bf16 v[44:47], v[144:147], v[200:203], 0
	v_mfma_f32_16x16x32_bf16 v[32:35], v[152:155], v[200:203], 0
	v_mfma_f32_16x16x32_bf16 v[20:23], v[144:147], v[208:211], 0
	v_mfma_f32_16x16x32_bf16 v[12:15], v[152:155], v[208:211], 0
	v_mfma_f32_16x16x32_bf16 v[60:63], v[148:151], v[188:191], v[60:63]
	v_mfma_f32_16x16x32_bf16 v[56:59], v[156:159], v[188:191], v[56:59]
	v_mfma_f32_16x16x32_bf16 v[52:55], v[148:151], v[196:199], v[52:55]
	v_mfma_f32_16x16x32_bf16 v[48:51], v[156:159], v[196:199], v[48:51]
	v_mfma_f32_16x16x32_bf16 v[44:47], v[148:151], v[204:207], v[44:47]
	v_mfma_f32_16x16x32_bf16 v[32:35], v[156:159], v[204:207], v[32:35]
	v_mfma_f32_16x16x32_bf16 v[20:23], v[148:151], v[212:215], v[20:23]
	v_mfma_f32_16x16x32_bf16 v[12:15], v[156:159], v[212:215], v[12:15]
	v_mfma_f32_16x16x32_bf16 v[40:43], v[160:163], v[184:187], 0
	v_mfma_f32_16x16x32_bf16 v[36:39], v[176:179], v[184:187], 0
	v_mfma_f32_16x16x32_bf16 v[28:31], v[160:163], v[192:195], 0
	v_mfma_f32_16x16x32_bf16 v[24:27], v[176:179], v[192:195], 0
	v_mfma_f32_16x16x32_bf16 v[16:19], v[160:163], v[200:203], 0
	v_mfma_f32_16x16x32_bf16 v[8:11], v[176:179], v[200:203], 0
	v_mfma_f32_16x16x32_bf16 v[4:7], v[160:163], v[208:211], 0
	v_mfma_f32_16x16x32_bf16 v[0:3], v[176:179], v[208:211], 0
	v_mfma_f32_16x16x32_bf16 v[40:43], v[172:175], v[188:191], v[40:43]
	v_mfma_f32_16x16x32_bf16 v[36:39], v[180:183], v[188:191], v[36:39]
	v_mfma_f32_16x16x32_bf16 v[28:31], v[172:175], v[196:199], v[28:31]
	v_mfma_f32_16x16x32_bf16 v[24:27], v[180:183], v[196:199], v[24:27]
	v_mfma_f32_16x16x32_bf16 v[16:19], v[172:175], v[204:207], v[16:19]
	v_mfma_f32_16x16x32_bf16 v[8:11], v[180:183], v[204:207], v[8:11]
	v_mfma_f32_16x16x32_bf16 v[4:7], v[172:175], v[212:215], v[4:7]
	v_mfma_f32_16x16x32_bf16 v[0:3], v[180:183], v[212:215], v[0:3]
	s_barrier
; #define PG8_STAGE(bufoff, gbase, voff) do { _Pragma("unroll") for (int _i = 0; _i < 2; ++_i) \
;         __builtin_amdgcn_global_load_lds((const unsigned*)((const char*)(gbase) + (voff)[_i]), (PG8_LAS unsigned*)(lds + (bufoff) + ldsw + _i * 8192), 16, 0, 0); } while (0)
; #define PG8_LDA(dst, b, h) do { _Pragma("unroll") for (int m = 0; m < 4; ++m) _Pragma("unroll") for (int k = 0; k < 2; ++k) dst[m][k] = *(const PG8_LAS bf16x8*)(lds + PG8_SA(b, h) + aoff + m * 2048 + k * 1024); } while (0)
; #define PG8_LDB(dst, b, h) do { _Pragma("unroll") for (int n = 0; n < 2; ++n) _Pragma("unroll") for (int k = 0; k < 2; ++k) dst[n][k] = *(const PG8_LAS bf16x8*)(lds + PG8_SB(b, h) + boff + n * 2048 + k * 1024); } while (0)
; #define PG8_MMA(ai, bj, At, Bt) do { __builtin_amdgcn_s_setprio(1); _Pragma("unroll") for (int m = 0; m < 4; ++m) _Pragma("unroll") for (int n = 0; n < 2; ++n) _Pragma("unroll") for (int k = 0; k < 2; ++k) \
;         acc[ai][bj][m][n] = __builtin_amdgcn_mfma_f32_16x16x32_bf16(Bt[n][k], At[m][k], acc[ai][bj][m][n], 0, 0, 0); __builtin_amdgcn_s_setprio(0); } while (0)
; #define PG8_WAIT_V(n) asm volatile("s_waitcnt vmcnt(" #n ")" ::: "memory")
; #define PG8_WAIT_L(n) asm volatile("s_waitcnt lgkmcnt(" #n ")" ::: "memory")
; #define PG8_BAR __builtin_amdgcn_s_barrier()
; #define PG8_SCHED __builtin_amdgcn_sched_barrier(0)
; template <class Epi, class Sched, bool ALIGN_EPI = false, bool SP2 = false>
; __device__ __forceinline__ void gemm_phase(PG8_LAS unsigned char* lds, const Gemm g, const Sched& S, const Epi& E) {
;     ...
;             PG8_LDB(B0, 1, 0); PG8_LDB(B1, 1, 1); PG8_SCHED; PG8_LDA(At, 1, 0); PG8_STAGE(PG8_SA(0, 1), a2 + hstep, voffA);
;             PG8_WAIT_V(8); PG8_WAIT_L(0); PG8_BAR; PG8_MMA(0, 0, At, B0); PG8_MMA(0, 1, At, B1); PG8_BAR; PG8_SCHED;
;             PG8_LDA(At, 1, 1); PG8_STAGE(PG8_SB(1, 0), b3, voffB); PG8_STAGE(PG8_SB(1, 1), b3 + hstep, voffB); PG8_STAGE(PG8_SA(1, 0), a3, voffA);
;             PG8_WAIT_V(8); PG8_WAIT_L(0); PG8_BAR; PG8_MMA(1, 0, At, B0); PG8_MMA(1, 1, At, B1); PG8_BAR; PG8_SCHED;
	s_add_i32 s57, 0, 0x18000
	s_add_i32 s58, 0, 0x1c000
	v_add_u32_e32 v156, s57, v167
	v_add_u32_e32 v180, s58, v167
	ds_read_b128 v[144:147], v156
	ds_read_b128 v[148:151], v156 offset:1024
	ds_read_b128 v[152:155], v156 offset:2048
	ds_read_b128 v[156:159], v156 offset:3072
	ds_read_b128 v[160:163], v180
	ds_read_b128 v[172:175], v180 offset:1024
	ds_read_b128 v[176:179], v180 offset:2048
	ds_read_b128 v[180:183], v180 offset:3072
	s_add_u32 s24, s30, 0x160000
	s_addc_u32 s25, s31, 0
	s_mov_b32 m0, s40
	ds_read_b128 v[184:187], v171 offset:32768
	ds_read_b128 v[188:191], v171 offset:33792
	ds_read_b128 v[192:195], v171 offset:34816
	ds_read_b128 v[196:199], v171 offset:35840
	ds_read_b128 v[200:203], v171 offset:36864
	ds_read_b128 v[204:207], v171 offset:37888
	ds_read_b128 v[208:211], v171 offset:38912
	ds_read_b128 v[212:215], v171 offset:39936
	global_load_lds_dwordx4 v128, s[24:25]
	s_mov_b32 m0, s41
	s_nop 0
	global_load_lds_dwordx4 v132, s[24:25]
	s_waitcnt vmcnt(8) lgkmcnt(0)
	s_barrier
	v_mfma_f32_16x16x32_bf16 v[124:127], v[144:147], v[184:187], v[124:127]
	v_mfma_f32_16x16x32_bf16 v[120:123], v[152:155], v[184:187], v[120:123]
	v_mfma_f32_16x16x32_bf16 v[116:119], v[144:147], v[192:195], v[116:119]
	v_mfma_f32_16x16x32_bf16 v[112:115], v[152:155], v[192:195], v[112:115]
	v_mfma_f32_16x16x32_bf16 v[108:111], v[144:147], v[200:203], v[108:111]
	v_mfma_f32_16x16x32_bf16 v[96:99], v[152:155], v[200:203], v[96:99]
	v_mfma_f32_16x16x32_bf16 v[84:87], v[144:147], v[208:211], v[84:87]
	v_mfma_f32_16x16x32_bf16 v[76:79], v[152:155], v[208:211], v[76:79]
	v_mfma_f32_16x16x32_bf16 v[124:127], v[148:151], v[188:191], v[124:127]
	v_mfma_f32_16x16x32_bf16 v[120:123], v[156:159], v[188:191], v[120:123]
	v_mfma_f32_16x16x32_bf16 v[116:119], v[148:151], v[196:199], v[116:119]
	v_mfma_f32_16x16x32_bf16 v[112:115], v[156:159], v[196:199], v[112:115]
	v_mfma_f32_16x16x32_bf16 v[108:111], v[148:151], v[204:207], v[108:111]
	v_mfma_f32_16x16x32_bf16 v[96:99], v[156:159], v[204:207], v[96:99]
	v_mfma_f32_16x16x32_bf16 v[84:87], v[148:151], v[212:215], v[84:87]
	v_mfma_f32_16x16x32_bf16 v[76:79], v[156:159], v[212:215], v[76:79]
	v_mfma_f32_16x16x32_bf16 v[104:107], v[160:163], v[184:187], v[104:107]
	v_mfma_f32_16x16x32_bf16 v[100:103], v[176:179], v[184:187], v[100:103]
	v_mfma_f32_16x16x32_bf16 v[92:95], v[160:163], v[192:195], v[92:95]
	v_mfma_f32_16x16x32_bf16 v[88:91], v[176:179], v[192:195], v[88:91]
	v_mfma_f32_16x16x32_bf16 v[80:83], v[160:163], v[200:203], v[80:83]
	v_mfma_f32_16x16x32_bf16 v[72:75], v[176:179], v[200:203], v[72:75]
	v_mfma_f32_16x16x32_bf16 v[68:71], v[160:163], v[208:211], v[68:71]
	v_mfma_f32_16x16x32_bf16 v[64:67], v[176:179], v[208:211], v[64:67]
	v_mfma_f32_16x16x32_bf16 v[104:107], v[172:175], v[188:191], v[104:107]
	v_mfma_f32_16x16x32_bf16 v[100:103], v[180:183], v[188:191], v[100:103]
	v_mfma_f32_16x16x32_bf16 v[92:95], v[172:175], v[196:199], v[92:95]
	v_mfma_f32_16x16x32_bf16 v[88:91], v[180:183], v[196:199], v[88:91]
	v_mfma_f32_16x16x32_bf16 v[80:83], v[172:175], v[204:207], v[80:83]
	v_mfma_f32_16x16x32_bf16 v[72:75], v[180:183], v[204:207], v[72:75]
	v_mfma_f32_16x16x32_bf16 v[68:71], v[172:175], v[212:215], v[68:71]
	v_mfma_f32_16x16x32_bf16 v[64:67], v[180:183], v[212:215], v[64:67]
	s_barrier
	s_add_i32 s24, s57, s37
	s_add_u32 s86, s28, 0x80
	s_addc_u32 s87, s29, 0
	s_mov_b32 m0, s24
	ds_read_b128 v[184:187], v171 offset:49152
	ds_read_b128 v[188:191], v171 offset:50176
	ds_read_b128 v[192:195], v171 offset:51200
	ds_read_b128 v[196:199], v171 offset:52224
	ds_read_b128 v[200:203], v171 offset:53248
	ds_read_b128 v[204:207], v171 offset:54272
	ds_read_b128 v[208:211], v171 offset:55296
	ds_read_b128 v[212:215], v171 offset:56320
	global_load_lds_dwordx4 v130, s[86:87]
	s_add_i32 m0, s24, 0x2000
	s_add_u32 s24, s28, 0x160080
	s_addc_u32 s25, s29, 0
	s_add_i32 s28, s58, s37
	global_load_lds_dwordx4 v134, s[86:87]
	s_mov_b32 m0, s28
	s_nop 0
	global_load_lds_dwordx4 v130, s[24:25]
	s_add_i32 m0, s28, 0x2000
	s_nop 0
	global_load_lds_dwordx4 v134, s[24:25]
	s_add_u32 s84, s30, 0x80
	s_addc_u32 s85, s31, 0
	s_mov_b32 m0, s45
	s_nop 0
	global_load_lds_dwordx4 v128, s[84:85]
	s_mov_b32 m0, s46
	s_nop 0
	global_load_lds_dwordx4 v132, s[84:85]
	s_waitcnt vmcnt(8) lgkmcnt(0)
	s_barrier
	v_mfma_f32_16x16x32_bf16 v[60:63], v[144:147], v[184:187], v[60:63]
	v_mfma_f32_16x16x32_bf16 v[56:59], v[152:155], v[184:187], v[56:59]
	v_mfma_f32_16x16x32_bf16 v[52:55], v[144:147], v[192:195], v[52:55]
	v_mfma_f32_16x16x32_bf16 v[48:51], v[152:155], v[192:195], v[48:51]
	v_mfma_f32_16x16x32_bf16 v[44:47], v[144:147], v[200:203], v[44:47]
	v_mfma_f32_16x16x32_bf16 v[32:35], v[152:155], v[200:203], v[32:35]
	v_mfma_f32_16x16x32_bf16 v[20:23], v[144:147], v[208:211], v[20:23]
	v_mfma_f32_16x16x32_bf16 v[12:15], v[152:155], v[208:211], v[12:15]
	v_mfma_f32_16x16x32_bf16 v[60:63], v[148:151], v[188:191], v[60:63]
	v_mfma_f32_16x16x32_bf16 v[56:59], v[156:159], v[188:191], v[56:59]
	v_mfma_f32_16x16x32_bf16 v[52:55], v[148:151], v[196:199], v[52:55]
	v_mfma_f32_16x16x32_bf16 v[48:51], v[156:159], v[196:199], v[48:51]
	v_mfma_f32_16x16x32_bf16 v[44:47], v[148:151], v[204:207], v[44:47]
	v_mfma_f32_16x16x32_bf16 v[32:35], v[156:159], v[204:207], v[32:35]
	v_mfma_f32_16x16x32_bf16 v[20:23], v[148:151], v[212:215], v[20:23]
	v_mfma_f32_16x16x32_bf16 v[12:15], v[156:159], v[212:215], v[12:15]
	v_mfma_f32_16x16x32_bf16 v[40:43], v[160:163], v[184:187], v[40:43]
	v_mfma_f32_16x16x32_bf16 v[36:39], v[176:179], v[184:187], v[36:39]
	v_mfma_f32_16x16x32_bf16 v[28:31], v[160:163], v[192:195], v[28:31]
	v_mfma_f32_16x16x32_bf16 v[24:27], v[176:179], v[192:195], v[24:27]
	v_mfma_f32_16x16x32_bf16 v[16:19], v[160:163], v[200:203], v[16:19]
	v_mfma_f32_16x16x32_bf16 v[8:11], v[176:179], v[200:203], v[8:11]
	v_mfma_f32_16x16x32_bf16 v[4:7], v[160:163], v[208:211], v[4:7]
	v_mfma_f32_16x16x32_bf16 v[0:3], v[176:179], v[208:211], v[0:3]
	v_mfma_f32_16x16x32_bf16 v[40:43], v[172:175], v[188:191], v[40:43]
	v_mfma_f32_16x16x32_bf16 v[36:39], v[180:183], v[188:191], v[36:39]
	v_mfma_f32_16x16x32_bf16 v[28:31], v[172:175], v[196:199], v[28:31]
	v_mfma_f32_16x16x32_bf16 v[24:27], v[180:183], v[196:199], v[24:27]
	v_mfma_f32_16x16x32_bf16 v[16:19], v[172:175], v[204:207], v[16:19]
	v_mfma_f32_16x16x32_bf16 v[8:11], v[180:183], v[204:207], v[8:11]
	v_mfma_f32_16x16x32_bf16 v[4:7], v[172:175], v[212:215], v[4:7]
	v_mfma_f32_16x16x32_bf16 v[0:3], v[180:183], v[212:215], v[0:3]
	s_barrier
	s_add_i32 s56, s56, 2
	s_add_u32 s54, s54, 0x100
	s_addc_u32 s55, s55, 0
	s_cmpk_gt_u32 s56, 0x55
	s_mov_b64 s[24:25], s[26:27]
; #define PG8_STAGE(bufoff, gbase, voff) do { _Pragma("unroll") for (int _i = 0; _i < 2; ++_i) \
;         __builtin_amdgcn_global_load_lds((const unsigned*)((const char*)(gbase) + (voff)[_i]), (PG8_LAS unsigned*)(lds + (bufoff) + ldsw + _i * 8192), 16, 0, 0); } while (0)
; #define PG8_LDA(dst, b, h) do { _Pragma("unroll") for (int m = 0; m < 4; ++m) _Pragma("unroll") for (int k = 0; k < 2; ++k) dst[m][k] = *(const PG8_LAS bf16x8*)(lds + PG8_SA(b, h) + aoff + m * 2048 + k * 1024); } while (0)
; #define PG8_LDB(dst, b, h) do { _Pragma("unroll") for (int n = 0; n < 2; ++n) _Pragma("unroll") for (int k = 0; k < 2; ++k) dst[n][k] = *(const PG8_LAS bf16x8*)(lds + PG8_SB(b, h) + boff + n * 2048 + k * 1024); } while (0)
; #define PG8_MMA(ai, bj, At, Bt) do { __builtin_amdgcn_s_setprio(1); _Pragma("unroll") for (int m = 0; m < 4; ++m) _Pragma("unroll") for (int n = 0; n < 2; ++n) _Pragma("unroll") for (int k = 0; k < 2; ++k) \
;         acc[ai][bj][m][n] = __builtin_amdgcn_mfma_f32_16x16x32_bf16(Bt[n][k], At[m][k], acc[ai][bj][m][n], 0, 0, 0); __builtin_amdgcn_s_setprio(0); } while (0)
; #define PG8_WAIT_V(n) asm volatile("s_waitcnt vmcnt(" #n ")" ::: "memory")
; #define PG8_WAIT_L(n) asm volatile("s_waitcnt lgkmcnt(" #n ")" ::: "memory")
; #define PG8_BAR __builtin_amdgcn_s_barrier()
; #define PG8_SCHED __builtin_amdgcn_sched_barrier(0)
; template <class Epi, class Sched, bool ALIGN_EPI = false, bool SP2 = false>
; __device__ __forceinline__ void gemm_phase(PG8_LAS unsigned char* lds, const Gemm g, const Sched& S, const Epi& E) {
;     ...
;             PG8_LDB(B0, 0, 0); PG8_LDB(B1, 0, 1); PG8_SCHED; PG8_LDA(At, 0, 0); PG8_STAGE(PG8_SA(1, 1), a1 + hstep, voffA);
;             PG8_WAIT_V(8); PG8_WAIT_L(0); PG8_BAR; PG8_MMA(0, 0, At, B0); PG8_MMA(0, 1, At, B1); PG8_BAR; PG8_SCHED;
;             PG8_LDA(At, 0, 1); PG8_STAGE(PG8_SB(0, 0), b2, voffB); PG8_STAGE(PG8_SB(0, 1), b2 + hstep, voffB); PG8_STAGE(PG8_SA(0, 0), a2, voffA);
;             PG8_WAIT_V(8); PG8_WAIT_L(0); PG8_BAR; PG8_MMA(1, 0, At, B0); PG8_MMA(1, 1, At, B1); PG8_BAR; PG8_SCHED;
.LBB0_1021:
	ds_read_b128 v[144:147], v169
	ds_read_b128 v[148:151], v169 offset:1024
	ds_read_b128 v[152:155], v169 offset:2048
	ds_read_b128 v[156:159], v169 offset:3072
	ds_read_b128 v[160:163], v170
	ds_read_b128 v[172:175], v170 offset:1024
	ds_read_b128 v[176:179], v170 offset:2048
	ds_read_b128 v[180:183], v170 offset:3072
	s_add_u32 s26, s24, 0x100
	s_addc_u32 s27, s25, 0
	s_cmpk_eq_i32 s56, 0x54
	s_cselect_b32 s31, s5, s27
	s_cselect_b32 s30, s4, s26
	s_cselect_b32 s29, s7, s55
	s_cselect_b32 s28, s6, s54
	s_add_i32 m0, s38, 0xc000
	ds_read_b128 v[184:187], v171
	ds_read_b128 v[188:191], v171 offset:1024
	ds_read_b128 v[192:195], v171 offset:2048
	ds_read_b128 v[196:199], v171 offset:3072
	ds_read_b128 v[200:203], v171 offset:4096
	ds_read_b128 v[204:207], v171 offset:5120
	ds_read_b128 v[208:211], v171 offset:6144
	ds_read_b128 v[212:215], v171 offset:7168
	global_load_lds_dwordx4 v136, s[24:25]
	s_add_i32 m0, s38, 0xe000
	s_nop 0
	global_load_lds_dwordx4 v138, s[24:25]
	s_waitcnt vmcnt(8) lgkmcnt(0)
	s_barrier
	v_mfma_f32_16x16x32_bf16 v[124:127], v[144:147], v[184:187], v[124:127]
	v_mfma_f32_16x16x32_bf16 v[120:123], v[152:155], v[184:187], v[120:123]
	v_mfma_f32_16x16x32_bf16 v[116:119], v[144:147], v[192:195], v[116:119]
	v_mfma_f32_16x16x32_bf16 v[112:115], v[152:155], v[192:195], v[112:115]
	v_mfma_f32_16x16x32_bf16 v[108:111], v[144:147], v[200:203], v[108:111]
	v_mfma_f32_16x16x32_bf16 v[96:99], v[152:155], v[200:203], v[96:99]
	v_mfma_f32_16x16x32_bf16 v[84:87], v[144:147], v[208:211], v[84:87]
	v_mfma_f32_16x16x32_bf16 v[76:79], v[152:155], v[208:211], v[76:79]
	v_mfma_f32_16x16x32_bf16 v[124:127], v[148:151], v[188:191], v[124:127]
	v_mfma_f32_16x16x32_bf16 v[120:123], v[156:159], v[188:191], v[120:123]
	v_mfma_f32_16x16x32_bf16 v[116:119], v[148:151], v[196:199], v[116:119]
	v_mfma_f32_16x16x32_bf16 v[112:115], v[156:159], v[196:199], v[112:115]
	v_mfma_f32_16x16x32_bf16 v[108:111], v[148:151], v[204:207], v[108:111]
	v_mfma_f32_16x16x32_bf16 v[96:99], v[156:159], v[204:207], v[96:99]
	v_mfma_f32_16x16x32_bf16 v[84:87], v[148:151], v[212:215], v[84:87]
	v_mfma_f32_16x16x32_bf16 v[76:79], v[156:159], v[212:215], v[76:79]
	v_mfma_f32_16x16x32_bf16 v[104:107], v[160:163], v[184:187], v[104:107]
	v_mfma_f32_16x16x32_bf16 v[100:103], v[176:179], v[184:187], v[100:103]
	v_mfma_f32_16x16x32_bf16 v[92:95], v[160:163], v[192:195], v[92:95]
	v_mfma_f32_16x16x32_bf16 v[88:91], v[176:179], v[192:195], v[88:91]
	v_mfma_f32_16x16x32_bf16 v[80:83], v[160:163], v[200:203], v[80:83]
	v_mfma_f32_16x16x32_bf16 v[72:75], v[176:179], v[200:203], v[72:75]
	v_mfma_f32_16x16x32_bf16 v[68:71], v[160:163], v[208:211], v[68:71]
	v_mfma_f32_16x16x32_bf16 v[64:67], v[176:179], v[208:211], v[64:67]
	v_mfma_f32_16x16x32_bf16 v[104:107], v[172:175], v[188:191], v[104:107]
	v_mfma_f32_16x16x32_bf16 v[100:103], v[180:183], v[188:191], v[100:103]
	v_mfma_f32_16x16x32_bf16 v[92:95], v[172:175], v[196:199], v[92:95]
	v_mfma_f32_16x16x32_bf16 v[88:91], v[180:183], v[196:199], v[88:91]
	v_mfma_f32_16x16x32_bf16 v[80:83], v[172:175], v[204:207], v[80:83]
	v_mfma_f32_16x16x32_bf16 v[72:75], v[180:183], v[204:207], v[72:75]
	v_mfma_f32_16x16x32_bf16 v[68:71], v[172:175], v[212:215], v[68:71]
	v_mfma_f32_16x16x32_bf16 v[64:67], v[180:183], v[212:215], v[64:67]
	s_barrier
	s_add_i32 s24, s48, s37
	s_mov_b32 m0, s24
	ds_read_b128 v[184:187], v171 offset:16384
	ds_read_b128 v[188:191], v171 offset:17408
	ds_read_b128 v[192:195], v171 offset:18432
	ds_read_b128 v[196:199], v171 offset:19456
	ds_read_b128 v[200:203], v171 offset:20480
	ds_read_b128 v[204:207], v171 offset:21504
	ds_read_b128 v[208:211], v171 offset:22528
	ds_read_b128 v[212:215], v171 offset:23552
	global_load_lds_dwordx4 v130, s[28:29]
	s_add_i32 m0, s24, 0x2000
	s_add_u32 s24, s28, 0x160000
	s_addc_u32 s25, s29, 0
	s_add_i32 s57, s49, s37
	global_load_lds_dwordx4 v134, s[28:29]
	s_mov_b32 m0, s57
	s_nop 0
	global_load_lds_dwordx4 v130, s[24:25]
	s_add_i32 m0, s57, 0x2000
	s_nop 0
	global_load_lds_dwordx4 v134, s[24:25]
	s_mov_b32 m0, s38
	s_nop 0
	global_load_lds_dwordx4 v128, s[30:31]
	s_mov_b32 m0, s39
	s_nop 0
	global_load_lds_dwordx4 v132, s[30:31]
	s_waitcnt vmcnt(8) lgkmcnt(0)
	s_barrier
	v_mfma_f32_16x16x32_bf16 v[60:63], v[144:147], v[184:187], v[60:63]
	v_mfma_f32_16x16x32_bf16 v[56:59], v[152:155], v[184:187], v[56:59]
	v_mfma_f32_16x16x32_bf16 v[52:55], v[144:147], v[192:195], v[52:55]
	v_mfma_f32_16x16x32_bf16 v[48:51], v[152:155], v[192:195], v[48:51]
	v_mfma_f32_16x16x32_bf16 v[44:47], v[144:147], v[200:203], v[44:47]
	v_mfma_f32_16x16x32_bf16 v[32:35], v[152:155], v[200:203], v[32:35]
	v_mfma_f32_16x16x32_bf16 v[20:23], v[144:147], v[208:211], v[20:23]
	v_mfma_f32_16x16x32_bf16 v[12:15], v[152:155], v[208:211], v[12:15]
	v_mfma_f32_16x16x32_bf16 v[60:63], v[148:151], v[188:191], v[60:63]
	v_mfma_f32_16x16x32_bf16 v[56:59], v[156:159], v[188:191], v[56:59]
	v_mfma_f32_16x16x32_bf16 v[52:55], v[148:151], v[196:199], v[52:55]
	v_mfma_f32_16x16x32_bf16 v[48:51], v[156:159], v[196:199], v[48:51]
	v_mfma_f32_16x16x32_bf16 v[44:47], v[148:151], v[204:207], v[44:47]
	v_mfma_f32_16x16x32_bf16 v[32:35], v[156:159], v[204:207], v[32:35]
	v_mfma_f32_16x16x32_bf16 v[20:23], v[148:151], v[212:215], v[20:23]
	v_mfma_f32_16x16x32_bf16 v[12:15], v[156:159], v[212:215], v[12:15]
	v_mfma_f32_16x16x32_bf16 v[40:43], v[160:163], v[184:187], v[40:43]
	v_mfma_f32_16x16x32_bf16 v[36:39], v[176:179], v[184:187], v[36:39]
	v_mfma_f32_16x16x32_bf16 v[28:31], v[160:163], v[192:195], v[28:31]
	v_mfma_f32_16x16x32_bf16 v[24:27], v[176:179], v[192:195], v[24:27]
	v_mfma_f32_16x16x32_bf16 v[16:19], v[160:163], v[200:203], v[16:19]
	v_mfma_f32_16x16x32_bf16 v[8:11], v[176:179], v[200:203], v[8:11]
	v_mfma_f32_16x16x32_bf16 v[4:7], v[160:163], v[208:211], v[4:7]
	v_mfma_f32_16x16x32_bf16 v[0:3], v[176:179], v[208:211], v[0:3]
	v_mfma_f32_16x16x32_bf16 v[40:43], v[172:175], v[188:191], v[40:43]
	v_mfma_f32_16x16x32_bf16 v[36:39], v[180:183], v[188:191], v[36:39]
	v_mfma_f32_16x16x32_bf16 v[28:31], v[172:175], v[196:199], v[28:31]
	v_mfma_f32_16x16x32_bf16 v[24:27], v[180:183], v[196:199], v[24:27]
	v_mfma_f32_16x16x32_bf16 v[16:19], v[172:175], v[204:207], v[16:19]
	v_mfma_f32_16x16x32_bf16 v[8:11], v[180:183], v[204:207], v[8:11]
	v_mfma_f32_16x16x32_bf16 v[4:7], v[172:175], v[212:215], v[4:7]
	v_mfma_f32_16x16x32_bf16 v[0:3], v[180:183], v[212:215], v[0:3]
	s_barrier
; #define PG8_STAGE(bufoff, gbase, voff) do { _Pragma("unroll") for (int _i = 0; _i < 2; ++_i) \
;         __builtin_amdgcn_global_load_lds((const unsigned*)((const char*)(gbase) + (voff)[_i]), (PG8_LAS unsigned*)(lds + (bufoff) + ldsw + _i * 8192), 16, 0, 0); } while (0)
; #define PG8_LDA(dst, b, h) do { _Pragma("unroll") for (int m = 0; m < 4; ++m) _Pragma("unroll") for (int k = 0; k < 2; ++k) dst[m][k] = *(const PG8_LAS bf16x8*)(lds + PG8_SA(b, h) + aoff + m * 2048 + k * 1024); } while (0)
; #define PG8_LDB(dst, b, h) do { _Pragma("unroll") for (int n = 0; n < 2; ++n) _Pragma("unroll") for (int k = 0; k < 2; ++k) dst[n][k] = *(const PG8_LAS bf16x8*)(lds + PG8_SB(b, h) + boff + n * 2048 + k * 1024); } while (0)
; #define PG8_MMA(ai, bj, At, Bt) do { __builtin_amdgcn_s_setprio(1); _Pragma("unroll") for (int m = 0; m < 4; ++m) _Pragma("unroll") for (int n = 0; n < 2; ++n) _Pragma("unroll") for (int k = 0; k < 2; ++k) \
;         acc[ai][bj][m][n] = __builtin_amdgcn_mfma_f32_16x16x32_bf16(Bt[n][k], At[m][k], acc[ai][bj][m][n], 0, 0, 0); __builtin_amdgcn_s_setprio(0); } while (0)
; #define PG8_WAIT_V(n) asm volatile("s_waitcnt vmcnt(" #n ")" ::: "memory")
; #define PG8_WAIT_L(n) asm volatile("s_waitcnt lgkmcnt(" #n ")" ::: "memory")
; #define PG8_BAR __builtin_amdgcn_s_barrier()
; #define PG8_SCHED __builtin_amdgcn_sched_barrier(0)
; template <class Epi, class Sched, bool ALIGN_EPI = false, bool SP2 = false>
; __device__ __forceinline__ void gemm_phase(PG8_LAS unsigned char* lds, const Gemm g, const Sched& S, const Epi& E) {
;     ...
;             PG8_LDB(B0, 1, 0); PG8_LDB(B1, 1, 1); PG8_SCHED; PG8_LDA(At, 1, 0); PG8_STAGE(PG8_SA(0, 1), a2 + hstep, voffA);
;             PG8_WAIT_V(8); PG8_WAIT_L(0); PG8_BAR; PG8_MMA(0, 0, At, B0); PG8_MMA(0, 1, At, B1); PG8_BAR; PG8_SCHED;
;             PG8_LDA(At, 1, 1); PG8_STAGE(PG8_SB(1, 0), b3, voffB); PG8_STAGE(PG8_SB(1, 1), b3 + hstep, voffB); PG8_STAGE(PG8_SA(1, 0), a3, voffA);
;             PG8_WAIT_V(8); PG8_WAIT_L(0); PG8_BAR; PG8_MMA(1, 0, At, B0); PG8_MMA(1, 1, At, B1); PG8_BAR; PG8_SCHED;
	s_add_i32 s57, 0, 0x18000
	s_add_i32 s58, 0, 0x1c000
	v_add_u32_e32 v156, s57, v167
	v_add_u32_e32 v180, s58, v167
	ds_read_b128 v[144:147], v156
	ds_read_b128 v[148:151], v156 offset:1024
	ds_read_b128 v[152:155], v156 offset:2048
	ds_read_b128 v[156:159], v156 offset:3072
	ds_read_b128 v[160:163], v180
	ds_read_b128 v[172:175], v180 offset:1024
	ds_read_b128 v[176:179], v180 offset:2048
	ds_read_b128 v[180:183], v180 offset:3072
	s_add_u32 s24, s30, 0x160000
	s_addc_u32 s25, s31, 0
	s_mov_b32 m0, s40
	ds_read_b128 v[184:187], v171 offset:32768
	ds_read_b128 v[188:191], v171 offset:33792
	ds_read_b128 v[192:195], v171 offset:34816
	ds_read_b128 v[196:199], v171 offset:35840
	ds_read_b128 v[200:203], v171 offset:36864
	ds_read_b128 v[204:207], v171 offset:37888
	ds_read_b128 v[208:211], v171 offset:38912
	ds_read_b128 v[212:215], v171 offset:39936
	global_load_lds_dwordx4 v128, s[24:25]
	s_mov_b32 m0, s41
	s_nop 0
	global_load_lds_dwordx4 v132, s[24:25]
	s_waitcnt vmcnt(8) lgkmcnt(0)
	s_barrier
	v_mfma_f32_16x16x32_bf16 v[124:127], v[144:147], v[184:187], v[124:127]
	v_mfma_f32_16x16x32_bf16 v[120:123], v[152:155], v[184:187], v[120:123]
	v_mfma_f32_16x16x32_bf16 v[116:119], v[144:147], v[192:195], v[116:119]
	v_mfma_f32_16x16x32_bf16 v[112:115], v[152:155], v[192:195], v[112:115]
	v_mfma_f32_16x16x32_bf16 v[108:111], v[144:147], v[200:203], v[108:111]
	v_mfma_f32_16x16x32_bf16 v[96:99], v[152:155], v[200:203], v[96:99]
	v_mfma_f32_16x16x32_bf16 v[84:87], v[144:147], v[208:211], v[84:87]
	v_mfma_f32_16x16x32_bf16 v[76:79], v[152:155], v[208:211], v[76:79]
	v_mfma_f32_16x16x32_bf16 v[124:127], v[148:151], v[188:191], v[124:127]
	v_mfma_f32_16x16x32_bf16 v[120:123], v[156:159], v[188:191], v[120:123]
	v_mfma_f32_16x16x32_bf16 v[116:119], v[148:151], v[196:199], v[116:119]
	v_mfma_f32_16x16x32_bf16 v[112:115], v[156:159], v[196:199], v[112:115]
	v_mfma_f32_16x16x32_bf16 v[108:111], v[148:151], v[204:207], v[108:111]
	v_mfma_f32_16x16x32_bf16 v[96:99], v[156:159], v[204:207], v[96:99]
	v_mfma_f32_16x16x32_bf16 v[84:87], v[148:151], v[212:215], v[84:87]
	v_mfma_f32_16x16x32_bf16 v[76:79], v[156:159], v[212:215], v[76:79]
	v_mfma_f32_16x16x32_bf16 v[104:107], v[160:163], v[184:187], v[104:107]
	v_mfma_f32_16x16x32_bf16 v[100:103], v[176:179], v[184:187], v[100:103]
	v_mfma_f32_16x16x32_bf16 v[92:95], v[160:163], v[192:195], v[92:95]
	v_mfma_f32_16x16x32_bf16 v[88:91], v[176:179], v[192:195], v[88:91]
	v_mfma_f32_16x16x32_bf16 v[80:83], v[160:163], v[200:203], v[80:83]
	v_mfma_f32_16x16x32_bf16 v[72:75], v[176:179], v[200:203], v[72:75]
	v_mfma_f32_16x16x32_bf16 v[68:71], v[160:163], v[208:211], v[68:71]
	v_mfma_f32_16x16x32_bf16 v[64:67], v[176:179], v[208:211], v[64:67]
	v_mfma_f32_16x16x32_bf16 v[104:107], v[172:175], v[188:191], v[104:107]
	v_mfma_f32_16x16x32_bf16 v[100:103], v[180:183], v[188:191], v[100:103]
	v_mfma_f32_16x16x32_bf16 v[92:95], v[172:175], v[196:199], v[92:95]
	v_mfma_f32_16x16x32_bf16 v[88:91], v[180:183], v[196:199], v[88:91]
	v_mfma_f32_16x16x32_bf16 v[80:83], v[172:175], v[204:207], v[80:83]
	v_mfma_f32_16x16x32_bf16 v[72:75], v[180:183], v[204:207], v[72:75]
	v_mfma_f32_16x16x32_bf16 v[68:71], v[172:175], v[212:215], v[68:71]
	v_mfma_f32_16x16x32_bf16 v[64:67], v[180:183], v[212:215], v[64:67]
	s_barrier
	s_add_i32 s24, s57, s37
	s_add_u32 s86, s28, 0x80
	s_addc_u32 s87, s29, 0
	s_mov_b32 m0, s24
	ds_read_b128 v[184:187], v171 offset:49152
	ds_read_b128 v[188:191], v171 offset:50176
	ds_read_b128 v[192:195], v171 offset:51200
	ds_read_b128 v[196:199], v171 offset:52224
	ds_read_b128 v[200:203], v171 offset:53248
	ds_read_b128 v[204:207], v171 offset:54272
	ds_read_b128 v[208:211], v171 offset:55296
	ds_read_b128 v[212:215], v171 offset:56320
	global_load_lds_dwordx4 v130, s[86:87]
	s_add_i32 m0, s24, 0x2000
	s_add_u32 s24, s28, 0x160080
	s_addc_u32 s25, s29, 0
	s_add_i32 s28, s58, s37
	global_load_lds_dwordx4 v134, s[86:87]
	s_mov_b32 m0, s28
	s_nop 0
	global_load_lds_dwordx4 v130, s[24:25]
	s_add_i32 m0, s28, 0x2000
	s_nop 0
	global_load_lds_dwordx4 v134, s[24:25]
	s_add_u32 s84, s30, 0x80
	s_addc_u32 s85, s31, 0
	s_mov_b32 m0, s45
	s_nop 0
	global_load_lds_dwordx4 v128, s[84:85]
	s_mov_b32 m0, s46
	s_nop 0
	global_load_lds_dwordx4 v132, s[84:85]
	s_waitcnt vmcnt(8) lgkmcnt(0)
	s_barrier
	v_mfma_f32_16x16x32_bf16 v[60:63], v[144:147], v[184:187], v[60:63]
	v_mfma_f32_16x16x32_bf16 v[56:59], v[152:155], v[184:187], v[56:59]
	v_mfma_f32_16x16x32_bf16 v[52:55], v[144:147], v[192:195], v[52:55]
	v_mfma_f32_16x16x32_bf16 v[48:51], v[152:155], v[192:195], v[48:51]
	v_mfma_f32_16x16x32_bf16 v[44:47], v[144:147], v[200:203], v[44:47]
	v_mfma_f32_16x16x32_bf16 v[32:35], v[152:155], v[200:203], v[32:35]
	v_mfma_f32_16x16x32_bf16 v[20:23], v[144:147], v[208:211], v[20:23]
	v_mfma_f32_16x16x32_bf16 v[12:15], v[152:155], v[208:211], v[12:15]
	v_mfma_f32_16x16x32_bf16 v[60:63], v[148:151], v[188:191], v[60:63]
	v_mfma_f32_16x16x32_bf16 v[56:59], v[156:159], v[188:191], v[56:59]
	v_mfma_f32_16x16x32_bf16 v[52:55], v[148:151], v[196:199], v[52:55]
	v_mfma_f32_16x16x32_bf16 v[48:51], v[156:159], v[196:199], v[48:51]
	v_mfma_f32_16x16x32_bf16 v[44:47], v[148:151], v[204:207], v[44:47]
	v_mfma_f32_16x16x32_bf16 v[32:35], v[156:159], v[204:207], v[32:35]
	v_mfma_f32_16x16x32_bf16 v[20:23], v[148:151], v[212:215], v[20:23]
	v_mfma_f32_16x16x32_bf16 v[12:15], v[156:159], v[212:215], v[12:15]
	v_mfma_f32_16x16x32_bf16 v[40:43], v[160:163], v[184:187], v[40:43]
	v_mfma_f32_16x16x32_bf16 v[36:39], v[176:179], v[184:187], v[36:39]
	v_mfma_f32_16x16x32_bf16 v[28:31], v[160:163], v[192:195], v[28:31]
	v_mfma_f32_16x16x32_bf16 v[24:27], v[176:179], v[192:195], v[24:27]
	v_mfma_f32_16x16x32_bf16 v[16:19], v[160:163], v[200:203], v[16:19]
	v_mfma_f32_16x16x32_bf16 v[8:11], v[176:179], v[200:203], v[8:11]
	v_mfma_f32_16x16x32_bf16 v[4:7], v[160:163], v[208:211], v[4:7]
	v_mfma_f32_16x16x32_bf16 v[0:3], v[176:179], v[208:211], v[0:3]
	v_mfma_f32_16x16x32_bf16 v[40:43], v[172:175], v[188:191], v[40:43]
	v_mfma_f32_16x16x32_bf16 v[36:39], v[180:183], v[188:191], v[36:39]
	v_mfma_f32_16x16x32_bf16 v[28:31], v[172:175], v[196:199], v[28:31]
	v_mfma_f32_16x16x32_bf16 v[24:27], v[180:183], v[196:199], v[24:27]
	v_mfma_f32_16x16x32_bf16 v[16:19], v[172:175], v[204:207], v[16:19]
	v_mfma_f32_16x16x32_bf16 v[8:11], v[180:183], v[204:207], v[8:11]
	v_mfma_f32_16x16x32_bf16 v[4:7], v[172:175], v[212:215], v[4:7]
	v_mfma_f32_16x16x32_bf16 v[0:3], v[180:183], v[212:215], v[0:3]
	s_barrier
;     __device__ __forceinline__ void operator()(const f32x4 (&acc)[2][2][4][2], const Unit& u, int wr, int wc, int fr, int fq) const {
;         const int row0 = u.pm * BM + wr * 64 + fr, col0 = u.pn * BM + wc * 32 + 8 * fq;
;         const float* gp = gate + (u.pm >> 5) * 18432 + col0;
;         f32x4 gv[2][2];
; #pragma unroll
;         for (int bj = 0; bj < 2; ++bj)
; #pragma unroll
;             for (int n = 0; n < 2; ++n) gv[bj][n] = *(const f32x4*)(gp + bj * HALF + 4 * n) * scale;
; #pragma unroll
;         for (int ai = 0; ai < 2; ++ai) { f32x4 r[4][2][2];
; #pragma unroll
;             for (int m = 0; m < 4; ++m) { const size_t off = (size_t)(row0 + ai * HALF + m * 16) * 2048 + col0;
; #pragma unroll
;                 for (int bj = 0; bj < 2; ++bj)
; #pragma unroll
;                     for (int n = 0; n < 2; ++n) r[m][bj][n] = *(const f32x4*)(res + off + bj * HALF + 4 * n); }
; #pragma unroll
;             for (int m = 0; m < 4; ++m) { const size_t off = (size_t)(row0 + ai * HALF + m * 16) * 2048 + col0;
; #pragma unroll
;                 for (int bj = 0; bj < 2; ++bj)
; #pragma unroll
;                     for (int n = 0; n < 2; ++n) *(f32x4*)(out + off + bj * HALF + 4 * n) = r[m][bj][n] + gv[bj][n] * acc[ai][bj][m][n]; } }
	s_add_i32 s56, s56, 2
	s_add_u32 s54, s54, 0x100
	s_addc_u32 s55, s55, 0
	s_cmpk_gt_u32 s56, 0x55
	s_mov_b64 s[24:25], s[26:27]
	s_cbranch_scc0 .LBB0_1021
	s_lshr_b32 s24, s52, 5
	s_mulk_i32 s24, 0x4800
	s_ashr_i32 s25, s24, 31
	v_lshl_or_b32 v144, s53, 8, v168
	s_lshl_b64 s[24:25], s[24:25], 2
	s_add_u32 s24, s43, s24
	v_ashrrev_i32_e32 v145, 31, v144
	s_addc_u32 s25, s44, s25
	v_lshlrev_b64 v[144:145], 2, v[144:145]
	v_lshl_add_u64 v[154:155], s[24:25], 0, v[144:145]
	global_load_dwordx4 v[146:149], v[154:155], off offset:16
	global_load_dwordx4 v[150:153], v[154:155], off
	global_load_dwordx4 v[172:175], v[154:155], off offset:528
	global_load_dwordx4 v[176:179], v[154:155], off offset:512
	v_lshl_add_u32 v154, s52, 8, v166
	v_ashrrev_i32_e32 v155, 31, v154
	v_lshl_add_u64 v[162:163], s[8:9], 0, v[144:145]
	v_lshlrev_b64 v[164:165], 13, v[154:155]
	v_lshl_add_u64 v[156:157], v[162:163], 0, v[164:165]
	global_load_dwordx4 v[180:183], v[156:157], off
	global_load_dwordx4 v[184:187], v[156:157], off offset:16
	global_load_dwordx4 v[188:191], v[156:157], off offset:528
	global_load_dwordx4 v[192:195], v[156:157], off offset:512
	v_or_b32_e32 v156, 16, v154
	v_ashrrev_i32_e32 v157, 31, v156
	v_lshlrev_b64 v[156:157], 13, v[156:157]
	v_lshl_add_u64 v[158:159], v[162:163], 0, v[156:157]
	global_load_dwordx4 v[196:199], v[158:159], off
	global_load_dwordx4 v[200:203], v[158:159], off offset:16
	global_load_dwordx4 v[204:207], v[158:159], off offset:528
	global_load_dwordx4 v[208:211], v[158:159], off offset:512
	v_or_b32_e32 v158, 32, v154
	v_ashrrev_i32_e32 v159, 31, v158
	v_lshlrev_b64 v[158:159], 13, v[158:159]
	v_or_b32_e32 v154, 48, v154
	v_lshl_add_u64 v[160:161], v[162:163], 0, v[158:159]
	v_ashrrev_i32_e32 v155, 31, v154
	global_load_dwordx4 v[212:215], v[160:161], off
	global_load_dwordx4 v[216:219], v[160:161], off offset:16
	global_load_dwordx4 v[220:223], v[160:161], off offset:512
	global_load_dwordx4 v[224:227], v[160:161], off offset:528
	v_lshlrev_b64 v[244:245], 13, v[154:155]
	v_lshl_add_u64 v[154:155], v[162:163], 0, v[244:245]
	global_load_dwordx4 v[228:231], v[154:155], off
	global_load_dwordx4 v[232:235], v[154:155], off offset:16
	global_load_dwordx4 v[236:239], v[154:155], off offset:512
	global_load_dwordx4 v[240:243], v[154:155], off offset:528
	v_lshl_add_u64 v[154:155], s[10:11], 0, v[164:165]
	v_lshl_add_u64 v[246:247], v[154:155], 0, v[144:145]
	v_lshl_add_u64 v[154:155], s[10:11], 0, v[156:157]
	v_lshl_add_u64 v[156:157], s[10:11], 0, v[158:159]
	v_lshl_add_u64 v[248:249], v[154:155], 0, v[144:145]
	v_lshl_add_u64 v[250:251], v[156:157], 0, v[144:145]
	s_and_b64 vcc, exec, s[0:1]
	s_mov_b32 s53, s50
	s_mov_b32 s52, s51
	s_mov_b64 s[26:27], s[6:7]
	s_mov_b64 s[24:25], s[4:5]
	s_waitcnt vmcnt(0)
	v_pk_mul_f32 v[154:155], v[148:149], 0.5 op_sel_hi:[1,0]
	v_pk_mul_f32 v[158:159], v[152:153], 0.5 op_sel_hi:[1,0]
	v_pk_mul_f32 v[160:161], v[150:151], 0.5 op_sel_hi:[1,0]
	v_pk_mul_f32 v[150:151], v[178:179], 0.5 op_sel_hi:[1,0]
	v_pk_mul_f32 v[152:153], v[176:177], 0.5 op_sel_hi:[1,0]
	v_pk_mul_f32 v[156:157], v[146:147], 0.5 op_sel_hi:[1,0]
	v_pk_mul_f32 v[146:147], v[174:175], 0.5 op_sel_hi:[1,0]
	v_pk_mul_f32 v[148:149], v[172:173], 0.5 op_sel_hi:[1,0]
	v_pk_fma_f32 v[126:127], v[126:127], v[158:159], v[182:183]
	v_pk_fma_f32 v[124:125], v[124:125], v[160:161], v[180:181]
	v_pk_fma_f32 v[122:123], v[122:123], v[154:155], v[186:187]
	v_pk_fma_f32 v[120:121], v[120:121], v[156:157], v[184:185]
	v_pk_fma_f32 v[106:107], v[106:107], v[150:151], v[194:195]
	v_pk_fma_f32 v[104:105], v[104:105], v[152:153], v[192:193]
	v_pk_fma_f32 v[102:103], v[102:103], v[146:147], v[190:191]
	v_pk_fma_f32 v[100:101], v[100:101], v[148:149], v[188:189]
	v_pk_fma_f32 v[118:119], v[118:119], v[158:159], v[198:199]
	v_pk_fma_f32 v[116:117], v[116:117], v[160:161], v[196:197]
	v_pk_fma_f32 v[114:115], v[114:115], v[154:155], v[202:203]
	v_pk_fma_f32 v[112:113], v[112:113], v[156:157], v[200:201]
	v_pk_fma_f32 v[82:83], v[82:83], v[150:151], v[222:223]
	v_pk_fma_f32 v[80:81], v[80:81], v[152:153], v[220:221]
	v_pk_fma_f32 v[94:95], v[94:95], v[150:151], v[210:211]
	v_pk_fma_f32 v[92:93], v[92:93], v[152:153], v[208:209]
	v_pk_fma_f32 v[90:91], v[90:91], v[146:147], v[206:207]
	v_pk_fma_f32 v[88:89], v[88:89], v[148:149], v[204:205]
	v_pk_fma_f32 v[110:111], v[110:111], v[158:159], v[214:215]
	v_pk_fma_f32 v[108:109], v[108:109], v[160:161], v[212:213]
	v_pk_fma_f32 v[98:99], v[98:99], v[154:155], v[218:219]
	v_pk_fma_f32 v[96:97], v[96:97], v[156:157], v[216:217]
	global_store_dwordx4 v[246:247], v[124:127], off
	global_store_dwordx4 v[246:247], v[120:123], off offset:16
	global_store_dwordx4 v[246:247], v[104:107], off offset:512
	global_store_dwordx4 v[246:247], v[100:103], off offset:528
	global_store_dwordx4 v[248:249], v[116:119], off
	global_store_dwordx4 v[248:249], v[112:115], off offset:16
	global_store_dwordx4 v[248:249], v[92:95], off offset:512
	global_store_dwordx4 v[248:249], v[88:91], off offset:528
	global_store_dwordx4 v[250:251], v[108:111], off
	global_store_dwordx4 v[250:251], v[96:99], off offset:16
	global_store_dwordx4 v[250:251], v[80:83], off offset:512
	v_pk_fma_f32 v[74:75], v[74:75], v[146:147], v[226:227]
	v_pk_fma_f32 v[72:73], v[72:73], v[148:149], v[224:225]
	v_lshl_add_u64 v[80:81], s[10:11], 0, v[244:245]
	global_store_dwordx4 v[250:251], v[72:75], off offset:528
; #define PG8_WAIT_V(n) asm volatile("s_waitcnt vmcnt(" #n ")" ::: "memory")
; #define PG8_BAR __builtin_amdgcn_s_barrier()
;     __device__ __forceinline__ void operator()(const f32x4 (&acc)[2][2][4][2], const Unit& u, int wr, int wc, int fr, int fq) const {
;     ...
;         for (int ai = 0; ai < 2; ++ai) { f32x4 r[4][2][2];
; #pragma unroll
;             for (int m = 0; m < 4; ++m) { const size_t off = (size_t)(row0 + ai * HALF + m * 16) * 2048 + col0;
; #pragma unroll
;                 for (int bj = 0; bj < 2; ++bj)
; #pragma unroll
;                     for (int n = 0; n < 2; ++n) r[m][bj][n] = *(const f32x4*)(res + off + bj * HALF + 4 * n); }
; #pragma unroll
;             for (int m = 0; m < 4; ++m) { const size_t off = (size_t)(row0 + ai * HALF + m * 16) * 2048 + col0;
; #pragma unroll
;                 for (int bj = 0; bj < 2; ++bj)
; #pragma unroll
;                     for (int n = 0; n < 2; ++n) *(f32x4*)(out + off + bj * HALF + 4 * n) = r[m][bj][n] + gv[bj][n] * acc[ai][bj][m][n]; } }
; template <class Epi, class Sched, bool ALIGN_EPI = false, bool SP2 = false>
; __device__ __forceinline__ void gemm_phase(PG8_LAS unsigned char* lds, const Gemm g, const Sched& S, const Epi& E) {
;     ...
;         if (!has_next) break;
; #pragma unroll
;         for (int a = 0; a < 2; ++a)
; #pragma unroll
;             for (int b = 0; b < 2; ++b)
; #pragma unroll
;                 for (int m = 0; m < 4; ++m)
; #pragma unroll
;                     for (int n = 0; n < 2; ++n) acc[a][b][m][n] = (f32x4){0.f, 0.f, 0.f, 0.f};
;         cur = nxt; cA = nA; cB = nB; ++ui;
;         if constexpr (ALIGN_EPI) { if (wr == 1) PG8_BAR; }
;     }
;     PG8_WAIT_V(0);
;     if constexpr (!ALIGN_EPI) { if (wr == 0) PG8_BAR; }
	v_lshl_add_u64 v[80:81], v[80:81], 0, v[144:145]
	v_pk_fma_f32 v[70:71], v[70:71], v[150:151], v[238:239]
	v_pk_fma_f32 v[74:75], v[86:87], v[158:159], v[230:231]
	v_pk_fma_f32 v[72:73], v[84:85], v[160:161], v[228:229]
	global_store_dwordx4 v[80:81], v[72:75], off
	v_pk_fma_f32 v[68:69], v[68:69], v[152:153], v[236:237]
	v_pk_fma_f32 v[66:67], v[66:67], v[146:147], v[242:243]
	v_pk_fma_f32 v[74:75], v[78:79], v[154:155], v[234:235]
	v_pk_fma_f32 v[72:73], v[76:77], v[156:157], v[232:233]
	v_pk_fma_f32 v[64:65], v[64:65], v[148:149], v[240:241]
	v_lshl_add_u64 v[172:173], v[164:165], 0, s[18:19]
	v_lshl_add_u64 v[174:175], v[164:165], 0, s[20:21]
	v_lshl_add_u64 v[176:177], v[164:165], 0, s[22:23]
	global_store_dwordx4 v[80:81], v[72:75], off offset:16
	global_store_dwordx4 v[80:81], v[68:71], off offset:512
	global_store_dwordx4 v[80:81], v[64:67], off offset:528
	v_lshl_add_u64 v[80:81], v[162:163], 0, v[172:173]
	v_lshl_add_u64 v[92:93], v[162:163], 0, v[174:175]
	v_lshl_add_u64 v[108:109], v[162:163], 0, v[176:177]
	global_load_dwordx4 v[64:67], v[80:81], off
	global_load_dwordx4 v[68:71], v[80:81], off offset:16
	global_load_dwordx4 v[72:75], v[80:81], off offset:512
	global_load_dwordx4 v[76:79], v[80:81], off offset:528
	s_nop 0
	global_load_dwordx4 v[80:83], v[92:93], off
	global_load_dwordx4 v[84:87], v[92:93], off offset:16
	global_load_dwordx4 v[88:91], v[92:93], off offset:512
	s_nop 0
	global_load_dwordx4 v[92:95], v[92:93], off offset:528
	s_nop 0
	global_load_dwordx4 v[96:99], v[108:109], off
	global_load_dwordx4 v[100:103], v[108:109], off offset:16
	global_load_dwordx4 v[104:107], v[108:109], off offset:512
	s_nop 0
	global_load_dwordx4 v[108:111], v[108:109], off offset:528
	v_lshl_add_u64 v[164:165], v[164:165], 0, s[12:13]
	v_lshl_add_u64 v[124:125], v[162:163], 0, v[164:165]
	global_load_dwordx4 v[112:115], v[124:125], off
	global_load_dwordx4 v[116:119], v[124:125], off offset:16
	global_load_dwordx4 v[120:123], v[124:125], off offset:512
	s_nop 0
	global_load_dwordx4 v[124:127], v[124:125], off offset:528
	v_lshl_add_u64 v[162:163], s[10:11], 0, v[172:173]
	v_lshl_add_u64 v[172:173], s[10:11], 0, v[174:175]
	v_lshl_add_u64 v[174:175], s[10:11], 0, v[176:177]
	v_lshl_add_u64 v[162:163], v[162:163], 0, v[144:145]
	v_lshl_add_u64 v[174:175], v[174:175], 0, v[144:145]
	v_lshl_add_u64 v[172:173], v[172:173], 0, v[144:145]
	s_waitcnt vmcnt(15)
	v_pk_fma_f32 v[62:63], v[62:63], v[158:159], v[66:67]
	v_pk_fma_f32 v[60:61], v[60:61], v[160:161], v[64:65]
	s_waitcnt vmcnt(14)
	v_pk_fma_f32 v[58:59], v[58:59], v[154:155], v[70:71]
	v_pk_fma_f32 v[56:57], v[56:57], v[156:157], v[68:69]
	s_waitcnt vmcnt(5)
	v_pk_fma_f32 v[18:19], v[18:19], v[150:151], v[106:107]
	v_pk_fma_f32 v[16:17], v[16:17], v[152:153], v[104:105]
	v_pk_fma_f32 v[42:43], v[42:43], v[150:151], v[74:75]
	v_pk_fma_f32 v[40:41], v[40:41], v[152:153], v[72:73]
	v_pk_fma_f32 v[38:39], v[38:39], v[146:147], v[78:79]
	v_pk_fma_f32 v[36:37], v[36:37], v[148:149], v[76:77]
	v_pk_fma_f32 v[54:55], v[54:55], v[158:159], v[82:83]
	v_pk_fma_f32 v[52:53], v[52:53], v[160:161], v[80:81]
	v_pk_fma_f32 v[50:51], v[50:51], v[154:155], v[86:87]
	v_pk_fma_f32 v[48:49], v[48:49], v[156:157], v[84:85]
	v_pk_fma_f32 v[30:31], v[30:31], v[150:151], v[90:91]
	v_pk_fma_f32 v[28:29], v[28:29], v[152:153], v[88:89]
	v_pk_fma_f32 v[26:27], v[26:27], v[146:147], v[94:95]
	v_pk_fma_f32 v[24:25], v[24:25], v[148:149], v[92:93]
	v_pk_fma_f32 v[46:47], v[46:47], v[158:159], v[98:99]
	v_pk_fma_f32 v[44:45], v[44:45], v[160:161], v[96:97]
	v_pk_fma_f32 v[34:35], v[34:35], v[154:155], v[102:103]
	v_pk_fma_f32 v[32:33], v[32:33], v[156:157], v[100:101]
	global_store_dwordx4 v[162:163], v[60:63], off
	global_store_dwordx4 v[162:163], v[56:59], off offset:16
	global_store_dwordx4 v[162:163], v[40:43], off offset:512
	global_store_dwordx4 v[162:163], v[36:39], off offset:528
	global_store_dwordx4 v[172:173], v[52:55], off
	global_store_dwordx4 v[172:173], v[48:51], off offset:16
	global_store_dwordx4 v[172:173], v[28:31], off offset:512
	global_store_dwordx4 v[172:173], v[24:27], off offset:528
	global_store_dwordx4 v[174:175], v[44:47], off
	global_store_dwordx4 v[174:175], v[32:35], off offset:16
	global_store_dwordx4 v[174:175], v[16:19], off offset:512
	s_waitcnt vmcnt(15)
	v_pk_fma_f32 v[10:11], v[10:11], v[146:147], v[110:111]
	v_pk_fma_f32 v[8:9], v[8:9], v[148:149], v[108:109]
	v_lshl_add_u64 v[16:17], s[10:11], 0, v[164:165]
	global_store_dwordx4 v[174:175], v[8:11], off offset:528
	v_lshl_add_u64 v[16:17], v[16:17], 0, v[144:145]
	s_waitcnt vmcnt(13)
	v_pk_fma_f32 v[6:7], v[6:7], v[150:151], v[122:123]
	v_pk_fma_f32 v[10:11], v[22:23], v[158:159], v[114:115]
	v_pk_fma_f32 v[8:9], v[20:21], v[160:161], v[112:113]
	global_store_dwordx4 v[16:17], v[8:11], off
	v_pk_fma_f32 v[4:5], v[4:5], v[152:153], v[120:121]
	s_waitcnt vmcnt(13)
	v_pk_fma_f32 v[2:3], v[2:3], v[146:147], v[126:127]
	v_pk_fma_f32 v[10:11], v[14:15], v[154:155], v[118:119]
	v_pk_fma_f32 v[8:9], v[12:13], v[156:157], v[116:117]
	v_pk_fma_f32 v[0:1], v[0:1], v[148:149], v[124:125]
	global_store_dwordx4 v[16:17], v[8:11], off offset:16
	global_store_dwordx4 v[16:17], v[4:7], off offset:512
	global_store_dwordx4 v[16:17], v[0:3], off offset:528
	s_cbranch_vccz .LBB0_1010
	s_waitcnt vmcnt(0)
	s_cmpk_gt_u32 s3, 0xff
	s_cbranch_scc1 .LBB0_1025
	s_barrier
